# hand-written attention item loops (all 3 dilation groups): contiguous K/V LDS rings with immediate ds offsets, bias+window-mask table, in-place softmax, no register rotation; plus lean grid barrier
# speedup vs baseline: 1.0275x; 1.0275x over previous
_Z8yoco_fwd6Params:
	s_load_dwordx8 s[36:43], s[0:1], 0x40
	s_load_dword s66, s[0:1], 0x68
	s_load_dwordx2 s[92:93], s[0:1], 0x60
	s_add_u32 s6, s0, 0x60
	v_and_b32_e32 v170, 0x3ff, v0
	s_mov_b32 s85, s2
	s_addc_u32 s7, s1, 0
	v_cmp_gt_u32_e32 vcc, 4, v170
	s_and_saveexec_b64 s[4:5], vcc
	v_lshl_add_u32 v1, v170, 2, 0
	v_add_u32_e32 v1, 0x20000, v1
	v_mov_b32_e32 v2, 0
	ds_write_b32 v1, v2
	s_or_b64 exec, exec, s[4:5]
	s_waitcnt lgkmcnt(0)
	s_mov_b32 s100, 0
	s_add_u32 s2, s42, 0xdc00000
	s_addc_u32 s3, s43, 0
	v_writelane_b32 v252, s2, 0
	s_barrier
	s_nop 0
	v_writelane_b32 v252, s3, 1
	s_getreg_b32 s2, hwreg(HW_REG_XCC_ID, 0, 4)
	v_cmp_eq_u32_e64 s[8:9], 0, v170
	s_mov_b64 s[4:5], exec
	s_nop 0
	v_writelane_b32 v252, s8, 2
	s_nop 1
	v_writelane_b32 v252, s9, 3
	s_and_b64 s[8:9], s[4:5], s[8:9]
	s_mov_b64 exec, s[8:9]
	s_cbranch_execz .LBB0_5
	s_mov_b64 s[8:9], exec
	v_mbcnt_lo_u32_b32 v1, s8, 0
	v_mbcnt_hi_u32_b32 v1, s9, v1
	v_cmp_eq_u32_e32 vcc, 0, v1
	s_and_b64 s[10:11], exec, vcc
	s_mov_b64 exec, s[10:11]
	s_cbranch_execz .LBB0_5
	s_lshl_b32 s2, s2, 8
	s_and_b32 s2, s2, 0xf00
	s_bcnt1_i32_b64 s3, s[8:9]
	v_mov_b32_e32 v1, s2
	v_mov_b32_e32 v2, s3
	v_readlane_b32 s2, v252, 0
	v_readlane_b32 s3, v252, 1
	s_nop 4
	global_atomic_add v1, v2, s[2:3] offset:1024

.LBB0_134:
	s_waitcnt vmcnt(0)
	s_barrier
	s_mov_b64 s[0:1], exec
	v_readlane_b32 s2, v252, 2
	v_readlane_b32 s3, v252, 3
	s_and_b64 s[2:3], s[0:1], s[2:3]
	s_mov_b64 exec, s[2:3]
	s_cbranch_execz .LBB0_186
	v_mov_b32_e32 v0, 0x20000
	ds_read_b64 v[0:1], v0
	s_getreg_b32 s44, hwreg(HW_REG_XCC_ID, 0, 4)
	s_lshl_b32 s44, s44, 7
	s_add_u32 s44, s44, 0xdc03600
	v_mov_b32_e32 v2, s44
	v_mov_b32_e32 v4, 1
	s_waitcnt vmcnt(0) lgkmcnt(0)
	global_atomic_add v5, v2, v4, s[42:43] sc0
	buffer_inv sc1
	s_add_u32 s100, s100, 1
	v_readfirstlane_b32 s46, v0
	v_readfirstlane_b32 s47, v1
	v_mov_b32_e32 v2, 0xdc03e00
	s_nop 3
	s_mul_i32 s48, s46, s100
	s_mul_i32 s49, s47, s100
	s_waitcnt vmcnt(1)
	v_readfirstlane_b32 s50, v5
	s_nop 3
	s_add_u32 s50, s50, 1
	s_cmp_lg_u32 s50, s48
	s_cbranch_scc1 .Lxb1_poll
	buffer_wbl2 sc1
	s_waitcnt vmcnt(0)
	global_atomic_add v2, v4, s[42:43]
.Lxb1_poll:
	s_mov_b32 s45, 0
.Lxb1_spin:
	global_load_dword v6, v2, s[42:43] sc1
	s_waitcnt vmcnt(0)
	v_readfirstlane_b32 s51, v6
	s_nop 3
	s_sub_u32 s51, s51, s49
	s_cmp_ge_i32 s51, 0
	s_cbranch_scc1 .Lxb1_done
	s_sleep 1
	s_add_u32 s45, s45, 1
	s_cmp_lt_u32 s45, 0x40000
	s_cbranch_scc1 .Lxb1_spin
.Lxb1_done:
	s_branch .LBB0_186
	s_add_i32 s3, 0, 0x20000
	v_mov_b32_e32 v0, s3
	s_getreg_b32 s2, hwreg(HW_REG_XCC_ID, 0, 4)
	s_waitcnt vmcnt(0) expcnt(0) lgkmcnt(0)
	ds_read_b32 v2, v0
	s_add_i32 s3, 0, 0x20004
	v_mov_b32_e32 v0, s3
	ds_read_b32 v0, v0
	s_and_b32 s2, s2, 15
	s_waitcnt lgkmcnt(1)
	v_cmp_ne_u32_e32 vcc, 0, v2
	s_cbranch_vccnz .LBB0_150
	s_add_u32 s4, s42, 0xdc00200
	s_addc_u32 s5, s43, 0
	s_add_u32 s6, s42, 0xdc00400
	s_addc_u32 s7, s43, 0
	s_add_u32 s12, s42, 0xdc00500
	s_addc_u32 s13, s43, 0
	s_add_u32 s18, s42, 0xdc00600
	s_addc_u32 s19, s43, 0
	s_add_u32 s20, s42, 0xdc00700
	s_addc_u32 s21, s43, 0
	s_add_u32 s22, s42, 0xdc00800
	s_addc_u32 s23, s43, 0
	s_add_u32 s24, s42, 0xdc00900
	s_addc_u32 s25, s43, 0
	s_add_u32 s26, s42, 0xdc00a00
	s_addc_u32 s27, s43, 0
	s_add_u32 s30, s42, 0xdc00b00
	s_addc_u32 s31, s43, 0
	s_add_u32 s34, s42, 0xdc00c00
	s_addc_u32 s35, s43, 0
	s_add_u32 s44, s42, 0xdc00d00
	s_addc_u32 s45, s43, 0
	s_add_u32 s46, s42, 0xdc00e00
	s_addc_u32 s47, s43, 0
	s_add_u32 s48, s42, 0xdc00f00
	s_addc_u32 s49, s43, 0
	s_add_u32 s50, s42, 0xdc01000
	s_addc_u32 s51, s43, 0
	s_add_u32 s52, s42, 0xdc01100
	s_addc_u32 s53, s43, 0
	s_add_u32 s54, s42, 0xdc01200
	s_addc_u32 s55, s43, 0
	s_mul_i32 s3, s93, s66
	s_add_u32 s56, s42, 0xdc01300
	s_mul_i32 s3, s3, s92
	s_addc_u32 s57, s43, 0
	s_mov_b32 s14, 1
	v_mov_b32_e32 v16, 0
	s_branch .LBB0_138

.LBB0_150:
	s_mov_b64 s[6:7], exec
	s_lshl_b32 s2, s2, 8
	v_readlane_b32 s4, v252, 0
	v_mbcnt_lo_u32_b32 v1, s6, 0
	v_readlane_b32 s5, v252, 1
	s_add_u32 s4, s4, s2
	v_mbcnt_hi_u32_b32 v1, s7, v1
	s_addc_u32 s5, s5, 0
	v_cmp_eq_u32_e32 vcc, 0, v1
	s_and_saveexec_b64 s[12:13], vcc
	s_cbranch_execz .LBB0_152
	s_bcnt1_i32_b64 s2, s[6:7]
	v_mov_b32_e32 v3, 0x1000
	v_mov_b32_e32 v4, s2
	global_atomic_add v3, v3, v4, s[4:5] offset:1024 sc0
.LBB0_152:
	s_or_b64 exec, exec, s[12:13]
	v_cvt_f32_u32_e32 v4, v2
	s_waitcnt vmcnt(0)
	v_readfirstlane_b32 s2, v3
	v_sub_u32_e32 v3, 0, v2
	v_rcp_iflag_f32_e32 v4, v4
	v_add_u32_e32 v5, s2, v1
	v_mul_f32_e32 v4, 0x4f7ffffe, v4
	v_cvt_u32_f32_e32 v4, v4
	v_mul_lo_u32 v1, v3, v4
	v_mul_hi_u32 v1, v4, v1
	v_add_u32_e32 v1, v4, v1
	v_mul_hi_u32 v1, v5, v1
	v_mul_lo_u32 v3, v1, v2
	v_sub_u32_e32 v3, v5, v3
	v_add_u32_e32 v4, 1, v1
	v_cmp_ge_u32_e32 vcc, v3, v2
	s_nop 1
	v_cndmask_b32_e32 v1, v1, v4, vcc
	v_sub_u32_e32 v4, v3, v2
	v_cndmask_b32_e32 v3, v3, v4, vcc
	v_add_u32_e32 v4, 1, v1
	v_cmp_ge_u32_e32 vcc, v3, v2
	v_add_u32_e32 v3, 1, v5
	s_nop 0
	v_cndmask_b32_e32 v1, v1, v4, vcc
	v_mul_lo_u32 v4, v2, v1
	v_add_u32_e32 v2, v4, v2
	v_cmp_ne_u32_e32 vcc, v3, v2
	s_and_saveexec_b64 s[2:3], vcc
	s_xor_b64 s[6:7], exec, s[2:3]
	s_cbranch_execz .LBB0_166
	s_waitcnt lgkmcnt(0)
	v_mov_b32_e32 v0, 0x2000
	global_load_dword v0, v0, s[4:5] offset:1024 sc1
	s_add_u32 s20, s4, 0x2400
	s_addc_u32 s21, s5, 0
	s_waitcnt vmcnt(0)
	v_cmp_eq_u32_e32 vcc, v0, v1
	s_and_saveexec_b64 s[12:13], vcc
	s_cbranch_execz .LBB0_165
	s_add_u32 s18, s42, 0xdc00200
	s_addc_u32 s19, s43, 0
	s_mov_b32 s2, 1
	s_mov_b64 s[22:23], 0
	v_mov_b32_e32 v0, 0
	s_branch .LBB0_156

.LBB0_165:
	s_or_b64 exec, exec, s[12:13]
	s_waitcnt vmcnt(0)
	buffer_inv sc1
	s_waitcnt vmcnt(0)

.LBB0_183:
	s_or_b64 exec, exec, s[6:7]
	s_mov_b64 s[6:7], exec
	v_mbcnt_lo_u32_b32 v0, s6, 0
	v_mbcnt_hi_u32_b32 v0, s7, v0
	v_cmp_eq_u32_e32 vcc, 0, v0
	s_waitcnt vmcnt(0)
	buffer_inv sc1
	s_and_saveexec_b64 s[12:13], vcc
	s_cbranch_execz .LBB0_185
	s_bcnt1_i32_b64 s2, s[6:7]
	v_mov_b32_e32 v0, 0x2000
	v_mov_b32_e32 v1, s2
	global_atomic_add v0, v1, s[4:5] offset:1024

.LBB0_241:
	s_waitcnt vmcnt(0)
	v_readlane_b32 s2, v252, 2
	v_readlane_b32 s3, v252, 3
	s_waitcnt vmcnt(0)
	s_barrier
	s_and_saveexec_b64 s[4:5], s[2:3]
	s_cbranch_execz .LBB0_293
	v_mov_b32_e32 v0, 0x20000
	ds_read_b64 v[0:1], v0
	s_getreg_b32 s44, hwreg(HW_REG_XCC_ID, 0, 4)
	s_lshl_b32 s44, s44, 7
	s_add_u32 s44, s44, 0xdc03600
	v_mov_b32_e32 v2, s44
	v_mov_b32_e32 v4, 1
	s_waitcnt vmcnt(0) lgkmcnt(0)
	global_atomic_add v5, v2, v4, s[42:43] sc0
	buffer_inv sc1
	s_add_u32 s100, s100, 1
	v_readfirstlane_b32 s46, v0
	v_readfirstlane_b32 s47, v1
	v_mov_b32_e32 v2, 0xdc03e00
	s_nop 3
	s_mul_i32 s48, s46, s100
	s_mul_i32 s49, s47, s100
	s_waitcnt vmcnt(1)
	v_readfirstlane_b32 s50, v5
	s_nop 3
	s_add_u32 s50, s50, 1
	s_cmp_lg_u32 s50, s48
	s_cbranch_scc1 .Lxb2_poll
	buffer_wbl2 sc1
	s_waitcnt vmcnt(0)
	global_atomic_add v2, v4, s[42:43]

.Lxb2_done:
	s_branch .LBB0_293
	v_mov_b32_e32 v0, s68
	s_getreg_b32 s2, hwreg(HW_REG_XCC_ID, 0, 4)
	s_waitcnt vmcnt(0) expcnt(0) lgkmcnt(0)
	ds_read_b32 v2, v0
	v_mov_b32_e32 v0, s69
	ds_read_b32 v0, v0
	s_and_b32 s2, s2, 15
	s_waitcnt lgkmcnt(1)
	v_cmp_ne_u32_e32 vcc, 0, v2
	s_cbranch_vccnz .LBB0_257
	s_mov_b32 s12, 1
	s_branch .LBB0_245

.LBB0_257:
	s_mov_b64 s[44:45], exec
	s_lshl_b32 s2, s2, 8
	v_readlane_b32 s6, v252, 0
	v_mbcnt_lo_u32_b32 v1, s44, 0
	v_readlane_b32 s7, v252, 1
	s_add_u32 s6, s6, s2
	v_mbcnt_hi_u32_b32 v1, s45, v1
	s_addc_u32 s7, s7, 0
	v_cmp_eq_u32_e32 vcc, 0, v1
	s_and_saveexec_b64 s[46:47], vcc
	s_cbranch_execz .LBB0_259
	s_bcnt1_i32_b64 s2, s[44:45]
	v_mov_b32_e32 v4, s2
	global_atomic_add v4, v168, v4, s[6:7] offset:1024 sc0
.LBB0_259:
	s_or_b64 exec, exec, s[46:47]
	v_cvt_f32_u32_e32 v5, v2
	s_waitcnt vmcnt(0)
	v_readfirstlane_b32 s2, v4
	v_sub_u32_e32 v4, 0, v2
	v_rcp_iflag_f32_e32 v5, v5
	v_add_u32_e32 v6, s2, v1
	v_mul_f32_e32 v5, 0x4f7ffffe, v5
	v_cvt_u32_f32_e32 v5, v5
	v_mul_lo_u32 v1, v4, v5
	v_mul_hi_u32 v1, v5, v1
	v_add_u32_e32 v1, v5, v1
	v_mul_hi_u32 v1, v6, v1
	v_mul_lo_u32 v4, v1, v2
	v_sub_u32_e32 v4, v6, v4
	v_add_u32_e32 v5, 1, v1
	v_cmp_ge_u32_e32 vcc, v4, v2
	s_nop 1
	v_cndmask_b32_e32 v1, v1, v5, vcc
	v_sub_u32_e32 v5, v4, v2
	v_cndmask_b32_e32 v4, v4, v5, vcc
	v_add_u32_e32 v5, 1, v1
	v_cmp_ge_u32_e32 vcc, v4, v2
	v_add_u32_e32 v4, 1, v6
	s_nop 0
	v_cndmask_b32_e32 v1, v1, v5, vcc
	v_mul_lo_u32 v5, v2, v1
	v_add_u32_e32 v2, v5, v2
	v_cmp_ne_u32_e32 vcc, v4, v2
	s_and_saveexec_b64 s[12:13], vcc
	s_xor_b64 s[44:45], exec, s[12:13]
	s_cbranch_execz .LBB0_273
	s_waitcnt lgkmcnt(0)
	global_load_dword v0, v169, s[6:7] offset:1024 sc1
	s_add_u32 s48, s6, 0x2400
	s_addc_u32 s49, s7, 0
	s_waitcnt vmcnt(0)
	v_cmp_eq_u32_e32 vcc, v0, v1
	s_and_saveexec_b64 s[46:47], vcc
	s_cbranch_execz .LBB0_272
	s_mov_b32 s2, 1
	s_mov_b64 s[50:51], 0
	s_branch .LBB0_263

.LBB0_272:
	s_or_b64 exec, exec, s[46:47]
	s_waitcnt vmcnt(0)
	buffer_inv sc1
	s_waitcnt vmcnt(0)

.LBB0_290:
	s_or_b64 exec, exec, s[44:45]
	s_mov_b64 s[44:45], exec
	v_mbcnt_lo_u32_b32 v0, s44, 0
	v_mbcnt_hi_u32_b32 v0, s45, v0
	v_cmp_eq_u32_e32 vcc, 0, v0
	s_waitcnt vmcnt(0)
	buffer_inv sc1
	s_and_saveexec_b64 s[46:47], vcc
	s_cbranch_execz .LBB0_292
	s_bcnt1_i32_b64 s2, s[44:45]
	v_mov_b32_e32 v0, s2
	global_atomic_add v169, v0, s[6:7] offset:1024

.LBB0_362:
	s_or_b64 exec, exec, s[0:1]
	s_waitcnt vmcnt(0)
	v_readlane_b32 s2, v252, 2
	v_readlane_b32 s3, v252, 3
	s_barrier
	s_and_saveexec_b64 s[0:1], s[2:3]
	s_cbranch_execz .LBB0_414
	v_mov_b32_e32 v0, 0x20000
	ds_read_b64 v[0:1], v0
	s_getreg_b32 s44, hwreg(HW_REG_XCC_ID, 0, 4)
	s_lshl_b32 s44, s44, 7
	s_add_u32 s44, s44, 0xdc03600
	v_mov_b32_e32 v2, s44
	v_mov_b32_e32 v4, 1
	s_waitcnt vmcnt(0) lgkmcnt(0)
	global_atomic_add v5, v2, v4, s[42:43] sc0
	buffer_inv sc1
	s_add_u32 s100, s100, 1
	v_readfirstlane_b32 s46, v0
	v_readfirstlane_b32 s47, v1
	v_mov_b32_e32 v2, 0xdc03e00
	s_nop 3
	s_mul_i32 s48, s46, s100
	s_mul_i32 s49, s47, s100
	s_waitcnt vmcnt(1)
	v_readfirstlane_b32 s50, v5
	s_nop 3
	s_add_u32 s50, s50, 1
	s_cmp_lg_u32 s50, s48
	s_cbranch_scc1 .Lxb3_poll
	buffer_wbl2 sc1
	s_waitcnt vmcnt(0)
	global_atomic_add v2, v4, s[42:43]

.LBB0_378:
	s_mov_b64 s[6:7], exec
	s_lshl_b32 s2, s2, 8
	v_readlane_b32 s4, v252, 0
	v_mbcnt_lo_u32_b32 v1, s6, 0
	v_readlane_b32 s5, v252, 1
	s_add_u32 s4, s4, s2
	v_mbcnt_hi_u32_b32 v1, s7, v1
	s_addc_u32 s5, s5, 0
	v_cmp_eq_u32_e32 vcc, 0, v1
	s_and_saveexec_b64 s[44:45], vcc
	s_cbranch_execz .LBB0_380
	s_bcnt1_i32_b64 s2, s[6:7]
	v_mov_b32_e32 v4, s2
	global_atomic_add v4, v168, v4, s[4:5] offset:1024 sc0
.LBB0_380:
	s_or_b64 exec, exec, s[44:45]
	v_cvt_f32_u32_e32 v5, v2
	s_waitcnt vmcnt(0)
	v_readfirstlane_b32 s2, v4
	v_sub_u32_e32 v4, 0, v2
	v_rcp_iflag_f32_e32 v5, v5
	v_add_u32_e32 v6, s2, v1
	v_mul_f32_e32 v5, 0x4f7ffffe, v5
	v_cvt_u32_f32_e32 v5, v5
	v_mul_lo_u32 v1, v4, v5
	v_mul_hi_u32 v1, v5, v1
	v_add_u32_e32 v1, v5, v1
	v_mul_hi_u32 v1, v6, v1
	v_mul_lo_u32 v4, v1, v2
	v_sub_u32_e32 v4, v6, v4
	v_add_u32_e32 v5, 1, v1
	v_cmp_ge_u32_e32 vcc, v4, v2
	s_nop 1
	v_cndmask_b32_e32 v1, v1, v5, vcc
	v_sub_u32_e32 v5, v4, v2
	v_cndmask_b32_e32 v4, v4, v5, vcc
	v_add_u32_e32 v5, 1, v1
	v_cmp_ge_u32_e32 vcc, v4, v2
	v_add_u32_e32 v4, 1, v6
	s_nop 0
	v_cndmask_b32_e32 v1, v1, v5, vcc
	v_mul_lo_u32 v5, v2, v1
	v_add_u32_e32 v2, v5, v2
	v_cmp_ne_u32_e32 vcc, v4, v2
	s_and_saveexec_b64 s[6:7], vcc
	s_xor_b64 s[6:7], exec, s[6:7]
	s_cbranch_execz .LBB0_394
	s_waitcnt lgkmcnt(0)
	global_load_dword v0, v169, s[4:5] offset:1024 sc1
	s_add_u32 s46, s4, 0x2400
	s_addc_u32 s47, s5, 0
	s_waitcnt vmcnt(0)
	v_cmp_eq_u32_e32 vcc, v0, v1
	s_and_saveexec_b64 s[44:45], vcc
	s_cbranch_execz .LBB0_393
	s_mov_b32 s2, 1
	s_mov_b64 s[48:49], 0
	s_branch .LBB0_384

.LBB0_393:
	s_or_b64 exec, exec, s[44:45]
	s_waitcnt vmcnt(0)
	buffer_inv sc1
	s_waitcnt vmcnt(0)

.LBB0_411:
	s_or_b64 exec, exec, s[6:7]
	s_mov_b64 s[6:7], exec
	v_mbcnt_lo_u32_b32 v0, s6, 0
	v_mbcnt_hi_u32_b32 v0, s7, v0
	v_cmp_eq_u32_e32 vcc, 0, v0
	s_waitcnt vmcnt(0)
	buffer_inv sc1
	s_and_saveexec_b64 s[44:45], vcc
	s_cbranch_execz .LBB0_413
	s_bcnt1_i32_b64 s2, s[6:7]
	v_mov_b32_e32 v0, s2
	global_atomic_add v169, v0, s[4:5] offset:1024

.LBB0_495:
	s_waitcnt vmcnt(0)
	s_waitcnt lgkmcnt(0)
	s_barrier
	s_mov_b64 s[0:1], exec
	v_readlane_b32 s2, v252, 2
	v_readlane_b32 s3, v252, 3
	s_and_b64 s[2:3], s[0:1], s[2:3]
	v_readlane_b32 s13, v253, 17
	s_mov_b64 exec, s[2:3]
	s_cbranch_execz .LBB0_188
	v_mov_b32_e32 v0, 0x20000
	ds_read_b64 v[0:1], v0
	s_getreg_b32 s44, hwreg(HW_REG_XCC_ID, 0, 4)
	s_lshl_b32 s44, s44, 7
	s_add_u32 s44, s44, 0xdc03600
	v_mov_b32_e32 v2, s44
	v_mov_b32_e32 v4, 1
	s_waitcnt vmcnt(0) lgkmcnt(0)
	global_atomic_add v5, v2, v4, s[42:43] sc0
	buffer_inv sc1
	s_add_u32 s100, s100, 1
	v_readfirstlane_b32 s46, v0
	v_readfirstlane_b32 s47, v1
	v_mov_b32_e32 v2, 0xdc03e00
	s_nop 3
	s_mul_i32 s48, s46, s100
	s_mul_i32 s49, s47, s100
	s_waitcnt vmcnt(1)
	v_readfirstlane_b32 s50, v5
	s_nop 3
	s_add_u32 s50, s50, 1
	s_cmp_lg_u32 s50, s48
	s_cbranch_scc1 .Lxb4_poll
	buffer_wbl2 sc1
	s_waitcnt vmcnt(0)
	global_atomic_add v2, v4, s[42:43]

.LBB0_541:
	s_mov_b64 s[6:7], exec
	s_lshl_b32 s2, s2, 8
	v_readlane_b32 s4, v252, 0
	v_mbcnt_lo_u32_b32 v1, s6, 0
	v_readlane_b32 s5, v252, 1
	s_add_u32 s4, s4, s2
	v_mbcnt_hi_u32_b32 v1, s7, v1
	s_addc_u32 s5, s5, 0
	v_cmp_eq_u32_e32 vcc, 0, v1
	s_and_saveexec_b64 s[44:45], vcc
	s_cbranch_execz .LBB0_543
	s_bcnt1_i32_b64 s2, s[6:7]
	v_mov_b32_e32 v4, s2
	global_atomic_add v4, v168, v4, s[4:5] offset:1024 sc0
.LBB0_543:
	s_or_b64 exec, exec, s[44:45]
	v_cvt_f32_u32_e32 v5, v2
	s_waitcnt vmcnt(0)
	v_readfirstlane_b32 s2, v4
	v_sub_u32_e32 v4, 0, v2
	v_rcp_iflag_f32_e32 v5, v5
	v_add_u32_e32 v6, s2, v1
	v_mul_f32_e32 v5, 0x4f7ffffe, v5
	v_cvt_u32_f32_e32 v5, v5
	v_mul_lo_u32 v1, v4, v5
	v_mul_hi_u32 v1, v5, v1
	v_add_u32_e32 v1, v5, v1
	v_mul_hi_u32 v1, v6, v1
	v_mul_lo_u32 v4, v1, v2
	v_sub_u32_e32 v4, v6, v4
	v_add_u32_e32 v5, 1, v1
	v_cmp_ge_u32_e32 vcc, v4, v2
	s_nop 1
	v_cndmask_b32_e32 v1, v1, v5, vcc
	v_sub_u32_e32 v5, v4, v2
	v_cndmask_b32_e32 v4, v4, v5, vcc
	v_add_u32_e32 v5, 1, v1
	v_cmp_ge_u32_e32 vcc, v4, v2
	v_add_u32_e32 v4, 1, v6
	s_nop 0
	v_cndmask_b32_e32 v1, v1, v5, vcc
	v_mul_lo_u32 v5, v2, v1
	v_add_u32_e32 v2, v5, v2
	v_cmp_ne_u32_e32 vcc, v4, v2
	s_and_saveexec_b64 s[2:3], vcc
	s_xor_b64 s[6:7], exec, s[2:3]
	s_cbranch_execz .LBB0_561
	s_waitcnt lgkmcnt(0)
	global_load_dword v0, v169, s[4:5] offset:1024 sc1
	s_add_u32 s46, s4, 0x2400
	s_addc_u32 s47, s5, 0
	s_waitcnt vmcnt(0)
	v_cmp_eq_u32_e32 vcc, v0, v1
	s_and_saveexec_b64 s[44:45], vcc
	s_cbranch_execz .LBB0_560
	s_mov_b32 s2, 1
	s_mov_b64 s[48:49], 0
	s_branch .LBB0_547

.LBB0_578:
	s_or_b64 exec, exec, s[6:7]
	s_mov_b64 s[6:7], exec
	v_mbcnt_lo_u32_b32 v0, s6, 0
	v_mbcnt_hi_u32_b32 v0, s7, v0
	v_cmp_eq_u32_e32 vcc, 0, v0
	s_waitcnt vmcnt(0)
	buffer_inv sc1
	s_and_saveexec_b64 s[44:45], vcc
	s_cbranch_execz .LBB0_187
	s_bcnt1_i32_b64 s2, s[6:7]
	v_mov_b32_e32 v0, s2
	global_atomic_add v169, v0, s[4:5] offset:1024
	s_branch .LBB0_187

.LBB0_682:
	s_waitcnt vmcnt(0)
	s_waitcnt vmcnt(0) lgkmcnt(0)
	s_barrier
	s_mov_b64 s[6:7], exec
	v_readlane_b32 s0, v252, 2
	v_readlane_b32 s1, v252, 3
	s_and_b64 s[0:1], s[6:7], s[0:1]
	s_mov_b64 exec, s[0:1]
	s_cbranch_execz .LBB0_734
	v_mov_b32_e32 v0, 0x20000
	ds_read_b64 v[0:1], v0
	s_getreg_b32 s44, hwreg(HW_REG_XCC_ID, 0, 4)
	s_lshl_b32 s44, s44, 7
	s_add_u32 s44, s44, 0xdc03600
	v_mov_b32_e32 v2, s44
	v_mov_b32_e32 v4, 1
	s_waitcnt vmcnt(0) lgkmcnt(0)
	global_atomic_add v5, v2, v4, s[42:43] sc0
	buffer_inv sc1
	s_add_u32 s100, s100, 1
	v_readfirstlane_b32 s46, v0
	v_readfirstlane_b32 s47, v1
	v_mov_b32_e32 v2, 0xdc03e00
	s_nop 3
	s_mul_i32 s48, s46, s100
	s_mul_i32 s49, s47, s100
	s_waitcnt vmcnt(1)
	v_readfirstlane_b32 s50, v5
	s_nop 3
	s_add_u32 s50, s50, 1
	s_cmp_lg_u32 s50, s48
	s_cbranch_scc1 .Lxb5_poll
	buffer_wbl2 sc1
	s_waitcnt vmcnt(0)
	global_atomic_add v2, v4, s[42:43]

.Lxb5_done:
	s_branch .LBB0_734
	v_readlane_b32 s1, v254, 46
	s_getreg_b32 s0, hwreg(HW_REG_XCC_ID, 0, 4)
	s_waitcnt vmcnt(0) expcnt(0) lgkmcnt(0)
	v_mov_b32_e32 v0, s1
	ds_read_b32 v2, v0
	v_readlane_b32 s1, v254, 47
	s_and_b32 s0, s0, 15
	s_waitcnt lgkmcnt(0)
	v_cmp_ne_u32_e32 vcc, 0, v2
	v_mov_b32_e32 v0, s1
	ds_read_b32 v0, v0
	s_cbranch_vccnz .LBB0_698
	s_mov_b32 s1, 1
	s_branch .LBB0_686

.LBB0_698:
	s_mov_b64 s[44:45], exec
	s_lshl_b32 s0, s0, 8
	v_readlane_b32 s2, v252, 0
	v_mbcnt_lo_u32_b32 v1, s44, 0
	v_readlane_b32 s3, v252, 1
	s_add_u32 s8, s2, s0
	v_mbcnt_hi_u32_b32 v1, s45, v1
	s_addc_u32 s9, s3, 0
	v_cmp_eq_u32_e32 vcc, 0, v1
	s_and_saveexec_b64 s[46:47], vcc
	s_cbranch_execz .LBB0_700
	s_bcnt1_i32_b64 s0, s[44:45]
	v_mov_b32_e32 v4, s0
	v_mov_b32_e32 v5, 0x1000
	global_atomic_add v4, v5, v4, s[8:9] offset:1024 sc0
.LBB0_700:
	s_or_b64 exec, exec, s[46:47]
	v_cvt_f32_u32_e32 v5, v2
	s_waitcnt vmcnt(0)
	v_readfirstlane_b32 s0, v4
	v_sub_u32_e32 v4, 0, v2
	v_rcp_iflag_f32_e32 v5, v5
	v_add_u32_e32 v6, s0, v1
	v_mul_f32_e32 v5, 0x4f7ffffe, v5
	v_cvt_u32_f32_e32 v5, v5
	v_mul_lo_u32 v1, v4, v5
	v_mul_hi_u32 v1, v5, v1
	v_add_u32_e32 v1, v5, v1
	v_mul_hi_u32 v1, v6, v1
	v_mul_lo_u32 v4, v1, v2
	v_sub_u32_e32 v4, v6, v4
	v_add_u32_e32 v5, 1, v1
	v_cmp_ge_u32_e32 vcc, v4, v2
	s_nop 1
	v_cndmask_b32_e32 v1, v1, v5, vcc
	v_sub_u32_e32 v5, v4, v2
	v_cndmask_b32_e32 v4, v4, v5, vcc
	v_add_u32_e32 v5, 1, v1
	v_cmp_ge_u32_e32 vcc, v4, v2
	v_add_u32_e32 v4, 1, v6
	s_nop 0
	v_cndmask_b32_e32 v1, v1, v5, vcc
	v_mul_lo_u32 v5, v2, v1
	v_add_u32_e32 v2, v5, v2
	v_cmp_ne_u32_e32 vcc, v4, v2
	s_and_saveexec_b64 s[0:1], vcc
	s_xor_b64 s[44:45], exec, s[0:1]
	s_cbranch_execz .LBB0_714
	s_waitcnt lgkmcnt(0)
	global_load_dword v0, v182, s[8:9] offset:1024 sc1
	s_add_u32 s48, s8, 0x2400
	s_addc_u32 s49, s9, 0
	s_waitcnt vmcnt(0)
	v_cmp_eq_u32_e32 vcc, v0, v1
	s_and_saveexec_b64 s[46:47], vcc
	s_cbranch_execz .LBB0_713
	s_mov_b32 s0, 1
	s_mov_b64 s[50:51], 0
	s_branch .LBB0_704

.LBB0_731:
	s_or_b64 exec, exec, s[44:45]
	s_mov_b64 s[44:45], exec
	v_mbcnt_lo_u32_b32 v0, s44, 0
	v_mbcnt_hi_u32_b32 v0, s45, v0
	v_cmp_eq_u32_e32 vcc, 0, v0
	s_waitcnt vmcnt(0)
	buffer_inv sc1
	s_and_saveexec_b64 s[46:47], vcc
	s_cbranch_execz .LBB0_733
	s_bcnt1_i32_b64 s0, s[44:45]
	v_mov_b32_e32 v0, s0
	global_atomic_add v182, v0, s[8:9] offset:1024

.LBB0_738:
	s_waitcnt vmcnt(0) lgkmcnt(0)
	s_mov_b32 s79, 0x3e38aa3b
	s_mov_b32 s77, 0xc000
	s_mov_b32 s78, 0xffffc000
	v_readlane_b32 s1, v253, 23
	v_readfirstlane_b32 s0, v170
	s_nop 3
	s_lshr_b32 s0, s0, 6
	s_and_b32 s74, s1, 7
	s_lshl_b32 s74, s74, 5
	s_lshr_b32 s75, s1, 3
	s_add_u32 s74, s74, s75
	s_lshl_b32 s74, s74, 3
	s_and_b32 s4, s74, 31
	s_lshr_b32 s75, s74, 5
	s_and_b32 s5, s75, 0
	s_lshr_b32 s75, s75, 0
	s_and_b32 s3, s75, 3
	s_lshr_b32 s2, s75, 2
	s_sub_u32 s6, 8, s0
	s_lshl_b32 s70, s0, 10
	s_lshl_b32 s74, s2, 21
	s_lshl_b32 s75, s3, 19
	s_add_u32 s74, s74, s75
	s_add_u32 s34, s40, s74
	s_addc_u32 s35, s41, 0
	s_mov_b32 s30, s34
	s_mov_b32 s31, s35
	s_lshl_b32 s74, s2, 16
	s_lshl_b32 s75, s3, 14
	s_add_u32 s74, s74, s75
	s_add_u32 s74, s74, 0xc000000
	s_add_u32 s58, s42, s74
	s_addc_u32 s59, s43, 0
	s_add_u32 s74, s2, 0
	s_lshl_b32 s74, s74, 2
	s_add_u32 s74, s74, s3
	s_lshl_b32 s74, s74, 19
	s_add_u32 s60, s42, s74
	s_addc_u32 s61, s43, 0
	s_lshl_b32 s74, s2, 6
	s_add_u32 s74, s74, 0
	s_lshl_b32 s74, s74, 15
	s_lshl_b32 s75, s3, 13
	s_add_u32 s74, s74, s75
	s_add_u32 s74, s74, 0x6000000
	s_add_u32 s64, s42, s74
	s_addc_u32 s65, s43, 0
	v_and_b32_e32 v141, 63, v170
	v_and_b32_e32 v241, 15, v141
	v_lshrrev_b32_e32 v242, 4, v141
	v_mov_b32_e32 v244, 0xf149f2ca
	v_mov_b32_e32 v248, 0
	v_mov_b32_e32 v249, 0
	v_lshrrev_b32_e32 v142, 1, v241
	v_xor_b32_e32 v142, v142, v242
	v_lshlrev_b32_e32 v142, 4, v142
	v_lshl_add_u32 v142, v241, 7, v142
	s_lshl_b32 s74, s0, 11
	v_add_u32_e32 v230, s74, v142
	v_xor_b32_e32 v231, 64, v230
	v_lshrrev_b32_e32 v142, 1, v242
	v_xor_b32_e32 v243, v142, v241
	v_and_b32_e32 v142, 1, v242
	v_lshlrev_b32_e32 v142, 3, v142
	v_lshl_add_u32 v142, v241, 8, v142
	v_add_u32_e32 v142, 0x10000, v142
	s_add_u32 s74, s0, 0
	s_and_b32 s75, s74, 7
	s_lshl_b32 s75, s75, 1
	s_lshr_b32 s74, s74, 3
	s_lshl_b32 s74, s74, 14
	v_xor_b32_e32 v143, s75, v243
	v_lshl_add_u32 v143, v143, 4, v142
	v_add_u32_e32 v221, s74, v143
	s_add_u32 s74, s0, 1
	s_and_b32 s75, s74, 7
	s_lshl_b32 s75, s75, 1
	s_lshr_b32 s74, s74, 3
	s_lshl_b32 s74, s74, 14
	v_xor_b32_e32 v143, s75, v243
	v_lshl_add_u32 v143, v143, 4, v142
	v_add_u32_e32 v222, s74, v143
	s_add_u32 s74, s0, 2
	s_and_b32 s75, s74, 7
	s_lshl_b32 s75, s75, 1
	s_lshr_b32 s74, s74, 3
	s_lshl_b32 s74, s74, 14
	v_xor_b32_e32 v143, s75, v243
	v_lshl_add_u32 v143, v143, 4, v142
	v_add_u32_e32 v223, s74, v143
	s_add_u32 s74, s0, 3
	s_and_b32 s75, s74, 7
	s_lshl_b32 s75, s75, 1
	s_lshr_b32 s74, s74, 3
	s_lshl_b32 s74, s74, 14
	v_xor_b32_e32 v143, s75, v243
	v_lshl_add_u32 v143, v143, 4, v142
	v_add_u32_e32 v224, s74, v143
	s_add_u32 s74, s0, 4
	s_and_b32 s75, s74, 7
	s_lshl_b32 s75, s75, 1
	s_lshr_b32 s74, s74, 3
	s_lshl_b32 s74, s74, 14
	v_xor_b32_e32 v143, s75, v243
	v_lshl_add_u32 v143, v143, 4, v142
	v_add_u32_e32 v225, s74, v143
	s_add_u32 s74, s0, 5
	s_and_b32 s75, s74, 7
	s_lshl_b32 s75, s75, 1
	s_lshr_b32 s74, s74, 3
	s_lshl_b32 s74, s74, 14
	v_xor_b32_e32 v143, s75, v243
	v_lshl_add_u32 v143, v143, 4, v142
	v_add_u32_e32 v226, s74, v143
	s_add_u32 s74, s0, 6
	s_and_b32 s75, s74, 7
	s_lshl_b32 s75, s75, 1
	s_lshr_b32 s74, s74, 3
	s_lshl_b32 s74, s74, 14
	v_xor_b32_e32 v143, s75, v243
	v_lshl_add_u32 v143, v143, 4, v142
	v_add_u32_e32 v227, s74, v143
	s_add_u32 s74, s0, 7
	s_and_b32 s75, s74, 7
	s_lshl_b32 s75, s75, 1
	s_lshr_b32 s74, s74, 3
	s_lshl_b32 s74, s74, 14
	v_xor_b32_e32 v143, s75, v243
	v_lshl_add_u32 v143, v143, 4, v142
	v_add_u32_e32 v228, s74, v143
	s_add_u32 s74, s0, 8
	s_and_b32 s75, s74, 7
	s_lshl_b32 s75, s75, 1
	s_lshr_b32 s74, s74, 3
	s_lshl_b32 s74, s74, 14
	v_xor_b32_e32 v143, s75, v243
	v_lshl_add_u32 v143, v143, 4, v142
	v_add_u32_e32 v229, s74, v143
	s_and_b32 s74, s0, 1
	s_lshl_b32 s74, s74, 2
	v_add_u32_e32 v142, s74, v242
	v_and_b32_e32 v143, 7, v141
	v_xor_b32_e32 v142, v142, v143
	v_lshlrev_b32_e32 v142, 4, v142
	v_lshrrev_b32_e32 v143, 3, v141
	s_lshl_b32 s74, s0, 3
	v_add_u32_e32 v143, s74, v143
	v_lshl_add_u32 v232, v143, 7, v142
	v_add_u32_e32 v233, 0x2000, v232
	s_and_b32 s74, s0, 3
	s_lshl_b32 s74, s74, 2
	v_add_u32_e32 v142, s74, v242
	v_xor_b32_e32 v142, v142, v241
	v_lshlrev_b32_e32 v142, 4, v142
	s_lshl_b32 s74, s0, 2
	v_add_u32_e32 v143, s74, v242
	v_lshl_add_u32 v234, v143, 15, v142
	v_add_u32_e32 v235, 0x100000, v234
	s_lshl_b32 s74, s0, 4
	v_add_u32_e32 v142, s74, v241
	v_lshlrev_b32_e32 v142, 0, v142
	v_lshlrev_b32_e32 v238, 2, v142
	v_lshlrev_b32_e32 v142, 7, v142
	v_lshl_add_u32 v236, v242, 4, v142
	v_lshl_add_u32 v237, v242, 3, v142
	v_xor_b32_e32 v142, 16, v141
	v_lshlrev_b32_e32 v239, 2, v142
	v_xor_b32_e32 v142, 32, v141
	v_lshlrev_b32_e32 v240, 2, v142
	s_add_u32 s74, s2, 1
	v_cvt_f32_u32_e32 v142, s74
	v_mul_f32_e32 v142, 0xc1000000, v142
	v_mul_f32_e32 v142, 0x3caaaaab, v142
	v_exp_f32_e32 v142, v142
	v_lshlrev_b32_e32 v144, 2, v242
	v_sub_u32_e32 v145, v241, v144
	v_mul_f32_e32 v142, 0x3f800000, v142
	v_add_u32_e32 v145, 0x80, v145
	v_mul_f32_e32 v142, 0x3fb8aa3b, v142
	v_cvt_f32_i32_e32 v145, v145
	s_nop 0
	v_mul_f32_e64 v143, -v142, v145
	v_fmamk_f32 v185, v142, 0x0, v143
	v_fmamk_f32 v186, v142, 0x3f800000, v143
	v_fmamk_f32 v187, v142, 0x40000000, v143
	v_fmamk_f32 v188, v142, 0x40400000, v143
	v_fmamk_f32 v189, v142, 0x41800000, v143
	v_fmamk_f32 v190, v142, 0x41880000, v143
	v_fmamk_f32 v191, v142, 0x41900000, v143
	v_fmamk_f32 v192, v142, 0x41980000, v143
	v_fmamk_f32 v193, v142, 0x42000000, v143
	v_fmamk_f32 v194, v142, 0x42040000, v143
	v_fmamk_f32 v195, v142, 0x42080000, v143
	v_fmamk_f32 v196, v142, 0x420c0000, v143
	v_fmamk_f32 v197, v142, 0x42400000, v143
	v_fmamk_f32 v198, v142, 0x42440000, v143
	v_fmamk_f32 v199, v142, 0x42480000, v143
	v_fmamk_f32 v200, v142, 0x424c0000, v143
	v_fmamk_f32 v201, v142, 0x42800000, v143
	v_fmamk_f32 v202, v142, 0x42820000, v143
	v_fmamk_f32 v203, v142, 0x42840000, v143
	v_fmamk_f32 v204, v142, 0x42860000, v143
	v_fmamk_f32 v205, v142, 0x42a00000, v143
	v_fmamk_f32 v206, v142, 0x42a20000, v143
	v_fmamk_f32 v207, v142, 0x42a40000, v143
	v_fmamk_f32 v208, v142, 0x42a60000, v143
	v_fmamk_f32 v209, v142, 0x42c00000, v143
	v_fmamk_f32 v210, v142, 0x42c20000, v143
	v_fmamk_f32 v211, v142, 0x42c40000, v143
	v_fmamk_f32 v212, v142, 0x42c60000, v143
	v_fmamk_f32 v213, v142, 0x42e00000, v143
	v_fmamk_f32 v214, v142, 0x42e20000, v143
	v_fmamk_f32 v215, v142, 0x42e40000, v143
	v_fmamk_f32 v216, v142, 0x42e60000, v143
	v_fmamk_f32 v217, v142, 0x43000000, v143
	v_fmamk_f32 v218, v142, 0x43010000, v143
	v_fmamk_f32 v219, v142, 0x43020000, v143
	v_fmamk_f32 v220, v142, 0x43030000, v143
	v_add_u32_e32 v145, 0, v144
	v_cmp_lt_u32_e32 vcc, v145, v241
	s_nop 1
	v_cndmask_b32_e32 v185, v185, v244, vcc
	v_cmp_gt_u32_e32 vcc, v145, v241
	s_nop 1
	v_cndmask_b32_e32 v217, v217, v244, vcc
	v_add_u32_e32 v145, 1, v144
	v_cmp_lt_u32_e32 vcc, v145, v241
	s_nop 1
	v_cndmask_b32_e32 v186, v186, v244, vcc
	v_cmp_gt_u32_e32 vcc, v145, v241
	s_nop 1
	v_cndmask_b32_e32 v218, v218, v244, vcc
	v_add_u32_e32 v145, 2, v144
	v_cmp_lt_u32_e32 vcc, v145, v241
	s_nop 1
	v_cndmask_b32_e32 v187, v187, v244, vcc
	v_cmp_gt_u32_e32 vcc, v145, v241
	s_nop 1
	v_cndmask_b32_e32 v219, v219, v244, vcc
	v_add_u32_e32 v145, 3, v144
	v_cmp_lt_u32_e32 vcc, v145, v241
	s_nop 1
	v_cndmask_b32_e32 v188, v188, v244, vcc
	v_cmp_gt_u32_e32 vcc, v145, v241
	s_nop 1
	v_cndmask_b32_e32 v220, v220, v244, vcc
	s_sub_u32 s76, s4, 1
	s_max_i32 s76, s76, 0
	s_mul_i32 s74, s5, 4096
	s_lshl_b32 s75, s76, 7
	s_add_u32 s74, s74, s75
	s_lshl_b32 s75, s74, 7
	s_add_u32 s16, s60, s75
	s_addc_u32 s17, s61, 0
	s_lshl_b32 s75, s74, 1
	s_add_u32 s24, s64, s75
	s_addc_u32 s25, s65, 0
	s_add_u32 m0, s70, 0xc000
	s_nop 0
	global_load_lds_dwordx4 v232, s[16:17]
	s_add_u32 m0, s70, 0xe000
	s_nop 0
	global_load_lds_dwordx4 v233, s[16:17]
	s_add_u32 m0, s70, 0x1c000
	s_nop 0
	global_load_lds_dwordx4 v234, s[24:25]
	s_add_u32 m0, s70, 0x1e000
	s_nop 0
	global_load_lds_dwordx4 v235, s[24:25]
	s_mul_i32 s74, s5, 4096
	s_lshl_b32 s75, s4, 7
	s_add_u32 s74, s74, s75
	s_lshl_b32 s75, s74, 7
	s_add_u32 s16, s60, s75
	s_addc_u32 s17, s61, 0
	s_lshl_b32 s75, s74, 1
	s_add_u32 s24, s64, s75
	s_addc_u32 s25, s65, 0
	s_add_u32 m0, s70, 0x0
	s_nop 0
	global_load_lds_dwordx4 v232, s[16:17]
	s_add_u32 m0, s70, 0x2000
	s_nop 0
	global_load_lds_dwordx4 v233, s[16:17]
	s_add_u32 m0, s70, 0x10000
	s_nop 0
	global_load_lds_dwordx4 v234, s[24:25]
	s_add_u32 m0, s70, 0x12000
	s_nop 0
	global_load_lds_dwordx4 v235, s[24:25]
	s_lshl_b32 s74, s4, 7
	s_add_u32 s74, s74, s5
	s_lshl_b32 s75, s74, 7
	s_add_u32 s10, s30, s75
	s_addc_u32 s11, s31, 0
	s_add_u32 s86, s34, s75
	s_addc_u32 s87, s35, 0
	s_lshl_b32 s75, s74, 2
	s_add_u32 s88, s58, s75
	s_addc_u32 s89, s59, 0
	global_load_dwordx4 v[96:99], v236, s[10:11]
	global_load_dwordx4 v[100:103], v236, s[10:11] offset:64
	s_mov_b32 s7, 0
.Lat738_loop:
	s_waitcnt vmcnt(0)
	s_barrier
	s_cmp_gt_u32 s6, 0
	s_cselect_b32 s74, s77, s78
	v_add_u32_e32 v146, s74, v230
	v_xor_b32_e32 v147, 64, v146
	ds_read_b128 v[4:7], v146 offset:0
	ds_read_b128 v[8:11], v147 offset:0
	s_cmp_gt_u32 s6, 1
	s_cselect_b32 s74, s77, s78
	v_add_u32_e32 v146, s74, v230
	v_xor_b32_e32 v147, 64, v146
	ds_read_b128 v[12:15], v146 offset:2048
	ds_read_b128 v[16:19], v147 offset:2048
	s_cmp_gt_u32 s6, 2
	s_cselect_b32 s74, s77, s78
	v_add_u32_e32 v146, s74, v230
	v_xor_b32_e32 v147, 64, v146
	ds_read_b128 v[20:23], v146 offset:4096
	ds_read_b128 v[24:27], v147 offset:4096
	s_cmp_gt_u32 s6, 3
	s_cselect_b32 s74, s77, s78
	v_add_u32_e32 v146, s74, v230
	v_xor_b32_e32 v147, 64, v146
	ds_read_b128 v[28:31], v146 offset:6144
	ds_read_b128 v[32:35], v147 offset:6144
	s_cmp_gt_u32 s6, 4
	s_cselect_b32 s74, s77, s78
	v_add_u32_e32 v146, s74, v230
	v_xor_b32_e32 v147, 64, v146
	ds_read_b128 v[36:39], v146 offset:8192
	ds_read_b128 v[40:43], v147 offset:8192
	s_cmp_eq_u32 s7, 0
	s_cbranch_scc1 .Lat738_i0_nopend
	global_store_dwordx2 v237, v[132:133], s[26:27]
	global_store_dwordx2 v237, v[134:135], s[26:27] offset:32
	global_store_dwordx2 v237, v[136:137], s[26:27] offset:64
	global_store_dwordx2 v237, v[138:139], s[26:27] offset:96
	s_mov_b64 s[90:91], exec
	s_mov_b64 exec, 0xffff
	global_store_dword v238, v140, s[28:29]
	s_mov_b64 exec, s[90:91]
.Lat738_i0_nopend:
	s_add_u32 s83, s4, 1
	s_mov_b32 s84, s5
	s_mul_i32 s74, s84, 4096
	s_lshl_b32 s75, s83, 7
	s_add_u32 s74, s74, s75
	s_lshl_b32 s75, s74, 7
	s_add_u32 s16, s60, s75
	s_addc_u32 s17, s61, 0
	s_lshl_b32 s75, s74, 1
	s_add_u32 s24, s64, s75
	s_addc_u32 s25, s65, 0
	s_add_u32 m0, s70, 0x4000
	s_nop 0
	global_load_lds_dwordx4 v232, s[16:17]
	s_add_u32 m0, s70, 0x6000
	s_nop 0
	global_load_lds_dwordx4 v233, s[16:17]
	s_add_u32 m0, s70, 0x14000
	s_nop 0
	global_load_lds_dwordx4 v234, s[24:25]
	s_add_u32 m0, s70, 0x16000
	s_nop 0
	global_load_lds_dwordx4 v235, s[24:25]
	s_lshl_b32 s74, s83, 7
	s_add_u32 s74, s74, s84
	s_lshl_b32 s75, s74, 7
	s_add_u32 s10, s30, s75
	s_addc_u32 s11, s31, 0
	s_add_u32 s12, s34, s75
	s_addc_u32 s13, s35, 0
	s_lshl_b32 s75, s74, 2
	s_add_u32 s14, s58, s75
	s_addc_u32 s15, s59, 0
	global_load_dwordx4 v[104:107], v236, s[10:11]
	global_load_dwordx4 v[108:111], v236, s[10:11] offset:64
	s_waitcnt lgkmcnt(0)
	v_mfma_f32_16x16x32_bf16 v[44:47], v[4:7], v[96:99], 0
	v_mfma_f32_16x16x32_bf16 v[48:51], v[12:15], v[96:99], 0
	v_mfma_f32_16x16x32_bf16 v[52:55], v[20:23], v[96:99], 0
	v_mfma_f32_16x16x32_bf16 v[56:59], v[28:31], v[96:99], 0
	v_mfma_f32_16x16x32_bf16 v[60:63], v[36:39], v[96:99], 0
	v_mfma_f32_16x16x32_bf16 v[44:47], v[8:11], v[100:103], v[44:47]
	v_mfma_f32_16x16x32_bf16 v[48:51], v[16:19], v[100:103], v[48:51]
	v_mfma_f32_16x16x32_bf16 v[52:55], v[24:27], v[100:103], v[52:55]
	v_mfma_f32_16x16x32_bf16 v[56:59], v[32:35], v[100:103], v[56:59]
	v_mfma_f32_16x16x32_bf16 v[60:63], v[40:43], v[100:103], v[60:63]
	s_cmp_gt_u32 s6, 5
	s_cselect_b32 s74, s77, s78
	v_add_u32_e32 v146, s74, v230
	v_xor_b32_e32 v147, 64, v146
	ds_read_b128 v[4:7], v146 offset:10240
	ds_read_b128 v[8:11], v147 offset:10240
	s_cmp_gt_u32 s6, 6
	s_cselect_b32 s74, s77, s78
	v_add_u32_e32 v146, s74, v230
	v_xor_b32_e32 v147, 64, v146
	ds_read_b128 v[12:15], v146 offset:12288
	ds_read_b128 v[16:19], v147 offset:12288
	s_cmp_gt_u32 s6, 7
	s_cselect_b32 s74, s77, s78
	v_add_u32_e32 v146, s74, v230
	v_xor_b32_e32 v147, 64, v146
	ds_read_b128 v[20:23], v146 offset:14336
	ds_read_b128 v[24:27], v147 offset:14336
	s_cmp_gt_u32 s6, 8
	s_cselect_b32 s74, s77, s78
	v_add_u32_e32 v146, s74, v230
	v_xor_b32_e32 v147, 64, v146
	ds_read_b128 v[28:31], v146 offset:16384
	ds_read_b128 v[32:35], v147 offset:16384
	s_nop 1
	v_fma_f32 v44, v44, s79, v185
	v_fma_f32 v45, v45, s79, v186
	v_fma_f32 v46, v46, s79, v187
	v_fma_f32 v47, v47, s79, v188
	v_fma_f32 v48, v48, s79, v189
	v_fma_f32 v49, v49, s79, v190
	v_fma_f32 v50, v50, s79, v191
	v_fma_f32 v51, v51, s79, v192
	v_fma_f32 v52, v52, s79, v193
	v_fma_f32 v53, v53, s79, v194
	v_fma_f32 v54, v54, s79, v195
	v_fma_f32 v55, v55, s79, v196
	v_fma_f32 v56, v56, s79, v197
	v_fma_f32 v57, v57, s79, v198
	v_fma_f32 v58, v58, s79, v199
	v_fma_f32 v59, v59, s79, v200
	v_fma_f32 v60, v60, s79, v201
	v_fma_f32 v61, v61, s79, v202
	v_fma_f32 v62, v62, s79, v203
	v_fma_f32 v63, v63, s79, v204
	s_waitcnt lgkmcnt(0)
	v_mfma_f32_16x16x32_bf16 v[64:67], v[4:7], v[96:99], 0
	v_mfma_f32_16x16x32_bf16 v[68:71], v[12:15], v[96:99], 0
	v_mfma_f32_16x16x32_bf16 v[72:75], v[20:23], v[96:99], 0
	v_mfma_f32_16x16x32_bf16 v[76:79], v[28:31], v[96:99], 0
	v_mfma_f32_16x16x32_bf16 v[64:67], v[8:11], v[100:103], v[64:67]
	v_mfma_f32_16x16x32_bf16 v[68:71], v[16:19], v[100:103], v[68:71]
	v_mfma_f32_16x16x32_bf16 v[72:75], v[24:27], v[100:103], v[72:75]
	v_mfma_f32_16x16x32_bf16 v[76:79], v[32:35], v[100:103], v[76:79]
	s_cmp_gt_u32 s6, 0
	s_cselect_b32 s74, 0, 0xffff0000
	v_add_u32_e32 v146, s74, v221
	ds_read_b64 v[4:5], v146 offset:49152
	ds_read_b64 v[8:9], v146 offset:53248
	ds_read_b64 v[12:13], v146 offset:57344
	ds_read_b64 v[16:17], v146 offset:61440
	s_cmp_gt_u32 s6, 1
	s_cselect_b32 s74, 0, 0xffff0000
	v_add_u32_e32 v146, s74, v222
	ds_read_b64 v[6:7], v146 offset:49152
	ds_read_b64 v[10:11], v146 offset:53248
	ds_read_b64 v[14:15], v146 offset:57344
	ds_read_b64 v[18:19], v146 offset:61440
	s_nop 1
	v_fma_f32 v64, v64, s79, v205
	v_fma_f32 v65, v65, s79, v206
	v_fma_f32 v66, v66, s79, v207
	v_fma_f32 v67, v67, s79, v208
	v_fma_f32 v68, v68, s79, v209
	v_fma_f32 v69, v69, s79, v210
	v_fma_f32 v70, v70, s79, v211
	v_fma_f32 v71, v71, s79, v212
	v_fma_f32 v72, v72, s79, v213
	v_fma_f32 v73, v73, s79, v214
	v_fma_f32 v74, v74, s79, v215
	v_fma_f32 v75, v75, s79, v216
	v_fma_f32 v76, v76, s79, v217
	v_fma_f32 v77, v77, s79, v218
	v_fma_f32 v78, v78, s79, v219
	v_fma_f32 v79, v79, s79, v220
	s_cmp_gt_u32 s6, 2
	s_cselect_b32 s74, 0, 0xffff0000
	v_add_u32_e32 v146, s74, v223
	ds_read_b64 v[20:21], v146 offset:49152
	ds_read_b64 v[24:25], v146 offset:53248
	ds_read_b64 v[28:29], v146 offset:57344
	ds_read_b64 v[32:33], v146 offset:61440
	s_cmp_gt_u32 s6, 3
	s_cselect_b32 s74, 0, 0xffff0000
	v_add_u32_e32 v146, s74, v224
	ds_read_b64 v[22:23], v146 offset:49152
	ds_read_b64 v[26:27], v146 offset:53248
	ds_read_b64 v[30:31], v146 offset:57344
	ds_read_b64 v[34:35], v146 offset:61440
	s_cmp_lg_u32 s4, 0
	s_cbranch_scc1 .Lat738_i0_nomask
	s_cmp_le_u32 s6, 0
	s_cbranch_scc1 .Lat738_i0_nomask
	v_mov_b32_e32 v44, v244
	v_mov_b32_e32 v45, v244
	v_mov_b32_e32 v46, v244
	v_mov_b32_e32 v47, v244
	s_cmp_le_u32 s6, 1
	s_cbranch_scc1 .Lat738_i0_nomask
	v_mov_b32_e32 v48, v244
	v_mov_b32_e32 v49, v244
	v_mov_b32_e32 v50, v244
	v_mov_b32_e32 v51, v244
	s_cmp_le_u32 s6, 2
	s_cbranch_scc1 .Lat738_i0_nomask
	v_mov_b32_e32 v52, v244
	v_mov_b32_e32 v53, v244
	v_mov_b32_e32 v54, v244
	v_mov_b32_e32 v55, v244
	s_cmp_le_u32 s6, 3
	s_cbranch_scc1 .Lat738_i0_nomask
	v_mov_b32_e32 v56, v244
	v_mov_b32_e32 v57, v244
	v_mov_b32_e32 v58, v244
	v_mov_b32_e32 v59, v244
	s_cmp_le_u32 s6, 4
	s_cbranch_scc1 .Lat738_i0_nomask
	v_mov_b32_e32 v60, v244
	v_mov_b32_e32 v61, v244
	v_mov_b32_e32 v62, v244
	v_mov_b32_e32 v63, v244
	s_cmp_le_u32 s6, 5
	s_cbranch_scc1 .Lat738_i0_nomask
	v_mov_b32_e32 v64, v244
	v_mov_b32_e32 v65, v244
	v_mov_b32_e32 v66, v244
	v_mov_b32_e32 v67, v244
	s_cmp_le_u32 s6, 6
	s_cbranch_scc1 .Lat738_i0_nomask
	v_mov_b32_e32 v68, v244
	v_mov_b32_e32 v69, v244
	v_mov_b32_e32 v70, v244
	v_mov_b32_e32 v71, v244
	s_cmp_le_u32 s6, 7
	s_cbranch_scc1 .Lat738_i0_nomask
	v_mov_b32_e32 v72, v244
	v_mov_b32_e32 v73, v244
	v_mov_b32_e32 v74, v244
	v_mov_b32_e32 v75, v244
.Lat738_i0_nomask:
	v_max3_f32 v245, v44, v45, v46
	v_max3_f32 v245, v245, v47, v48
	v_max3_f32 v245, v245, v49, v50
	v_max3_f32 v245, v245, v51, v52
	v_max3_f32 v245, v245, v53, v54
	v_max3_f32 v245, v245, v55, v56
	v_max3_f32 v245, v245, v57, v58
	v_max3_f32 v245, v245, v59, v60
	v_max3_f32 v245, v245, v61, v62
	v_max3_f32 v245, v245, v63, v64
	v_max3_f32 v245, v245, v65, v66
	v_max3_f32 v245, v245, v67, v68
	v_max3_f32 v245, v245, v69, v70
	v_max3_f32 v245, v245, v71, v72
	v_max3_f32 v245, v245, v73, v74
	v_max3_f32 v245, v245, v75, v76
	v_max3_f32 v245, v245, v77, v78
	v_max_f32_e32 v245, v245, v79
	ds_bpermute_b32 v148, v239, v245
	s_waitcnt lgkmcnt(0)
	v_max_f32_e32 v245, v245, v148
	ds_bpermute_b32 v148, v240, v245
	s_waitcnt lgkmcnt(0)
	v_max_f32_e32 v245, v245, v148
	v_sub_f32_e32 v44, v44, v245
	v_sub_f32_e32 v45, v45, v245
	v_sub_f32_e32 v46, v46, v245
	v_sub_f32_e32 v47, v47, v245
	v_exp_f32_e32 v44, v44
	v_exp_f32_e32 v45, v45
	v_exp_f32_e32 v46, v46
	v_exp_f32_e32 v47, v47
	v_sub_f32_e32 v48, v48, v245
	v_sub_f32_e32 v49, v49, v245
	v_sub_f32_e32 v50, v50, v245
	v_sub_f32_e32 v51, v51, v245
	v_exp_f32_e32 v48, v48
	v_exp_f32_e32 v49, v49
	v_exp_f32_e32 v50, v50
	v_exp_f32_e32 v51, v51
	v_mov_b32_e32 v149, v44
	v_mov_b32_e32 v150, v45
	v_mov_b32_e32 v151, v46
	v_mov_b32_e32 v152, v47
	v_cvt_pk_bf16_f32 v44, v44, v45
	v_cvt_pk_bf16_f32 v45, v46, v47
	v_sub_f32_e32 v52, v52, v245
	v_sub_f32_e32 v53, v53, v245
	v_sub_f32_e32 v54, v54, v245
	v_sub_f32_e32 v55, v55, v245
	v_exp_f32_e32 v52, v52
	v_exp_f32_e32 v53, v53
	v_exp_f32_e32 v54, v54
	v_exp_f32_e32 v55, v55
	v_add_f32_e32 v149, v149, v48
	v_add_f32_e32 v150, v150, v49
	v_add_f32_e32 v151, v151, v50
	v_add_f32_e32 v152, v152, v51
	v_cvt_pk_bf16_f32 v46, v48, v49
	v_cvt_pk_bf16_f32 v47, v50, v51
	v_sub_f32_e32 v56, v56, v245
	v_sub_f32_e32 v57, v57, v245
	v_sub_f32_e32 v58, v58, v245
	v_sub_f32_e32 v59, v59, v245
	v_exp_f32_e32 v56, v56
	v_exp_f32_e32 v57, v57
	v_exp_f32_e32 v58, v58
	v_exp_f32_e32 v59, v59
	v_add_f32_e32 v149, v149, v52
	v_add_f32_e32 v150, v150, v53
	v_add_f32_e32 v151, v151, v54
	v_add_f32_e32 v152, v152, v55
	v_cvt_pk_bf16_f32 v52, v52, v53
	v_cvt_pk_bf16_f32 v53, v54, v55
	v_sub_f32_e32 v60, v60, v245
	v_sub_f32_e32 v61, v61, v245
	v_sub_f32_e32 v62, v62, v245
	v_sub_f32_e32 v63, v63, v245
	v_exp_f32_e32 v60, v60
	v_exp_f32_e32 v61, v61
	v_exp_f32_e32 v62, v62
	v_exp_f32_e32 v63, v63
	v_add_f32_e32 v149, v149, v56
	v_add_f32_e32 v150, v150, v57
	v_add_f32_e32 v151, v151, v58
	v_add_f32_e32 v152, v152, v59
	v_cvt_pk_bf16_f32 v54, v56, v57
	v_cvt_pk_bf16_f32 v55, v58, v59
	v_sub_f32_e32 v64, v64, v245
	v_sub_f32_e32 v65, v65, v245
	v_sub_f32_e32 v66, v66, v245
	v_sub_f32_e32 v67, v67, v245
	v_exp_f32_e32 v64, v64
	v_exp_f32_e32 v65, v65
	v_exp_f32_e32 v66, v66
	v_exp_f32_e32 v67, v67
	v_add_f32_e32 v149, v149, v60
	v_add_f32_e32 v150, v150, v61
	v_add_f32_e32 v151, v151, v62
	v_add_f32_e32 v152, v152, v63
	v_cvt_pk_bf16_f32 v60, v60, v61
	v_cvt_pk_bf16_f32 v61, v62, v63
	v_sub_f32_e32 v68, v68, v245
	v_sub_f32_e32 v69, v69, v245
	v_sub_f32_e32 v70, v70, v245
	v_sub_f32_e32 v71, v71, v245
	v_exp_f32_e32 v68, v68
	v_exp_f32_e32 v69, v69
	v_exp_f32_e32 v70, v70
	v_exp_f32_e32 v71, v71
	v_add_f32_e32 v149, v149, v64
	v_add_f32_e32 v150, v150, v65
	v_add_f32_e32 v151, v151, v66
	v_add_f32_e32 v152, v152, v67
	v_cvt_pk_bf16_f32 v62, v64, v65
	v_cvt_pk_bf16_f32 v63, v66, v67
	v_sub_f32_e32 v72, v72, v245
	v_sub_f32_e32 v73, v73, v245
	v_sub_f32_e32 v74, v74, v245
	v_sub_f32_e32 v75, v75, v245
	v_exp_f32_e32 v72, v72
	v_exp_f32_e32 v73, v73
	v_exp_f32_e32 v74, v74
	v_exp_f32_e32 v75, v75
	v_add_f32_e32 v149, v149, v68
	v_add_f32_e32 v150, v150, v69
	v_add_f32_e32 v151, v151, v70
	v_add_f32_e32 v152, v152, v71
	v_cvt_pk_bf16_f32 v68, v68, v69
	v_cvt_pk_bf16_f32 v69, v70, v71
	v_sub_f32_e32 v76, v76, v245
	v_sub_f32_e32 v77, v77, v245
	v_sub_f32_e32 v78, v78, v245
	v_sub_f32_e32 v79, v79, v245
	v_exp_f32_e32 v76, v76
	v_exp_f32_e32 v77, v77
	v_exp_f32_e32 v78, v78
	v_exp_f32_e32 v79, v79
	v_add_f32_e32 v149, v149, v72
	v_add_f32_e32 v150, v150, v73
	v_add_f32_e32 v151, v151, v74
	v_add_f32_e32 v152, v152, v75
	v_cvt_pk_bf16_f32 v70, v72, v73
	v_cvt_pk_bf16_f32 v71, v74, v75
	s_nop 0
	v_add_f32_e32 v149, v149, v76
	v_add_f32_e32 v150, v150, v77
	v_add_f32_e32 v151, v151, v78
	v_add_f32_e32 v152, v152, v79
	v_cvt_pk_bf16_f32 v76, v76, v77
	v_cvt_pk_bf16_f32 v77, v78, v79
	v_mov_b32_e32 v78, 0
	v_mov_b32_e32 v79, 0
	v_add_f32_e32 v149, v149, v150
	v_add_f32_e32 v151, v151, v152
	v_add_f32_e32 v246, v149, v151
	s_waitcnt lgkmcnt(0)
	v_mfma_f32_16x16x32_bf16 v[80:83], v[4:7], v[44:47], 0
	v_mfma_f32_16x16x32_bf16 v[84:87], v[8:11], v[44:47], 0
	v_mfma_f32_16x16x32_bf16 v[88:91], v[12:15], v[44:47], 0
	v_mfma_f32_16x16x32_bf16 v[92:95], v[16:19], v[44:47], 0
	s_cmp_gt_u32 s6, 4
	s_cselect_b32 s74, 0, 0xffff0000
	v_add_u32_e32 v146, s74, v225
	ds_read_b64 v[4:5], v146 offset:49152
	ds_read_b64 v[8:9], v146 offset:53248
	ds_read_b64 v[12:13], v146 offset:57344
	ds_read_b64 v[16:17], v146 offset:61440
	s_cmp_gt_u32 s6, 5
	s_cselect_b32 s74, 0, 0xffff0000
	v_add_u32_e32 v146, s74, v226
	ds_read_b64 v[6:7], v146 offset:49152
	ds_read_b64 v[10:11], v146 offset:53248
	ds_read_b64 v[14:15], v146 offset:57344
	ds_read_b64 v[18:19], v146 offset:61440
	v_mfma_f32_16x16x32_bf16 v[80:83], v[20:23], v[52:55], v[80:83]
	v_mfma_f32_16x16x32_bf16 v[84:87], v[24:27], v[52:55], v[84:87]
	v_mfma_f32_16x16x32_bf16 v[88:91], v[28:31], v[52:55], v[88:91]
	v_mfma_f32_16x16x32_bf16 v[92:95], v[32:35], v[52:55], v[92:95]
	s_cmp_gt_u32 s6, 6
	s_cselect_b32 s74, 0, 0xffff0000
	v_add_u32_e32 v146, s74, v227
	ds_read_b64 v[20:21], v146 offset:49152
	ds_read_b64 v[24:25], v146 offset:53248
	ds_read_b64 v[28:29], v146 offset:57344
	ds_read_b64 v[32:33], v146 offset:61440
	s_cmp_gt_u32 s6, 7
	s_cselect_b32 s74, 0, 0xffff0000
	v_add_u32_e32 v146, s74, v228
	ds_read_b64 v[22:23], v146 offset:49152
	ds_read_b64 v[26:27], v146 offset:53248
	ds_read_b64 v[30:31], v146 offset:57344
	ds_read_b64 v[34:35], v146 offset:61440
	ds_bpermute_b32 v148, v239, v246
	s_waitcnt lgkmcnt(9)
	v_mfma_f32_16x16x32_bf16 v[80:83], v[4:7], v[60:63], v[80:83]
	v_mfma_f32_16x16x32_bf16 v[84:87], v[8:11], v[60:63], v[84:87]
	v_mfma_f32_16x16x32_bf16 v[88:91], v[12:15], v[60:63], v[88:91]
	v_mfma_f32_16x16x32_bf16 v[92:95], v[16:19], v[60:63], v[92:95]
	s_cmp_gt_u32 s6, 8
	s_cselect_b32 s74, 0, 0xffff0000
	v_add_u32_e32 v146, s74, v229
	ds_read_b64 v[4:5], v146 offset:49152
	ds_read_b64 v[8:9], v146 offset:53248
	ds_read_b64 v[12:13], v146 offset:57344
	ds_read_b64 v[16:17], v146 offset:61440
	v_mov_b32_e32 v6, 0
	v_mov_b32_e32 v7, 0
	v_mov_b32_e32 v10, 0
	v_mov_b32_e32 v11, 0
	v_mov_b32_e32 v14, 0
	v_mov_b32_e32 v15, 0
	v_mov_b32_e32 v18, 0
	v_mov_b32_e32 v19, 0
	s_waitcnt lgkmcnt(5)
	v_mfma_f32_16x16x32_bf16 v[80:83], v[20:23], v[68:71], v[80:83]
	v_mfma_f32_16x16x32_bf16 v[84:87], v[24:27], v[68:71], v[84:87]
	v_mfma_f32_16x16x32_bf16 v[88:91], v[28:31], v[68:71], v[88:91]
	v_mfma_f32_16x16x32_bf16 v[92:95], v[32:35], v[68:71], v[92:95]
	s_waitcnt lgkmcnt(0)
	v_add_f32_e32 v246, v246, v148
	s_nop 0
	v_mfma_f32_16x16x32_bf16 v[80:83], v[4:7], v[76:79], v[80:83]
	v_mfma_f32_16x16x32_bf16 v[84:87], v[8:11], v[76:79], v[84:87]
	v_mfma_f32_16x16x32_bf16 v[88:91], v[12:15], v[76:79], v[88:91]
	v_mfma_f32_16x16x32_bf16 v[92:95], v[16:19], v[76:79], v[92:95]
	ds_bpermute_b32 v148, v240, v246
	s_waitcnt lgkmcnt(0)
	v_add_f32_e32 v246, v246, v148
	v_rcp_f32_e32 v149, v246
	v_log_f32_e32 v150, v246
	s_nop 0
	v_add_f32_e32 v151, v245, v150
	v_mul_f32_e32 v151, 0x3f317218, v151
	v_mov_b32_e32 v140, v151
	v_mul_f32_e32 v80, v80, v149
	v_mul_f32_e32 v81, v81, v149
	v_mul_f32_e32 v82, v82, v149
	v_mul_f32_e32 v83, v83, v149
	v_mul_f32_e32 v84, v84, v149
	v_mul_f32_e32 v85, v85, v149
	v_mul_f32_e32 v86, v86, v149
	v_mul_f32_e32 v87, v87, v149
	v_mul_f32_e32 v88, v88, v149
	v_mul_f32_e32 v89, v89, v149
	v_mul_f32_e32 v90, v90, v149
	v_mul_f32_e32 v91, v91, v149
	v_mul_f32_e32 v92, v92, v149
	v_mul_f32_e32 v93, v93, v149
	v_mul_f32_e32 v94, v94, v149
	v_mul_f32_e32 v95, v95, v149
	v_cvt_pk_bf16_f32 v132, v80, v81
	v_cvt_pk_bf16_f32 v133, v82, v83
	v_cvt_pk_bf16_f32 v134, v84, v85
	v_cvt_pk_bf16_f32 v135, v86, v87
	v_cvt_pk_bf16_f32 v136, v88, v89
	v_cvt_pk_bf16_f32 v137, v90, v91
	v_cvt_pk_bf16_f32 v138, v92, v93
	v_cvt_pk_bf16_f32 v139, v94, v95
	s_mov_b64 s[26:27], s[86:87]
	s_mov_b64 s[28:29], s[88:89]
	s_mov_b64 s[86:87], s[12:13]
	s_mov_b64 s[88:89], s[14:15]
	s_mov_b32 s4, s83
	s_mov_b32 s5, s84
	s_waitcnt vmcnt(0)
	s_barrier
	ds_read_b128 v[4:7], v230 offset:0
	ds_read_b128 v[8:11], v231 offset:0
	ds_read_b128 v[12:15], v230 offset:2048
	ds_read_b128 v[16:19], v231 offset:2048
	ds_read_b128 v[20:23], v230 offset:4096
	ds_read_b128 v[24:27], v231 offset:4096
	ds_read_b128 v[28:31], v230 offset:6144
	ds_read_b128 v[32:35], v231 offset:6144
	ds_read_b128 v[36:39], v230 offset:8192
	ds_read_b128 v[40:43], v231 offset:8192
	global_store_dwordx2 v237, v[132:133], s[26:27]
	global_store_dwordx2 v237, v[134:135], s[26:27] offset:32
	global_store_dwordx2 v237, v[136:137], s[26:27] offset:64
	global_store_dwordx2 v237, v[138:139], s[26:27] offset:96
	s_mov_b64 s[90:91], exec
	s_mov_b64 exec, 0xffff
	global_store_dword v238, v140, s[28:29]
	s_mov_b64 exec, s[90:91]
	s_add_u32 s83, s4, 1
	s_mov_b32 s84, s5
	s_mul_i32 s74, s84, 4096
	s_lshl_b32 s75, s83, 7
	s_add_u32 s74, s74, s75
	s_lshl_b32 s75, s74, 7
	s_add_u32 s16, s60, s75
	s_addc_u32 s17, s61, 0
	s_lshl_b32 s75, s74, 1
	s_add_u32 s24, s64, s75
	s_addc_u32 s25, s65, 0
	s_add_u32 m0, s70, 0x8000
	s_nop 0
	global_load_lds_dwordx4 v232, s[16:17]
	s_add_u32 m0, s70, 0xa000
	s_nop 0
	global_load_lds_dwordx4 v233, s[16:17]
	s_add_u32 m0, s70, 0x18000
	s_nop 0
	global_load_lds_dwordx4 v234, s[24:25]
	s_add_u32 m0, s70, 0x1a000
	s_nop 0
	global_load_lds_dwordx4 v235, s[24:25]
	s_lshl_b32 s74, s83, 7
	s_add_u32 s74, s74, s84
	s_lshl_b32 s75, s74, 7
	s_add_u32 s10, s30, s75
	s_addc_u32 s11, s31, 0
	s_add_u32 s12, s34, s75
	s_addc_u32 s13, s35, 0
	s_lshl_b32 s75, s74, 2
	s_add_u32 s14, s58, s75
	s_addc_u32 s15, s59, 0
	global_load_dwordx4 v[96:99], v236, s[10:11]
	global_load_dwordx4 v[100:103], v236, s[10:11] offset:64
	s_waitcnt lgkmcnt(0)
	v_mfma_f32_16x16x32_bf16 v[44:47], v[4:7], v[104:107], 0
	v_mfma_f32_16x16x32_bf16 v[48:51], v[12:15], v[104:107], 0
	v_mfma_f32_16x16x32_bf16 v[52:55], v[20:23], v[104:107], 0
	v_mfma_f32_16x16x32_bf16 v[56:59], v[28:31], v[104:107], 0
	v_mfma_f32_16x16x32_bf16 v[60:63], v[36:39], v[104:107], 0
	v_mfma_f32_16x16x32_bf16 v[44:47], v[8:11], v[108:111], v[44:47]
	v_mfma_f32_16x16x32_bf16 v[48:51], v[16:19], v[108:111], v[48:51]
	v_mfma_f32_16x16x32_bf16 v[52:55], v[24:27], v[108:111], v[52:55]
	v_mfma_f32_16x16x32_bf16 v[56:59], v[32:35], v[108:111], v[56:59]
	v_mfma_f32_16x16x32_bf16 v[60:63], v[40:43], v[108:111], v[60:63]
	ds_read_b128 v[4:7], v230 offset:10240
	ds_read_b128 v[8:11], v231 offset:10240
	ds_read_b128 v[12:15], v230 offset:12288
	ds_read_b128 v[16:19], v231 offset:12288
	ds_read_b128 v[20:23], v230 offset:14336
	ds_read_b128 v[24:27], v231 offset:14336
	ds_read_b128 v[28:31], v230 offset:16384
	ds_read_b128 v[32:35], v231 offset:16384
	s_nop 1
	v_fma_f32 v44, v44, s79, v185
	v_fma_f32 v45, v45, s79, v186
	v_fma_f32 v46, v46, s79, v187
	v_fma_f32 v47, v47, s79, v188
	v_fma_f32 v48, v48, s79, v189
	v_fma_f32 v49, v49, s79, v190
	v_fma_f32 v50, v50, s79, v191
	v_fma_f32 v51, v51, s79, v192
	v_fma_f32 v52, v52, s79, v193
	v_fma_f32 v53, v53, s79, v194
	v_fma_f32 v54, v54, s79, v195
	v_fma_f32 v55, v55, s79, v196
	v_fma_f32 v56, v56, s79, v197
	v_fma_f32 v57, v57, s79, v198
	v_fma_f32 v58, v58, s79, v199
	v_fma_f32 v59, v59, s79, v200
	v_fma_f32 v60, v60, s79, v201
	v_fma_f32 v61, v61, s79, v202
	v_fma_f32 v62, v62, s79, v203
	v_fma_f32 v63, v63, s79, v204
	s_waitcnt lgkmcnt(0)
	v_mfma_f32_16x16x32_bf16 v[64:67], v[4:7], v[104:107], 0
	v_mfma_f32_16x16x32_bf16 v[68:71], v[12:15], v[104:107], 0
	v_mfma_f32_16x16x32_bf16 v[72:75], v[20:23], v[104:107], 0
	v_mfma_f32_16x16x32_bf16 v[76:79], v[28:31], v[104:107], 0
	v_mfma_f32_16x16x32_bf16 v[64:67], v[8:11], v[108:111], v[64:67]
	v_mfma_f32_16x16x32_bf16 v[68:71], v[16:19], v[108:111], v[68:71]
	v_mfma_f32_16x16x32_bf16 v[72:75], v[24:27], v[108:111], v[72:75]
	v_mfma_f32_16x16x32_bf16 v[76:79], v[32:35], v[108:111], v[76:79]
	ds_read_b64 v[4:5], v221 offset:0
	ds_read_b64 v[8:9], v221 offset:4096
	ds_read_b64 v[12:13], v221 offset:8192
	ds_read_b64 v[16:17], v221 offset:12288
	ds_read_b64 v[6:7], v222 offset:0
	ds_read_b64 v[10:11], v222 offset:4096
	ds_read_b64 v[14:15], v222 offset:8192
	ds_read_b64 v[18:19], v222 offset:12288
	s_nop 1
	v_fma_f32 v64, v64, s79, v205
	v_fma_f32 v65, v65, s79, v206
	v_fma_f32 v66, v66, s79, v207
	v_fma_f32 v67, v67, s79, v208
	v_fma_f32 v68, v68, s79, v209
	v_fma_f32 v69, v69, s79, v210
	v_fma_f32 v70, v70, s79, v211
	v_fma_f32 v71, v71, s79, v212
	v_fma_f32 v72, v72, s79, v213
	v_fma_f32 v73, v73, s79, v214
	v_fma_f32 v74, v74, s79, v215
	v_fma_f32 v75, v75, s79, v216
	v_fma_f32 v76, v76, s79, v217
	v_fma_f32 v77, v77, s79, v218
	v_fma_f32 v78, v78, s79, v219
	v_fma_f32 v79, v79, s79, v220
	ds_read_b64 v[20:21], v223 offset:0
	ds_read_b64 v[24:25], v223 offset:4096
	ds_read_b64 v[28:29], v223 offset:8192
	ds_read_b64 v[32:33], v223 offset:12288
	ds_read_b64 v[22:23], v224 offset:0
	ds_read_b64 v[26:27], v224 offset:4096
	ds_read_b64 v[30:31], v224 offset:8192
	ds_read_b64 v[34:35], v224 offset:12288
	s_cmp_lg_u32 s4, 0
	s_cbranch_scc1 .Lat738_i1_nomask
	s_cmp_le_u32 s6, 0
	s_cbranch_scc1 .Lat738_i1_nomask
	v_mov_b32_e32 v44, v244
	v_mov_b32_e32 v45, v244
	v_mov_b32_e32 v46, v244
	v_mov_b32_e32 v47, v244
	s_cmp_le_u32 s6, 1
	s_cbranch_scc1 .Lat738_i1_nomask
	v_mov_b32_e32 v48, v244
	v_mov_b32_e32 v49, v244
	v_mov_b32_e32 v50, v244
	v_mov_b32_e32 v51, v244
	s_cmp_le_u32 s6, 2
	s_cbranch_scc1 .Lat738_i1_nomask
	v_mov_b32_e32 v52, v244
	v_mov_b32_e32 v53, v244
	v_mov_b32_e32 v54, v244
	v_mov_b32_e32 v55, v244
	s_cmp_le_u32 s6, 3
	s_cbranch_scc1 .Lat738_i1_nomask
	v_mov_b32_e32 v56, v244
	v_mov_b32_e32 v57, v244
	v_mov_b32_e32 v58, v244
	v_mov_b32_e32 v59, v244
	s_cmp_le_u32 s6, 4
	s_cbranch_scc1 .Lat738_i1_nomask
	v_mov_b32_e32 v60, v244
	v_mov_b32_e32 v61, v244
	v_mov_b32_e32 v62, v244
	v_mov_b32_e32 v63, v244
	s_cmp_le_u32 s6, 5
	s_cbranch_scc1 .Lat738_i1_nomask
	v_mov_b32_e32 v64, v244
	v_mov_b32_e32 v65, v244
	v_mov_b32_e32 v66, v244
	v_mov_b32_e32 v67, v244
	s_cmp_le_u32 s6, 6
	s_cbranch_scc1 .Lat738_i1_nomask
	v_mov_b32_e32 v68, v244
	v_mov_b32_e32 v69, v244
	v_mov_b32_e32 v70, v244
	v_mov_b32_e32 v71, v244
	s_cmp_le_u32 s6, 7
	s_cbranch_scc1 .Lat738_i1_nomask
	v_mov_b32_e32 v72, v244
	v_mov_b32_e32 v73, v244
	v_mov_b32_e32 v74, v244
	v_mov_b32_e32 v75, v244
.Lat738_i1_nomask:
	v_max3_f32 v245, v44, v45, v46
	v_max3_f32 v245, v245, v47, v48
	v_max3_f32 v245, v245, v49, v50
	v_max3_f32 v245, v245, v51, v52
	v_max3_f32 v245, v245, v53, v54
	v_max3_f32 v245, v245, v55, v56
	v_max3_f32 v245, v245, v57, v58
	v_max3_f32 v245, v245, v59, v60
	v_max3_f32 v245, v245, v61, v62
	v_max3_f32 v245, v245, v63, v64
	v_max3_f32 v245, v245, v65, v66
	v_max3_f32 v245, v245, v67, v68
	v_max3_f32 v245, v245, v69, v70
	v_max3_f32 v245, v245, v71, v72
	v_max3_f32 v245, v245, v73, v74
	v_max3_f32 v245, v245, v75, v76
	v_max3_f32 v245, v245, v77, v78
	v_max_f32_e32 v245, v245, v79
	ds_bpermute_b32 v148, v239, v245
	s_waitcnt lgkmcnt(0)
	v_max_f32_e32 v245, v245, v148
	ds_bpermute_b32 v148, v240, v245
	s_waitcnt lgkmcnt(0)
	v_max_f32_e32 v245, v245, v148
	v_sub_f32_e32 v44, v44, v245
	v_sub_f32_e32 v45, v45, v245
	v_sub_f32_e32 v46, v46, v245
	v_sub_f32_e32 v47, v47, v245
	v_exp_f32_e32 v44, v44
	v_exp_f32_e32 v45, v45
	v_exp_f32_e32 v46, v46
	v_exp_f32_e32 v47, v47
	v_sub_f32_e32 v48, v48, v245
	v_sub_f32_e32 v49, v49, v245
	v_sub_f32_e32 v50, v50, v245
	v_sub_f32_e32 v51, v51, v245
	v_exp_f32_e32 v48, v48
	v_exp_f32_e32 v49, v49
	v_exp_f32_e32 v50, v50
	v_exp_f32_e32 v51, v51
	v_mov_b32_e32 v149, v44
	v_mov_b32_e32 v150, v45
	v_mov_b32_e32 v151, v46
	v_mov_b32_e32 v152, v47
	v_cvt_pk_bf16_f32 v44, v44, v45
	v_cvt_pk_bf16_f32 v45, v46, v47
	v_sub_f32_e32 v52, v52, v245
	v_sub_f32_e32 v53, v53, v245
	v_sub_f32_e32 v54, v54, v245
	v_sub_f32_e32 v55, v55, v245
	v_exp_f32_e32 v52, v52
	v_exp_f32_e32 v53, v53
	v_exp_f32_e32 v54, v54
	v_exp_f32_e32 v55, v55
	v_add_f32_e32 v149, v149, v48
	v_add_f32_e32 v150, v150, v49
	v_add_f32_e32 v151, v151, v50
	v_add_f32_e32 v152, v152, v51
	v_cvt_pk_bf16_f32 v46, v48, v49
	v_cvt_pk_bf16_f32 v47, v50, v51
	v_sub_f32_e32 v56, v56, v245
	v_sub_f32_e32 v57, v57, v245
	v_sub_f32_e32 v58, v58, v245
	v_sub_f32_e32 v59, v59, v245
	v_exp_f32_e32 v56, v56
	v_exp_f32_e32 v57, v57
	v_exp_f32_e32 v58, v58
	v_exp_f32_e32 v59, v59
	v_add_f32_e32 v149, v149, v52
	v_add_f32_e32 v150, v150, v53
	v_add_f32_e32 v151, v151, v54
	v_add_f32_e32 v152, v152, v55
	v_cvt_pk_bf16_f32 v52, v52, v53
	v_cvt_pk_bf16_f32 v53, v54, v55
	v_sub_f32_e32 v60, v60, v245
	v_sub_f32_e32 v61, v61, v245
	v_sub_f32_e32 v62, v62, v245
	v_sub_f32_e32 v63, v63, v245
	v_exp_f32_e32 v60, v60
	v_exp_f32_e32 v61, v61
	v_exp_f32_e32 v62, v62
	v_exp_f32_e32 v63, v63
	v_add_f32_e32 v149, v149, v56
	v_add_f32_e32 v150, v150, v57
	v_add_f32_e32 v151, v151, v58
	v_add_f32_e32 v152, v152, v59
	v_cvt_pk_bf16_f32 v54, v56, v57
	v_cvt_pk_bf16_f32 v55, v58, v59
	v_sub_f32_e32 v64, v64, v245
	v_sub_f32_e32 v65, v65, v245
	v_sub_f32_e32 v66, v66, v245
	v_sub_f32_e32 v67, v67, v245
	v_exp_f32_e32 v64, v64
	v_exp_f32_e32 v65, v65
	v_exp_f32_e32 v66, v66
	v_exp_f32_e32 v67, v67
	v_add_f32_e32 v149, v149, v60
	v_add_f32_e32 v150, v150, v61
	v_add_f32_e32 v151, v151, v62
	v_add_f32_e32 v152, v152, v63
	v_cvt_pk_bf16_f32 v60, v60, v61
	v_cvt_pk_bf16_f32 v61, v62, v63
	v_sub_f32_e32 v68, v68, v245
	v_sub_f32_e32 v69, v69, v245
	v_sub_f32_e32 v70, v70, v245
	v_sub_f32_e32 v71, v71, v245
	v_exp_f32_e32 v68, v68
	v_exp_f32_e32 v69, v69
	v_exp_f32_e32 v70, v70
	v_exp_f32_e32 v71, v71
	v_add_f32_e32 v149, v149, v64
	v_add_f32_e32 v150, v150, v65
	v_add_f32_e32 v151, v151, v66
	v_add_f32_e32 v152, v152, v67
	v_cvt_pk_bf16_f32 v62, v64, v65
	v_cvt_pk_bf16_f32 v63, v66, v67
	v_sub_f32_e32 v72, v72, v245
	v_sub_f32_e32 v73, v73, v245
	v_sub_f32_e32 v74, v74, v245
	v_sub_f32_e32 v75, v75, v245
	v_exp_f32_e32 v72, v72
	v_exp_f32_e32 v73, v73
	v_exp_f32_e32 v74, v74
	v_exp_f32_e32 v75, v75
	v_add_f32_e32 v149, v149, v68
	v_add_f32_e32 v150, v150, v69
	v_add_f32_e32 v151, v151, v70
	v_add_f32_e32 v152, v152, v71
	v_cvt_pk_bf16_f32 v68, v68, v69
	v_cvt_pk_bf16_f32 v69, v70, v71
	v_sub_f32_e32 v76, v76, v245
	v_sub_f32_e32 v77, v77, v245
	v_sub_f32_e32 v78, v78, v245
	v_sub_f32_e32 v79, v79, v245
	v_exp_f32_e32 v76, v76
	v_exp_f32_e32 v77, v77
	v_exp_f32_e32 v78, v78
	v_exp_f32_e32 v79, v79
	v_add_f32_e32 v149, v149, v72
	v_add_f32_e32 v150, v150, v73
	v_add_f32_e32 v151, v151, v74
	v_add_f32_e32 v152, v152, v75
	v_cvt_pk_bf16_f32 v70, v72, v73
	v_cvt_pk_bf16_f32 v71, v74, v75
	s_nop 0
	v_add_f32_e32 v149, v149, v76
	v_add_f32_e32 v150, v150, v77
	v_add_f32_e32 v151, v151, v78
	v_add_f32_e32 v152, v152, v79
	v_cvt_pk_bf16_f32 v76, v76, v77
	v_cvt_pk_bf16_f32 v77, v78, v79
	v_mov_b32_e32 v78, 0
	v_mov_b32_e32 v79, 0
	v_add_f32_e32 v149, v149, v150
	v_add_f32_e32 v151, v151, v152
	v_add_f32_e32 v246, v149, v151
	s_waitcnt lgkmcnt(0)
	v_mfma_f32_16x16x32_bf16 v[80:83], v[4:7], v[44:47], 0
	v_mfma_f32_16x16x32_bf16 v[84:87], v[8:11], v[44:47], 0
	v_mfma_f32_16x16x32_bf16 v[88:91], v[12:15], v[44:47], 0
	v_mfma_f32_16x16x32_bf16 v[92:95], v[16:19], v[44:47], 0
	ds_read_b64 v[4:5], v225 offset:0
	ds_read_b64 v[8:9], v225 offset:4096
	ds_read_b64 v[12:13], v225 offset:8192
	ds_read_b64 v[16:17], v225 offset:12288
	ds_read_b64 v[6:7], v226 offset:0
	ds_read_b64 v[10:11], v226 offset:4096
	ds_read_b64 v[14:15], v226 offset:8192
	ds_read_b64 v[18:19], v226 offset:12288
	v_mfma_f32_16x16x32_bf16 v[80:83], v[20:23], v[52:55], v[80:83]
	v_mfma_f32_16x16x32_bf16 v[84:87], v[24:27], v[52:55], v[84:87]
	v_mfma_f32_16x16x32_bf16 v[88:91], v[28:31], v[52:55], v[88:91]
	v_mfma_f32_16x16x32_bf16 v[92:95], v[32:35], v[52:55], v[92:95]
	ds_read_b64 v[20:21], v227 offset:0
	ds_read_b64 v[24:25], v227 offset:4096
	ds_read_b64 v[28:29], v227 offset:8192
	ds_read_b64 v[32:33], v227 offset:12288
	ds_read_b64 v[22:23], v228 offset:0
	ds_read_b64 v[26:27], v228 offset:4096
	ds_read_b64 v[30:31], v228 offset:8192
	ds_read_b64 v[34:35], v228 offset:12288
	ds_bpermute_b32 v148, v239, v246
	s_waitcnt lgkmcnt(9)
	v_mfma_f32_16x16x32_bf16 v[80:83], v[4:7], v[60:63], v[80:83]
	v_mfma_f32_16x16x32_bf16 v[84:87], v[8:11], v[60:63], v[84:87]
	v_mfma_f32_16x16x32_bf16 v[88:91], v[12:15], v[60:63], v[88:91]
	v_mfma_f32_16x16x32_bf16 v[92:95], v[16:19], v[60:63], v[92:95]
	ds_read_b64 v[4:5], v229 offset:0
	ds_read_b64 v[8:9], v229 offset:4096
	ds_read_b64 v[12:13], v229 offset:8192
	ds_read_b64 v[16:17], v229 offset:12288
	v_mov_b32_e32 v6, 0
	v_mov_b32_e32 v7, 0
	v_mov_b32_e32 v10, 0
	v_mov_b32_e32 v11, 0
	v_mov_b32_e32 v14, 0
	v_mov_b32_e32 v15, 0
	v_mov_b32_e32 v18, 0
	v_mov_b32_e32 v19, 0
	s_waitcnt lgkmcnt(5)
	v_mfma_f32_16x16x32_bf16 v[80:83], v[20:23], v[68:71], v[80:83]
	v_mfma_f32_16x16x32_bf16 v[84:87], v[24:27], v[68:71], v[84:87]
	v_mfma_f32_16x16x32_bf16 v[88:91], v[28:31], v[68:71], v[88:91]
	v_mfma_f32_16x16x32_bf16 v[92:95], v[32:35], v[68:71], v[92:95]
	s_waitcnt lgkmcnt(0)
	v_add_f32_e32 v246, v246, v148
	s_nop 0
	v_mfma_f32_16x16x32_bf16 v[80:83], v[4:7], v[76:79], v[80:83]
	v_mfma_f32_16x16x32_bf16 v[84:87], v[8:11], v[76:79], v[84:87]
	v_mfma_f32_16x16x32_bf16 v[88:91], v[12:15], v[76:79], v[88:91]
	v_mfma_f32_16x16x32_bf16 v[92:95], v[16:19], v[76:79], v[92:95]
	ds_bpermute_b32 v148, v240, v246
	s_waitcnt lgkmcnt(0)
	v_add_f32_e32 v246, v246, v148
	v_rcp_f32_e32 v149, v246
	v_log_f32_e32 v150, v246
	s_nop 0
	v_add_f32_e32 v151, v245, v150
	v_mul_f32_e32 v151, 0x3f317218, v151
	v_mov_b32_e32 v140, v151
	v_mul_f32_e32 v80, v80, v149
	v_mul_f32_e32 v81, v81, v149
	v_mul_f32_e32 v82, v82, v149
	v_mul_f32_e32 v83, v83, v149
	v_mul_f32_e32 v84, v84, v149
	v_mul_f32_e32 v85, v85, v149
	v_mul_f32_e32 v86, v86, v149
	v_mul_f32_e32 v87, v87, v149
	v_mul_f32_e32 v88, v88, v149
	v_mul_f32_e32 v89, v89, v149
	v_mul_f32_e32 v90, v90, v149
	v_mul_f32_e32 v91, v91, v149
	v_mul_f32_e32 v92, v92, v149
	v_mul_f32_e32 v93, v93, v149
	v_mul_f32_e32 v94, v94, v149
	v_mul_f32_e32 v95, v95, v149
	v_cvt_pk_bf16_f32 v132, v80, v81
	v_cvt_pk_bf16_f32 v133, v82, v83
	v_cvt_pk_bf16_f32 v134, v84, v85
	v_cvt_pk_bf16_f32 v135, v86, v87
	v_cvt_pk_bf16_f32 v136, v88, v89
	v_cvt_pk_bf16_f32 v137, v90, v91
	v_cvt_pk_bf16_f32 v138, v92, v93
	v_cvt_pk_bf16_f32 v139, v94, v95
	s_mov_b64 s[26:27], s[86:87]
	s_mov_b64 s[28:29], s[88:89]
	s_mov_b64 s[86:87], s[12:13]
	s_mov_b64 s[88:89], s[14:15]
	s_mov_b32 s4, s83
	s_mov_b32 s5, s84
	s_waitcnt vmcnt(0)
	s_barrier
	ds_read_b128 v[4:7], v230 offset:16384
	ds_read_b128 v[8:11], v231 offset:16384
	ds_read_b128 v[12:15], v230 offset:18432
	ds_read_b128 v[16:19], v231 offset:18432
	ds_read_b128 v[20:23], v230 offset:20480
	ds_read_b128 v[24:27], v231 offset:20480
	ds_read_b128 v[28:31], v230 offset:22528
	ds_read_b128 v[32:35], v231 offset:22528
	ds_read_b128 v[36:39], v230 offset:24576
	ds_read_b128 v[40:43], v231 offset:24576
	global_store_dwordx2 v237, v[132:133], s[26:27]
	global_store_dwordx2 v237, v[134:135], s[26:27] offset:32
	global_store_dwordx2 v237, v[136:137], s[26:27] offset:64
	global_store_dwordx2 v237, v[138:139], s[26:27] offset:96
	s_mov_b64 s[90:91], exec
	s_mov_b64 exec, 0xffff
	global_store_dword v238, v140, s[28:29]
	s_mov_b64 exec, s[90:91]
	s_add_u32 s83, s4, 1
	s_mov_b32 s84, s5
	s_mul_i32 s74, s84, 4096
	s_lshl_b32 s75, s83, 7
	s_add_u32 s74, s74, s75
	s_lshl_b32 s75, s74, 7
	s_add_u32 s16, s60, s75
	s_addc_u32 s17, s61, 0
	s_lshl_b32 s75, s74, 1
	s_add_u32 s24, s64, s75
	s_addc_u32 s25, s65, 0
	s_add_u32 m0, s70, 0xc000
	s_nop 0
	global_load_lds_dwordx4 v232, s[16:17]
	s_add_u32 m0, s70, 0xe000
	s_nop 0
	global_load_lds_dwordx4 v233, s[16:17]
	s_add_u32 m0, s70, 0x1c000
	s_nop 0
	global_load_lds_dwordx4 v234, s[24:25]
	s_add_u32 m0, s70, 0x1e000
	s_nop 0
	global_load_lds_dwordx4 v235, s[24:25]
	s_lshl_b32 s74, s83, 7
	s_add_u32 s74, s74, s84
	s_lshl_b32 s75, s74, 7
	s_add_u32 s10, s30, s75
	s_addc_u32 s11, s31, 0
	s_add_u32 s12, s34, s75
	s_addc_u32 s13, s35, 0
	s_lshl_b32 s75, s74, 2
	s_add_u32 s14, s58, s75
	s_addc_u32 s15, s59, 0
	global_load_dwordx4 v[104:107], v236, s[10:11]
	global_load_dwordx4 v[108:111], v236, s[10:11] offset:64
	s_waitcnt lgkmcnt(0)
	v_mfma_f32_16x16x32_bf16 v[44:47], v[4:7], v[96:99], 0
	v_mfma_f32_16x16x32_bf16 v[48:51], v[12:15], v[96:99], 0
	v_mfma_f32_16x16x32_bf16 v[52:55], v[20:23], v[96:99], 0
	v_mfma_f32_16x16x32_bf16 v[56:59], v[28:31], v[96:99], 0
	v_mfma_f32_16x16x32_bf16 v[60:63], v[36:39], v[96:99], 0
	v_mfma_f32_16x16x32_bf16 v[44:47], v[8:11], v[100:103], v[44:47]
	v_mfma_f32_16x16x32_bf16 v[48:51], v[16:19], v[100:103], v[48:51]
	v_mfma_f32_16x16x32_bf16 v[52:55], v[24:27], v[100:103], v[52:55]
	v_mfma_f32_16x16x32_bf16 v[56:59], v[32:35], v[100:103], v[56:59]
	v_mfma_f32_16x16x32_bf16 v[60:63], v[40:43], v[100:103], v[60:63]
	ds_read_b128 v[4:7], v230 offset:26624
	ds_read_b128 v[8:11], v231 offset:26624
	ds_read_b128 v[12:15], v230 offset:28672
	ds_read_b128 v[16:19], v231 offset:28672
	ds_read_b128 v[20:23], v230 offset:30720
	ds_read_b128 v[24:27], v231 offset:30720
	ds_read_b128 v[28:31], v230 offset:32768
	ds_read_b128 v[32:35], v231 offset:32768
	s_nop 1
	v_fma_f32 v44, v44, s79, v185
	v_fma_f32 v45, v45, s79, v186
	v_fma_f32 v46, v46, s79, v187
	v_fma_f32 v47, v47, s79, v188
	v_fma_f32 v48, v48, s79, v189
	v_fma_f32 v49, v49, s79, v190
	v_fma_f32 v50, v50, s79, v191
	v_fma_f32 v51, v51, s79, v192
	v_fma_f32 v52, v52, s79, v193
	v_fma_f32 v53, v53, s79, v194
	v_fma_f32 v54, v54, s79, v195
	v_fma_f32 v55, v55, s79, v196
	v_fma_f32 v56, v56, s79, v197
	v_fma_f32 v57, v57, s79, v198
	v_fma_f32 v58, v58, s79, v199
	v_fma_f32 v59, v59, s79, v200
	v_fma_f32 v60, v60, s79, v201
	v_fma_f32 v61, v61, s79, v202
	v_fma_f32 v62, v62, s79, v203
	v_fma_f32 v63, v63, s79, v204
	s_waitcnt lgkmcnt(0)
	v_mfma_f32_16x16x32_bf16 v[64:67], v[4:7], v[96:99], 0
	v_mfma_f32_16x16x32_bf16 v[68:71], v[12:15], v[96:99], 0
	v_mfma_f32_16x16x32_bf16 v[72:75], v[20:23], v[96:99], 0
	v_mfma_f32_16x16x32_bf16 v[76:79], v[28:31], v[96:99], 0
	v_mfma_f32_16x16x32_bf16 v[64:67], v[8:11], v[100:103], v[64:67]
	v_mfma_f32_16x16x32_bf16 v[68:71], v[16:19], v[100:103], v[68:71]
	v_mfma_f32_16x16x32_bf16 v[72:75], v[24:27], v[100:103], v[72:75]
	v_mfma_f32_16x16x32_bf16 v[76:79], v[32:35], v[100:103], v[76:79]
	ds_read_b64 v[4:5], v221 offset:16384
	ds_read_b64 v[8:9], v221 offset:20480
	ds_read_b64 v[12:13], v221 offset:24576
	ds_read_b64 v[16:17], v221 offset:28672
	ds_read_b64 v[6:7], v222 offset:16384
	ds_read_b64 v[10:11], v222 offset:20480
	ds_read_b64 v[14:15], v222 offset:24576
	ds_read_b64 v[18:19], v222 offset:28672
	s_nop 1
	v_fma_f32 v64, v64, s79, v205
	v_fma_f32 v65, v65, s79, v206
	v_fma_f32 v66, v66, s79, v207
	v_fma_f32 v67, v67, s79, v208
	v_fma_f32 v68, v68, s79, v209
	v_fma_f32 v69, v69, s79, v210
	v_fma_f32 v70, v70, s79, v211
	v_fma_f32 v71, v71, s79, v212
	v_fma_f32 v72, v72, s79, v213
	v_fma_f32 v73, v73, s79, v214
	v_fma_f32 v74, v74, s79, v215
	v_fma_f32 v75, v75, s79, v216
	v_fma_f32 v76, v76, s79, v217
	v_fma_f32 v77, v77, s79, v218
	v_fma_f32 v78, v78, s79, v219
	v_fma_f32 v79, v79, s79, v220
	ds_read_b64 v[20:21], v223 offset:16384
	ds_read_b64 v[24:25], v223 offset:20480
	ds_read_b64 v[28:29], v223 offset:24576
	ds_read_b64 v[32:33], v223 offset:28672
	ds_read_b64 v[22:23], v224 offset:16384
	ds_read_b64 v[26:27], v224 offset:20480
	ds_read_b64 v[30:31], v224 offset:24576
	ds_read_b64 v[34:35], v224 offset:28672
	s_cmp_lg_u32 s4, 0
	s_cbranch_scc1 .Lat738_i2_nomask
	s_cmp_le_u32 s6, 0
	s_cbranch_scc1 .Lat738_i2_nomask
	v_mov_b32_e32 v44, v244
	v_mov_b32_e32 v45, v244
	v_mov_b32_e32 v46, v244
	v_mov_b32_e32 v47, v244
	s_cmp_le_u32 s6, 1
	s_cbranch_scc1 .Lat738_i2_nomask
	v_mov_b32_e32 v48, v244
	v_mov_b32_e32 v49, v244
	v_mov_b32_e32 v50, v244
	v_mov_b32_e32 v51, v244
	s_cmp_le_u32 s6, 2
	s_cbranch_scc1 .Lat738_i2_nomask
	v_mov_b32_e32 v52, v244
	v_mov_b32_e32 v53, v244
	v_mov_b32_e32 v54, v244
	v_mov_b32_e32 v55, v244
	s_cmp_le_u32 s6, 3
	s_cbranch_scc1 .Lat738_i2_nomask
	v_mov_b32_e32 v56, v244
	v_mov_b32_e32 v57, v244
	v_mov_b32_e32 v58, v244
	v_mov_b32_e32 v59, v244
	s_cmp_le_u32 s6, 4
	s_cbranch_scc1 .Lat738_i2_nomask
	v_mov_b32_e32 v60, v244
	v_mov_b32_e32 v61, v244
	v_mov_b32_e32 v62, v244
	v_mov_b32_e32 v63, v244
	s_cmp_le_u32 s6, 5
	s_cbranch_scc1 .Lat738_i2_nomask
	v_mov_b32_e32 v64, v244
	v_mov_b32_e32 v65, v244
	v_mov_b32_e32 v66, v244
	v_mov_b32_e32 v67, v244
	s_cmp_le_u32 s6, 6
	s_cbranch_scc1 .Lat738_i2_nomask
	v_mov_b32_e32 v68, v244
	v_mov_b32_e32 v69, v244
	v_mov_b32_e32 v70, v244
	v_mov_b32_e32 v71, v244
	s_cmp_le_u32 s6, 7
	s_cbranch_scc1 .Lat738_i2_nomask
	v_mov_b32_e32 v72, v244
	v_mov_b32_e32 v73, v244
	v_mov_b32_e32 v74, v244
	v_mov_b32_e32 v75, v244
.Lat738_i2_nomask:
	v_max3_f32 v245, v44, v45, v46
	v_max3_f32 v245, v245, v47, v48
	v_max3_f32 v245, v245, v49, v50
	v_max3_f32 v245, v245, v51, v52
	v_max3_f32 v245, v245, v53, v54
	v_max3_f32 v245, v245, v55, v56
	v_max3_f32 v245, v245, v57, v58
	v_max3_f32 v245, v245, v59, v60
	v_max3_f32 v245, v245, v61, v62
	v_max3_f32 v245, v245, v63, v64
	v_max3_f32 v245, v245, v65, v66
	v_max3_f32 v245, v245, v67, v68
	v_max3_f32 v245, v245, v69, v70
	v_max3_f32 v245, v245, v71, v72
	v_max3_f32 v245, v245, v73, v74
	v_max3_f32 v245, v245, v75, v76
	v_max3_f32 v245, v245, v77, v78
	v_max_f32_e32 v245, v245, v79
	ds_bpermute_b32 v148, v239, v245
	s_waitcnt lgkmcnt(0)
	v_max_f32_e32 v245, v245, v148
	ds_bpermute_b32 v148, v240, v245
	s_waitcnt lgkmcnt(0)
	v_max_f32_e32 v245, v245, v148
	v_sub_f32_e32 v44, v44, v245
	v_sub_f32_e32 v45, v45, v245
	v_sub_f32_e32 v46, v46, v245
	v_sub_f32_e32 v47, v47, v245
	v_exp_f32_e32 v44, v44
	v_exp_f32_e32 v45, v45
	v_exp_f32_e32 v46, v46
	v_exp_f32_e32 v47, v47
	v_sub_f32_e32 v48, v48, v245
	v_sub_f32_e32 v49, v49, v245
	v_sub_f32_e32 v50, v50, v245
	v_sub_f32_e32 v51, v51, v245
	v_exp_f32_e32 v48, v48
	v_exp_f32_e32 v49, v49
	v_exp_f32_e32 v50, v50
	v_exp_f32_e32 v51, v51
	v_mov_b32_e32 v149, v44
	v_mov_b32_e32 v150, v45
	v_mov_b32_e32 v151, v46
	v_mov_b32_e32 v152, v47
	v_cvt_pk_bf16_f32 v44, v44, v45
	v_cvt_pk_bf16_f32 v45, v46, v47
	v_sub_f32_e32 v52, v52, v245
	v_sub_f32_e32 v53, v53, v245
	v_sub_f32_e32 v54, v54, v245
	v_sub_f32_e32 v55, v55, v245
	v_exp_f32_e32 v52, v52
	v_exp_f32_e32 v53, v53
	v_exp_f32_e32 v54, v54
	v_exp_f32_e32 v55, v55
	v_add_f32_e32 v149, v149, v48
	v_add_f32_e32 v150, v150, v49
	v_add_f32_e32 v151, v151, v50
	v_add_f32_e32 v152, v152, v51
	v_cvt_pk_bf16_f32 v46, v48, v49
	v_cvt_pk_bf16_f32 v47, v50, v51
	v_sub_f32_e32 v56, v56, v245
	v_sub_f32_e32 v57, v57, v245
	v_sub_f32_e32 v58, v58, v245
	v_sub_f32_e32 v59, v59, v245
	v_exp_f32_e32 v56, v56
	v_exp_f32_e32 v57, v57
	v_exp_f32_e32 v58, v58
	v_exp_f32_e32 v59, v59
	v_add_f32_e32 v149, v149, v52
	v_add_f32_e32 v150, v150, v53
	v_add_f32_e32 v151, v151, v54
	v_add_f32_e32 v152, v152, v55
	v_cvt_pk_bf16_f32 v52, v52, v53
	v_cvt_pk_bf16_f32 v53, v54, v55
	v_sub_f32_e32 v60, v60, v245
	v_sub_f32_e32 v61, v61, v245
	v_sub_f32_e32 v62, v62, v245
	v_sub_f32_e32 v63, v63, v245
	v_exp_f32_e32 v60, v60
	v_exp_f32_e32 v61, v61
	v_exp_f32_e32 v62, v62
	v_exp_f32_e32 v63, v63
	v_add_f32_e32 v149, v149, v56
	v_add_f32_e32 v150, v150, v57
	v_add_f32_e32 v151, v151, v58
	v_add_f32_e32 v152, v152, v59
	v_cvt_pk_bf16_f32 v54, v56, v57
	v_cvt_pk_bf16_f32 v55, v58, v59
	v_sub_f32_e32 v64, v64, v245
	v_sub_f32_e32 v65, v65, v245
	v_sub_f32_e32 v66, v66, v245
	v_sub_f32_e32 v67, v67, v245
	v_exp_f32_e32 v64, v64
	v_exp_f32_e32 v65, v65
	v_exp_f32_e32 v66, v66
	v_exp_f32_e32 v67, v67
	v_add_f32_e32 v149, v149, v60
	v_add_f32_e32 v150, v150, v61
	v_add_f32_e32 v151, v151, v62
	v_add_f32_e32 v152, v152, v63
	v_cvt_pk_bf16_f32 v60, v60, v61
	v_cvt_pk_bf16_f32 v61, v62, v63
	v_sub_f32_e32 v68, v68, v245
	v_sub_f32_e32 v69, v69, v245
	v_sub_f32_e32 v70, v70, v245
	v_sub_f32_e32 v71, v71, v245
	v_exp_f32_e32 v68, v68
	v_exp_f32_e32 v69, v69
	v_exp_f32_e32 v70, v70
	v_exp_f32_e32 v71, v71
	v_add_f32_e32 v149, v149, v64
	v_add_f32_e32 v150, v150, v65
	v_add_f32_e32 v151, v151, v66
	v_add_f32_e32 v152, v152, v67
	v_cvt_pk_bf16_f32 v62, v64, v65
	v_cvt_pk_bf16_f32 v63, v66, v67
	v_sub_f32_e32 v72, v72, v245
	v_sub_f32_e32 v73, v73, v245
	v_sub_f32_e32 v74, v74, v245
	v_sub_f32_e32 v75, v75, v245
	v_exp_f32_e32 v72, v72
	v_exp_f32_e32 v73, v73
	v_exp_f32_e32 v74, v74
	v_exp_f32_e32 v75, v75
	v_add_f32_e32 v149, v149, v68
	v_add_f32_e32 v150, v150, v69
	v_add_f32_e32 v151, v151, v70
	v_add_f32_e32 v152, v152, v71
	v_cvt_pk_bf16_f32 v68, v68, v69
	v_cvt_pk_bf16_f32 v69, v70, v71
	v_sub_f32_e32 v76, v76, v245
	v_sub_f32_e32 v77, v77, v245
	v_sub_f32_e32 v78, v78, v245
	v_sub_f32_e32 v79, v79, v245
	v_exp_f32_e32 v76, v76
	v_exp_f32_e32 v77, v77
	v_exp_f32_e32 v78, v78
	v_exp_f32_e32 v79, v79
	v_add_f32_e32 v149, v149, v72
	v_add_f32_e32 v150, v150, v73
	v_add_f32_e32 v151, v151, v74
	v_add_f32_e32 v152, v152, v75
	v_cvt_pk_bf16_f32 v70, v72, v73
	v_cvt_pk_bf16_f32 v71, v74, v75
	s_nop 0
	v_add_f32_e32 v149, v149, v76
	v_add_f32_e32 v150, v150, v77
	v_add_f32_e32 v151, v151, v78
	v_add_f32_e32 v152, v152, v79
	v_cvt_pk_bf16_f32 v76, v76, v77
	v_cvt_pk_bf16_f32 v77, v78, v79
	v_mov_b32_e32 v78, 0
	v_mov_b32_e32 v79, 0
	v_add_f32_e32 v149, v149, v150
	v_add_f32_e32 v151, v151, v152
	v_add_f32_e32 v246, v149, v151
	s_waitcnt lgkmcnt(0)
	v_mfma_f32_16x16x32_bf16 v[80:83], v[4:7], v[44:47], 0
	v_mfma_f32_16x16x32_bf16 v[84:87], v[8:11], v[44:47], 0
	v_mfma_f32_16x16x32_bf16 v[88:91], v[12:15], v[44:47], 0
	v_mfma_f32_16x16x32_bf16 v[92:95], v[16:19], v[44:47], 0
	ds_read_b64 v[4:5], v225 offset:16384
	ds_read_b64 v[8:9], v225 offset:20480
	ds_read_b64 v[12:13], v225 offset:24576
	ds_read_b64 v[16:17], v225 offset:28672
	ds_read_b64 v[6:7], v226 offset:16384
	ds_read_b64 v[10:11], v226 offset:20480
	ds_read_b64 v[14:15], v226 offset:24576
	ds_read_b64 v[18:19], v226 offset:28672
	v_mfma_f32_16x16x32_bf16 v[80:83], v[20:23], v[52:55], v[80:83]
	v_mfma_f32_16x16x32_bf16 v[84:87], v[24:27], v[52:55], v[84:87]
	v_mfma_f32_16x16x32_bf16 v[88:91], v[28:31], v[52:55], v[88:91]
	v_mfma_f32_16x16x32_bf16 v[92:95], v[32:35], v[52:55], v[92:95]
	ds_read_b64 v[20:21], v227 offset:16384
	ds_read_b64 v[24:25], v227 offset:20480
	ds_read_b64 v[28:29], v227 offset:24576
	ds_read_b64 v[32:33], v227 offset:28672
	ds_read_b64 v[22:23], v228 offset:16384
	ds_read_b64 v[26:27], v228 offset:20480
	ds_read_b64 v[30:31], v228 offset:24576
	ds_read_b64 v[34:35], v228 offset:28672
	ds_bpermute_b32 v148, v239, v246
	s_waitcnt lgkmcnt(9)
	v_mfma_f32_16x16x32_bf16 v[80:83], v[4:7], v[60:63], v[80:83]
	v_mfma_f32_16x16x32_bf16 v[84:87], v[8:11], v[60:63], v[84:87]
	v_mfma_f32_16x16x32_bf16 v[88:91], v[12:15], v[60:63], v[88:91]
	v_mfma_f32_16x16x32_bf16 v[92:95], v[16:19], v[60:63], v[92:95]
	ds_read_b64 v[4:5], v229 offset:16384
	ds_read_b64 v[8:9], v229 offset:20480
	ds_read_b64 v[12:13], v229 offset:24576
	ds_read_b64 v[16:17], v229 offset:28672
	v_mov_b32_e32 v6, 0
	v_mov_b32_e32 v7, 0
	v_mov_b32_e32 v10, 0
	v_mov_b32_e32 v11, 0
	v_mov_b32_e32 v14, 0
	v_mov_b32_e32 v15, 0
	v_mov_b32_e32 v18, 0
	v_mov_b32_e32 v19, 0
	s_waitcnt lgkmcnt(5)
	v_mfma_f32_16x16x32_bf16 v[80:83], v[20:23], v[68:71], v[80:83]
	v_mfma_f32_16x16x32_bf16 v[84:87], v[24:27], v[68:71], v[84:87]
	v_mfma_f32_16x16x32_bf16 v[88:91], v[28:31], v[68:71], v[88:91]
	v_mfma_f32_16x16x32_bf16 v[92:95], v[32:35], v[68:71], v[92:95]
	s_waitcnt lgkmcnt(0)
	v_add_f32_e32 v246, v246, v148
	s_nop 0
	v_mfma_f32_16x16x32_bf16 v[80:83], v[4:7], v[76:79], v[80:83]
	v_mfma_f32_16x16x32_bf16 v[84:87], v[8:11], v[76:79], v[84:87]
	v_mfma_f32_16x16x32_bf16 v[88:91], v[12:15], v[76:79], v[88:91]
	v_mfma_f32_16x16x32_bf16 v[92:95], v[16:19], v[76:79], v[92:95]
	ds_bpermute_b32 v148, v240, v246
	s_waitcnt lgkmcnt(0)
	v_add_f32_e32 v246, v246, v148
	v_rcp_f32_e32 v149, v246
	v_log_f32_e32 v150, v246
	s_nop 0
	v_add_f32_e32 v151, v245, v150
	v_mul_f32_e32 v151, 0x3f317218, v151
	v_mov_b32_e32 v140, v151
	v_mul_f32_e32 v80, v80, v149
	v_mul_f32_e32 v81, v81, v149
	v_mul_f32_e32 v82, v82, v149
	v_mul_f32_e32 v83, v83, v149
	v_mul_f32_e32 v84, v84, v149
	v_mul_f32_e32 v85, v85, v149
	v_mul_f32_e32 v86, v86, v149
	v_mul_f32_e32 v87, v87, v149
	v_mul_f32_e32 v88, v88, v149
	v_mul_f32_e32 v89, v89, v149
	v_mul_f32_e32 v90, v90, v149
	v_mul_f32_e32 v91, v91, v149
	v_mul_f32_e32 v92, v92, v149
	v_mul_f32_e32 v93, v93, v149
	v_mul_f32_e32 v94, v94, v149
	v_mul_f32_e32 v95, v95, v149
	v_cvt_pk_bf16_f32 v132, v80, v81
	v_cvt_pk_bf16_f32 v133, v82, v83
	v_cvt_pk_bf16_f32 v134, v84, v85
	v_cvt_pk_bf16_f32 v135, v86, v87
	v_cvt_pk_bf16_f32 v136, v88, v89
	v_cvt_pk_bf16_f32 v137, v90, v91
	v_cvt_pk_bf16_f32 v138, v92, v93
	v_cvt_pk_bf16_f32 v139, v94, v95
	s_mov_b64 s[26:27], s[86:87]
	s_mov_b64 s[28:29], s[88:89]
	s_mov_b64 s[86:87], s[12:13]
	s_mov_b64 s[88:89], s[14:15]
	s_mov_b32 s4, s83
	s_mov_b32 s5, s84
	s_waitcnt vmcnt(0)
	s_barrier
	ds_read_b128 v[4:7], v230 offset:32768
	ds_read_b128 v[8:11], v231 offset:32768
	ds_read_b128 v[12:15], v230 offset:34816
	ds_read_b128 v[16:19], v231 offset:34816
	ds_read_b128 v[20:23], v230 offset:36864
	ds_read_b128 v[24:27], v231 offset:36864
	ds_read_b128 v[28:31], v230 offset:38912
	ds_read_b128 v[32:35], v231 offset:38912
	ds_read_b128 v[36:39], v230 offset:40960
	ds_read_b128 v[40:43], v231 offset:40960
	global_store_dwordx2 v237, v[132:133], s[26:27]
	global_store_dwordx2 v237, v[134:135], s[26:27] offset:32
	global_store_dwordx2 v237, v[136:137], s[26:27] offset:64
	global_store_dwordx2 v237, v[138:139], s[26:27] offset:96
	s_mov_b64 s[90:91], exec
	s_mov_b64 exec, 0xffff
	global_store_dword v238, v140, s[28:29]
	s_mov_b64 exec, s[90:91]
	s_cmp_eq_u32 s7, 1
	s_cbranch_scc1 .Lat738_i3_nonext
	s_add_u32 s83, s4, 1
	s_mov_b32 s84, s5
	s_mul_i32 s74, s84, 4096
	s_lshl_b32 s75, s83, 7
	s_add_u32 s74, s74, s75
	s_lshl_b32 s75, s74, 7
	s_add_u32 s16, s60, s75
	s_addc_u32 s17, s61, 0
	s_lshl_b32 s75, s74, 1
	s_add_u32 s24, s64, s75
	s_addc_u32 s25, s65, 0
	s_add_u32 m0, s70, 0x0
	s_nop 0
	global_load_lds_dwordx4 v232, s[16:17]
	s_add_u32 m0, s70, 0x2000
	s_nop 0
	global_load_lds_dwordx4 v233, s[16:17]
	s_add_u32 m0, s70, 0x10000
	s_nop 0
	global_load_lds_dwordx4 v234, s[24:25]
	s_add_u32 m0, s70, 0x12000
	s_nop 0
	global_load_lds_dwordx4 v235, s[24:25]
	s_lshl_b32 s74, s83, 7
	s_add_u32 s74, s74, s84
	s_lshl_b32 s75, s74, 7
	s_add_u32 s10, s30, s75
	s_addc_u32 s11, s31, 0
	s_add_u32 s12, s34, s75
	s_addc_u32 s13, s35, 0
	s_lshl_b32 s75, s74, 2
	s_add_u32 s14, s58, s75
	s_addc_u32 s15, s59, 0
	global_load_dwordx4 v[96:99], v236, s[10:11]
	global_load_dwordx4 v[100:103], v236, s[10:11] offset:64
.Lat738_i3_nonext:
	s_waitcnt lgkmcnt(0)
	v_mfma_f32_16x16x32_bf16 v[44:47], v[4:7], v[104:107], 0
	v_mfma_f32_16x16x32_bf16 v[48:51], v[12:15], v[104:107], 0
	v_mfma_f32_16x16x32_bf16 v[52:55], v[20:23], v[104:107], 0
	v_mfma_f32_16x16x32_bf16 v[56:59], v[28:31], v[104:107], 0
	v_mfma_f32_16x16x32_bf16 v[60:63], v[36:39], v[104:107], 0
	v_mfma_f32_16x16x32_bf16 v[44:47], v[8:11], v[108:111], v[44:47]
	v_mfma_f32_16x16x32_bf16 v[48:51], v[16:19], v[108:111], v[48:51]
	v_mfma_f32_16x16x32_bf16 v[52:55], v[24:27], v[108:111], v[52:55]
	v_mfma_f32_16x16x32_bf16 v[56:59], v[32:35], v[108:111], v[56:59]
	v_mfma_f32_16x16x32_bf16 v[60:63], v[40:43], v[108:111], v[60:63]
	ds_read_b128 v[4:7], v230 offset:43008
	ds_read_b128 v[8:11], v231 offset:43008
	ds_read_b128 v[12:15], v230 offset:45056
	ds_read_b128 v[16:19], v231 offset:45056
	ds_read_b128 v[20:23], v230 offset:47104
	ds_read_b128 v[24:27], v231 offset:47104
	ds_read_b128 v[28:31], v230 offset:49152
	ds_read_b128 v[32:35], v231 offset:49152
	s_nop 1
	v_fma_f32 v44, v44, s79, v185
	v_fma_f32 v45, v45, s79, v186
	v_fma_f32 v46, v46, s79, v187
	v_fma_f32 v47, v47, s79, v188
	v_fma_f32 v48, v48, s79, v189
	v_fma_f32 v49, v49, s79, v190
	v_fma_f32 v50, v50, s79, v191
	v_fma_f32 v51, v51, s79, v192
	v_fma_f32 v52, v52, s79, v193
	v_fma_f32 v53, v53, s79, v194
	v_fma_f32 v54, v54, s79, v195
	v_fma_f32 v55, v55, s79, v196
	v_fma_f32 v56, v56, s79, v197
	v_fma_f32 v57, v57, s79, v198
	v_fma_f32 v58, v58, s79, v199
	v_fma_f32 v59, v59, s79, v200
	v_fma_f32 v60, v60, s79, v201
	v_fma_f32 v61, v61, s79, v202
	v_fma_f32 v62, v62, s79, v203
	v_fma_f32 v63, v63, s79, v204
	s_waitcnt lgkmcnt(0)
	v_mfma_f32_16x16x32_bf16 v[64:67], v[4:7], v[104:107], 0
	v_mfma_f32_16x16x32_bf16 v[68:71], v[12:15], v[104:107], 0
	v_mfma_f32_16x16x32_bf16 v[72:75], v[20:23], v[104:107], 0
	v_mfma_f32_16x16x32_bf16 v[76:79], v[28:31], v[104:107], 0
	v_mfma_f32_16x16x32_bf16 v[64:67], v[8:11], v[108:111], v[64:67]
	v_mfma_f32_16x16x32_bf16 v[68:71], v[16:19], v[108:111], v[68:71]
	v_mfma_f32_16x16x32_bf16 v[72:75], v[24:27], v[108:111], v[72:75]
	v_mfma_f32_16x16x32_bf16 v[76:79], v[32:35], v[108:111], v[76:79]
	ds_read_b64 v[4:5], v221 offset:32768
	ds_read_b64 v[8:9], v221 offset:36864
	ds_read_b64 v[12:13], v221 offset:40960
	ds_read_b64 v[16:17], v221 offset:45056
	ds_read_b64 v[6:7], v222 offset:32768
	ds_read_b64 v[10:11], v222 offset:36864
	ds_read_b64 v[14:15], v222 offset:40960
	ds_read_b64 v[18:19], v222 offset:45056
	s_nop 1
	v_fma_f32 v64, v64, s79, v205
	v_fma_f32 v65, v65, s79, v206
	v_fma_f32 v66, v66, s79, v207
	v_fma_f32 v67, v67, s79, v208
	v_fma_f32 v68, v68, s79, v209
	v_fma_f32 v69, v69, s79, v210
	v_fma_f32 v70, v70, s79, v211
	v_fma_f32 v71, v71, s79, v212
	v_fma_f32 v72, v72, s79, v213
	v_fma_f32 v73, v73, s79, v214
	v_fma_f32 v74, v74, s79, v215
	v_fma_f32 v75, v75, s79, v216
	v_fma_f32 v76, v76, s79, v217
	v_fma_f32 v77, v77, s79, v218
	v_fma_f32 v78, v78, s79, v219
	v_fma_f32 v79, v79, s79, v220
	ds_read_b64 v[20:21], v223 offset:32768
	ds_read_b64 v[24:25], v223 offset:36864
	ds_read_b64 v[28:29], v223 offset:40960
	ds_read_b64 v[32:33], v223 offset:45056
	ds_read_b64 v[22:23], v224 offset:32768
	ds_read_b64 v[26:27], v224 offset:36864
	ds_read_b64 v[30:31], v224 offset:40960
	ds_read_b64 v[34:35], v224 offset:45056
	s_cmp_lg_u32 s4, 0
	s_cbranch_scc1 .Lat738_i3_nomask
	s_cmp_le_u32 s6, 0
	s_cbranch_scc1 .Lat738_i3_nomask
	v_mov_b32_e32 v44, v244
	v_mov_b32_e32 v45, v244
	v_mov_b32_e32 v46, v244
	v_mov_b32_e32 v47, v244
	s_cmp_le_u32 s6, 1
	s_cbranch_scc1 .Lat738_i3_nomask
	v_mov_b32_e32 v48, v244
	v_mov_b32_e32 v49, v244
	v_mov_b32_e32 v50, v244
	v_mov_b32_e32 v51, v244
	s_cmp_le_u32 s6, 2
	s_cbranch_scc1 .Lat738_i3_nomask
	v_mov_b32_e32 v52, v244
	v_mov_b32_e32 v53, v244
	v_mov_b32_e32 v54, v244
	v_mov_b32_e32 v55, v244
	s_cmp_le_u32 s6, 3
	s_cbranch_scc1 .Lat738_i3_nomask
	v_mov_b32_e32 v56, v244
	v_mov_b32_e32 v57, v244
	v_mov_b32_e32 v58, v244
	v_mov_b32_e32 v59, v244
	s_cmp_le_u32 s6, 4
	s_cbranch_scc1 .Lat738_i3_nomask
	v_mov_b32_e32 v60, v244
	v_mov_b32_e32 v61, v244
	v_mov_b32_e32 v62, v244
	v_mov_b32_e32 v63, v244
	s_cmp_le_u32 s6, 5
	s_cbranch_scc1 .Lat738_i3_nomask
	v_mov_b32_e32 v64, v244
	v_mov_b32_e32 v65, v244
	v_mov_b32_e32 v66, v244
	v_mov_b32_e32 v67, v244
	s_cmp_le_u32 s6, 6
	s_cbranch_scc1 .Lat738_i3_nomask
	v_mov_b32_e32 v68, v244
	v_mov_b32_e32 v69, v244
	v_mov_b32_e32 v70, v244
	v_mov_b32_e32 v71, v244
	s_cmp_le_u32 s6, 7
	s_cbranch_scc1 .Lat738_i3_nomask
	v_mov_b32_e32 v72, v244
	v_mov_b32_e32 v73, v244
	v_mov_b32_e32 v74, v244
	v_mov_b32_e32 v75, v244
.Lat738_i3_nomask:
	v_max3_f32 v245, v44, v45, v46
	v_max3_f32 v245, v245, v47, v48
	v_max3_f32 v245, v245, v49, v50
	v_max3_f32 v245, v245, v51, v52
	v_max3_f32 v245, v245, v53, v54
	v_max3_f32 v245, v245, v55, v56
	v_max3_f32 v245, v245, v57, v58
	v_max3_f32 v245, v245, v59, v60
	v_max3_f32 v245, v245, v61, v62
	v_max3_f32 v245, v245, v63, v64
	v_max3_f32 v245, v245, v65, v66
	v_max3_f32 v245, v245, v67, v68
	v_max3_f32 v245, v245, v69, v70
	v_max3_f32 v245, v245, v71, v72
	v_max3_f32 v245, v245, v73, v74
	v_max3_f32 v245, v245, v75, v76
	v_max3_f32 v245, v245, v77, v78
	v_max_f32_e32 v245, v245, v79
	ds_bpermute_b32 v148, v239, v245
	s_waitcnt lgkmcnt(0)
	v_max_f32_e32 v245, v245, v148
	ds_bpermute_b32 v148, v240, v245
	s_waitcnt lgkmcnt(0)
	v_max_f32_e32 v245, v245, v148
	v_sub_f32_e32 v44, v44, v245
	v_sub_f32_e32 v45, v45, v245
	v_sub_f32_e32 v46, v46, v245
	v_sub_f32_e32 v47, v47, v245
	v_exp_f32_e32 v44, v44
	v_exp_f32_e32 v45, v45
	v_exp_f32_e32 v46, v46
	v_exp_f32_e32 v47, v47
	v_sub_f32_e32 v48, v48, v245
	v_sub_f32_e32 v49, v49, v245
	v_sub_f32_e32 v50, v50, v245
	v_sub_f32_e32 v51, v51, v245
	v_exp_f32_e32 v48, v48
	v_exp_f32_e32 v49, v49
	v_exp_f32_e32 v50, v50
	v_exp_f32_e32 v51, v51
	v_mov_b32_e32 v149, v44
	v_mov_b32_e32 v150, v45
	v_mov_b32_e32 v151, v46
	v_mov_b32_e32 v152, v47
	v_cvt_pk_bf16_f32 v44, v44, v45
	v_cvt_pk_bf16_f32 v45, v46, v47
	v_sub_f32_e32 v52, v52, v245
	v_sub_f32_e32 v53, v53, v245
	v_sub_f32_e32 v54, v54, v245
	v_sub_f32_e32 v55, v55, v245
	v_exp_f32_e32 v52, v52
	v_exp_f32_e32 v53, v53
	v_exp_f32_e32 v54, v54
	v_exp_f32_e32 v55, v55
	v_add_f32_e32 v149, v149, v48
	v_add_f32_e32 v150, v150, v49
	v_add_f32_e32 v151, v151, v50
	v_add_f32_e32 v152, v152, v51
	v_cvt_pk_bf16_f32 v46, v48, v49
	v_cvt_pk_bf16_f32 v47, v50, v51
	v_sub_f32_e32 v56, v56, v245
	v_sub_f32_e32 v57, v57, v245
	v_sub_f32_e32 v58, v58, v245
	v_sub_f32_e32 v59, v59, v245
	v_exp_f32_e32 v56, v56
	v_exp_f32_e32 v57, v57
	v_exp_f32_e32 v58, v58
	v_exp_f32_e32 v59, v59
	v_add_f32_e32 v149, v149, v52
	v_add_f32_e32 v150, v150, v53
	v_add_f32_e32 v151, v151, v54
	v_add_f32_e32 v152, v152, v55
	v_cvt_pk_bf16_f32 v52, v52, v53
	v_cvt_pk_bf16_f32 v53, v54, v55
	v_sub_f32_e32 v60, v60, v245
	v_sub_f32_e32 v61, v61, v245
	v_sub_f32_e32 v62, v62, v245
	v_sub_f32_e32 v63, v63, v245
	v_exp_f32_e32 v60, v60
	v_exp_f32_e32 v61, v61
	v_exp_f32_e32 v62, v62
	v_exp_f32_e32 v63, v63
	v_add_f32_e32 v149, v149, v56
	v_add_f32_e32 v150, v150, v57
	v_add_f32_e32 v151, v151, v58
	v_add_f32_e32 v152, v152, v59
	v_cvt_pk_bf16_f32 v54, v56, v57
	v_cvt_pk_bf16_f32 v55, v58, v59
	v_sub_f32_e32 v64, v64, v245
	v_sub_f32_e32 v65, v65, v245
	v_sub_f32_e32 v66, v66, v245
	v_sub_f32_e32 v67, v67, v245
	v_exp_f32_e32 v64, v64
	v_exp_f32_e32 v65, v65
	v_exp_f32_e32 v66, v66
	v_exp_f32_e32 v67, v67
	v_add_f32_e32 v149, v149, v60
	v_add_f32_e32 v150, v150, v61
	v_add_f32_e32 v151, v151, v62
	v_add_f32_e32 v152, v152, v63
	v_cvt_pk_bf16_f32 v60, v60, v61
	v_cvt_pk_bf16_f32 v61, v62, v63
	v_sub_f32_e32 v68, v68, v245
	v_sub_f32_e32 v69, v69, v245
	v_sub_f32_e32 v70, v70, v245
	v_sub_f32_e32 v71, v71, v245
	v_exp_f32_e32 v68, v68
	v_exp_f32_e32 v69, v69
	v_exp_f32_e32 v70, v70
	v_exp_f32_e32 v71, v71
	v_add_f32_e32 v149, v149, v64
	v_add_f32_e32 v150, v150, v65
	v_add_f32_e32 v151, v151, v66
	v_add_f32_e32 v152, v152, v67
	v_cvt_pk_bf16_f32 v62, v64, v65
	v_cvt_pk_bf16_f32 v63, v66, v67
	v_sub_f32_e32 v72, v72, v245
	v_sub_f32_e32 v73, v73, v245
	v_sub_f32_e32 v74, v74, v245
	v_sub_f32_e32 v75, v75, v245
	v_exp_f32_e32 v72, v72
	v_exp_f32_e32 v73, v73
	v_exp_f32_e32 v74, v74
	v_exp_f32_e32 v75, v75
	v_add_f32_e32 v149, v149, v68
	v_add_f32_e32 v150, v150, v69
	v_add_f32_e32 v151, v151, v70
	v_add_f32_e32 v152, v152, v71
	v_cvt_pk_bf16_f32 v68, v68, v69
	v_cvt_pk_bf16_f32 v69, v70, v71
	v_sub_f32_e32 v76, v76, v245
	v_sub_f32_e32 v77, v77, v245
	v_sub_f32_e32 v78, v78, v245
	v_sub_f32_e32 v79, v79, v245
	v_exp_f32_e32 v76, v76
	v_exp_f32_e32 v77, v77
	v_exp_f32_e32 v78, v78
	v_exp_f32_e32 v79, v79
	v_add_f32_e32 v149, v149, v72
	v_add_f32_e32 v150, v150, v73
	v_add_f32_e32 v151, v151, v74
	v_add_f32_e32 v152, v152, v75
	v_cvt_pk_bf16_f32 v70, v72, v73
	v_cvt_pk_bf16_f32 v71, v74, v75
	s_nop 0
	v_add_f32_e32 v149, v149, v76
	v_add_f32_e32 v150, v150, v77
	v_add_f32_e32 v151, v151, v78
	v_add_f32_e32 v152, v152, v79
	v_cvt_pk_bf16_f32 v76, v76, v77
	v_cvt_pk_bf16_f32 v77, v78, v79
	v_mov_b32_e32 v78, 0
	v_mov_b32_e32 v79, 0
	v_add_f32_e32 v149, v149, v150
	v_add_f32_e32 v151, v151, v152
	v_add_f32_e32 v246, v149, v151
	s_waitcnt lgkmcnt(0)
	v_mfma_f32_16x16x32_bf16 v[80:83], v[4:7], v[44:47], 0
	v_mfma_f32_16x16x32_bf16 v[84:87], v[8:11], v[44:47], 0
	v_mfma_f32_16x16x32_bf16 v[88:91], v[12:15], v[44:47], 0
	v_mfma_f32_16x16x32_bf16 v[92:95], v[16:19], v[44:47], 0
	ds_read_b64 v[4:5], v225 offset:32768
	ds_read_b64 v[8:9], v225 offset:36864
	ds_read_b64 v[12:13], v225 offset:40960
	ds_read_b64 v[16:17], v225 offset:45056
	ds_read_b64 v[6:7], v226 offset:32768
	ds_read_b64 v[10:11], v226 offset:36864
	ds_read_b64 v[14:15], v226 offset:40960
	ds_read_b64 v[18:19], v226 offset:45056
	v_mfma_f32_16x16x32_bf16 v[80:83], v[20:23], v[52:55], v[80:83]
	v_mfma_f32_16x16x32_bf16 v[84:87], v[24:27], v[52:55], v[84:87]
	v_mfma_f32_16x16x32_bf16 v[88:91], v[28:31], v[52:55], v[88:91]
	v_mfma_f32_16x16x32_bf16 v[92:95], v[32:35], v[52:55], v[92:95]
	ds_read_b64 v[20:21], v227 offset:32768
	ds_read_b64 v[24:25], v227 offset:36864
	ds_read_b64 v[28:29], v227 offset:40960
	ds_read_b64 v[32:33], v227 offset:45056
	ds_read_b64 v[22:23], v228 offset:32768
	ds_read_b64 v[26:27], v228 offset:36864
	ds_read_b64 v[30:31], v228 offset:40960
	ds_read_b64 v[34:35], v228 offset:45056
	ds_bpermute_b32 v148, v239, v246
	s_waitcnt lgkmcnt(9)
	v_mfma_f32_16x16x32_bf16 v[80:83], v[4:7], v[60:63], v[80:83]
	v_mfma_f32_16x16x32_bf16 v[84:87], v[8:11], v[60:63], v[84:87]
	v_mfma_f32_16x16x32_bf16 v[88:91], v[12:15], v[60:63], v[88:91]
	v_mfma_f32_16x16x32_bf16 v[92:95], v[16:19], v[60:63], v[92:95]
	ds_read_b64 v[4:5], v229 offset:32768
	ds_read_b64 v[8:9], v229 offset:36864
	ds_read_b64 v[12:13], v229 offset:40960
	ds_read_b64 v[16:17], v229 offset:45056
	v_mov_b32_e32 v6, 0
	v_mov_b32_e32 v7, 0
	v_mov_b32_e32 v10, 0
	v_mov_b32_e32 v11, 0
	v_mov_b32_e32 v14, 0
	v_mov_b32_e32 v15, 0
	v_mov_b32_e32 v18, 0
	v_mov_b32_e32 v19, 0
	s_waitcnt lgkmcnt(5)
	v_mfma_f32_16x16x32_bf16 v[80:83], v[20:23], v[68:71], v[80:83]
	v_mfma_f32_16x16x32_bf16 v[84:87], v[24:27], v[68:71], v[84:87]
	v_mfma_f32_16x16x32_bf16 v[88:91], v[28:31], v[68:71], v[88:91]
	v_mfma_f32_16x16x32_bf16 v[92:95], v[32:35], v[68:71], v[92:95]
	s_waitcnt lgkmcnt(0)
	v_add_f32_e32 v246, v246, v148
	s_nop 0
	v_mfma_f32_16x16x32_bf16 v[80:83], v[4:7], v[76:79], v[80:83]
	v_mfma_f32_16x16x32_bf16 v[84:87], v[8:11], v[76:79], v[84:87]
	v_mfma_f32_16x16x32_bf16 v[88:91], v[12:15], v[76:79], v[88:91]
	v_mfma_f32_16x16x32_bf16 v[92:95], v[16:19], v[76:79], v[92:95]
	ds_bpermute_b32 v148, v240, v246
	s_waitcnt lgkmcnt(0)
	v_add_f32_e32 v246, v246, v148
	v_rcp_f32_e32 v149, v246
	v_log_f32_e32 v150, v246
	s_nop 0
	v_add_f32_e32 v151, v245, v150
	v_mul_f32_e32 v151, 0x3f317218, v151
	v_mov_b32_e32 v140, v151
	v_mul_f32_e32 v80, v80, v149
	v_mul_f32_e32 v81, v81, v149
	v_mul_f32_e32 v82, v82, v149
	v_mul_f32_e32 v83, v83, v149
	v_mul_f32_e32 v84, v84, v149
	v_mul_f32_e32 v85, v85, v149
	v_mul_f32_e32 v86, v86, v149
	v_mul_f32_e32 v87, v87, v149
	v_mul_f32_e32 v88, v88, v149
	v_mul_f32_e32 v89, v89, v149
	v_mul_f32_e32 v90, v90, v149
	v_mul_f32_e32 v91, v91, v149
	v_mul_f32_e32 v92, v92, v149
	v_mul_f32_e32 v93, v93, v149
	v_mul_f32_e32 v94, v94, v149
	v_mul_f32_e32 v95, v95, v149
	v_cvt_pk_bf16_f32 v132, v80, v81
	v_cvt_pk_bf16_f32 v133, v82, v83
	v_cvt_pk_bf16_f32 v134, v84, v85
	v_cvt_pk_bf16_f32 v135, v86, v87
	v_cvt_pk_bf16_f32 v136, v88, v89
	v_cvt_pk_bf16_f32 v137, v90, v91
	v_cvt_pk_bf16_f32 v138, v92, v93
	v_cvt_pk_bf16_f32 v139, v94, v95
	s_mov_b64 s[26:27], s[86:87]
	s_mov_b64 s[28:29], s[88:89]
	s_mov_b64 s[86:87], s[12:13]
	s_mov_b64 s[88:89], s[14:15]
	s_mov_b32 s4, s83
	s_mov_b32 s5, s84
	s_add_u32 s7, s7, 1
	s_cmp_lt_u32 s7, 2
	s_cbranch_scc1 .Lat738_loop
	s_setprio 0
	global_store_dwordx2 v237, v[132:133], s[26:27]
	global_store_dwordx2 v237, v[134:135], s[26:27] offset:32
	global_store_dwordx2 v237, v[136:137], s[26:27] offset:64
	global_store_dwordx2 v237, v[138:139], s[26:27] offset:96
	s_mov_b64 s[90:91], exec
	s_mov_b64 exec, 0xffff
	global_store_dword v238, v140, s[28:29]
	s_mov_b64 exec, s[90:91]
	s_mov_b64 s[0:1], s[42:43]
	v_writelane_b32 v253, s0, 4
	s_waitcnt vmcnt(0)
	v_readlane_b32 s34, v252, 27
	v_readlane_b32 s36, v252, 29
	v_writelane_b32 v253, s1, 5
	v_readlane_b32 s70, v252, 31
	v_readlane_b32 s56, v253, 19
	v_readlane_b32 s16, v253, 21
	v_readlane_b32 s74, v252, 33
	v_readlane_b32 s76, v252, 35
	v_readlane_b32 s78, v252, 37
	s_mov_b64 s[6:7], 0
	v_readlane_b32 s85, v253, 23
	v_readlane_b32 s92, v253, 24
	v_readlane_b32 s35, v252, 28
	v_readlane_b32 s57, v253, 20
	v_readlane_b32 s17, v253, 22
	v_readlane_b32 s37, v252, 30
	v_readlane_b32 s71, v252, 32
	v_readlane_b32 s75, v252, 34
	v_readlane_b32 s77, v252, 36
	v_readlane_b32 s79, v252, 38
	s_barrier
	v_readlane_b32 s93, v253, 25

.Lat768_i3_nomask:
	v_max3_f32 v245, v44, v45, v46
	v_max3_f32 v245, v245, v47, v48
	v_max3_f32 v245, v245, v49, v50
	v_max3_f32 v245, v245, v51, v52
	v_max3_f32 v245, v245, v53, v54
	v_max3_f32 v245, v245, v55, v56
	v_max3_f32 v245, v245, v57, v58
	v_max3_f32 v245, v245, v59, v60
	v_max3_f32 v245, v245, v61, v62
	v_max3_f32 v245, v245, v63, v64
	v_max3_f32 v245, v245, v65, v66
	v_max3_f32 v245, v245, v67, v68
	v_max3_f32 v245, v245, v69, v70
	v_max3_f32 v245, v245, v71, v72
	v_max3_f32 v245, v245, v73, v74
	v_max3_f32 v245, v245, v75, v76
	v_max3_f32 v245, v245, v77, v78
	v_max_f32_e32 v245, v245, v79
	ds_bpermute_b32 v148, v239, v245
	s_waitcnt lgkmcnt(0)
	v_max_f32_e32 v245, v245, v148
	ds_bpermute_b32 v148, v240, v245
	s_waitcnt lgkmcnt(0)
	v_max_f32_e32 v245, v245, v148
	v_sub_f32_e32 v44, v44, v245
	v_sub_f32_e32 v45, v45, v245
	v_sub_f32_e32 v46, v46, v245
	v_sub_f32_e32 v47, v47, v245
	v_exp_f32_e32 v44, v44
	v_exp_f32_e32 v45, v45
	v_exp_f32_e32 v46, v46
	v_exp_f32_e32 v47, v47
	v_sub_f32_e32 v48, v48, v245
	v_sub_f32_e32 v49, v49, v245
	v_sub_f32_e32 v50, v50, v245
	v_sub_f32_e32 v51, v51, v245
	v_exp_f32_e32 v48, v48
	v_exp_f32_e32 v49, v49
	v_exp_f32_e32 v50, v50
	v_exp_f32_e32 v51, v51
	v_mov_b32_e32 v149, v44
	v_mov_b32_e32 v150, v45
	v_mov_b32_e32 v151, v46
	v_mov_b32_e32 v152, v47
	v_cvt_pk_bf16_f32 v44, v44, v45
	v_cvt_pk_bf16_f32 v45, v46, v47
	v_sub_f32_e32 v52, v52, v245
	v_sub_f32_e32 v53, v53, v245
	v_sub_f32_e32 v54, v54, v245
	v_sub_f32_e32 v55, v55, v245
	v_exp_f32_e32 v52, v52
	v_exp_f32_e32 v53, v53
	v_exp_f32_e32 v54, v54
	v_exp_f32_e32 v55, v55
	v_add_f32_e32 v149, v149, v48
	v_add_f32_e32 v150, v150, v49
	v_add_f32_e32 v151, v151, v50
	v_add_f32_e32 v152, v152, v51
	v_cvt_pk_bf16_f32 v46, v48, v49
	v_cvt_pk_bf16_f32 v47, v50, v51
	v_sub_f32_e32 v56, v56, v245
	v_sub_f32_e32 v57, v57, v245
	v_sub_f32_e32 v58, v58, v245
	v_sub_f32_e32 v59, v59, v245
	v_exp_f32_e32 v56, v56
	v_exp_f32_e32 v57, v57
	v_exp_f32_e32 v58, v58
	v_exp_f32_e32 v59, v59
	v_add_f32_e32 v149, v149, v52
	v_add_f32_e32 v150, v150, v53
	v_add_f32_e32 v151, v151, v54
	v_add_f32_e32 v152, v152, v55
	v_cvt_pk_bf16_f32 v52, v52, v53
	v_cvt_pk_bf16_f32 v53, v54, v55
	v_sub_f32_e32 v60, v60, v245
	v_sub_f32_e32 v61, v61, v245
	v_sub_f32_e32 v62, v62, v245
	v_sub_f32_e32 v63, v63, v245
	v_exp_f32_e32 v60, v60
	v_exp_f32_e32 v61, v61
	v_exp_f32_e32 v62, v62
	v_exp_f32_e32 v63, v63
	v_add_f32_e32 v149, v149, v56
	v_add_f32_e32 v150, v150, v57
	v_add_f32_e32 v151, v151, v58
	v_add_f32_e32 v152, v152, v59
	v_cvt_pk_bf16_f32 v54, v56, v57
	v_cvt_pk_bf16_f32 v55, v58, v59
	v_sub_f32_e32 v64, v64, v245
	v_sub_f32_e32 v65, v65, v245
	v_sub_f32_e32 v66, v66, v245
	v_sub_f32_e32 v67, v67, v245
	v_exp_f32_e32 v64, v64
	v_exp_f32_e32 v65, v65
	v_exp_f32_e32 v66, v66
	v_exp_f32_e32 v67, v67
	v_add_f32_e32 v149, v149, v60
	v_add_f32_e32 v150, v150, v61
	v_add_f32_e32 v151, v151, v62
	v_add_f32_e32 v152, v152, v63
	v_cvt_pk_bf16_f32 v60, v60, v61
	v_cvt_pk_bf16_f32 v61, v62, v63
	v_sub_f32_e32 v68, v68, v245
	v_sub_f32_e32 v69, v69, v245
	v_sub_f32_e32 v70, v70, v245
	v_sub_f32_e32 v71, v71, v245
	v_exp_f32_e32 v68, v68
	v_exp_f32_e32 v69, v69
	v_exp_f32_e32 v70, v70
	v_exp_f32_e32 v71, v71
	v_add_f32_e32 v149, v149, v64
	v_add_f32_e32 v150, v150, v65
	v_add_f32_e32 v151, v151, v66
	v_add_f32_e32 v152, v152, v67
	v_cvt_pk_bf16_f32 v62, v64, v65
	v_cvt_pk_bf16_f32 v63, v66, v67
	v_sub_f32_e32 v72, v72, v245
	v_sub_f32_e32 v73, v73, v245
	v_sub_f32_e32 v74, v74, v245
	v_sub_f32_e32 v75, v75, v245
	v_exp_f32_e32 v72, v72
	v_exp_f32_e32 v73, v73
	v_exp_f32_e32 v74, v74
	v_exp_f32_e32 v75, v75
	v_add_f32_e32 v149, v149, v68
	v_add_f32_e32 v150, v150, v69
	v_add_f32_e32 v151, v151, v70
	v_add_f32_e32 v152, v152, v71
	v_cvt_pk_bf16_f32 v68, v68, v69
	v_cvt_pk_bf16_f32 v69, v70, v71
	v_sub_f32_e32 v76, v76, v245
	v_sub_f32_e32 v77, v77, v245
	v_sub_f32_e32 v78, v78, v245
	v_sub_f32_e32 v79, v79, v245
	v_exp_f32_e32 v76, v76
	v_exp_f32_e32 v77, v77
	v_exp_f32_e32 v78, v78
	v_exp_f32_e32 v79, v79
	v_add_f32_e32 v149, v149, v72
	v_add_f32_e32 v150, v150, v73
	v_add_f32_e32 v151, v151, v74
	v_add_f32_e32 v152, v152, v75
	v_cvt_pk_bf16_f32 v70, v72, v73
	v_cvt_pk_bf16_f32 v71, v74, v75
	s_nop 0
	v_add_f32_e32 v149, v149, v76
	v_add_f32_e32 v150, v150, v77
	v_add_f32_e32 v151, v151, v78
	v_add_f32_e32 v152, v152, v79
	v_cvt_pk_bf16_f32 v76, v76, v77
	v_cvt_pk_bf16_f32 v77, v78, v79
	v_mov_b32_e32 v78, 0
	v_mov_b32_e32 v79, 0
	v_add_f32_e32 v149, v149, v150
	v_add_f32_e32 v151, v151, v152
	v_add_f32_e32 v246, v149, v151
	s_waitcnt lgkmcnt(0)
	v_mfma_f32_16x16x32_bf16 v[80:83], v[4:7], v[44:47], 0
	v_mfma_f32_16x16x32_bf16 v[84:87], v[8:11], v[44:47], 0
	v_mfma_f32_16x16x32_bf16 v[88:91], v[12:15], v[44:47], 0
	v_mfma_f32_16x16x32_bf16 v[92:95], v[16:19], v[44:47], 0
	ds_read_b64 v[4:5], v225 offset:32768
	ds_read_b64 v[8:9], v225 offset:36864
	ds_read_b64 v[12:13], v225 offset:40960
	ds_read_b64 v[16:17], v225 offset:45056
	ds_read_b64 v[6:7], v226 offset:32768
	ds_read_b64 v[10:11], v226 offset:36864
	ds_read_b64 v[14:15], v226 offset:40960
	ds_read_b64 v[18:19], v226 offset:45056
	v_mfma_f32_16x16x32_bf16 v[80:83], v[20:23], v[52:55], v[80:83]
	v_mfma_f32_16x16x32_bf16 v[84:87], v[24:27], v[52:55], v[84:87]
	v_mfma_f32_16x16x32_bf16 v[88:91], v[28:31], v[52:55], v[88:91]
	v_mfma_f32_16x16x32_bf16 v[92:95], v[32:35], v[52:55], v[92:95]
	ds_read_b64 v[20:21], v227 offset:32768
	ds_read_b64 v[24:25], v227 offset:36864
	ds_read_b64 v[28:29], v227 offset:40960
	ds_read_b64 v[32:33], v227 offset:45056
	ds_read_b64 v[22:23], v228 offset:32768
	ds_read_b64 v[26:27], v228 offset:36864
	ds_read_b64 v[30:31], v228 offset:40960
	ds_read_b64 v[34:35], v228 offset:45056
	ds_bpermute_b32 v148, v239, v246
	s_waitcnt lgkmcnt(9)
	v_mfma_f32_16x16x32_bf16 v[80:83], v[4:7], v[60:63], v[80:83]
	v_mfma_f32_16x16x32_bf16 v[84:87], v[8:11], v[60:63], v[84:87]
	v_mfma_f32_16x16x32_bf16 v[88:91], v[12:15], v[60:63], v[88:91]
	v_mfma_f32_16x16x32_bf16 v[92:95], v[16:19], v[60:63], v[92:95]
	ds_read_b64 v[4:5], v229 offset:32768
	ds_read_b64 v[8:9], v229 offset:36864
	ds_read_b64 v[12:13], v229 offset:40960
	ds_read_b64 v[16:17], v229 offset:45056
	v_mov_b32_e32 v6, 0
	v_mov_b32_e32 v7, 0
	v_mov_b32_e32 v10, 0
	v_mov_b32_e32 v11, 0
	v_mov_b32_e32 v14, 0
	v_mov_b32_e32 v15, 0
	v_mov_b32_e32 v18, 0
	v_mov_b32_e32 v19, 0
	s_waitcnt lgkmcnt(5)
	v_mfma_f32_16x16x32_bf16 v[80:83], v[20:23], v[68:71], v[80:83]
	v_mfma_f32_16x16x32_bf16 v[84:87], v[24:27], v[68:71], v[84:87]
	v_mfma_f32_16x16x32_bf16 v[88:91], v[28:31], v[68:71], v[88:91]
	v_mfma_f32_16x16x32_bf16 v[92:95], v[32:35], v[68:71], v[92:95]
	s_waitcnt lgkmcnt(0)
	v_add_f32_e32 v246, v246, v148
	s_nop 0
	v_mfma_f32_16x16x32_bf16 v[80:83], v[4:7], v[76:79], v[80:83]
	v_mfma_f32_16x16x32_bf16 v[84:87], v[8:11], v[76:79], v[84:87]
	v_mfma_f32_16x16x32_bf16 v[88:91], v[12:15], v[76:79], v[88:91]
	v_mfma_f32_16x16x32_bf16 v[92:95], v[16:19], v[76:79], v[92:95]
	ds_bpermute_b32 v148, v240, v246
	s_waitcnt lgkmcnt(0)
	v_add_f32_e32 v246, v246, v148
	v_rcp_f32_e32 v149, v246
	v_log_f32_e32 v150, v246
	s_nop 0
	v_add_f32_e32 v151, v245, v150
	v_mul_f32_e32 v151, 0x3f317218, v151
	v_mov_b32_e32 v140, v151
	v_mul_f32_e32 v80, v80, v149
	v_mul_f32_e32 v81, v81, v149
	v_mul_f32_e32 v82, v82, v149
	v_mul_f32_e32 v83, v83, v149
	v_mul_f32_e32 v84, v84, v149
	v_mul_f32_e32 v85, v85, v149
	v_mul_f32_e32 v86, v86, v149
	v_mul_f32_e32 v87, v87, v149
	v_mul_f32_e32 v88, v88, v149
	v_mul_f32_e32 v89, v89, v149
	v_mul_f32_e32 v90, v90, v149
	v_mul_f32_e32 v91, v91, v149
	v_mul_f32_e32 v92, v92, v149
	v_mul_f32_e32 v93, v93, v149
	v_mul_f32_e32 v94, v94, v149
	v_mul_f32_e32 v95, v95, v149
	v_cvt_pk_bf16_f32 v132, v80, v81
	v_cvt_pk_bf16_f32 v133, v82, v83
	v_cvt_pk_bf16_f32 v134, v84, v85
	v_cvt_pk_bf16_f32 v135, v86, v87
	v_cvt_pk_bf16_f32 v136, v88, v89
	v_cvt_pk_bf16_f32 v137, v90, v91
	v_cvt_pk_bf16_f32 v138, v92, v93
	v_cvt_pk_bf16_f32 v139, v94, v95
	s_mov_b64 s[26:27], s[86:87]
	s_mov_b64 s[28:29], s[88:89]
	s_mov_b64 s[86:87], s[12:13]
	s_mov_b64 s[88:89], s[14:15]
	s_mov_b32 s4, s83
	s_mov_b32 s5, s84
	s_add_u32 s7, s7, 1
	s_cmp_lt_u32 s7, 2
	s_cbranch_scc1 .Lat768_loop
	s_setprio 0
	global_store_dwordx2 v237, v[132:133], s[26:27]
	global_store_dwordx2 v237, v[134:135], s[26:27] offset:32
	global_store_dwordx2 v237, v[136:137], s[26:27] offset:64
	global_store_dwordx2 v237, v[138:139], s[26:27] offset:96
	s_mov_b64 s[90:91], exec
	s_mov_b64 exec, 0xffff
	global_store_dword v238, v140, s[28:29]
	s_mov_b64 exec, s[90:91]
	v_readlane_b32 s0, v253, 62
	v_readlane_b32 s1, v253, 63
	s_waitcnt vmcnt(0)
	v_readlane_b32 s34, v252, 27
	v_writelane_b32 v253, s0, 4
	v_readlane_b32 s36, v252, 29
	v_readlane_b32 s70, v252, 31
	v_writelane_b32 v253, s1, 5
	v_readlane_b32 s74, v252, 33
	v_readlane_b32 s56, v253, 19
	v_readlane_b32 s16, v253, 21
	v_readlane_b32 s76, v252, 35
	v_readlane_b32 s78, v252, 37
	s_barrier
	v_readlane_b32 s35, v252, 28
	v_readlane_b32 s57, v253, 20
	v_readlane_b32 s17, v253, 22
	v_readlane_b32 s37, v252, 30
	v_readlane_b32 s71, v252, 32
	v_readlane_b32 s75, v252, 34
	v_readlane_b32 s77, v252, 36
	v_readlane_b32 s79, v252, 38
.LBB0_789:
	v_mov_b32_e32 v0, v170
	v_readlane_b32 s6, v253, 57
	v_readfirstlane_b32 s0, v0
	v_and_b32_e32 v4, 63, v0
	s_ashr_i32 s0, s0, 6
	v_mov_b32_e32 v5, v4
	s_lshl_b32 s1, s0, 3
	v_ashrrev_i32_e32 v6, 3, v5
	v_add_u32_e32 v0, s1, v6
	v_lshrrev_b32_e32 v1, 1, v0
	v_xor_b32_e32 v2, v1, v5
	v_ashrrev_i32_e32 v1, 31, v0
	v_lshlrev_b64 v[0:1], 7, v[0:1]
	v_readlane_b32 s7, v253, 58
	v_lshlrev_b32_e32 v2, 4, v2
	v_and_b32_e32 v2, 0x70, v2
	v_lshl_add_u64 v[0:1], s[6:7], 0, v[0:1]
	s_lshl_b32 s2, s0, 10
	s_add_i32 s82, 0, 0x18000
	s_add_i32 s3, s0, 8
	v_lshl_add_u64 v[0:1], v[0:1], 0, v[2:3]
	s_add_i32 m0, s82, s2
	s_lshl_b32 s4, s3, 3
	global_load_lds_dwordx4 v[0:1], off
	v_add_u32_e32 v0, s4, v6
	v_lshrrev_b32_e32 v1, 1, v0
	v_xor_b32_e32 v2, v1, v5
	v_ashrrev_i32_e32 v1, 31, v0
	v_lshlrev_b64 v[0:1], 7, v[0:1]
	v_lshlrev_b32_e32 v2, 4, v2
	v_lshl_add_u64 v[0:1], s[6:7], 0, v[0:1]
	v_and_b32_e32 v2, 0x70, v2
	s_lshl_b32 s5, s3, 10
	v_lshl_add_u64 v[0:1], v[0:1], 0, v[2:3]
	s_add_i32 m0, s82, s5
	v_ashrrev_i32_e32 v6, 4, v5
	s_lshl_b32 s0, s0, 2
	global_load_lds_dwordx4 v[0:1], off
	v_add_u32_e32 v0, s0, v6
	v_xor_b32_e32 v2, v0, v5
	v_ashrrev_i32_e32 v1, 31, v0
	v_readlane_b32 s8, v253, 59
	v_lshlrev_b64 v[0:1], 15, v[0:1]
	v_readlane_b32 s9, v253, 60
	v_lshlrev_b32_e32 v2, 4, v2
	v_and_b32_e32 v2, 0xf0, v2
	v_lshl_add_u64 v[0:1], s[8:9], 0, v[0:1]
	s_add_i32 s62, 0, 0x1c000
	v_lshl_add_u64 v[0:1], v[0:1], 0, v[2:3]
	s_add_i32 m0, s62, s2
	s_lshl_b32 s3, s3, 2
	global_load_lds_dwordx4 v[0:1], off
	v_add_u32_e32 v0, s3, v6
	v_xor_b32_e32 v2, v0, v5
	v_ashrrev_i32_e32 v1, 31, v0
	v_lshlrev_b64 v[0:1], 15, v[0:1]
	v_lshlrev_b32_e32 v2, 4, v2
	v_lshl_add_u64 v[0:1], s[8:9], 0, v[0:1]
	v_and_b32_e32 v2, 0xf0, v2
	v_lshl_add_u64 v[0:1], v[0:1], 0, v[2:3]
	s_add_i32 m0, s62, s5
	s_nop 0
	global_load_lds_dwordx4 v[0:1], off
	s_nop 0
	v_ashrrev_i32_e32 v5, 3, v4
	v_add_u32_e32 v0, s1, v5
	v_lshrrev_b32_e32 v1, 1, v0
	v_xor_b32_e32 v2, v1, v4
	v_ashrrev_i32_e32 v1, 31, v0
	v_lshlrev_b64 v[0:1], 7, v[0:1]
	v_lshlrev_b32_e32 v2, 4, v2
	v_lshl_add_u64 v[0:1], s[6:7], 0, v[0:1]
	v_and_b32_e32 v2, 0x70, v2
	s_add_i32 s1, s2, 0
	v_lshl_add_u64 v[0:1], v[0:1], 0, v[2:3]
	s_mov_b32 m0, s1
	s_add_i32 s2, s5, 0
	global_load_lds_dwordx4 v[0:1], off
	v_add_u32_e32 v0, s4, v5
	v_lshrrev_b32_e32 v1, 1, v0
	v_xor_b32_e32 v2, v1, v4
	v_ashrrev_i32_e32 v1, 31, v0
	v_lshlrev_b64 v[0:1], 7, v[0:1]
	v_lshlrev_b32_e32 v2, 4, v2
	v_lshl_add_u64 v[0:1], s[6:7], 0, v[0:1]
	v_and_b32_e32 v2, 0x70, v2
	v_lshl_add_u64 v[0:1], v[0:1], 0, v[2:3]
	s_mov_b32 m0, s2
	v_ashrrev_i32_e32 v5, 4, v4
	global_load_lds_dwordx4 v[0:1], off
	v_add_u32_e32 v0, s0, v5
	v_xor_b32_e32 v2, v0, v4
	v_ashrrev_i32_e32 v1, 31, v0
	v_lshlrev_b64 v[0:1], 15, v[0:1]
	v_lshlrev_b32_e32 v2, 4, v2
	v_lshl_add_u64 v[0:1], s[8:9], 0, v[0:1]
	v_and_b32_e32 v2, 0xf0, v2
	v_lshl_add_u64 v[0:1], v[0:1], 0, v[2:3]
	s_add_i32 m0, s1, 0x4000
	s_nop 0
	global_load_lds_dwordx4 v[0:1], off
	v_add_u32_e32 v0, s3, v5
	v_xor_b32_e32 v2, v0, v4
	v_ashrrev_i32_e32 v1, 31, v0
	v_lshlrev_b64 v[0:1], 15, v[0:1]
	v_lshlrev_b32_e32 v2, 4, v2
	v_lshl_add_u64 v[0:1], s[8:9], 0, v[0:1]
	v_and_b32_e32 v2, 0xf0, v2
	v_lshl_add_u64 v[0:1], v[0:1], 0, v[2:3]
	s_add_i32 m0, s2, 0x4000
	s_nop 0
	global_load_lds_dwordx4 v[0:1], off
	s_waitcnt vmcnt(0)
	s_waitcnt vmcnt(0) lgkmcnt(0)
	s_barrier
	s_mov_b64 s[4:5], exec
	v_readlane_b32 s0, v252, 2
	v_readlane_b32 s1, v252, 3
	s_and_b64 s[0:1], s[4:5], s[0:1]
	s_mov_b64 exec, s[0:1]
	s_cbranch_execz .LBB0_841
	v_mov_b32_e32 v0, 0x20000
	ds_read_b64 v[0:1], v0
	s_getreg_b32 s44, hwreg(HW_REG_XCC_ID, 0, 4)
	s_lshl_b32 s44, s44, 7
	s_add_u32 s44, s44, 0xdc03600
	v_mov_b32_e32 v2, s44
	v_mov_b32_e32 v4, 1
	s_waitcnt vmcnt(0) lgkmcnt(0)
	global_atomic_add v5, v2, v4, s[42:43] sc0
	buffer_inv sc1
	s_add_u32 s100, s100, 1
	v_readfirstlane_b32 s46, v0
	v_readfirstlane_b32 s47, v1
	v_mov_b32_e32 v2, 0xdc03e00
	s_nop 3
	s_mul_i32 s48, s46, s100
	s_mul_i32 s49, s47, s100
	s_waitcnt vmcnt(1)
	v_readfirstlane_b32 s50, v5
	s_nop 3
	s_add_u32 s50, s50, 1
	s_cmp_lg_u32 s50, s48
	s_cbranch_scc1 .Lxb6_poll
	buffer_wbl2 sc1
	s_waitcnt vmcnt(0)
	global_atomic_add v2, v4, s[42:43]

.LBB0_805:
	s_mov_b64 s[44:45], exec
	s_lshl_b32 s0, s0, 8
	v_readlane_b32 s2, v252, 0
	v_mbcnt_lo_u32_b32 v1, s44, 0
	v_readlane_b32 s3, v252, 1
	s_add_u32 s6, s2, s0
	v_mbcnt_hi_u32_b32 v1, s45, v1
	s_addc_u32 s7, s3, 0
	v_cmp_eq_u32_e32 vcc, 0, v1
	s_and_saveexec_b64 s[46:47], vcc
	s_cbranch_execz .LBB0_807
	s_bcnt1_i32_b64 s0, s[44:45]
	v_mov_b32_e32 v4, s0
	v_mov_b32_e32 v5, 0x1000
	global_atomic_add v4, v5, v4, s[6:7] offset:1024 sc0
.LBB0_807:
	s_or_b64 exec, exec, s[46:47]
	v_cvt_f32_u32_e32 v5, v2
	s_waitcnt vmcnt(0)
	v_readfirstlane_b32 s0, v4
	v_sub_u32_e32 v4, 0, v2
	v_rcp_iflag_f32_e32 v5, v5
	v_add_u32_e32 v6, s0, v1
	v_mul_f32_e32 v5, 0x4f7ffffe, v5
	v_cvt_u32_f32_e32 v5, v5
	v_mul_lo_u32 v1, v4, v5
	v_mul_hi_u32 v1, v5, v1
	v_add_u32_e32 v1, v5, v1
	v_mul_hi_u32 v1, v6, v1
	v_mul_lo_u32 v4, v1, v2
	v_sub_u32_e32 v4, v6, v4
	v_add_u32_e32 v5, 1, v1
	v_cmp_ge_u32_e32 vcc, v4, v2
	s_nop 1
	v_cndmask_b32_e32 v1, v1, v5, vcc
	v_sub_u32_e32 v5, v4, v2
	v_cndmask_b32_e32 v4, v4, v5, vcc
	v_add_u32_e32 v5, 1, v1
	v_cmp_ge_u32_e32 vcc, v4, v2
	v_add_u32_e32 v4, 1, v6
	s_nop 0
	v_cndmask_b32_e32 v1, v1, v5, vcc
	v_mul_lo_u32 v5, v2, v1
	v_add_u32_e32 v2, v5, v2
	v_cmp_ne_u32_e32 vcc, v4, v2
	s_and_saveexec_b64 s[0:1], vcc
	s_xor_b64 s[44:45], exec, s[0:1]
	s_cbranch_execz .LBB0_821
	s_waitcnt lgkmcnt(0)
	global_load_dword v0, v182, s[6:7] offset:1024 sc1
	s_add_u32 s48, s6, 0x2400
	s_addc_u32 s49, s7, 0
	s_waitcnt vmcnt(0)
	v_cmp_eq_u32_e32 vcc, v0, v1
	s_and_saveexec_b64 s[46:47], vcc
	s_cbranch_execz .LBB0_820
	s_mov_b32 s0, 1
	s_mov_b64 s[50:51], 0
	s_branch .LBB0_811

.LBB0_838:
	s_or_b64 exec, exec, s[44:45]
	s_mov_b64 s[44:45], exec
	v_mbcnt_lo_u32_b32 v0, s44, 0
	v_mbcnt_hi_u32_b32 v0, s45, v0
	v_cmp_eq_u32_e32 vcc, 0, v0
	s_waitcnt vmcnt(0)
	buffer_inv sc1
	s_and_saveexec_b64 s[46:47], vcc
	s_cbranch_execz .LBB0_840
	s_bcnt1_i32_b64 s0, s[44:45]
	v_mov_b32_e32 v0, s0
	global_atomic_add v182, v0, s[6:7] offset:1024

.LBB0_844:
	s_waitcnt vmcnt(0) lgkmcnt(0)
	s_mov_b32 s79, 0x3e38aa3b
	s_mov_b32 s77, 0xc000
	s_mov_b32 s78, 0xffffc000
	v_readlane_b32 s1, v253, 23
	v_readfirstlane_b32 s0, v170
	s_nop 3
	s_lshr_b32 s0, s0, 6
	s_and_b32 s74, s1, 7
	s_lshl_b32 s74, s74, 5
	s_lshr_b32 s75, s1, 3
	s_add_u32 s74, s74, s75
	s_lshl_b32 s74, s74, 3
	s_and_b32 s4, s74, 7
	s_lshr_b32 s75, s74, 3
	s_and_b32 s5, s75, 3
	s_lshr_b32 s75, s75, 2
	s_and_b32 s3, s75, 3
	s_lshr_b32 s2, s75, 2
	s_sub_u32 s6, 8, s0
	s_lshl_b32 s70, s0, 10
	s_lshl_b32 s74, s2, 21
	s_lshl_b32 s75, s3, 19
	s_add_u32 s74, s74, s75
	s_add_u32 s34, s40, s74
	s_addc_u32 s35, s41, 0
	s_add_u32 s30, s34, 0x2000000
	s_addc_u32 s31, s35, 0
	s_lshl_b32 s74, s2, 16
	s_lshl_b32 s75, s3, 14
	s_add_u32 s74, s74, s75
	s_add_u32 s74, s74, 0xc000000
	s_add_u32 s58, s42, s74
	s_addc_u32 s59, s43, 0
	s_add_u32 s74, s2, 16
	s_lshl_b32 s74, s74, 2
	s_add_u32 s74, s74, s3
	s_lshl_b32 s74, s74, 19
	s_add_u32 s60, s42, s74
	s_addc_u32 s61, s43, 0
	s_lshl_b32 s74, s2, 6
	s_add_u32 s74, s74, 1024
	s_lshl_b32 s74, s74, 15
	s_lshl_b32 s75, s3, 13
	s_add_u32 s74, s74, s75
	s_add_u32 s74, s74, 0x6000000
	s_add_u32 s64, s42, s74
	s_addc_u32 s65, s43, 0
	v_and_b32_e32 v141, 63, v170
	v_and_b32_e32 v241, 15, v141
	v_lshrrev_b32_e32 v242, 4, v141
	v_mov_b32_e32 v244, 0xf149f2ca
	v_mov_b32_e32 v248, 0
	v_mov_b32_e32 v249, 0
	v_lshrrev_b32_e32 v142, 1, v241
	v_xor_b32_e32 v142, v142, v242
	v_lshlrev_b32_e32 v142, 4, v142
	v_lshl_add_u32 v142, v241, 7, v142
	s_lshl_b32 s74, s0, 11
	v_add_u32_e32 v230, s74, v142
	v_xor_b32_e32 v231, 64, v230
	v_lshrrev_b32_e32 v142, 1, v242
	v_xor_b32_e32 v243, v142, v241
	v_and_b32_e32 v142, 1, v242
	v_lshlrev_b32_e32 v142, 3, v142
	v_lshl_add_u32 v142, v241, 8, v142
	v_add_u32_e32 v142, 0x10000, v142
	s_add_u32 s74, s0, 0
	s_and_b32 s75, s74, 7
	s_lshl_b32 s75, s75, 1
	s_lshr_b32 s74, s74, 3
	s_lshl_b32 s74, s74, 14
	v_xor_b32_e32 v143, s75, v243
	v_lshl_add_u32 v143, v143, 4, v142
	v_add_u32_e32 v221, s74, v143
	s_add_u32 s74, s0, 1
	s_and_b32 s75, s74, 7
	s_lshl_b32 s75, s75, 1
	s_lshr_b32 s74, s74, 3
	s_lshl_b32 s74, s74, 14
	v_xor_b32_e32 v143, s75, v243
	v_lshl_add_u32 v143, v143, 4, v142
	v_add_u32_e32 v222, s74, v143
	s_add_u32 s74, s0, 2
	s_and_b32 s75, s74, 7
	s_lshl_b32 s75, s75, 1
	s_lshr_b32 s74, s74, 3
	s_lshl_b32 s74, s74, 14
	v_xor_b32_e32 v143, s75, v243
	v_lshl_add_u32 v143, v143, 4, v142
	v_add_u32_e32 v223, s74, v143
	s_add_u32 s74, s0, 3
	s_and_b32 s75, s74, 7
	s_lshl_b32 s75, s75, 1
	s_lshr_b32 s74, s74, 3
	s_lshl_b32 s74, s74, 14
	v_xor_b32_e32 v143, s75, v243
	v_lshl_add_u32 v143, v143, 4, v142
	v_add_u32_e32 v224, s74, v143
	s_add_u32 s74, s0, 4
	s_and_b32 s75, s74, 7
	s_lshl_b32 s75, s75, 1
	s_lshr_b32 s74, s74, 3
	s_lshl_b32 s74, s74, 14
	v_xor_b32_e32 v143, s75, v243
	v_lshl_add_u32 v143, v143, 4, v142
	v_add_u32_e32 v225, s74, v143
	s_add_u32 s74, s0, 5
	s_and_b32 s75, s74, 7
	s_lshl_b32 s75, s75, 1
	s_lshr_b32 s74, s74, 3
	s_lshl_b32 s74, s74, 14
	v_xor_b32_e32 v143, s75, v243
	v_lshl_add_u32 v143, v143, 4, v142
	v_add_u32_e32 v226, s74, v143
	s_add_u32 s74, s0, 6
	s_and_b32 s75, s74, 7
	s_lshl_b32 s75, s75, 1
	s_lshr_b32 s74, s74, 3
	s_lshl_b32 s74, s74, 14
	v_xor_b32_e32 v143, s75, v243
	v_lshl_add_u32 v143, v143, 4, v142
	v_add_u32_e32 v227, s74, v143
	s_add_u32 s74, s0, 7
	s_and_b32 s75, s74, 7
	s_lshl_b32 s75, s75, 1
	s_lshr_b32 s74, s74, 3
	s_lshl_b32 s74, s74, 14
	v_xor_b32_e32 v143, s75, v243
	v_lshl_add_u32 v143, v143, 4, v142
	v_add_u32_e32 v228, s74, v143
	s_add_u32 s74, s0, 8
	s_and_b32 s75, s74, 7
	s_lshl_b32 s75, s75, 1
	s_lshr_b32 s74, s74, 3
	s_lshl_b32 s74, s74, 14
	v_xor_b32_e32 v143, s75, v243
	v_lshl_add_u32 v143, v143, 4, v142
	v_add_u32_e32 v229, s74, v143
	s_and_b32 s74, s0, 1
	s_lshl_b32 s74, s74, 2
	v_add_u32_e32 v142, s74, v242
	v_and_b32_e32 v143, 7, v141
	v_xor_b32_e32 v142, v142, v143
	v_lshlrev_b32_e32 v142, 4, v142
	v_lshrrev_b32_e32 v143, 3, v141
	s_lshl_b32 s74, s0, 3
	v_add_u32_e32 v143, s74, v143
	v_lshl_add_u32 v232, v143, 7, v142
	v_add_u32_e32 v233, 0x2000, v232
	s_and_b32 s74, s0, 3
	s_lshl_b32 s74, s74, 2
	v_add_u32_e32 v142, s74, v242
	v_xor_b32_e32 v142, v142, v241
	v_lshlrev_b32_e32 v142, 4, v142
	s_lshl_b32 s74, s0, 2
	v_add_u32_e32 v143, s74, v242
	v_lshl_add_u32 v234, v143, 15, v142
	v_add_u32_e32 v235, 0x100000, v234
	s_lshl_b32 s74, s0, 4
	v_add_u32_e32 v142, s74, v241
	v_lshlrev_b32_e32 v142, 2, v142
	v_lshlrev_b32_e32 v238, 2, v142
	v_lshlrev_b32_e32 v142, 7, v142
	v_lshl_add_u32 v236, v242, 4, v142
	v_lshl_add_u32 v237, v242, 3, v142
	v_xor_b32_e32 v142, 16, v141
	v_lshlrev_b32_e32 v239, 2, v142
	v_xor_b32_e32 v142, 32, v141
	v_lshlrev_b32_e32 v240, 2, v142
	s_add_u32 s74, s2, 17
	v_cvt_f32_u32_e32 v142, s74
	v_mul_f32_e32 v142, 0xc1000000, v142
	v_mul_f32_e32 v142, 0x3caaaaab, v142
	v_exp_f32_e32 v142, v142
	v_lshlrev_b32_e32 v144, 2, v242
	v_sub_u32_e32 v145, v241, v144
	v_mul_f32_e32 v142, 0x40800000, v142
	v_add_u32_e32 v145, 0x80, v145
	v_mul_f32_e32 v142, 0x3fb8aa3b, v142
	v_cvt_f32_i32_e32 v145, v145
	s_nop 0
	v_mul_f32_e64 v143, -v142, v145
	v_fmamk_f32 v185, v142, 0x0, v143
	v_fmamk_f32 v186, v142, 0x3f800000, v143
	v_fmamk_f32 v187, v142, 0x40000000, v143
	v_fmamk_f32 v188, v142, 0x40400000, v143
	v_fmamk_f32 v189, v142, 0x41800000, v143
	v_fmamk_f32 v190, v142, 0x41880000, v143
	v_fmamk_f32 v191, v142, 0x41900000, v143
	v_fmamk_f32 v192, v142, 0x41980000, v143
	v_fmamk_f32 v193, v142, 0x42000000, v143
	v_fmamk_f32 v194, v142, 0x42040000, v143
	v_fmamk_f32 v195, v142, 0x42080000, v143
	v_fmamk_f32 v196, v142, 0x420c0000, v143
	v_fmamk_f32 v197, v142, 0x42400000, v143
	v_fmamk_f32 v198, v142, 0x42440000, v143
	v_fmamk_f32 v199, v142, 0x42480000, v143
	v_fmamk_f32 v200, v142, 0x424c0000, v143
	v_fmamk_f32 v201, v142, 0x42800000, v143
	v_fmamk_f32 v202, v142, 0x42820000, v143
	v_fmamk_f32 v203, v142, 0x42840000, v143
	v_fmamk_f32 v204, v142, 0x42860000, v143
	v_fmamk_f32 v205, v142, 0x42a00000, v143
	v_fmamk_f32 v206, v142, 0x42a20000, v143
	v_fmamk_f32 v207, v142, 0x42a40000, v143
	v_fmamk_f32 v208, v142, 0x42a60000, v143
	v_fmamk_f32 v209, v142, 0x42c00000, v143
	v_fmamk_f32 v210, v142, 0x42c20000, v143
	v_fmamk_f32 v211, v142, 0x42c40000, v143
	v_fmamk_f32 v212, v142, 0x42c60000, v143
	v_fmamk_f32 v213, v142, 0x42e00000, v143
	v_fmamk_f32 v214, v142, 0x42e20000, v143
	v_fmamk_f32 v215, v142, 0x42e40000, v143
	v_fmamk_f32 v216, v142, 0x42e60000, v143
	v_fmamk_f32 v217, v142, 0x43000000, v143
	v_fmamk_f32 v218, v142, 0x43010000, v143
	v_fmamk_f32 v219, v142, 0x43020000, v143
	v_fmamk_f32 v220, v142, 0x43030000, v143
	v_add_u32_e32 v145, 0, v144
	v_cmp_lt_u32_e32 vcc, v145, v241
	s_nop 1
	v_cndmask_b32_e32 v185, v185, v244, vcc
	v_cmp_gt_u32_e32 vcc, v145, v241
	s_nop 1
	v_cndmask_b32_e32 v217, v217, v244, vcc
	v_add_u32_e32 v145, 1, v144
	v_cmp_lt_u32_e32 vcc, v145, v241
	s_nop 1
	v_cndmask_b32_e32 v186, v186, v244, vcc
	v_cmp_gt_u32_e32 vcc, v145, v241
	s_nop 1
	v_cndmask_b32_e32 v218, v218, v244, vcc
	v_add_u32_e32 v145, 2, v144
	v_cmp_lt_u32_e32 vcc, v145, v241
	s_nop 1
	v_cndmask_b32_e32 v187, v187, v244, vcc
	v_cmp_gt_u32_e32 vcc, v145, v241
	s_nop 1
	v_cndmask_b32_e32 v219, v219, v244, vcc
	v_add_u32_e32 v145, 3, v144
	v_cmp_lt_u32_e32 vcc, v145, v241
	s_nop 1
	v_cndmask_b32_e32 v188, v188, v244, vcc
	v_cmp_gt_u32_e32 vcc, v145, v241
	s_nop 1
	v_cndmask_b32_e32 v220, v220, v244, vcc
	s_sub_u32 s76, s4, 1
	s_max_i32 s76, s76, 0
	s_mul_i32 s74, s5, 1024
	s_lshl_b32 s75, s76, 7
	s_add_u32 s74, s74, s75
	s_lshl_b32 s75, s74, 7
	s_add_u32 s16, s60, s75
	s_addc_u32 s17, s61, 0
	s_lshl_b32 s75, s74, 1
	s_add_u32 s24, s64, s75
	s_addc_u32 s25, s65, 0
	s_add_u32 m0, s70, 0xc000
	s_nop 0
	global_load_lds_dwordx4 v232, s[16:17]
	s_add_u32 m0, s70, 0xe000
	s_nop 0
	global_load_lds_dwordx4 v233, s[16:17]
	s_add_u32 m0, s70, 0x1c000
	s_nop 0
	global_load_lds_dwordx4 v234, s[24:25]
	s_add_u32 m0, s70, 0x1e000
	s_nop 0
	global_load_lds_dwordx4 v235, s[24:25]
	s_mul_i32 s74, s5, 1024
	s_lshl_b32 s75, s4, 7
	s_add_u32 s74, s74, s75
	s_lshl_b32 s75, s74, 7
	s_add_u32 s16, s60, s75
	s_addc_u32 s17, s61, 0
	s_lshl_b32 s75, s74, 1
	s_add_u32 s24, s64, s75
	s_addc_u32 s25, s65, 0
	s_add_u32 m0, s70, 0x0
	s_nop 0
	global_load_lds_dwordx4 v232, s[16:17]
	s_add_u32 m0, s70, 0x2000
	s_nop 0
	global_load_lds_dwordx4 v233, s[16:17]
	s_add_u32 m0, s70, 0x10000
	s_nop 0
	global_load_lds_dwordx4 v234, s[24:25]
	s_add_u32 m0, s70, 0x12000
	s_nop 0
	global_load_lds_dwordx4 v235, s[24:25]
	s_lshl_b32 s74, s4, 9
	s_add_u32 s74, s74, s5
	s_lshl_b32 s75, s74, 7
	s_add_u32 s10, s30, s75
	s_addc_u32 s11, s31, 0
	s_add_u32 s86, s34, s75
	s_addc_u32 s87, s35, 0
	s_lshl_b32 s75, s74, 2
	s_add_u32 s88, s58, s75
	s_addc_u32 s89, s59, 0
	global_load_dwordx4 v[96:99], v236, s[10:11]
	global_load_dwordx4 v[100:103], v236, s[10:11] offset:64
	global_load_dwordx2 v[112:113], v237, s[86:87]
	global_load_dwordx2 v[114:115], v237, s[86:87] offset:32
	global_load_dwordx2 v[116:117], v237, s[86:87] offset:64
	global_load_dwordx2 v[118:119], v237, s[86:87] offset:96
	global_load_dword v120, v238, s[88:89]
	s_mov_b32 s7, 0

.Lat844_i0_nopend:
	s_add_u32 s83, s4, 1
	s_mov_b32 s84, s5
	s_mul_i32 s74, s84, 1024
	s_lshl_b32 s75, s83, 7
	s_add_u32 s74, s74, s75
	s_lshl_b32 s75, s74, 7
	s_add_u32 s16, s60, s75
	s_addc_u32 s17, s61, 0
	s_lshl_b32 s75, s74, 1
	s_add_u32 s24, s64, s75
	s_addc_u32 s25, s65, 0
	s_add_u32 m0, s70, 0x4000
	s_nop 0
	global_load_lds_dwordx4 v232, s[16:17]
	s_add_u32 m0, s70, 0x6000
	s_nop 0
	global_load_lds_dwordx4 v233, s[16:17]
	s_add_u32 m0, s70, 0x14000
	s_nop 0
	global_load_lds_dwordx4 v234, s[24:25]
	s_add_u32 m0, s70, 0x16000
	s_nop 0
	global_load_lds_dwordx4 v235, s[24:25]
	s_lshl_b32 s74, s83, 9
	s_add_u32 s74, s74, s84
	s_lshl_b32 s75, s74, 7
	s_add_u32 s10, s30, s75
	s_addc_u32 s11, s31, 0
	s_add_u32 s12, s34, s75
	s_addc_u32 s13, s35, 0
	s_lshl_b32 s75, s74, 2
	s_add_u32 s14, s58, s75
	s_addc_u32 s15, s59, 0
	global_load_dwordx4 v[104:107], v236, s[10:11]
	global_load_dwordx4 v[108:111], v236, s[10:11] offset:64
	global_load_dwordx2 v[122:123], v237, s[12:13]
	global_load_dwordx2 v[124:125], v237, s[12:13] offset:32
	global_load_dwordx2 v[126:127], v237, s[12:13] offset:64
	global_load_dwordx2 v[128:129], v237, s[12:13] offset:96
	global_load_dword v121, v238, s[14:15]
	s_waitcnt lgkmcnt(0)
	v_mfma_f32_16x16x32_bf16 v[44:47], v[4:7], v[96:99], 0
	v_mfma_f32_16x16x32_bf16 v[48:51], v[12:15], v[96:99], 0
	v_mfma_f32_16x16x32_bf16 v[52:55], v[20:23], v[96:99], 0
	v_mfma_f32_16x16x32_bf16 v[56:59], v[28:31], v[96:99], 0
	v_mfma_f32_16x16x32_bf16 v[60:63], v[36:39], v[96:99], 0
	v_mfma_f32_16x16x32_bf16 v[44:47], v[8:11], v[100:103], v[44:47]
	v_mfma_f32_16x16x32_bf16 v[48:51], v[16:19], v[100:103], v[48:51]
	v_mfma_f32_16x16x32_bf16 v[52:55], v[24:27], v[100:103], v[52:55]
	v_mfma_f32_16x16x32_bf16 v[56:59], v[32:35], v[100:103], v[56:59]
	v_mfma_f32_16x16x32_bf16 v[60:63], v[40:43], v[100:103], v[60:63]
	s_cmp_gt_u32 s6, 5
	s_cselect_b32 s74, s77, s78
	v_add_u32_e32 v146, s74, v230
	v_xor_b32_e32 v147, 64, v146
	ds_read_b128 v[4:7], v146 offset:10240
	ds_read_b128 v[8:11], v147 offset:10240
	s_cmp_gt_u32 s6, 6
	s_cselect_b32 s74, s77, s78
	v_add_u32_e32 v146, s74, v230
	v_xor_b32_e32 v147, 64, v146
	ds_read_b128 v[12:15], v146 offset:12288
	ds_read_b128 v[16:19], v147 offset:12288
	s_cmp_gt_u32 s6, 7
	s_cselect_b32 s74, s77, s78
	v_add_u32_e32 v146, s74, v230
	v_xor_b32_e32 v147, 64, v146
	ds_read_b128 v[20:23], v146 offset:14336
	ds_read_b128 v[24:27], v147 offset:14336
	s_cmp_gt_u32 s6, 8
	s_cselect_b32 s74, s77, s78
	v_add_u32_e32 v146, s74, v230
	v_xor_b32_e32 v147, 64, v146
	ds_read_b128 v[28:31], v146 offset:16384
	ds_read_b128 v[32:35], v147 offset:16384
	s_nop 1
	v_fma_f32 v44, v44, s79, v185
	v_fma_f32 v45, v45, s79, v186
	v_fma_f32 v46, v46, s79, v187
	v_fma_f32 v47, v47, s79, v188
	v_fma_f32 v48, v48, s79, v189
	v_fma_f32 v49, v49, s79, v190
	v_fma_f32 v50, v50, s79, v191
	v_fma_f32 v51, v51, s79, v192
	v_fma_f32 v52, v52, s79, v193
	v_fma_f32 v53, v53, s79, v194
	v_fma_f32 v54, v54, s79, v195
	v_fma_f32 v55, v55, s79, v196
	v_fma_f32 v56, v56, s79, v197
	v_fma_f32 v57, v57, s79, v198
	v_fma_f32 v58, v58, s79, v199
	v_fma_f32 v59, v59, s79, v200
	v_fma_f32 v60, v60, s79, v201
	v_fma_f32 v61, v61, s79, v202
	v_fma_f32 v62, v62, s79, v203
	v_fma_f32 v63, v63, s79, v204
	s_waitcnt lgkmcnt(0)
	v_mfma_f32_16x16x32_bf16 v[64:67], v[4:7], v[96:99], 0
	v_mfma_f32_16x16x32_bf16 v[68:71], v[12:15], v[96:99], 0
	v_mfma_f32_16x16x32_bf16 v[72:75], v[20:23], v[96:99], 0
	v_mfma_f32_16x16x32_bf16 v[76:79], v[28:31], v[96:99], 0
	v_mfma_f32_16x16x32_bf16 v[64:67], v[8:11], v[100:103], v[64:67]
	v_mfma_f32_16x16x32_bf16 v[68:71], v[16:19], v[100:103], v[68:71]
	v_mfma_f32_16x16x32_bf16 v[72:75], v[24:27], v[100:103], v[72:75]
	v_mfma_f32_16x16x32_bf16 v[76:79], v[32:35], v[100:103], v[76:79]
	s_cmp_gt_u32 s6, 0
	s_cselect_b32 s74, 0, 0xffff0000
	v_add_u32_e32 v146, s74, v221
	ds_read_b64 v[4:5], v146 offset:49152
	ds_read_b64 v[8:9], v146 offset:53248
	ds_read_b64 v[12:13], v146 offset:57344
	ds_read_b64 v[16:17], v146 offset:61440
	s_cmp_gt_u32 s6, 1
	s_cselect_b32 s74, 0, 0xffff0000
	v_add_u32_e32 v146, s74, v222
	ds_read_b64 v[6:7], v146 offset:49152
	ds_read_b64 v[10:11], v146 offset:53248
	ds_read_b64 v[14:15], v146 offset:57344
	ds_read_b64 v[18:19], v146 offset:61440
	s_nop 1
	v_fma_f32 v64, v64, s79, v205
	v_fma_f32 v65, v65, s79, v206
	v_fma_f32 v66, v66, s79, v207
	v_fma_f32 v67, v67, s79, v208
	v_fma_f32 v68, v68, s79, v209
	v_fma_f32 v69, v69, s79, v210
	v_fma_f32 v70, v70, s79, v211
	v_fma_f32 v71, v71, s79, v212
	v_fma_f32 v72, v72, s79, v213
	v_fma_f32 v73, v73, s79, v214
	v_fma_f32 v74, v74, s79, v215
	v_fma_f32 v75, v75, s79, v216
	v_fma_f32 v76, v76, s79, v217
	v_fma_f32 v77, v77, s79, v218
	v_fma_f32 v78, v78, s79, v219
	v_fma_f32 v79, v79, s79, v220
	s_cmp_gt_u32 s6, 2
	s_cselect_b32 s74, 0, 0xffff0000
	v_add_u32_e32 v146, s74, v223
	ds_read_b64 v[20:21], v146 offset:49152
	ds_read_b64 v[24:25], v146 offset:53248
	ds_read_b64 v[28:29], v146 offset:57344
	ds_read_b64 v[32:33], v146 offset:61440
	s_cmp_gt_u32 s6, 3
	s_cselect_b32 s74, 0, 0xffff0000
	v_add_u32_e32 v146, s74, v224
	ds_read_b64 v[22:23], v146 offset:49152
	ds_read_b64 v[26:27], v146 offset:53248
	ds_read_b64 v[30:31], v146 offset:57344
	ds_read_b64 v[34:35], v146 offset:61440
	s_cmp_lg_u32 s4, 0
	s_cbranch_scc1 .Lat844_i0_nomask
	s_cmp_le_u32 s6, 0
	s_cbranch_scc1 .Lat844_i0_nomask
	v_mov_b32_e32 v44, v244
	v_mov_b32_e32 v45, v244
	v_mov_b32_e32 v46, v244
	v_mov_b32_e32 v47, v244
	s_cmp_le_u32 s6, 1
	s_cbranch_scc1 .Lat844_i0_nomask
	v_mov_b32_e32 v48, v244
	v_mov_b32_e32 v49, v244
	v_mov_b32_e32 v50, v244
	v_mov_b32_e32 v51, v244
	s_cmp_le_u32 s6, 2
	s_cbranch_scc1 .Lat844_i0_nomask
	v_mov_b32_e32 v52, v244
	v_mov_b32_e32 v53, v244
	v_mov_b32_e32 v54, v244
	v_mov_b32_e32 v55, v244
	s_cmp_le_u32 s6, 3
	s_cbranch_scc1 .Lat844_i0_nomask
	v_mov_b32_e32 v56, v244
	v_mov_b32_e32 v57, v244
	v_mov_b32_e32 v58, v244
	v_mov_b32_e32 v59, v244
	s_cmp_le_u32 s6, 4
	s_cbranch_scc1 .Lat844_i0_nomask
	v_mov_b32_e32 v60, v244
	v_mov_b32_e32 v61, v244
	v_mov_b32_e32 v62, v244
	v_mov_b32_e32 v63, v244
	s_cmp_le_u32 s6, 5
	s_cbranch_scc1 .Lat844_i0_nomask
	v_mov_b32_e32 v64, v244
	v_mov_b32_e32 v65, v244
	v_mov_b32_e32 v66, v244
	v_mov_b32_e32 v67, v244
	s_cmp_le_u32 s6, 6
	s_cbranch_scc1 .Lat844_i0_nomask
	v_mov_b32_e32 v68, v244
	v_mov_b32_e32 v69, v244
	v_mov_b32_e32 v70, v244
	v_mov_b32_e32 v71, v244
	s_cmp_le_u32 s6, 7
	s_cbranch_scc1 .Lat844_i0_nomask
	v_mov_b32_e32 v72, v244
	v_mov_b32_e32 v73, v244
	v_mov_b32_e32 v74, v244
	v_mov_b32_e32 v75, v244
.Lat844_i0_nomask:
	v_max3_f32 v245, v44, v45, v46
	v_max3_f32 v245, v245, v47, v48
	v_max3_f32 v245, v245, v49, v50
	v_max3_f32 v245, v245, v51, v52
	v_max3_f32 v245, v245, v53, v54
	v_max3_f32 v245, v245, v55, v56
	v_max3_f32 v245, v245, v57, v58
	v_max3_f32 v245, v245, v59, v60
	v_max3_f32 v245, v245, v61, v62
	v_max3_f32 v245, v245, v63, v64
	v_max3_f32 v245, v245, v65, v66
	v_max3_f32 v245, v245, v67, v68
	v_max3_f32 v245, v245, v69, v70
	v_max3_f32 v245, v245, v71, v72
	v_max3_f32 v245, v245, v73, v74
	v_max3_f32 v245, v245, v75, v76
	v_max3_f32 v245, v245, v77, v78
	v_max_f32_e32 v245, v245, v79
	ds_bpermute_b32 v148, v239, v245
	s_waitcnt lgkmcnt(0)
	v_max_f32_e32 v245, v245, v148
	ds_bpermute_b32 v148, v240, v245
	s_waitcnt lgkmcnt(0)
	v_max_f32_e32 v245, v245, v148
	v_sub_f32_e32 v44, v44, v245
	v_sub_f32_e32 v45, v45, v245
	v_sub_f32_e32 v46, v46, v245
	v_sub_f32_e32 v47, v47, v245
	v_exp_f32_e32 v44, v44
	v_exp_f32_e32 v45, v45
	v_exp_f32_e32 v46, v46
	v_exp_f32_e32 v47, v47
	v_sub_f32_e32 v48, v48, v245
	v_sub_f32_e32 v49, v49, v245
	v_sub_f32_e32 v50, v50, v245
	v_sub_f32_e32 v51, v51, v245
	v_exp_f32_e32 v48, v48
	v_exp_f32_e32 v49, v49
	v_exp_f32_e32 v50, v50
	v_exp_f32_e32 v51, v51
	v_mov_b32_e32 v149, v44
	v_mov_b32_e32 v150, v45
	v_mov_b32_e32 v151, v46
	v_mov_b32_e32 v152, v47
	v_cvt_pk_bf16_f32 v44, v44, v45
	v_cvt_pk_bf16_f32 v45, v46, v47
	v_sub_f32_e32 v52, v52, v245
	v_sub_f32_e32 v53, v53, v245
	v_sub_f32_e32 v54, v54, v245
	v_sub_f32_e32 v55, v55, v245
	v_exp_f32_e32 v52, v52
	v_exp_f32_e32 v53, v53
	v_exp_f32_e32 v54, v54
	v_exp_f32_e32 v55, v55
	v_add_f32_e32 v149, v149, v48
	v_add_f32_e32 v150, v150, v49
	v_add_f32_e32 v151, v151, v50
	v_add_f32_e32 v152, v152, v51
	v_cvt_pk_bf16_f32 v46, v48, v49
	v_cvt_pk_bf16_f32 v47, v50, v51
	v_sub_f32_e32 v56, v56, v245
	v_sub_f32_e32 v57, v57, v245
	v_sub_f32_e32 v58, v58, v245
	v_sub_f32_e32 v59, v59, v245
	v_exp_f32_e32 v56, v56
	v_exp_f32_e32 v57, v57
	v_exp_f32_e32 v58, v58
	v_exp_f32_e32 v59, v59
	v_add_f32_e32 v149, v149, v52
	v_add_f32_e32 v150, v150, v53
	v_add_f32_e32 v151, v151, v54
	v_add_f32_e32 v152, v152, v55
	v_cvt_pk_bf16_f32 v52, v52, v53
	v_cvt_pk_bf16_f32 v53, v54, v55
	v_sub_f32_e32 v60, v60, v245
	v_sub_f32_e32 v61, v61, v245
	v_sub_f32_e32 v62, v62, v245
	v_sub_f32_e32 v63, v63, v245
	v_exp_f32_e32 v60, v60
	v_exp_f32_e32 v61, v61
	v_exp_f32_e32 v62, v62
	v_exp_f32_e32 v63, v63
	v_add_f32_e32 v149, v149, v56
	v_add_f32_e32 v150, v150, v57
	v_add_f32_e32 v151, v151, v58
	v_add_f32_e32 v152, v152, v59
	v_cvt_pk_bf16_f32 v54, v56, v57
	v_cvt_pk_bf16_f32 v55, v58, v59
	v_sub_f32_e32 v64, v64, v245
	v_sub_f32_e32 v65, v65, v245
	v_sub_f32_e32 v66, v66, v245
	v_sub_f32_e32 v67, v67, v245
	v_exp_f32_e32 v64, v64
	v_exp_f32_e32 v65, v65
	v_exp_f32_e32 v66, v66
	v_exp_f32_e32 v67, v67
	v_add_f32_e32 v149, v149, v60
	v_add_f32_e32 v150, v150, v61
	v_add_f32_e32 v151, v151, v62
	v_add_f32_e32 v152, v152, v63
	v_cvt_pk_bf16_f32 v60, v60, v61
	v_cvt_pk_bf16_f32 v61, v62, v63
	v_sub_f32_e32 v68, v68, v245
	v_sub_f32_e32 v69, v69, v245
	v_sub_f32_e32 v70, v70, v245
	v_sub_f32_e32 v71, v71, v245
	v_exp_f32_e32 v68, v68
	v_exp_f32_e32 v69, v69
	v_exp_f32_e32 v70, v70
	v_exp_f32_e32 v71, v71
	v_add_f32_e32 v149, v149, v64
	v_add_f32_e32 v150, v150, v65
	v_add_f32_e32 v151, v151, v66
	v_add_f32_e32 v152, v152, v67
	v_cvt_pk_bf16_f32 v62, v64, v65
	v_cvt_pk_bf16_f32 v63, v66, v67
	v_sub_f32_e32 v72, v72, v245
	v_sub_f32_e32 v73, v73, v245
	v_sub_f32_e32 v74, v74, v245
	v_sub_f32_e32 v75, v75, v245
	v_exp_f32_e32 v72, v72
	v_exp_f32_e32 v73, v73
	v_exp_f32_e32 v74, v74
	v_exp_f32_e32 v75, v75
	v_add_f32_e32 v149, v149, v68
	v_add_f32_e32 v150, v150, v69
	v_add_f32_e32 v151, v151, v70
	v_add_f32_e32 v152, v152, v71
	v_cvt_pk_bf16_f32 v68, v68, v69
	v_cvt_pk_bf16_f32 v69, v70, v71
	v_sub_f32_e32 v76, v76, v245
	v_sub_f32_e32 v77, v77, v245
	v_sub_f32_e32 v78, v78, v245
	v_sub_f32_e32 v79, v79, v245
	v_exp_f32_e32 v76, v76
	v_exp_f32_e32 v77, v77
	v_exp_f32_e32 v78, v78
	v_exp_f32_e32 v79, v79
	v_add_f32_e32 v149, v149, v72
	v_add_f32_e32 v150, v150, v73
	v_add_f32_e32 v151, v151, v74
	v_add_f32_e32 v152, v152, v75
	v_cvt_pk_bf16_f32 v70, v72, v73
	v_cvt_pk_bf16_f32 v71, v74, v75
	s_nop 0
	v_add_f32_e32 v149, v149, v76
	v_add_f32_e32 v150, v150, v77
	v_add_f32_e32 v151, v151, v78
	v_add_f32_e32 v152, v152, v79
	v_cvt_pk_bf16_f32 v76, v76, v77
	v_cvt_pk_bf16_f32 v77, v78, v79
	v_mov_b32_e32 v78, 0
	v_mov_b32_e32 v79, 0
	v_add_f32_e32 v149, v149, v150
	v_add_f32_e32 v151, v151, v152
	v_add_f32_e32 v246, v149, v151
	s_waitcnt lgkmcnt(0)
	v_mfma_f32_16x16x32_bf16 v[80:83], v[4:7], v[44:47], 0
	v_mfma_f32_16x16x32_bf16 v[84:87], v[8:11], v[44:47], 0
	v_mfma_f32_16x16x32_bf16 v[88:91], v[12:15], v[44:47], 0
	v_mfma_f32_16x16x32_bf16 v[92:95], v[16:19], v[44:47], 0
	s_cmp_gt_u32 s6, 4
	s_cselect_b32 s74, 0, 0xffff0000
	v_add_u32_e32 v146, s74, v225
	ds_read_b64 v[4:5], v146 offset:49152
	ds_read_b64 v[8:9], v146 offset:53248
	ds_read_b64 v[12:13], v146 offset:57344
	ds_read_b64 v[16:17], v146 offset:61440
	s_cmp_gt_u32 s6, 5
	s_cselect_b32 s74, 0, 0xffff0000
	v_add_u32_e32 v146, s74, v226
	ds_read_b64 v[6:7], v146 offset:49152
	ds_read_b64 v[10:11], v146 offset:53248
	ds_read_b64 v[14:15], v146 offset:57344
	ds_read_b64 v[18:19], v146 offset:61440
	v_mfma_f32_16x16x32_bf16 v[80:83], v[20:23], v[52:55], v[80:83]
	v_mfma_f32_16x16x32_bf16 v[84:87], v[24:27], v[52:55], v[84:87]
	v_mfma_f32_16x16x32_bf16 v[88:91], v[28:31], v[52:55], v[88:91]
	v_mfma_f32_16x16x32_bf16 v[92:95], v[32:35], v[52:55], v[92:95]
	s_cmp_gt_u32 s6, 6
	s_cselect_b32 s74, 0, 0xffff0000
	v_add_u32_e32 v146, s74, v227
	ds_read_b64 v[20:21], v146 offset:49152
	ds_read_b64 v[24:25], v146 offset:53248
	ds_read_b64 v[28:29], v146 offset:57344
	ds_read_b64 v[32:33], v146 offset:61440
	s_cmp_gt_u32 s6, 7
	s_cselect_b32 s74, 0, 0xffff0000
	v_add_u32_e32 v146, s74, v228
	ds_read_b64 v[22:23], v146 offset:49152
	ds_read_b64 v[26:27], v146 offset:53248
	ds_read_b64 v[30:31], v146 offset:57344
	ds_read_b64 v[34:35], v146 offset:61440
	ds_bpermute_b32 v148, v239, v246
	s_waitcnt lgkmcnt(9)
	v_mfma_f32_16x16x32_bf16 v[80:83], v[4:7], v[60:63], v[80:83]
	v_mfma_f32_16x16x32_bf16 v[84:87], v[8:11], v[60:63], v[84:87]
	v_mfma_f32_16x16x32_bf16 v[88:91], v[12:15], v[60:63], v[88:91]
	v_mfma_f32_16x16x32_bf16 v[92:95], v[16:19], v[60:63], v[92:95]
	s_cmp_gt_u32 s6, 8
	s_cselect_b32 s74, 0, 0xffff0000
	v_add_u32_e32 v146, s74, v229
	ds_read_b64 v[4:5], v146 offset:49152
	ds_read_b64 v[8:9], v146 offset:53248
	ds_read_b64 v[12:13], v146 offset:57344
	ds_read_b64 v[16:17], v146 offset:61440
	v_mov_b32_e32 v6, 0
	v_mov_b32_e32 v7, 0
	v_mov_b32_e32 v10, 0
	v_mov_b32_e32 v11, 0
	v_mov_b32_e32 v14, 0
	v_mov_b32_e32 v15, 0
	v_mov_b32_e32 v18, 0
	v_mov_b32_e32 v19, 0
	s_waitcnt lgkmcnt(5)
	v_mfma_f32_16x16x32_bf16 v[80:83], v[20:23], v[68:71], v[80:83]
	v_mfma_f32_16x16x32_bf16 v[84:87], v[24:27], v[68:71], v[84:87]
	v_mfma_f32_16x16x32_bf16 v[88:91], v[28:31], v[68:71], v[88:91]
	v_mfma_f32_16x16x32_bf16 v[92:95], v[32:35], v[68:71], v[92:95]
	s_waitcnt lgkmcnt(0)
	v_add_f32_e32 v246, v246, v148
	s_nop 0
	v_mfma_f32_16x16x32_bf16 v[80:83], v[4:7], v[76:79], v[80:83]
	v_mfma_f32_16x16x32_bf16 v[84:87], v[8:11], v[76:79], v[84:87]
	v_mfma_f32_16x16x32_bf16 v[88:91], v[12:15], v[76:79], v[88:91]
	v_mfma_f32_16x16x32_bf16 v[92:95], v[16:19], v[76:79], v[92:95]
	ds_bpermute_b32 v148, v240, v246
	s_waitcnt lgkmcnt(0)
	v_add_f32_e32 v246, v246, v148
	v_rcp_f32_e32 v149, v246
	v_log_f32_e32 v150, v246
	s_nop 0
	v_add_f32_e32 v151, v245, v150
	v_mul_f32_e32 v151, 0x3f317218, v151
	v_max_f32_e32 v152, v120, v151
	v_sub_f32_e32 v153, v120, v152
	v_sub_f32_e32 v154, v151, v152
	v_mul_f32_e32 v153, 0x3fb8aa3b, v153
	v_mul_f32_e32 v154, 0x3fb8aa3b, v154
	v_exp_f32_e32 v153, v153
	v_exp_f32_e32 v154, v154
	s_nop 0
	v_add_f32_e32 v155, v153, v154
	v_rcp_f32_e32 v146, v155
	v_log_f32_e32 v150, v155
	s_nop 0
	v_mul_f32_e32 v154, v154, v146
	v_mul_f32_e32 v146, v153, v146
	v_mul_f32_e32 v147, v149, v154
	v_mul_f32_e32 v150, 0x3f317218, v150
	v_add_f32_e32 v140, v152, v150
	v_mul_f32_e32 v80, v80, v147
	v_mul_f32_e32 v81, v81, v147
	v_mul_f32_e32 v82, v82, v147
	v_mul_f32_e32 v83, v83, v147
	v_mul_f32_e32 v84, v84, v147
	v_mul_f32_e32 v85, v85, v147
	v_mul_f32_e32 v86, v86, v147
	v_mul_f32_e32 v87, v87, v147
	v_mul_f32_e32 v88, v88, v147
	v_mul_f32_e32 v89, v89, v147
	v_mul_f32_e32 v90, v90, v147
	v_mul_f32_e32 v91, v91, v147
	v_mul_f32_e32 v92, v92, v147
	v_mul_f32_e32 v93, v93, v147
	v_mul_f32_e32 v94, v94, v147
	v_mul_f32_e32 v95, v95, v147
	v_lshlrev_b32_e32 v141, 16, v112
	v_and_b32_e32 v142, 0xffff0000, v112
	v_lshlrev_b32_e32 v143, 16, v113
	v_and_b32_e32 v144, 0xffff0000, v113
	v_fmac_f32_e32 v80, v146, v141
	v_fmac_f32_e32 v81, v146, v142
	v_fmac_f32_e32 v82, v146, v143
	v_fmac_f32_e32 v83, v146, v144
	v_cvt_pk_bf16_f32 v132, v80, v81
	v_cvt_pk_bf16_f32 v133, v82, v83
	v_lshlrev_b32_e32 v141, 16, v114
	v_and_b32_e32 v142, 0xffff0000, v114
	v_lshlrev_b32_e32 v143, 16, v115
	v_and_b32_e32 v144, 0xffff0000, v115
	v_fmac_f32_e32 v84, v146, v141
	v_fmac_f32_e32 v85, v146, v142
	v_fmac_f32_e32 v86, v146, v143
	v_fmac_f32_e32 v87, v146, v144
	v_cvt_pk_bf16_f32 v134, v84, v85
	v_cvt_pk_bf16_f32 v135, v86, v87
	v_lshlrev_b32_e32 v141, 16, v116
	v_and_b32_e32 v142, 0xffff0000, v116
	v_lshlrev_b32_e32 v143, 16, v117
	v_and_b32_e32 v144, 0xffff0000, v117
	v_fmac_f32_e32 v88, v146, v141
	v_fmac_f32_e32 v89, v146, v142
	v_fmac_f32_e32 v90, v146, v143
	v_fmac_f32_e32 v91, v146, v144
	v_cvt_pk_bf16_f32 v136, v88, v89
	v_cvt_pk_bf16_f32 v137, v90, v91
	v_lshlrev_b32_e32 v141, 16, v118
	v_and_b32_e32 v142, 0xffff0000, v118
	v_lshlrev_b32_e32 v143, 16, v119
	v_and_b32_e32 v144, 0xffff0000, v119
	v_fmac_f32_e32 v92, v146, v141
	v_fmac_f32_e32 v93, v146, v142
	v_fmac_f32_e32 v94, v146, v143
	v_fmac_f32_e32 v95, v146, v144
	v_cvt_pk_bf16_f32 v138, v92, v93
	v_cvt_pk_bf16_f32 v139, v94, v95
	s_mov_b64 s[26:27], s[86:87]
	s_mov_b64 s[28:29], s[88:89]
	s_mov_b64 s[86:87], s[12:13]
	s_mov_b64 s[88:89], s[14:15]
	s_mov_b32 s4, s83
	s_mov_b32 s5, s84
	s_waitcnt vmcnt(0)
	s_barrier
	ds_read_b128 v[4:7], v230 offset:0
	ds_read_b128 v[8:11], v231 offset:0
	ds_read_b128 v[12:15], v230 offset:2048
	ds_read_b128 v[16:19], v231 offset:2048
	ds_read_b128 v[20:23], v230 offset:4096
	ds_read_b128 v[24:27], v231 offset:4096
	ds_read_b128 v[28:31], v230 offset:6144
	ds_read_b128 v[32:35], v231 offset:6144
	ds_read_b128 v[36:39], v230 offset:8192
	ds_read_b128 v[40:43], v231 offset:8192
	global_store_dwordx2 v237, v[132:133], s[26:27]
	global_store_dwordx2 v237, v[134:135], s[26:27] offset:32
	global_store_dwordx2 v237, v[136:137], s[26:27] offset:64
	global_store_dwordx2 v237, v[138:139], s[26:27] offset:96
	s_mov_b64 s[90:91], exec
	s_mov_b64 exec, 0xffff
	global_store_dword v238, v140, s[28:29]
	s_mov_b64 exec, s[90:91]
	s_add_u32 s83, s4, 1
	s_mov_b32 s84, s5
	s_mul_i32 s74, s84, 1024
	s_lshl_b32 s75, s83, 7
	s_add_u32 s74, s74, s75
	s_lshl_b32 s75, s74, 7
	s_add_u32 s16, s60, s75
	s_addc_u32 s17, s61, 0
	s_lshl_b32 s75, s74, 1
	s_add_u32 s24, s64, s75
	s_addc_u32 s25, s65, 0
	s_add_u32 m0, s70, 0x8000
	s_nop 0
	global_load_lds_dwordx4 v232, s[16:17]
	s_add_u32 m0, s70, 0xa000
	s_nop 0
	global_load_lds_dwordx4 v233, s[16:17]
	s_add_u32 m0, s70, 0x18000
	s_nop 0
	global_load_lds_dwordx4 v234, s[24:25]
	s_add_u32 m0, s70, 0x1a000
	s_nop 0
	global_load_lds_dwordx4 v235, s[24:25]
	s_lshl_b32 s74, s83, 9
	s_add_u32 s74, s74, s84
	s_lshl_b32 s75, s74, 7
	s_add_u32 s10, s30, s75
	s_addc_u32 s11, s31, 0
	s_add_u32 s12, s34, s75
	s_addc_u32 s13, s35, 0
	s_lshl_b32 s75, s74, 2
	s_add_u32 s14, s58, s75
	s_addc_u32 s15, s59, 0
	global_load_dwordx4 v[96:99], v236, s[10:11]
	global_load_dwordx4 v[100:103], v236, s[10:11] offset:64
	global_load_dwordx2 v[112:113], v237, s[12:13]
	global_load_dwordx2 v[114:115], v237, s[12:13] offset:32
	global_load_dwordx2 v[116:117], v237, s[12:13] offset:64
	global_load_dwordx2 v[118:119], v237, s[12:13] offset:96
	global_load_dword v120, v238, s[14:15]
	s_waitcnt lgkmcnt(0)
	v_mfma_f32_16x16x32_bf16 v[44:47], v[4:7], v[104:107], 0
	v_mfma_f32_16x16x32_bf16 v[48:51], v[12:15], v[104:107], 0
	v_mfma_f32_16x16x32_bf16 v[52:55], v[20:23], v[104:107], 0
	v_mfma_f32_16x16x32_bf16 v[56:59], v[28:31], v[104:107], 0
	v_mfma_f32_16x16x32_bf16 v[60:63], v[36:39], v[104:107], 0
	v_mfma_f32_16x16x32_bf16 v[44:47], v[8:11], v[108:111], v[44:47]
	v_mfma_f32_16x16x32_bf16 v[48:51], v[16:19], v[108:111], v[48:51]
	v_mfma_f32_16x16x32_bf16 v[52:55], v[24:27], v[108:111], v[52:55]
	v_mfma_f32_16x16x32_bf16 v[56:59], v[32:35], v[108:111], v[56:59]
	v_mfma_f32_16x16x32_bf16 v[60:63], v[40:43], v[108:111], v[60:63]
	ds_read_b128 v[4:7], v230 offset:10240
	ds_read_b128 v[8:11], v231 offset:10240
	ds_read_b128 v[12:15], v230 offset:12288
	ds_read_b128 v[16:19], v231 offset:12288
	ds_read_b128 v[20:23], v230 offset:14336
	ds_read_b128 v[24:27], v231 offset:14336
	ds_read_b128 v[28:31], v230 offset:16384
	ds_read_b128 v[32:35], v231 offset:16384
	s_nop 1
	v_fma_f32 v44, v44, s79, v185
	v_fma_f32 v45, v45, s79, v186
	v_fma_f32 v46, v46, s79, v187
	v_fma_f32 v47, v47, s79, v188
	v_fma_f32 v48, v48, s79, v189
	v_fma_f32 v49, v49, s79, v190
	v_fma_f32 v50, v50, s79, v191
	v_fma_f32 v51, v51, s79, v192
	v_fma_f32 v52, v52, s79, v193
	v_fma_f32 v53, v53, s79, v194
	v_fma_f32 v54, v54, s79, v195
	v_fma_f32 v55, v55, s79, v196
	v_fma_f32 v56, v56, s79, v197
	v_fma_f32 v57, v57, s79, v198
	v_fma_f32 v58, v58, s79, v199
	v_fma_f32 v59, v59, s79, v200
	v_fma_f32 v60, v60, s79, v201
	v_fma_f32 v61, v61, s79, v202
	v_fma_f32 v62, v62, s79, v203
	v_fma_f32 v63, v63, s79, v204
	s_waitcnt lgkmcnt(0)
	v_mfma_f32_16x16x32_bf16 v[64:67], v[4:7], v[104:107], 0
	v_mfma_f32_16x16x32_bf16 v[68:71], v[12:15], v[104:107], 0
	v_mfma_f32_16x16x32_bf16 v[72:75], v[20:23], v[104:107], 0
	v_mfma_f32_16x16x32_bf16 v[76:79], v[28:31], v[104:107], 0
	v_mfma_f32_16x16x32_bf16 v[64:67], v[8:11], v[108:111], v[64:67]
	v_mfma_f32_16x16x32_bf16 v[68:71], v[16:19], v[108:111], v[68:71]
	v_mfma_f32_16x16x32_bf16 v[72:75], v[24:27], v[108:111], v[72:75]
	v_mfma_f32_16x16x32_bf16 v[76:79], v[32:35], v[108:111], v[76:79]
	ds_read_b64 v[4:5], v221 offset:0
	ds_read_b64 v[8:9], v221 offset:4096
	ds_read_b64 v[12:13], v221 offset:8192
	ds_read_b64 v[16:17], v221 offset:12288
	ds_read_b64 v[6:7], v222 offset:0
	ds_read_b64 v[10:11], v222 offset:4096
	ds_read_b64 v[14:15], v222 offset:8192
	ds_read_b64 v[18:19], v222 offset:12288
	s_nop 1
	v_fma_f32 v64, v64, s79, v205
	v_fma_f32 v65, v65, s79, v206
	v_fma_f32 v66, v66, s79, v207
	v_fma_f32 v67, v67, s79, v208
	v_fma_f32 v68, v68, s79, v209
	v_fma_f32 v69, v69, s79, v210
	v_fma_f32 v70, v70, s79, v211
	v_fma_f32 v71, v71, s79, v212
	v_fma_f32 v72, v72, s79, v213
	v_fma_f32 v73, v73, s79, v214
	v_fma_f32 v74, v74, s79, v215
	v_fma_f32 v75, v75, s79, v216
	v_fma_f32 v76, v76, s79, v217
	v_fma_f32 v77, v77, s79, v218
	v_fma_f32 v78, v78, s79, v219
	v_fma_f32 v79, v79, s79, v220
	ds_read_b64 v[20:21], v223 offset:0
	ds_read_b64 v[24:25], v223 offset:4096
	ds_read_b64 v[28:29], v223 offset:8192
	ds_read_b64 v[32:33], v223 offset:12288
	ds_read_b64 v[22:23], v224 offset:0
	ds_read_b64 v[26:27], v224 offset:4096
	ds_read_b64 v[30:31], v224 offset:8192
	ds_read_b64 v[34:35], v224 offset:12288
	s_cmp_lg_u32 s4, 0
	s_cbranch_scc1 .Lat844_i1_nomask
	s_cmp_le_u32 s6, 0
	s_cbranch_scc1 .Lat844_i1_nomask
	v_mov_b32_e32 v44, v244
	v_mov_b32_e32 v45, v244
	v_mov_b32_e32 v46, v244
	v_mov_b32_e32 v47, v244
	s_cmp_le_u32 s6, 1
	s_cbranch_scc1 .Lat844_i1_nomask
	v_mov_b32_e32 v48, v244
	v_mov_b32_e32 v49, v244
	v_mov_b32_e32 v50, v244
	v_mov_b32_e32 v51, v244
	s_cmp_le_u32 s6, 2
	s_cbranch_scc1 .Lat844_i1_nomask
	v_mov_b32_e32 v52, v244
	v_mov_b32_e32 v53, v244
	v_mov_b32_e32 v54, v244
	v_mov_b32_e32 v55, v244
	s_cmp_le_u32 s6, 3
	s_cbranch_scc1 .Lat844_i1_nomask
	v_mov_b32_e32 v56, v244
	v_mov_b32_e32 v57, v244
	v_mov_b32_e32 v58, v244
	v_mov_b32_e32 v59, v244
	s_cmp_le_u32 s6, 4
	s_cbranch_scc1 .Lat844_i1_nomask
	v_mov_b32_e32 v60, v244
	v_mov_b32_e32 v61, v244
	v_mov_b32_e32 v62, v244
	v_mov_b32_e32 v63, v244
	s_cmp_le_u32 s6, 5
	s_cbranch_scc1 .Lat844_i1_nomask
	v_mov_b32_e32 v64, v244
	v_mov_b32_e32 v65, v244
	v_mov_b32_e32 v66, v244
	v_mov_b32_e32 v67, v244
	s_cmp_le_u32 s6, 6
	s_cbranch_scc1 .Lat844_i1_nomask
	v_mov_b32_e32 v68, v244
	v_mov_b32_e32 v69, v244
	v_mov_b32_e32 v70, v244
	v_mov_b32_e32 v71, v244
	s_cmp_le_u32 s6, 7
	s_cbranch_scc1 .Lat844_i1_nomask
	v_mov_b32_e32 v72, v244
	v_mov_b32_e32 v73, v244
	v_mov_b32_e32 v74, v244
	v_mov_b32_e32 v75, v244
.Lat844_i1_nomask:
	v_max3_f32 v245, v44, v45, v46
	v_max3_f32 v245, v245, v47, v48
	v_max3_f32 v245, v245, v49, v50
	v_max3_f32 v245, v245, v51, v52
	v_max3_f32 v245, v245, v53, v54
	v_max3_f32 v245, v245, v55, v56
	v_max3_f32 v245, v245, v57, v58
	v_max3_f32 v245, v245, v59, v60
	v_max3_f32 v245, v245, v61, v62
	v_max3_f32 v245, v245, v63, v64
	v_max3_f32 v245, v245, v65, v66
	v_max3_f32 v245, v245, v67, v68
	v_max3_f32 v245, v245, v69, v70
	v_max3_f32 v245, v245, v71, v72
	v_max3_f32 v245, v245, v73, v74
	v_max3_f32 v245, v245, v75, v76
	v_max3_f32 v245, v245, v77, v78
	v_max_f32_e32 v245, v245, v79
	ds_bpermute_b32 v148, v239, v245
	s_waitcnt lgkmcnt(0)
	v_max_f32_e32 v245, v245, v148
	ds_bpermute_b32 v148, v240, v245
	s_waitcnt lgkmcnt(0)
	v_max_f32_e32 v245, v245, v148
	v_sub_f32_e32 v44, v44, v245
	v_sub_f32_e32 v45, v45, v245
	v_sub_f32_e32 v46, v46, v245
	v_sub_f32_e32 v47, v47, v245
	v_exp_f32_e32 v44, v44
	v_exp_f32_e32 v45, v45
	v_exp_f32_e32 v46, v46
	v_exp_f32_e32 v47, v47
	v_sub_f32_e32 v48, v48, v245
	v_sub_f32_e32 v49, v49, v245
	v_sub_f32_e32 v50, v50, v245
	v_sub_f32_e32 v51, v51, v245
	v_exp_f32_e32 v48, v48
	v_exp_f32_e32 v49, v49
	v_exp_f32_e32 v50, v50
	v_exp_f32_e32 v51, v51
	v_mov_b32_e32 v149, v44
	v_mov_b32_e32 v150, v45
	v_mov_b32_e32 v151, v46
	v_mov_b32_e32 v152, v47
	v_cvt_pk_bf16_f32 v44, v44, v45
	v_cvt_pk_bf16_f32 v45, v46, v47
	v_sub_f32_e32 v52, v52, v245
	v_sub_f32_e32 v53, v53, v245
	v_sub_f32_e32 v54, v54, v245
	v_sub_f32_e32 v55, v55, v245
	v_exp_f32_e32 v52, v52
	v_exp_f32_e32 v53, v53
	v_exp_f32_e32 v54, v54
	v_exp_f32_e32 v55, v55
	v_add_f32_e32 v149, v149, v48
	v_add_f32_e32 v150, v150, v49
	v_add_f32_e32 v151, v151, v50
	v_add_f32_e32 v152, v152, v51
	v_cvt_pk_bf16_f32 v46, v48, v49
	v_cvt_pk_bf16_f32 v47, v50, v51
	v_sub_f32_e32 v56, v56, v245
	v_sub_f32_e32 v57, v57, v245
	v_sub_f32_e32 v58, v58, v245
	v_sub_f32_e32 v59, v59, v245
	v_exp_f32_e32 v56, v56
	v_exp_f32_e32 v57, v57
	v_exp_f32_e32 v58, v58
	v_exp_f32_e32 v59, v59
	v_add_f32_e32 v149, v149, v52
	v_add_f32_e32 v150, v150, v53
	v_add_f32_e32 v151, v151, v54
	v_add_f32_e32 v152, v152, v55
	v_cvt_pk_bf16_f32 v52, v52, v53
	v_cvt_pk_bf16_f32 v53, v54, v55
	v_sub_f32_e32 v60, v60, v245
	v_sub_f32_e32 v61, v61, v245
	v_sub_f32_e32 v62, v62, v245
	v_sub_f32_e32 v63, v63, v245
	v_exp_f32_e32 v60, v60
	v_exp_f32_e32 v61, v61
	v_exp_f32_e32 v62, v62
	v_exp_f32_e32 v63, v63
	v_add_f32_e32 v149, v149, v56
	v_add_f32_e32 v150, v150, v57
	v_add_f32_e32 v151, v151, v58
	v_add_f32_e32 v152, v152, v59
	v_cvt_pk_bf16_f32 v54, v56, v57
	v_cvt_pk_bf16_f32 v55, v58, v59
	v_sub_f32_e32 v64, v64, v245
	v_sub_f32_e32 v65, v65, v245
	v_sub_f32_e32 v66, v66, v245
	v_sub_f32_e32 v67, v67, v245
	v_exp_f32_e32 v64, v64
	v_exp_f32_e32 v65, v65
	v_exp_f32_e32 v66, v66
	v_exp_f32_e32 v67, v67
	v_add_f32_e32 v149, v149, v60
	v_add_f32_e32 v150, v150, v61
	v_add_f32_e32 v151, v151, v62
	v_add_f32_e32 v152, v152, v63
	v_cvt_pk_bf16_f32 v60, v60, v61
	v_cvt_pk_bf16_f32 v61, v62, v63
	v_sub_f32_e32 v68, v68, v245
	v_sub_f32_e32 v69, v69, v245
	v_sub_f32_e32 v70, v70, v245
	v_sub_f32_e32 v71, v71, v245
	v_exp_f32_e32 v68, v68
	v_exp_f32_e32 v69, v69
	v_exp_f32_e32 v70, v70
	v_exp_f32_e32 v71, v71
	v_add_f32_e32 v149, v149, v64
	v_add_f32_e32 v150, v150, v65
	v_add_f32_e32 v151, v151, v66
	v_add_f32_e32 v152, v152, v67
	v_cvt_pk_bf16_f32 v62, v64, v65
	v_cvt_pk_bf16_f32 v63, v66, v67
	v_sub_f32_e32 v72, v72, v245
	v_sub_f32_e32 v73, v73, v245
	v_sub_f32_e32 v74, v74, v245
	v_sub_f32_e32 v75, v75, v245
	v_exp_f32_e32 v72, v72
	v_exp_f32_e32 v73, v73
	v_exp_f32_e32 v74, v74
	v_exp_f32_e32 v75, v75
	v_add_f32_e32 v149, v149, v68
	v_add_f32_e32 v150, v150, v69
	v_add_f32_e32 v151, v151, v70
	v_add_f32_e32 v152, v152, v71
	v_cvt_pk_bf16_f32 v68, v68, v69
	v_cvt_pk_bf16_f32 v69, v70, v71
	v_sub_f32_e32 v76, v76, v245
	v_sub_f32_e32 v77, v77, v245
	v_sub_f32_e32 v78, v78, v245
	v_sub_f32_e32 v79, v79, v245
	v_exp_f32_e32 v76, v76
	v_exp_f32_e32 v77, v77
	v_exp_f32_e32 v78, v78
	v_exp_f32_e32 v79, v79
	v_add_f32_e32 v149, v149, v72
	v_add_f32_e32 v150, v150, v73
	v_add_f32_e32 v151, v151, v74
	v_add_f32_e32 v152, v152, v75
	v_cvt_pk_bf16_f32 v70, v72, v73
	v_cvt_pk_bf16_f32 v71, v74, v75
	s_nop 0
	v_add_f32_e32 v149, v149, v76
	v_add_f32_e32 v150, v150, v77
	v_add_f32_e32 v151, v151, v78
	v_add_f32_e32 v152, v152, v79
	v_cvt_pk_bf16_f32 v76, v76, v77
	v_cvt_pk_bf16_f32 v77, v78, v79
	v_mov_b32_e32 v78, 0
	v_mov_b32_e32 v79, 0
	v_add_f32_e32 v149, v149, v150
	v_add_f32_e32 v151, v151, v152
	v_add_f32_e32 v246, v149, v151
	s_waitcnt lgkmcnt(0)
	v_mfma_f32_16x16x32_bf16 v[80:83], v[4:7], v[44:47], 0
	v_mfma_f32_16x16x32_bf16 v[84:87], v[8:11], v[44:47], 0
	v_mfma_f32_16x16x32_bf16 v[88:91], v[12:15], v[44:47], 0
	v_mfma_f32_16x16x32_bf16 v[92:95], v[16:19], v[44:47], 0
	ds_read_b64 v[4:5], v225 offset:0
	ds_read_b64 v[8:9], v225 offset:4096
	ds_read_b64 v[12:13], v225 offset:8192
	ds_read_b64 v[16:17], v225 offset:12288
	ds_read_b64 v[6:7], v226 offset:0
	ds_read_b64 v[10:11], v226 offset:4096
	ds_read_b64 v[14:15], v226 offset:8192
	ds_read_b64 v[18:19], v226 offset:12288
	v_mfma_f32_16x16x32_bf16 v[80:83], v[20:23], v[52:55], v[80:83]
	v_mfma_f32_16x16x32_bf16 v[84:87], v[24:27], v[52:55], v[84:87]
	v_mfma_f32_16x16x32_bf16 v[88:91], v[28:31], v[52:55], v[88:91]
	v_mfma_f32_16x16x32_bf16 v[92:95], v[32:35], v[52:55], v[92:95]
	ds_read_b64 v[20:21], v227 offset:0
	ds_read_b64 v[24:25], v227 offset:4096
	ds_read_b64 v[28:29], v227 offset:8192
	ds_read_b64 v[32:33], v227 offset:12288
	ds_read_b64 v[22:23], v228 offset:0
	ds_read_b64 v[26:27], v228 offset:4096
	ds_read_b64 v[30:31], v228 offset:8192
	ds_read_b64 v[34:35], v228 offset:12288
	ds_bpermute_b32 v148, v239, v246
	s_waitcnt lgkmcnt(9)
	v_mfma_f32_16x16x32_bf16 v[80:83], v[4:7], v[60:63], v[80:83]
	v_mfma_f32_16x16x32_bf16 v[84:87], v[8:11], v[60:63], v[84:87]
	v_mfma_f32_16x16x32_bf16 v[88:91], v[12:15], v[60:63], v[88:91]
	v_mfma_f32_16x16x32_bf16 v[92:95], v[16:19], v[60:63], v[92:95]
	ds_read_b64 v[4:5], v229 offset:0
	ds_read_b64 v[8:9], v229 offset:4096
	ds_read_b64 v[12:13], v229 offset:8192
	ds_read_b64 v[16:17], v229 offset:12288
	v_mov_b32_e32 v6, 0
	v_mov_b32_e32 v7, 0
	v_mov_b32_e32 v10, 0
	v_mov_b32_e32 v11, 0
	v_mov_b32_e32 v14, 0
	v_mov_b32_e32 v15, 0
	v_mov_b32_e32 v18, 0
	v_mov_b32_e32 v19, 0
	s_waitcnt lgkmcnt(5)
	v_mfma_f32_16x16x32_bf16 v[80:83], v[20:23], v[68:71], v[80:83]
	v_mfma_f32_16x16x32_bf16 v[84:87], v[24:27], v[68:71], v[84:87]
	v_mfma_f32_16x16x32_bf16 v[88:91], v[28:31], v[68:71], v[88:91]
	v_mfma_f32_16x16x32_bf16 v[92:95], v[32:35], v[68:71], v[92:95]
	s_waitcnt lgkmcnt(0)
	v_add_f32_e32 v246, v246, v148
	s_nop 0
	v_mfma_f32_16x16x32_bf16 v[80:83], v[4:7], v[76:79], v[80:83]
	v_mfma_f32_16x16x32_bf16 v[84:87], v[8:11], v[76:79], v[84:87]
	v_mfma_f32_16x16x32_bf16 v[88:91], v[12:15], v[76:79], v[88:91]
	v_mfma_f32_16x16x32_bf16 v[92:95], v[16:19], v[76:79], v[92:95]
	ds_bpermute_b32 v148, v240, v246
	s_waitcnt lgkmcnt(0)
	v_add_f32_e32 v246, v246, v148
	v_rcp_f32_e32 v149, v246
	v_log_f32_e32 v150, v246
	s_nop 0
	v_add_f32_e32 v151, v245, v150
	v_mul_f32_e32 v151, 0x3f317218, v151
	v_max_f32_e32 v152, v121, v151
	v_sub_f32_e32 v153, v121, v152
	v_sub_f32_e32 v154, v151, v152
	v_mul_f32_e32 v153, 0x3fb8aa3b, v153
	v_mul_f32_e32 v154, 0x3fb8aa3b, v154
	v_exp_f32_e32 v153, v153
	v_exp_f32_e32 v154, v154
	s_nop 0
	v_add_f32_e32 v155, v153, v154
	v_rcp_f32_e32 v146, v155
	v_log_f32_e32 v150, v155
	s_nop 0
	v_mul_f32_e32 v154, v154, v146
	v_mul_f32_e32 v146, v153, v146
	v_mul_f32_e32 v147, v149, v154
	v_mul_f32_e32 v150, 0x3f317218, v150
	v_add_f32_e32 v140, v152, v150
	v_mul_f32_e32 v80, v80, v147
	v_mul_f32_e32 v81, v81, v147
	v_mul_f32_e32 v82, v82, v147
	v_mul_f32_e32 v83, v83, v147
	v_mul_f32_e32 v84, v84, v147
	v_mul_f32_e32 v85, v85, v147
	v_mul_f32_e32 v86, v86, v147
	v_mul_f32_e32 v87, v87, v147
	v_mul_f32_e32 v88, v88, v147
	v_mul_f32_e32 v89, v89, v147
	v_mul_f32_e32 v90, v90, v147
	v_mul_f32_e32 v91, v91, v147
	v_mul_f32_e32 v92, v92, v147
	v_mul_f32_e32 v93, v93, v147
	v_mul_f32_e32 v94, v94, v147
	v_mul_f32_e32 v95, v95, v147
	v_lshlrev_b32_e32 v141, 16, v122
	v_and_b32_e32 v142, 0xffff0000, v122
	v_lshlrev_b32_e32 v143, 16, v123
	v_and_b32_e32 v144, 0xffff0000, v123
	v_fmac_f32_e32 v80, v146, v141
	v_fmac_f32_e32 v81, v146, v142
	v_fmac_f32_e32 v82, v146, v143
	v_fmac_f32_e32 v83, v146, v144
	v_cvt_pk_bf16_f32 v132, v80, v81
	v_cvt_pk_bf16_f32 v133, v82, v83
	v_lshlrev_b32_e32 v141, 16, v124
	v_and_b32_e32 v142, 0xffff0000, v124
	v_lshlrev_b32_e32 v143, 16, v125
	v_and_b32_e32 v144, 0xffff0000, v125
	v_fmac_f32_e32 v84, v146, v141
	v_fmac_f32_e32 v85, v146, v142
	v_fmac_f32_e32 v86, v146, v143
	v_fmac_f32_e32 v87, v146, v144
	v_cvt_pk_bf16_f32 v134, v84, v85
	v_cvt_pk_bf16_f32 v135, v86, v87
	v_lshlrev_b32_e32 v141, 16, v126
	v_and_b32_e32 v142, 0xffff0000, v126
	v_lshlrev_b32_e32 v143, 16, v127
	v_and_b32_e32 v144, 0xffff0000, v127
	v_fmac_f32_e32 v88, v146, v141
	v_fmac_f32_e32 v89, v146, v142
	v_fmac_f32_e32 v90, v146, v143
	v_fmac_f32_e32 v91, v146, v144
	v_cvt_pk_bf16_f32 v136, v88, v89
	v_cvt_pk_bf16_f32 v137, v90, v91
	v_lshlrev_b32_e32 v141, 16, v128
	v_and_b32_e32 v142, 0xffff0000, v128
	v_lshlrev_b32_e32 v143, 16, v129
	v_and_b32_e32 v144, 0xffff0000, v129
	v_fmac_f32_e32 v92, v146, v141
	v_fmac_f32_e32 v93, v146, v142
	v_fmac_f32_e32 v94, v146, v143
	v_fmac_f32_e32 v95, v146, v144
	v_cvt_pk_bf16_f32 v138, v92, v93
	v_cvt_pk_bf16_f32 v139, v94, v95
	s_mov_b64 s[26:27], s[86:87]
	s_mov_b64 s[28:29], s[88:89]
	s_mov_b64 s[86:87], s[12:13]
	s_mov_b64 s[88:89], s[14:15]
	s_mov_b32 s4, s83
	s_mov_b32 s5, s84
	s_waitcnt vmcnt(0)
	s_barrier
	ds_read_b128 v[4:7], v230 offset:16384
	ds_read_b128 v[8:11], v231 offset:16384
	ds_read_b128 v[12:15], v230 offset:18432
	ds_read_b128 v[16:19], v231 offset:18432
	ds_read_b128 v[20:23], v230 offset:20480
	ds_read_b128 v[24:27], v231 offset:20480
	ds_read_b128 v[28:31], v230 offset:22528
	ds_read_b128 v[32:35], v231 offset:22528
	ds_read_b128 v[36:39], v230 offset:24576
	ds_read_b128 v[40:43], v231 offset:24576
	global_store_dwordx2 v237, v[132:133], s[26:27]
	global_store_dwordx2 v237, v[134:135], s[26:27] offset:32
	global_store_dwordx2 v237, v[136:137], s[26:27] offset:64
	global_store_dwordx2 v237, v[138:139], s[26:27] offset:96
	s_mov_b64 s[90:91], exec
	s_mov_b64 exec, 0xffff
	global_store_dword v238, v140, s[28:29]
	s_mov_b64 exec, s[90:91]
	s_add_u32 s83, s4, 1
	s_mov_b32 s84, s5
	s_mul_i32 s74, s84, 1024
	s_lshl_b32 s75, s83, 7
	s_add_u32 s74, s74, s75
	s_lshl_b32 s75, s74, 7
	s_add_u32 s16, s60, s75
	s_addc_u32 s17, s61, 0
	s_lshl_b32 s75, s74, 1
	s_add_u32 s24, s64, s75
	s_addc_u32 s25, s65, 0
	s_add_u32 m0, s70, 0xc000
	s_nop 0
	global_load_lds_dwordx4 v232, s[16:17]
	s_add_u32 m0, s70, 0xe000
	s_nop 0
	global_load_lds_dwordx4 v233, s[16:17]
	s_add_u32 m0, s70, 0x1c000
	s_nop 0
	global_load_lds_dwordx4 v234, s[24:25]
	s_add_u32 m0, s70, 0x1e000
	s_nop 0
	global_load_lds_dwordx4 v235, s[24:25]
	s_lshl_b32 s74, s83, 9
	s_add_u32 s74, s74, s84
	s_lshl_b32 s75, s74, 7
	s_add_u32 s10, s30, s75
	s_addc_u32 s11, s31, 0
	s_add_u32 s12, s34, s75
	s_addc_u32 s13, s35, 0
	s_lshl_b32 s75, s74, 2
	s_add_u32 s14, s58, s75
	s_addc_u32 s15, s59, 0
	global_load_dwordx4 v[104:107], v236, s[10:11]
	global_load_dwordx4 v[108:111], v236, s[10:11] offset:64
	global_load_dwordx2 v[122:123], v237, s[12:13]
	global_load_dwordx2 v[124:125], v237, s[12:13] offset:32
	global_load_dwordx2 v[126:127], v237, s[12:13] offset:64
	global_load_dwordx2 v[128:129], v237, s[12:13] offset:96
	global_load_dword v121, v238, s[14:15]
	s_waitcnt lgkmcnt(0)
	v_mfma_f32_16x16x32_bf16 v[44:47], v[4:7], v[96:99], 0
	v_mfma_f32_16x16x32_bf16 v[48:51], v[12:15], v[96:99], 0
	v_mfma_f32_16x16x32_bf16 v[52:55], v[20:23], v[96:99], 0
	v_mfma_f32_16x16x32_bf16 v[56:59], v[28:31], v[96:99], 0
	v_mfma_f32_16x16x32_bf16 v[60:63], v[36:39], v[96:99], 0
	v_mfma_f32_16x16x32_bf16 v[44:47], v[8:11], v[100:103], v[44:47]
	v_mfma_f32_16x16x32_bf16 v[48:51], v[16:19], v[100:103], v[48:51]
	v_mfma_f32_16x16x32_bf16 v[52:55], v[24:27], v[100:103], v[52:55]
	v_mfma_f32_16x16x32_bf16 v[56:59], v[32:35], v[100:103], v[56:59]
	v_mfma_f32_16x16x32_bf16 v[60:63], v[40:43], v[100:103], v[60:63]
	ds_read_b128 v[4:7], v230 offset:26624
	ds_read_b128 v[8:11], v231 offset:26624
	ds_read_b128 v[12:15], v230 offset:28672
	ds_read_b128 v[16:19], v231 offset:28672
	ds_read_b128 v[20:23], v230 offset:30720
	ds_read_b128 v[24:27], v231 offset:30720
	ds_read_b128 v[28:31], v230 offset:32768
	ds_read_b128 v[32:35], v231 offset:32768
	s_nop 1
	v_fma_f32 v44, v44, s79, v185
	v_fma_f32 v45, v45, s79, v186
	v_fma_f32 v46, v46, s79, v187
	v_fma_f32 v47, v47, s79, v188
	v_fma_f32 v48, v48, s79, v189
	v_fma_f32 v49, v49, s79, v190
	v_fma_f32 v50, v50, s79, v191
	v_fma_f32 v51, v51, s79, v192
	v_fma_f32 v52, v52, s79, v193
	v_fma_f32 v53, v53, s79, v194
	v_fma_f32 v54, v54, s79, v195
	v_fma_f32 v55, v55, s79, v196
	v_fma_f32 v56, v56, s79, v197
	v_fma_f32 v57, v57, s79, v198
	v_fma_f32 v58, v58, s79, v199
	v_fma_f32 v59, v59, s79, v200
	v_fma_f32 v60, v60, s79, v201
	v_fma_f32 v61, v61, s79, v202
	v_fma_f32 v62, v62, s79, v203
	v_fma_f32 v63, v63, s79, v204
	s_waitcnt lgkmcnt(0)
	v_mfma_f32_16x16x32_bf16 v[64:67], v[4:7], v[96:99], 0
	v_mfma_f32_16x16x32_bf16 v[68:71], v[12:15], v[96:99], 0
	v_mfma_f32_16x16x32_bf16 v[72:75], v[20:23], v[96:99], 0
	v_mfma_f32_16x16x32_bf16 v[76:79], v[28:31], v[96:99], 0
	v_mfma_f32_16x16x32_bf16 v[64:67], v[8:11], v[100:103], v[64:67]
	v_mfma_f32_16x16x32_bf16 v[68:71], v[16:19], v[100:103], v[68:71]
	v_mfma_f32_16x16x32_bf16 v[72:75], v[24:27], v[100:103], v[72:75]
	v_mfma_f32_16x16x32_bf16 v[76:79], v[32:35], v[100:103], v[76:79]
	ds_read_b64 v[4:5], v221 offset:16384
	ds_read_b64 v[8:9], v221 offset:20480
	ds_read_b64 v[12:13], v221 offset:24576
	ds_read_b64 v[16:17], v221 offset:28672
	ds_read_b64 v[6:7], v222 offset:16384
	ds_read_b64 v[10:11], v222 offset:20480
	ds_read_b64 v[14:15], v222 offset:24576
	ds_read_b64 v[18:19], v222 offset:28672
	s_nop 1
	v_fma_f32 v64, v64, s79, v205
	v_fma_f32 v65, v65, s79, v206
	v_fma_f32 v66, v66, s79, v207
	v_fma_f32 v67, v67, s79, v208
	v_fma_f32 v68, v68, s79, v209
	v_fma_f32 v69, v69, s79, v210
	v_fma_f32 v70, v70, s79, v211
	v_fma_f32 v71, v71, s79, v212
	v_fma_f32 v72, v72, s79, v213
	v_fma_f32 v73, v73, s79, v214
	v_fma_f32 v74, v74, s79, v215
	v_fma_f32 v75, v75, s79, v216
	v_fma_f32 v76, v76, s79, v217
	v_fma_f32 v77, v77, s79, v218
	v_fma_f32 v78, v78, s79, v219
	v_fma_f32 v79, v79, s79, v220
	ds_read_b64 v[20:21], v223 offset:16384
	ds_read_b64 v[24:25], v223 offset:20480
	ds_read_b64 v[28:29], v223 offset:24576
	ds_read_b64 v[32:33], v223 offset:28672
	ds_read_b64 v[22:23], v224 offset:16384
	ds_read_b64 v[26:27], v224 offset:20480
	ds_read_b64 v[30:31], v224 offset:24576
	ds_read_b64 v[34:35], v224 offset:28672
	s_cmp_lg_u32 s4, 0
	s_cbranch_scc1 .Lat844_i2_nomask
	s_cmp_le_u32 s6, 0
	s_cbranch_scc1 .Lat844_i2_nomask
	v_mov_b32_e32 v44, v244
	v_mov_b32_e32 v45, v244
	v_mov_b32_e32 v46, v244
	v_mov_b32_e32 v47, v244
	s_cmp_le_u32 s6, 1
	s_cbranch_scc1 .Lat844_i2_nomask
	v_mov_b32_e32 v48, v244
	v_mov_b32_e32 v49, v244
	v_mov_b32_e32 v50, v244
	v_mov_b32_e32 v51, v244
	s_cmp_le_u32 s6, 2
	s_cbranch_scc1 .Lat844_i2_nomask
	v_mov_b32_e32 v52, v244
	v_mov_b32_e32 v53, v244
	v_mov_b32_e32 v54, v244
	v_mov_b32_e32 v55, v244
	s_cmp_le_u32 s6, 3
	s_cbranch_scc1 .Lat844_i2_nomask
	v_mov_b32_e32 v56, v244
	v_mov_b32_e32 v57, v244
	v_mov_b32_e32 v58, v244
	v_mov_b32_e32 v59, v244
	s_cmp_le_u32 s6, 4
	s_cbranch_scc1 .Lat844_i2_nomask
	v_mov_b32_e32 v60, v244
	v_mov_b32_e32 v61, v244
	v_mov_b32_e32 v62, v244
	v_mov_b32_e32 v63, v244
	s_cmp_le_u32 s6, 5
	s_cbranch_scc1 .Lat844_i2_nomask
	v_mov_b32_e32 v64, v244
	v_mov_b32_e32 v65, v244
	v_mov_b32_e32 v66, v244
	v_mov_b32_e32 v67, v244
	s_cmp_le_u32 s6, 6
	s_cbranch_scc1 .Lat844_i2_nomask
	v_mov_b32_e32 v68, v244
	v_mov_b32_e32 v69, v244
	v_mov_b32_e32 v70, v244
	v_mov_b32_e32 v71, v244
	s_cmp_le_u32 s6, 7
	s_cbranch_scc1 .Lat844_i2_nomask
	v_mov_b32_e32 v72, v244
	v_mov_b32_e32 v73, v244
	v_mov_b32_e32 v74, v244
	v_mov_b32_e32 v75, v244
.Lat844_i2_nomask:
	v_max3_f32 v245, v44, v45, v46
	v_max3_f32 v245, v245, v47, v48
	v_max3_f32 v245, v245, v49, v50
	v_max3_f32 v245, v245, v51, v52
	v_max3_f32 v245, v245, v53, v54
	v_max3_f32 v245, v245, v55, v56
	v_max3_f32 v245, v245, v57, v58
	v_max3_f32 v245, v245, v59, v60
	v_max3_f32 v245, v245, v61, v62
	v_max3_f32 v245, v245, v63, v64
	v_max3_f32 v245, v245, v65, v66
	v_max3_f32 v245, v245, v67, v68
	v_max3_f32 v245, v245, v69, v70
	v_max3_f32 v245, v245, v71, v72
	v_max3_f32 v245, v245, v73, v74
	v_max3_f32 v245, v245, v75, v76
	v_max3_f32 v245, v245, v77, v78
	v_max_f32_e32 v245, v245, v79
	ds_bpermute_b32 v148, v239, v245
	s_waitcnt lgkmcnt(0)
	v_max_f32_e32 v245, v245, v148
	ds_bpermute_b32 v148, v240, v245
	s_waitcnt lgkmcnt(0)
	v_max_f32_e32 v245, v245, v148
	v_sub_f32_e32 v44, v44, v245
	v_sub_f32_e32 v45, v45, v245
	v_sub_f32_e32 v46, v46, v245
	v_sub_f32_e32 v47, v47, v245
	v_exp_f32_e32 v44, v44
	v_exp_f32_e32 v45, v45
	v_exp_f32_e32 v46, v46
	v_exp_f32_e32 v47, v47
	v_sub_f32_e32 v48, v48, v245
	v_sub_f32_e32 v49, v49, v245
	v_sub_f32_e32 v50, v50, v245
	v_sub_f32_e32 v51, v51, v245
	v_exp_f32_e32 v48, v48
	v_exp_f32_e32 v49, v49
	v_exp_f32_e32 v50, v50
	v_exp_f32_e32 v51, v51
	v_mov_b32_e32 v149, v44
	v_mov_b32_e32 v150, v45
	v_mov_b32_e32 v151, v46
	v_mov_b32_e32 v152, v47
	v_cvt_pk_bf16_f32 v44, v44, v45
	v_cvt_pk_bf16_f32 v45, v46, v47
	v_sub_f32_e32 v52, v52, v245
	v_sub_f32_e32 v53, v53, v245
	v_sub_f32_e32 v54, v54, v245
	v_sub_f32_e32 v55, v55, v245
	v_exp_f32_e32 v52, v52
	v_exp_f32_e32 v53, v53
	v_exp_f32_e32 v54, v54
	v_exp_f32_e32 v55, v55
	v_add_f32_e32 v149, v149, v48
	v_add_f32_e32 v150, v150, v49
	v_add_f32_e32 v151, v151, v50
	v_add_f32_e32 v152, v152, v51
	v_cvt_pk_bf16_f32 v46, v48, v49
	v_cvt_pk_bf16_f32 v47, v50, v51
	v_sub_f32_e32 v56, v56, v245
	v_sub_f32_e32 v57, v57, v245
	v_sub_f32_e32 v58, v58, v245
	v_sub_f32_e32 v59, v59, v245
	v_exp_f32_e32 v56, v56
	v_exp_f32_e32 v57, v57
	v_exp_f32_e32 v58, v58
	v_exp_f32_e32 v59, v59
	v_add_f32_e32 v149, v149, v52
	v_add_f32_e32 v150, v150, v53
	v_add_f32_e32 v151, v151, v54
	v_add_f32_e32 v152, v152, v55
	v_cvt_pk_bf16_f32 v52, v52, v53
	v_cvt_pk_bf16_f32 v53, v54, v55
	v_sub_f32_e32 v60, v60, v245
	v_sub_f32_e32 v61, v61, v245
	v_sub_f32_e32 v62, v62, v245
	v_sub_f32_e32 v63, v63, v245
	v_exp_f32_e32 v60, v60
	v_exp_f32_e32 v61, v61
	v_exp_f32_e32 v62, v62
	v_exp_f32_e32 v63, v63
	v_add_f32_e32 v149, v149, v56
	v_add_f32_e32 v150, v150, v57
	v_add_f32_e32 v151, v151, v58
	v_add_f32_e32 v152, v152, v59
	v_cvt_pk_bf16_f32 v54, v56, v57
	v_cvt_pk_bf16_f32 v55, v58, v59
	v_sub_f32_e32 v64, v64, v245
	v_sub_f32_e32 v65, v65, v245
	v_sub_f32_e32 v66, v66, v245
	v_sub_f32_e32 v67, v67, v245
	v_exp_f32_e32 v64, v64
	v_exp_f32_e32 v65, v65
	v_exp_f32_e32 v66, v66
	v_exp_f32_e32 v67, v67
	v_add_f32_e32 v149, v149, v60
	v_add_f32_e32 v150, v150, v61
	v_add_f32_e32 v151, v151, v62
	v_add_f32_e32 v152, v152, v63
	v_cvt_pk_bf16_f32 v60, v60, v61
	v_cvt_pk_bf16_f32 v61, v62, v63
	v_sub_f32_e32 v68, v68, v245
	v_sub_f32_e32 v69, v69, v245
	v_sub_f32_e32 v70, v70, v245
	v_sub_f32_e32 v71, v71, v245
	v_exp_f32_e32 v68, v68
	v_exp_f32_e32 v69, v69
	v_exp_f32_e32 v70, v70
	v_exp_f32_e32 v71, v71
	v_add_f32_e32 v149, v149, v64
	v_add_f32_e32 v150, v150, v65
	v_add_f32_e32 v151, v151, v66
	v_add_f32_e32 v152, v152, v67
	v_cvt_pk_bf16_f32 v62, v64, v65
	v_cvt_pk_bf16_f32 v63, v66, v67
	v_sub_f32_e32 v72, v72, v245
	v_sub_f32_e32 v73, v73, v245
	v_sub_f32_e32 v74, v74, v245
	v_sub_f32_e32 v75, v75, v245
	v_exp_f32_e32 v72, v72
	v_exp_f32_e32 v73, v73
	v_exp_f32_e32 v74, v74
	v_exp_f32_e32 v75, v75
	v_add_f32_e32 v149, v149, v68
	v_add_f32_e32 v150, v150, v69
	v_add_f32_e32 v151, v151, v70
	v_add_f32_e32 v152, v152, v71
	v_cvt_pk_bf16_f32 v68, v68, v69
	v_cvt_pk_bf16_f32 v69, v70, v71
	v_sub_f32_e32 v76, v76, v245
	v_sub_f32_e32 v77, v77, v245
	v_sub_f32_e32 v78, v78, v245
	v_sub_f32_e32 v79, v79, v245
	v_exp_f32_e32 v76, v76
	v_exp_f32_e32 v77, v77
	v_exp_f32_e32 v78, v78
	v_exp_f32_e32 v79, v79
	v_add_f32_e32 v149, v149, v72
	v_add_f32_e32 v150, v150, v73
	v_add_f32_e32 v151, v151, v74
	v_add_f32_e32 v152, v152, v75
	v_cvt_pk_bf16_f32 v70, v72, v73
	v_cvt_pk_bf16_f32 v71, v74, v75
	s_nop 0
	v_add_f32_e32 v149, v149, v76
	v_add_f32_e32 v150, v150, v77
	v_add_f32_e32 v151, v151, v78
	v_add_f32_e32 v152, v152, v79
	v_cvt_pk_bf16_f32 v76, v76, v77
	v_cvt_pk_bf16_f32 v77, v78, v79
	v_mov_b32_e32 v78, 0
	v_mov_b32_e32 v79, 0
	v_add_f32_e32 v149, v149, v150
	v_add_f32_e32 v151, v151, v152
	v_add_f32_e32 v246, v149, v151
	s_waitcnt lgkmcnt(0)
	v_mfma_f32_16x16x32_bf16 v[80:83], v[4:7], v[44:47], 0
	v_mfma_f32_16x16x32_bf16 v[84:87], v[8:11], v[44:47], 0
	v_mfma_f32_16x16x32_bf16 v[88:91], v[12:15], v[44:47], 0
	v_mfma_f32_16x16x32_bf16 v[92:95], v[16:19], v[44:47], 0
	ds_read_b64 v[4:5], v225 offset:16384
	ds_read_b64 v[8:9], v225 offset:20480
	ds_read_b64 v[12:13], v225 offset:24576
	ds_read_b64 v[16:17], v225 offset:28672
	ds_read_b64 v[6:7], v226 offset:16384
	ds_read_b64 v[10:11], v226 offset:20480
	ds_read_b64 v[14:15], v226 offset:24576
	ds_read_b64 v[18:19], v226 offset:28672
	v_mfma_f32_16x16x32_bf16 v[80:83], v[20:23], v[52:55], v[80:83]
	v_mfma_f32_16x16x32_bf16 v[84:87], v[24:27], v[52:55], v[84:87]
	v_mfma_f32_16x16x32_bf16 v[88:91], v[28:31], v[52:55], v[88:91]
	v_mfma_f32_16x16x32_bf16 v[92:95], v[32:35], v[52:55], v[92:95]
	ds_read_b64 v[20:21], v227 offset:16384
	ds_read_b64 v[24:25], v227 offset:20480
	ds_read_b64 v[28:29], v227 offset:24576
	ds_read_b64 v[32:33], v227 offset:28672
	ds_read_b64 v[22:23], v228 offset:16384
	ds_read_b64 v[26:27], v228 offset:20480
	ds_read_b64 v[30:31], v228 offset:24576
	ds_read_b64 v[34:35], v228 offset:28672
	ds_bpermute_b32 v148, v239, v246
	s_waitcnt lgkmcnt(9)
	v_mfma_f32_16x16x32_bf16 v[80:83], v[4:7], v[60:63], v[80:83]
	v_mfma_f32_16x16x32_bf16 v[84:87], v[8:11], v[60:63], v[84:87]
	v_mfma_f32_16x16x32_bf16 v[88:91], v[12:15], v[60:63], v[88:91]
	v_mfma_f32_16x16x32_bf16 v[92:95], v[16:19], v[60:63], v[92:95]
	ds_read_b64 v[4:5], v229 offset:16384
	ds_read_b64 v[8:9], v229 offset:20480
	ds_read_b64 v[12:13], v229 offset:24576
	ds_read_b64 v[16:17], v229 offset:28672
	v_mov_b32_e32 v6, 0
	v_mov_b32_e32 v7, 0
	v_mov_b32_e32 v10, 0
	v_mov_b32_e32 v11, 0
	v_mov_b32_e32 v14, 0
	v_mov_b32_e32 v15, 0
	v_mov_b32_e32 v18, 0
	v_mov_b32_e32 v19, 0
	s_waitcnt lgkmcnt(5)
	v_mfma_f32_16x16x32_bf16 v[80:83], v[20:23], v[68:71], v[80:83]
	v_mfma_f32_16x16x32_bf16 v[84:87], v[24:27], v[68:71], v[84:87]
	v_mfma_f32_16x16x32_bf16 v[88:91], v[28:31], v[68:71], v[88:91]
	v_mfma_f32_16x16x32_bf16 v[92:95], v[32:35], v[68:71], v[92:95]
	s_waitcnt lgkmcnt(0)
	v_add_f32_e32 v246, v246, v148
	s_nop 0
	v_mfma_f32_16x16x32_bf16 v[80:83], v[4:7], v[76:79], v[80:83]
	v_mfma_f32_16x16x32_bf16 v[84:87], v[8:11], v[76:79], v[84:87]
	v_mfma_f32_16x16x32_bf16 v[88:91], v[12:15], v[76:79], v[88:91]
	v_mfma_f32_16x16x32_bf16 v[92:95], v[16:19], v[76:79], v[92:95]
	ds_bpermute_b32 v148, v240, v246
	s_waitcnt lgkmcnt(0)
	v_add_f32_e32 v246, v246, v148
	v_rcp_f32_e32 v149, v246
	v_log_f32_e32 v150, v246
	s_nop 0
	v_add_f32_e32 v151, v245, v150
	v_mul_f32_e32 v151, 0x3f317218, v151
	v_max_f32_e32 v152, v120, v151
	v_sub_f32_e32 v153, v120, v152
	v_sub_f32_e32 v154, v151, v152
	v_mul_f32_e32 v153, 0x3fb8aa3b, v153
	v_mul_f32_e32 v154, 0x3fb8aa3b, v154
	v_exp_f32_e32 v153, v153
	v_exp_f32_e32 v154, v154
	s_nop 0
	v_add_f32_e32 v155, v153, v154
	v_rcp_f32_e32 v146, v155
	v_log_f32_e32 v150, v155
	s_nop 0
	v_mul_f32_e32 v154, v154, v146
	v_mul_f32_e32 v146, v153, v146
	v_mul_f32_e32 v147, v149, v154
	v_mul_f32_e32 v150, 0x3f317218, v150
	v_add_f32_e32 v140, v152, v150
	v_mul_f32_e32 v80, v80, v147
	v_mul_f32_e32 v81, v81, v147
	v_mul_f32_e32 v82, v82, v147
	v_mul_f32_e32 v83, v83, v147
	v_mul_f32_e32 v84, v84, v147
	v_mul_f32_e32 v85, v85, v147
	v_mul_f32_e32 v86, v86, v147
	v_mul_f32_e32 v87, v87, v147
	v_mul_f32_e32 v88, v88, v147
	v_mul_f32_e32 v89, v89, v147
	v_mul_f32_e32 v90, v90, v147
	v_mul_f32_e32 v91, v91, v147
	v_mul_f32_e32 v92, v92, v147
	v_mul_f32_e32 v93, v93, v147
	v_mul_f32_e32 v94, v94, v147
	v_mul_f32_e32 v95, v95, v147
	v_lshlrev_b32_e32 v141, 16, v112
	v_and_b32_e32 v142, 0xffff0000, v112
	v_lshlrev_b32_e32 v143, 16, v113
	v_and_b32_e32 v144, 0xffff0000, v113
	v_fmac_f32_e32 v80, v146, v141
	v_fmac_f32_e32 v81, v146, v142
	v_fmac_f32_e32 v82, v146, v143
	v_fmac_f32_e32 v83, v146, v144
	v_cvt_pk_bf16_f32 v132, v80, v81
	v_cvt_pk_bf16_f32 v133, v82, v83
	v_lshlrev_b32_e32 v141, 16, v114
	v_and_b32_e32 v142, 0xffff0000, v114
	v_lshlrev_b32_e32 v143, 16, v115
	v_and_b32_e32 v144, 0xffff0000, v115
	v_fmac_f32_e32 v84, v146, v141
	v_fmac_f32_e32 v85, v146, v142
	v_fmac_f32_e32 v86, v146, v143
	v_fmac_f32_e32 v87, v146, v144
	v_cvt_pk_bf16_f32 v134, v84, v85
	v_cvt_pk_bf16_f32 v135, v86, v87
	v_lshlrev_b32_e32 v141, 16, v116
	v_and_b32_e32 v142, 0xffff0000, v116
	v_lshlrev_b32_e32 v143, 16, v117
	v_and_b32_e32 v144, 0xffff0000, v117
	v_fmac_f32_e32 v88, v146, v141
	v_fmac_f32_e32 v89, v146, v142
	v_fmac_f32_e32 v90, v146, v143
	v_fmac_f32_e32 v91, v146, v144
	v_cvt_pk_bf16_f32 v136, v88, v89
	v_cvt_pk_bf16_f32 v137, v90, v91
	v_lshlrev_b32_e32 v141, 16, v118
	v_and_b32_e32 v142, 0xffff0000, v118
	v_lshlrev_b32_e32 v143, 16, v119
	v_and_b32_e32 v144, 0xffff0000, v119
	v_fmac_f32_e32 v92, v146, v141
	v_fmac_f32_e32 v93, v146, v142
	v_fmac_f32_e32 v94, v146, v143
	v_fmac_f32_e32 v95, v146, v144
	v_cvt_pk_bf16_f32 v138, v92, v93
	v_cvt_pk_bf16_f32 v139, v94, v95
	s_mov_b64 s[26:27], s[86:87]
	s_mov_b64 s[28:29], s[88:89]
	s_mov_b64 s[86:87], s[12:13]
	s_mov_b64 s[88:89], s[14:15]
	s_mov_b32 s4, s83
	s_mov_b32 s5, s84
	s_waitcnt vmcnt(0)
	s_barrier
	ds_read_b128 v[4:7], v230 offset:32768
	ds_read_b128 v[8:11], v231 offset:32768
	ds_read_b128 v[12:15], v230 offset:34816
	ds_read_b128 v[16:19], v231 offset:34816
	ds_read_b128 v[20:23], v230 offset:36864
	ds_read_b128 v[24:27], v231 offset:36864
	ds_read_b128 v[28:31], v230 offset:38912
	ds_read_b128 v[32:35], v231 offset:38912
	ds_read_b128 v[36:39], v230 offset:40960
	ds_read_b128 v[40:43], v231 offset:40960
	global_store_dwordx2 v237, v[132:133], s[26:27]
	global_store_dwordx2 v237, v[134:135], s[26:27] offset:32
	global_store_dwordx2 v237, v[136:137], s[26:27] offset:64
	global_store_dwordx2 v237, v[138:139], s[26:27] offset:96
	s_mov_b64 s[90:91], exec
	s_mov_b64 exec, 0xffff
	global_store_dword v238, v140, s[28:29]
	s_mov_b64 exec, s[90:91]
	s_cmp_eq_u32 s7, 1
	s_cbranch_scc1 .Lat844_i3_nonext
	s_add_u32 s83, s4, 1
	s_mov_b32 s84, s5
	s_mul_i32 s74, s84, 1024
	s_lshl_b32 s75, s83, 7
	s_add_u32 s74, s74, s75
	s_lshl_b32 s75, s74, 7
	s_add_u32 s16, s60, s75
	s_addc_u32 s17, s61, 0
	s_lshl_b32 s75, s74, 1
	s_add_u32 s24, s64, s75
	s_addc_u32 s25, s65, 0
	s_add_u32 m0, s70, 0x0
	s_nop 0
	global_load_lds_dwordx4 v232, s[16:17]
	s_add_u32 m0, s70, 0x2000
	s_nop 0
	global_load_lds_dwordx4 v233, s[16:17]
	s_add_u32 m0, s70, 0x10000
	s_nop 0
	global_load_lds_dwordx4 v234, s[24:25]
	s_add_u32 m0, s70, 0x12000
	s_nop 0
	global_load_lds_dwordx4 v235, s[24:25]
	s_lshl_b32 s74, s83, 9
	s_add_u32 s74, s74, s84
	s_lshl_b32 s75, s74, 7
	s_add_u32 s10, s30, s75
	s_addc_u32 s11, s31, 0
	s_add_u32 s12, s34, s75
	s_addc_u32 s13, s35, 0
	s_lshl_b32 s75, s74, 2
	s_add_u32 s14, s58, s75
	s_addc_u32 s15, s59, 0
	global_load_dwordx4 v[96:99], v236, s[10:11]
	global_load_dwordx4 v[100:103], v236, s[10:11] offset:64
	global_load_dwordx2 v[112:113], v237, s[12:13]
	global_load_dwordx2 v[114:115], v237, s[12:13] offset:32
	global_load_dwordx2 v[116:117], v237, s[12:13] offset:64
	global_load_dwordx2 v[118:119], v237, s[12:13] offset:96
	global_load_dword v120, v238, s[14:15]

.Lat844_i3_nomask:
	v_max3_f32 v245, v44, v45, v46
	v_max3_f32 v245, v245, v47, v48
	v_max3_f32 v245, v245, v49, v50
	v_max3_f32 v245, v245, v51, v52
	v_max3_f32 v245, v245, v53, v54
	v_max3_f32 v245, v245, v55, v56
	v_max3_f32 v245, v245, v57, v58
	v_max3_f32 v245, v245, v59, v60
	v_max3_f32 v245, v245, v61, v62
	v_max3_f32 v245, v245, v63, v64
	v_max3_f32 v245, v245, v65, v66
	v_max3_f32 v245, v245, v67, v68
	v_max3_f32 v245, v245, v69, v70
	v_max3_f32 v245, v245, v71, v72
	v_max3_f32 v245, v245, v73, v74
	v_max3_f32 v245, v245, v75, v76
	v_max3_f32 v245, v245, v77, v78
	v_max_f32_e32 v245, v245, v79
	ds_bpermute_b32 v148, v239, v245
	s_waitcnt lgkmcnt(0)
	v_max_f32_e32 v245, v245, v148
	ds_bpermute_b32 v148, v240, v245
	s_waitcnt lgkmcnt(0)
	v_max_f32_e32 v245, v245, v148
	v_sub_f32_e32 v44, v44, v245
	v_sub_f32_e32 v45, v45, v245
	v_sub_f32_e32 v46, v46, v245
	v_sub_f32_e32 v47, v47, v245
	v_exp_f32_e32 v44, v44
	v_exp_f32_e32 v45, v45
	v_exp_f32_e32 v46, v46
	v_exp_f32_e32 v47, v47
	v_sub_f32_e32 v48, v48, v245
	v_sub_f32_e32 v49, v49, v245
	v_sub_f32_e32 v50, v50, v245
	v_sub_f32_e32 v51, v51, v245
	v_exp_f32_e32 v48, v48
	v_exp_f32_e32 v49, v49
	v_exp_f32_e32 v50, v50
	v_exp_f32_e32 v51, v51
	v_mov_b32_e32 v149, v44
	v_mov_b32_e32 v150, v45
	v_mov_b32_e32 v151, v46
	v_mov_b32_e32 v152, v47
	v_cvt_pk_bf16_f32 v44, v44, v45
	v_cvt_pk_bf16_f32 v45, v46, v47
	v_sub_f32_e32 v52, v52, v245
	v_sub_f32_e32 v53, v53, v245
	v_sub_f32_e32 v54, v54, v245
	v_sub_f32_e32 v55, v55, v245
	v_exp_f32_e32 v52, v52
	v_exp_f32_e32 v53, v53
	v_exp_f32_e32 v54, v54
	v_exp_f32_e32 v55, v55
	v_add_f32_e32 v149, v149, v48
	v_add_f32_e32 v150, v150, v49
	v_add_f32_e32 v151, v151, v50
	v_add_f32_e32 v152, v152, v51
	v_cvt_pk_bf16_f32 v46, v48, v49
	v_cvt_pk_bf16_f32 v47, v50, v51
	v_sub_f32_e32 v56, v56, v245
	v_sub_f32_e32 v57, v57, v245
	v_sub_f32_e32 v58, v58, v245
	v_sub_f32_e32 v59, v59, v245
	v_exp_f32_e32 v56, v56
	v_exp_f32_e32 v57, v57
	v_exp_f32_e32 v58, v58
	v_exp_f32_e32 v59, v59
	v_add_f32_e32 v149, v149, v52
	v_add_f32_e32 v150, v150, v53
	v_add_f32_e32 v151, v151, v54
	v_add_f32_e32 v152, v152, v55
	v_cvt_pk_bf16_f32 v52, v52, v53
	v_cvt_pk_bf16_f32 v53, v54, v55
	v_sub_f32_e32 v60, v60, v245
	v_sub_f32_e32 v61, v61, v245
	v_sub_f32_e32 v62, v62, v245
	v_sub_f32_e32 v63, v63, v245
	v_exp_f32_e32 v60, v60
	v_exp_f32_e32 v61, v61
	v_exp_f32_e32 v62, v62
	v_exp_f32_e32 v63, v63
	v_add_f32_e32 v149, v149, v56
	v_add_f32_e32 v150, v150, v57
	v_add_f32_e32 v151, v151, v58
	v_add_f32_e32 v152, v152, v59
	v_cvt_pk_bf16_f32 v54, v56, v57
	v_cvt_pk_bf16_f32 v55, v58, v59
	v_sub_f32_e32 v64, v64, v245
	v_sub_f32_e32 v65, v65, v245
	v_sub_f32_e32 v66, v66, v245
	v_sub_f32_e32 v67, v67, v245
	v_exp_f32_e32 v64, v64
	v_exp_f32_e32 v65, v65
	v_exp_f32_e32 v66, v66
	v_exp_f32_e32 v67, v67
	v_add_f32_e32 v149, v149, v60
	v_add_f32_e32 v150, v150, v61
	v_add_f32_e32 v151, v151, v62
	v_add_f32_e32 v152, v152, v63
	v_cvt_pk_bf16_f32 v60, v60, v61
	v_cvt_pk_bf16_f32 v61, v62, v63
	v_sub_f32_e32 v68, v68, v245
	v_sub_f32_e32 v69, v69, v245
	v_sub_f32_e32 v70, v70, v245
	v_sub_f32_e32 v71, v71, v245
	v_exp_f32_e32 v68, v68
	v_exp_f32_e32 v69, v69
	v_exp_f32_e32 v70, v70
	v_exp_f32_e32 v71, v71
	v_add_f32_e32 v149, v149, v64
	v_add_f32_e32 v150, v150, v65
	v_add_f32_e32 v151, v151, v66
	v_add_f32_e32 v152, v152, v67
	v_cvt_pk_bf16_f32 v62, v64, v65
	v_cvt_pk_bf16_f32 v63, v66, v67
	v_sub_f32_e32 v72, v72, v245
	v_sub_f32_e32 v73, v73, v245
	v_sub_f32_e32 v74, v74, v245
	v_sub_f32_e32 v75, v75, v245
	v_exp_f32_e32 v72, v72
	v_exp_f32_e32 v73, v73
	v_exp_f32_e32 v74, v74
	v_exp_f32_e32 v75, v75
	v_add_f32_e32 v149, v149, v68
	v_add_f32_e32 v150, v150, v69
	v_add_f32_e32 v151, v151, v70
	v_add_f32_e32 v152, v152, v71
	v_cvt_pk_bf16_f32 v68, v68, v69
	v_cvt_pk_bf16_f32 v69, v70, v71
	v_sub_f32_e32 v76, v76, v245
	v_sub_f32_e32 v77, v77, v245
	v_sub_f32_e32 v78, v78, v245
	v_sub_f32_e32 v79, v79, v245
	v_exp_f32_e32 v76, v76
	v_exp_f32_e32 v77, v77
	v_exp_f32_e32 v78, v78
	v_exp_f32_e32 v79, v79
	v_add_f32_e32 v149, v149, v72
	v_add_f32_e32 v150, v150, v73
	v_add_f32_e32 v151, v151, v74
	v_add_f32_e32 v152, v152, v75
	v_cvt_pk_bf16_f32 v70, v72, v73
	v_cvt_pk_bf16_f32 v71, v74, v75
	s_nop 0
	v_add_f32_e32 v149, v149, v76
	v_add_f32_e32 v150, v150, v77
	v_add_f32_e32 v151, v151, v78
	v_add_f32_e32 v152, v152, v79
	v_cvt_pk_bf16_f32 v76, v76, v77
	v_cvt_pk_bf16_f32 v77, v78, v79
	v_mov_b32_e32 v78, 0
	v_mov_b32_e32 v79, 0
	v_add_f32_e32 v149, v149, v150
	v_add_f32_e32 v151, v151, v152
	v_add_f32_e32 v246, v149, v151
	s_waitcnt lgkmcnt(0)
	v_mfma_f32_16x16x32_bf16 v[80:83], v[4:7], v[44:47], 0
	v_mfma_f32_16x16x32_bf16 v[84:87], v[8:11], v[44:47], 0
	v_mfma_f32_16x16x32_bf16 v[88:91], v[12:15], v[44:47], 0
	v_mfma_f32_16x16x32_bf16 v[92:95], v[16:19], v[44:47], 0
	ds_read_b64 v[4:5], v225 offset:32768
	ds_read_b64 v[8:9], v225 offset:36864
	ds_read_b64 v[12:13], v225 offset:40960
	ds_read_b64 v[16:17], v225 offset:45056
	ds_read_b64 v[6:7], v226 offset:32768
	ds_read_b64 v[10:11], v226 offset:36864
	ds_read_b64 v[14:15], v226 offset:40960
	ds_read_b64 v[18:19], v226 offset:45056
	v_mfma_f32_16x16x32_bf16 v[80:83], v[20:23], v[52:55], v[80:83]
	v_mfma_f32_16x16x32_bf16 v[84:87], v[24:27], v[52:55], v[84:87]
	v_mfma_f32_16x16x32_bf16 v[88:91], v[28:31], v[52:55], v[88:91]
	v_mfma_f32_16x16x32_bf16 v[92:95], v[32:35], v[52:55], v[92:95]
	ds_read_b64 v[20:21], v227 offset:32768
	ds_read_b64 v[24:25], v227 offset:36864
	ds_read_b64 v[28:29], v227 offset:40960
	ds_read_b64 v[32:33], v227 offset:45056
	ds_read_b64 v[22:23], v228 offset:32768
	ds_read_b64 v[26:27], v228 offset:36864
	ds_read_b64 v[30:31], v228 offset:40960
	ds_read_b64 v[34:35], v228 offset:45056
	ds_bpermute_b32 v148, v239, v246
	s_waitcnt lgkmcnt(9)
	v_mfma_f32_16x16x32_bf16 v[80:83], v[4:7], v[60:63], v[80:83]
	v_mfma_f32_16x16x32_bf16 v[84:87], v[8:11], v[60:63], v[84:87]
	v_mfma_f32_16x16x32_bf16 v[88:91], v[12:15], v[60:63], v[88:91]
	v_mfma_f32_16x16x32_bf16 v[92:95], v[16:19], v[60:63], v[92:95]
	ds_read_b64 v[4:5], v229 offset:32768
	ds_read_b64 v[8:9], v229 offset:36864
	ds_read_b64 v[12:13], v229 offset:40960
	ds_read_b64 v[16:17], v229 offset:45056
	v_mov_b32_e32 v6, 0
	v_mov_b32_e32 v7, 0
	v_mov_b32_e32 v10, 0
	v_mov_b32_e32 v11, 0
	v_mov_b32_e32 v14, 0
	v_mov_b32_e32 v15, 0
	v_mov_b32_e32 v18, 0
	v_mov_b32_e32 v19, 0
	s_waitcnt lgkmcnt(5)
	v_mfma_f32_16x16x32_bf16 v[80:83], v[20:23], v[68:71], v[80:83]
	v_mfma_f32_16x16x32_bf16 v[84:87], v[24:27], v[68:71], v[84:87]
	v_mfma_f32_16x16x32_bf16 v[88:91], v[28:31], v[68:71], v[88:91]
	v_mfma_f32_16x16x32_bf16 v[92:95], v[32:35], v[68:71], v[92:95]
	s_waitcnt lgkmcnt(0)
	v_add_f32_e32 v246, v246, v148
	s_nop 0
	v_mfma_f32_16x16x32_bf16 v[80:83], v[4:7], v[76:79], v[80:83]
	v_mfma_f32_16x16x32_bf16 v[84:87], v[8:11], v[76:79], v[84:87]
	v_mfma_f32_16x16x32_bf16 v[88:91], v[12:15], v[76:79], v[88:91]
	v_mfma_f32_16x16x32_bf16 v[92:95], v[16:19], v[76:79], v[92:95]
	ds_bpermute_b32 v148, v240, v246
	s_waitcnt lgkmcnt(0)
	v_add_f32_e32 v246, v246, v148
	v_rcp_f32_e32 v149, v246
	v_log_f32_e32 v150, v246
	s_nop 0
	v_add_f32_e32 v151, v245, v150
	v_mul_f32_e32 v151, 0x3f317218, v151
	v_max_f32_e32 v152, v121, v151
	v_sub_f32_e32 v153, v121, v152
	v_sub_f32_e32 v154, v151, v152
	v_mul_f32_e32 v153, 0x3fb8aa3b, v153
	v_mul_f32_e32 v154, 0x3fb8aa3b, v154
	v_exp_f32_e32 v153, v153
	v_exp_f32_e32 v154, v154
	s_nop 0
	v_add_f32_e32 v155, v153, v154
	v_rcp_f32_e32 v146, v155
	v_log_f32_e32 v150, v155
	s_nop 0
	v_mul_f32_e32 v154, v154, v146
	v_mul_f32_e32 v146, v153, v146
	v_mul_f32_e32 v147, v149, v154
	v_mul_f32_e32 v150, 0x3f317218, v150
	v_add_f32_e32 v140, v152, v150
	v_mul_f32_e32 v80, v80, v147
	v_mul_f32_e32 v81, v81, v147
	v_mul_f32_e32 v82, v82, v147
	v_mul_f32_e32 v83, v83, v147
	v_mul_f32_e32 v84, v84, v147
	v_mul_f32_e32 v85, v85, v147
	v_mul_f32_e32 v86, v86, v147
	v_mul_f32_e32 v87, v87, v147
	v_mul_f32_e32 v88, v88, v147
	v_mul_f32_e32 v89, v89, v147
	v_mul_f32_e32 v90, v90, v147
	v_mul_f32_e32 v91, v91, v147
	v_mul_f32_e32 v92, v92, v147
	v_mul_f32_e32 v93, v93, v147
	v_mul_f32_e32 v94, v94, v147
	v_mul_f32_e32 v95, v95, v147
	v_lshlrev_b32_e32 v141, 16, v122
	v_and_b32_e32 v142, 0xffff0000, v122
	v_lshlrev_b32_e32 v143, 16, v123
	v_and_b32_e32 v144, 0xffff0000, v123
	v_fmac_f32_e32 v80, v146, v141
	v_fmac_f32_e32 v81, v146, v142
	v_fmac_f32_e32 v82, v146, v143
	v_fmac_f32_e32 v83, v146, v144
	v_cvt_pk_bf16_f32 v132, v80, v81
	v_cvt_pk_bf16_f32 v133, v82, v83
	v_lshlrev_b32_e32 v141, 16, v124
	v_and_b32_e32 v142, 0xffff0000, v124
	v_lshlrev_b32_e32 v143, 16, v125
	v_and_b32_e32 v144, 0xffff0000, v125
	v_fmac_f32_e32 v84, v146, v141
	v_fmac_f32_e32 v85, v146, v142
	v_fmac_f32_e32 v86, v146, v143
	v_fmac_f32_e32 v87, v146, v144
	v_cvt_pk_bf16_f32 v134, v84, v85
	v_cvt_pk_bf16_f32 v135, v86, v87
	v_lshlrev_b32_e32 v141, 16, v126
	v_and_b32_e32 v142, 0xffff0000, v126
	v_lshlrev_b32_e32 v143, 16, v127
	v_and_b32_e32 v144, 0xffff0000, v127
	v_fmac_f32_e32 v88, v146, v141
	v_fmac_f32_e32 v89, v146, v142
	v_fmac_f32_e32 v90, v146, v143
	v_fmac_f32_e32 v91, v146, v144
	v_cvt_pk_bf16_f32 v136, v88, v89
	v_cvt_pk_bf16_f32 v137, v90, v91
	v_lshlrev_b32_e32 v141, 16, v128
	v_and_b32_e32 v142, 0xffff0000, v128
	v_lshlrev_b32_e32 v143, 16, v129
	v_and_b32_e32 v144, 0xffff0000, v129
	v_fmac_f32_e32 v92, v146, v141
	v_fmac_f32_e32 v93, v146, v142
	v_fmac_f32_e32 v94, v146, v143
	v_fmac_f32_e32 v95, v146, v144
	v_cvt_pk_bf16_f32 v138, v92, v93
	v_cvt_pk_bf16_f32 v139, v94, v95
	s_mov_b64 s[26:27], s[86:87]
	s_mov_b64 s[28:29], s[88:89]
	s_mov_b64 s[86:87], s[12:13]
	s_mov_b64 s[88:89], s[14:15]
	s_mov_b32 s4, s83
	s_mov_b32 s5, s84
	s_add_u32 s7, s7, 1
	s_cmp_lt_u32 s7, 2
	s_cbranch_scc1 .Lat844_loop
	s_setprio 0
	global_store_dwordx2 v237, v[132:133], s[26:27]
	global_store_dwordx2 v237, v[134:135], s[26:27] offset:32
	global_store_dwordx2 v237, v[136:137], s[26:27] offset:64
	global_store_dwordx2 v237, v[138:139], s[26:27] offset:96
	s_mov_b64 s[90:91], exec
	s_mov_b64 exec, 0xffff
	global_store_dword v238, v140, s[28:29]
	s_mov_b64 exec, s[90:91]
	s_mov_b32 s67, 0x10000
	s_mov_b32 s68, 0x14000
	v_mov_b32_e32 v183, v239
	v_mov_b32_e32 v184, v240
	s_waitcnt vmcnt(0)
	s_barrier
	s_waitcnt vmcnt(0)
	s_barrier
	s_mov_b64 s[4:5], exec
	v_readlane_b32 s0, v252, 2
	v_readlane_b32 s30, v253, 24
	v_readlane_b32 s1, v252, 3
	v_readlane_b32 s31, v253, 25
	v_readlane_b32 s34, v253, 15
	v_readlane_b32 s36, v252, 27
	v_readlane_b32 s8, v253, 19
	v_readlane_b32 s10, v253, 21
	v_readlane_b32 s38, v252, 29
	v_readlane_b32 s60, v252, 31
	v_readlane_b32 s64, v252, 33
	v_readlane_b32 s70, v252, 35
	v_readlane_b32 s74, v252, 37
	s_and_b64 s[0:1], s[4:5], s[0:1]
	v_readlane_b32 s28, v253, 23
	v_readlane_b32 s35, v253, 16
	v_readlane_b32 s29, v252, 26
	v_readlane_b32 s31, v253, 18
	v_readlane_b32 s37, v252, 28
	v_readlane_b32 s9, v253, 20
	v_readlane_b32 s11, v253, 22
	v_readlane_b32 s39, v252, 30
	v_readlane_b32 s61, v252, 32
	v_readlane_b32 s65, v252, 34
	v_readlane_b32 s71, v252, 36
	v_readlane_b32 s75, v252, 38
	v_readlane_b32 s63, v253, 17
	s_mov_b64 exec, s[0:1]
	s_cbranch_execz .LBB0_916
	v_mov_b32_e32 v0, 0x20000
	ds_read_b64 v[0:1], v0
	s_getreg_b32 s44, hwreg(HW_REG_XCC_ID, 0, 4)
	s_lshl_b32 s44, s44, 7
	s_add_u32 s44, s44, 0xdc03600
	v_mov_b32_e32 v2, s44
	v_mov_b32_e32 v4, 1
	s_waitcnt vmcnt(0) lgkmcnt(0)
	global_atomic_add v5, v2, v4, s[42:43] sc0
	buffer_inv sc1
	s_add_u32 s100, s100, 1
	v_readfirstlane_b32 s46, v0
	v_readfirstlane_b32 s47, v1
	v_mov_b32_e32 v2, 0xdc03e00
	s_nop 3
	s_mul_i32 s48, s46, s100
	s_mul_i32 s49, s47, s100
	s_waitcnt vmcnt(1)
	v_readfirstlane_b32 s50, v5
	s_nop 3
	s_add_u32 s50, s50, 1
	s_cmp_lg_u32 s50, s48
	s_cbranch_scc1 .Lxb7_poll
	buffer_wbl2 sc1
	s_waitcnt vmcnt(0)
	global_atomic_add v2, v4, s[42:43]

.LBB0_880:
	s_mov_b64 s[44:45], exec
	s_lshl_b32 s0, s0, 8
	v_readlane_b32 s2, v252, 0
	v_mbcnt_lo_u32_b32 v1, s44, 0
	v_readlane_b32 s3, v252, 1
	s_add_u32 s6, s2, s0
	v_mbcnt_hi_u32_b32 v1, s45, v1
	s_addc_u32 s7, s3, 0
	v_cmp_eq_u32_e32 vcc, 0, v1
	s_and_saveexec_b64 s[46:47], vcc
	s_cbranch_execz .LBB0_882
	s_bcnt1_i32_b64 s0, s[44:45]
	v_mov_b32_e32 v4, s0
	v_mov_b32_e32 v5, 0x1000
	global_atomic_add v4, v5, v4, s[6:7] offset:1024 sc0
.LBB0_882:
	s_or_b64 exec, exec, s[46:47]
	v_cvt_f32_u32_e32 v5, v2
	s_waitcnt vmcnt(0)
	v_readfirstlane_b32 s0, v4
	v_sub_u32_e32 v4, 0, v2
	v_rcp_iflag_f32_e32 v5, v5
	v_add_u32_e32 v6, s0, v1
	v_mul_f32_e32 v5, 0x4f7ffffe, v5
	v_cvt_u32_f32_e32 v5, v5
	v_mul_lo_u32 v1, v4, v5
	v_mul_hi_u32 v1, v5, v1
	v_add_u32_e32 v1, v5, v1
	v_mul_hi_u32 v1, v6, v1
	v_mul_lo_u32 v4, v1, v2
	v_sub_u32_e32 v4, v6, v4
	v_add_u32_e32 v5, 1, v1
	v_cmp_ge_u32_e32 vcc, v4, v2
	s_nop 1
	v_cndmask_b32_e32 v1, v1, v5, vcc
	v_sub_u32_e32 v5, v4, v2
	v_cndmask_b32_e32 v4, v4, v5, vcc
	v_add_u32_e32 v5, 1, v1
	v_cmp_ge_u32_e32 vcc, v4, v2
	v_add_u32_e32 v4, 1, v6
	s_nop 0
	v_cndmask_b32_e32 v1, v1, v5, vcc
	v_mul_lo_u32 v5, v2, v1
	v_add_u32_e32 v2, v5, v2
	v_cmp_ne_u32_e32 vcc, v4, v2
	s_and_saveexec_b64 s[0:1], vcc
	s_xor_b64 s[44:45], exec, s[0:1]
	s_cbranch_execz .LBB0_896
	s_waitcnt lgkmcnt(0)
	global_load_dword v0, v182, s[6:7] offset:1024 sc1
	s_add_u32 s48, s6, 0x2400
	s_addc_u32 s49, s7, 0
	s_waitcnt vmcnt(0)
	v_cmp_eq_u32_e32 vcc, v0, v1
	s_and_saveexec_b64 s[46:47], vcc
	s_cbranch_execz .LBB0_895
	s_mov_b32 s0, 1
	s_mov_b64 s[50:51], 0
	s_branch .LBB0_886

.LBB0_936:
	v_mov_b32_e32 v0, v170
	v_readlane_b32 s6, v254, 7
	v_readfirstlane_b32 s0, v0
	v_and_b32_e32 v4, 63, v0
	s_ashr_i32 s0, s0, 6
	v_mov_b32_e32 v5, v4
	s_lshl_b32 s1, s0, 3
	v_ashrrev_i32_e32 v6, 3, v5
	v_add_u32_e32 v0, s1, v6
	v_lshrrev_b32_e32 v1, 1, v0
	v_xor_b32_e32 v2, v1, v5
	v_ashrrev_i32_e32 v1, 31, v0
	v_lshlrev_b64 v[0:1], 7, v[0:1]
	v_readlane_b32 s7, v254, 8
	v_lshlrev_b32_e32 v2, 4, v2
	v_and_b32_e32 v2, 0x70, v2
	v_lshl_add_u64 v[0:1], s[6:7], 0, v[0:1]
	s_lshl_b32 s2, s0, 10
	s_add_i32 s3, s0, 8
	v_lshl_add_u64 v[0:1], v[0:1], 0, v[2:3]
	s_add_i32 m0, s82, s2
	s_lshl_b32 s4, s3, 3
	global_load_lds_dwordx4 v[0:1], off
	v_add_u32_e32 v0, s4, v6
	v_lshrrev_b32_e32 v1, 1, v0
	v_xor_b32_e32 v2, v1, v5
	v_ashrrev_i32_e32 v1, 31, v0
	v_lshlrev_b64 v[0:1], 7, v[0:1]
	v_lshlrev_b32_e32 v2, 4, v2
	v_lshl_add_u64 v[0:1], s[6:7], 0, v[0:1]
	v_and_b32_e32 v2, 0x70, v2
	s_lshl_b32 s5, s3, 10
	v_lshl_add_u64 v[0:1], v[0:1], 0, v[2:3]
	s_add_i32 m0, s82, s5
	v_ashrrev_i32_e32 v6, 4, v5
	s_lshl_b32 s0, s0, 2
	global_load_lds_dwordx4 v[0:1], off
	v_add_u32_e32 v0, s0, v6
	v_xor_b32_e32 v2, v0, v5
	v_ashrrev_i32_e32 v1, 31, v0
	v_readlane_b32 s12, v254, 13
	v_lshlrev_b64 v[0:1], 15, v[0:1]
	v_readlane_b32 s13, v254, 14
	v_lshlrev_b32_e32 v2, 4, v2
	v_and_b32_e32 v2, 0xf0, v2
	v_lshl_add_u64 v[0:1], s[12:13], 0, v[0:1]
	v_lshl_add_u64 v[0:1], v[0:1], 0, v[2:3]
	s_add_i32 m0, s62, s2
	s_lshl_b32 s3, s3, 2
	global_load_lds_dwordx4 v[0:1], off
	v_add_u32_e32 v0, s3, v6
	v_xor_b32_e32 v2, v0, v5
	v_ashrrev_i32_e32 v1, 31, v0
	v_lshlrev_b64 v[0:1], 15, v[0:1]
	v_lshlrev_b32_e32 v2, 4, v2
	v_lshl_add_u64 v[0:1], s[12:13], 0, v[0:1]
	v_and_b32_e32 v2, 0xf0, v2
	v_lshl_add_u64 v[0:1], v[0:1], 0, v[2:3]
	s_add_i32 m0, s62, s5
	s_nop 0
	global_load_lds_dwordx4 v[0:1], off
	s_nop 0
	v_ashrrev_i32_e32 v5, 3, v4
	v_add_u32_e32 v0, s1, v5
	v_lshrrev_b32_e32 v1, 1, v0
	v_xor_b32_e32 v2, v1, v4
	v_ashrrev_i32_e32 v1, 31, v0
	v_lshlrev_b64 v[0:1], 7, v[0:1]
	v_lshlrev_b32_e32 v2, 4, v2
	v_lshl_add_u64 v[0:1], s[6:7], 0, v[0:1]
	v_and_b32_e32 v2, 0x70, v2
	s_add_i32 s1, s2, 0
	v_lshl_add_u64 v[0:1], v[0:1], 0, v[2:3]
	s_mov_b32 m0, s1
	s_add_i32 s2, s5, 0
	global_load_lds_dwordx4 v[0:1], off
	v_add_u32_e32 v0, s4, v5
	v_lshrrev_b32_e32 v1, 1, v0
	v_xor_b32_e32 v2, v1, v4
	v_ashrrev_i32_e32 v1, 31, v0
	v_lshlrev_b64 v[0:1], 7, v[0:1]
	v_lshlrev_b32_e32 v2, 4, v2
	v_lshl_add_u64 v[0:1], s[6:7], 0, v[0:1]
	v_and_b32_e32 v2, 0x70, v2
	v_lshl_add_u64 v[0:1], v[0:1], 0, v[2:3]
	s_mov_b32 m0, s2
	v_ashrrev_i32_e32 v5, 4, v4
	global_load_lds_dwordx4 v[0:1], off
	v_add_u32_e32 v0, s0, v5
	v_xor_b32_e32 v2, v0, v4
	v_ashrrev_i32_e32 v1, 31, v0
	v_lshlrev_b64 v[0:1], 15, v[0:1]
	v_lshlrev_b32_e32 v2, 4, v2
	v_lshl_add_u64 v[0:1], s[12:13], 0, v[0:1]
	v_and_b32_e32 v2, 0xf0, v2
	v_lshl_add_u64 v[0:1], v[0:1], 0, v[2:3]
	s_add_i32 m0, s1, 0x4000
	s_nop 0
	global_load_lds_dwordx4 v[0:1], off
	v_add_u32_e32 v0, s3, v5
	v_xor_b32_e32 v2, v0, v4
	v_ashrrev_i32_e32 v1, 31, v0
	v_lshlrev_b64 v[0:1], 15, v[0:1]
	v_lshlrev_b32_e32 v2, 4, v2
	v_lshl_add_u64 v[0:1], s[12:13], 0, v[0:1]
	v_and_b32_e32 v2, 0xf0, v2
	v_lshl_add_u64 v[0:1], v[0:1], 0, v[2:3]
	s_add_i32 m0, s2, 0x4000
	s_nop 0
	global_load_lds_dwordx4 v[0:1], off
	s_waitcnt vmcnt(0)
	s_waitcnt vmcnt(0) lgkmcnt(0)
	s_barrier
	s_mov_b64 s[4:5], exec
	v_readlane_b32 s0, v252, 2
	v_readlane_b32 s1, v252, 3
	s_and_b64 s[0:1], s[4:5], s[0:1]
	s_mov_b64 exec, s[0:1]
	s_cbranch_execz .LBB0_988
	v_mov_b32_e32 v0, 0x20000
	ds_read_b64 v[0:1], v0
	s_getreg_b32 s44, hwreg(HW_REG_XCC_ID, 0, 4)
	s_lshl_b32 s44, s44, 7
	s_add_u32 s44, s44, 0xdc03600
	v_mov_b32_e32 v2, s44
	v_mov_b32_e32 v4, 1
	s_waitcnt vmcnt(0) lgkmcnt(0)
	global_atomic_add v5, v2, v4, s[42:43] sc0
	buffer_inv sc1
	s_add_u32 s100, s100, 1
	v_readfirstlane_b32 s46, v0
	v_readfirstlane_b32 s47, v1
	v_mov_b32_e32 v2, 0xdc03e00
	s_nop 3
	s_mul_i32 s48, s46, s100
	s_mul_i32 s49, s47, s100
	s_waitcnt vmcnt(1)
	v_readfirstlane_b32 s50, v5
	s_nop 3
	s_add_u32 s50, s50, 1
	s_cmp_lg_u32 s50, s48
	s_cbranch_scc1 .Lxb8_poll
	buffer_wbl2 sc1
	s_waitcnt vmcnt(0)
	global_atomic_add v2, v4, s[42:43]

.LBB0_952:
	s_mov_b64 s[44:45], exec
	s_lshl_b32 s0, s0, 8
	v_readlane_b32 s2, v252, 0
	v_mbcnt_lo_u32_b32 v1, s44, 0
	v_readlane_b32 s3, v252, 1
	s_add_u32 s6, s2, s0
	v_mbcnt_hi_u32_b32 v1, s45, v1
	s_addc_u32 s7, s3, 0
	v_cmp_eq_u32_e32 vcc, 0, v1
	s_and_saveexec_b64 s[46:47], vcc
	s_cbranch_execz .LBB0_954
	s_bcnt1_i32_b64 s0, s[44:45]
	v_mov_b32_e32 v4, s0
	v_mov_b32_e32 v5, 0x1000
	global_atomic_add v4, v5, v4, s[6:7] offset:1024 sc0
.LBB0_954:
	s_or_b64 exec, exec, s[46:47]
	v_cvt_f32_u32_e32 v5, v2
	s_waitcnt vmcnt(0)
	v_readfirstlane_b32 s0, v4
	v_sub_u32_e32 v4, 0, v2
	v_rcp_iflag_f32_e32 v5, v5
	v_add_u32_e32 v6, s0, v1
	v_mul_f32_e32 v5, 0x4f7ffffe, v5
	v_cvt_u32_f32_e32 v5, v5
	v_mul_lo_u32 v1, v4, v5
	v_mul_hi_u32 v1, v5, v1
	v_add_u32_e32 v1, v5, v1
	v_mul_hi_u32 v1, v6, v1
	v_mul_lo_u32 v4, v1, v2
	v_sub_u32_e32 v4, v6, v4
	v_add_u32_e32 v5, 1, v1
	v_cmp_ge_u32_e32 vcc, v4, v2
	s_nop 1
	v_cndmask_b32_e32 v1, v1, v5, vcc
	v_sub_u32_e32 v5, v4, v2
	v_cndmask_b32_e32 v4, v4, v5, vcc
	v_add_u32_e32 v5, 1, v1
	v_cmp_ge_u32_e32 vcc, v4, v2
	v_add_u32_e32 v4, 1, v6
	s_nop 0
	v_cndmask_b32_e32 v1, v1, v5, vcc
	v_mul_lo_u32 v5, v2, v1
	v_add_u32_e32 v2, v5, v2
	v_cmp_ne_u32_e32 vcc, v4, v2
	s_and_saveexec_b64 s[0:1], vcc
	s_xor_b64 s[44:45], exec, s[0:1]
	s_cbranch_execz .LBB0_968
	s_waitcnt lgkmcnt(0)
	global_load_dword v0, v182, s[6:7] offset:1024 sc1
	s_add_u32 s48, s6, 0x2400
	s_addc_u32 s49, s7, 0
	s_waitcnt vmcnt(0)
	v_cmp_eq_u32_e32 vcc, v0, v1
	s_and_saveexec_b64 s[46:47], vcc
	s_cbranch_execz .LBB0_967
	s_mov_b32 s0, 1
	s_mov_b64 s[50:51], 0
	s_branch .LBB0_958

.LBB0_991:
	s_waitcnt vmcnt(0) lgkmcnt(0)
	s_mov_b32 s79, 0x3e38aa3b
	s_mov_b32 s77, 0xc000
	s_mov_b32 s78, 0xffffc000
	v_readlane_b32 s1, v253, 23
	v_readfirstlane_b32 s0, v170
	s_nop 3
	s_lshr_b32 s0, s0, 6
	s_and_b32 s74, s1, 7
	s_lshl_b32 s74, s74, 5
	s_lshr_b32 s75, s1, 3
	s_add_u32 s74, s74, s75
	s_lshl_b32 s74, s74, 3
	s_and_b32 s4, s74, 1
	s_lshr_b32 s75, s74, 1
	s_and_b32 s5, s75, 15
	s_lshr_b32 s75, s75, 4
	s_and_b32 s3, s75, 3
	s_lshr_b32 s2, s75, 2
	s_sub_u32 s6, 8, s0
	s_lshl_b32 s70, s0, 10
	s_lshl_b32 s74, s2, 21
	s_lshl_b32 s75, s3, 19
	s_add_u32 s74, s74, s75
	s_add_u32 s34, s40, s74
	s_addc_u32 s35, s41, 0
	s_add_u32 s30, s34, 0x2000000
	s_addc_u32 s31, s35, 0
	s_lshl_b32 s74, s2, 16
	s_lshl_b32 s75, s3, 14
	s_add_u32 s74, s74, s75
	s_add_u32 s74, s74, 0xc000000
	s_add_u32 s58, s42, s74
	s_addc_u32 s59, s43, 0
	s_add_u32 s74, s2, 32
	s_lshl_b32 s74, s74, 2
	s_add_u32 s74, s74, s3
	s_lshl_b32 s74, s74, 19
	s_add_u32 s60, s42, s74
	s_addc_u32 s61, s43, 0
	s_lshl_b32 s74, s2, 6
	s_add_u32 s74, s74, 2048
	s_lshl_b32 s74, s74, 15
	s_lshl_b32 s75, s3, 13
	s_add_u32 s74, s74, s75
	s_add_u32 s74, s74, 0x6000000
	s_add_u32 s64, s42, s74
	s_addc_u32 s65, s43, 0
	v_and_b32_e32 v141, 63, v170
	v_and_b32_e32 v241, 15, v141
	v_lshrrev_b32_e32 v242, 4, v141
	v_mov_b32_e32 v244, 0xf149f2ca
	v_mov_b32_e32 v248, 0
	v_mov_b32_e32 v249, 0
	v_lshrrev_b32_e32 v142, 1, v241
	v_xor_b32_e32 v142, v142, v242
	v_lshlrev_b32_e32 v142, 4, v142
	v_lshl_add_u32 v142, v241, 7, v142
	s_lshl_b32 s74, s0, 11
	v_add_u32_e32 v230, s74, v142
	v_xor_b32_e32 v231, 64, v230
	v_lshrrev_b32_e32 v142, 1, v242
	v_xor_b32_e32 v243, v142, v241
	v_and_b32_e32 v142, 1, v242
	v_lshlrev_b32_e32 v142, 3, v142
	v_lshl_add_u32 v142, v241, 8, v142
	v_add_u32_e32 v142, 0x10000, v142
	s_add_u32 s74, s0, 0
	s_and_b32 s75, s74, 7
	s_lshl_b32 s75, s75, 1
	s_lshr_b32 s74, s74, 3
	s_lshl_b32 s74, s74, 14
	v_xor_b32_e32 v143, s75, v243
	v_lshl_add_u32 v143, v143, 4, v142
	v_add_u32_e32 v221, s74, v143
	s_add_u32 s74, s0, 1
	s_and_b32 s75, s74, 7
	s_lshl_b32 s75, s75, 1
	s_lshr_b32 s74, s74, 3
	s_lshl_b32 s74, s74, 14
	v_xor_b32_e32 v143, s75, v243
	v_lshl_add_u32 v143, v143, 4, v142
	v_add_u32_e32 v222, s74, v143
	s_add_u32 s74, s0, 2
	s_and_b32 s75, s74, 7
	s_lshl_b32 s75, s75, 1
	s_lshr_b32 s74, s74, 3
	s_lshl_b32 s74, s74, 14
	v_xor_b32_e32 v143, s75, v243
	v_lshl_add_u32 v143, v143, 4, v142
	v_add_u32_e32 v223, s74, v143
	s_add_u32 s74, s0, 3
	s_and_b32 s75, s74, 7
	s_lshl_b32 s75, s75, 1
	s_lshr_b32 s74, s74, 3
	s_lshl_b32 s74, s74, 14
	v_xor_b32_e32 v143, s75, v243
	v_lshl_add_u32 v143, v143, 4, v142
	v_add_u32_e32 v224, s74, v143
	s_add_u32 s74, s0, 4
	s_and_b32 s75, s74, 7
	s_lshl_b32 s75, s75, 1
	s_lshr_b32 s74, s74, 3
	s_lshl_b32 s74, s74, 14
	v_xor_b32_e32 v143, s75, v243
	v_lshl_add_u32 v143, v143, 4, v142
	v_add_u32_e32 v225, s74, v143
	s_add_u32 s74, s0, 5
	s_and_b32 s75, s74, 7
	s_lshl_b32 s75, s75, 1
	s_lshr_b32 s74, s74, 3
	s_lshl_b32 s74, s74, 14
	v_xor_b32_e32 v143, s75, v243
	v_lshl_add_u32 v143, v143, 4, v142
	v_add_u32_e32 v226, s74, v143
	s_add_u32 s74, s0, 6
	s_and_b32 s75, s74, 7
	s_lshl_b32 s75, s75, 1
	s_lshr_b32 s74, s74, 3
	s_lshl_b32 s74, s74, 14
	v_xor_b32_e32 v143, s75, v243
	v_lshl_add_u32 v143, v143, 4, v142
	v_add_u32_e32 v227, s74, v143
	s_add_u32 s74, s0, 7
	s_and_b32 s75, s74, 7
	s_lshl_b32 s75, s75, 1
	s_lshr_b32 s74, s74, 3
	s_lshl_b32 s74, s74, 14
	v_xor_b32_e32 v143, s75, v243
	v_lshl_add_u32 v143, v143, 4, v142
	v_add_u32_e32 v228, s74, v143
	s_add_u32 s74, s0, 8
	s_and_b32 s75, s74, 7
	s_lshl_b32 s75, s75, 1
	s_lshr_b32 s74, s74, 3
	s_lshl_b32 s74, s74, 14
	v_xor_b32_e32 v143, s75, v243
	v_lshl_add_u32 v143, v143, 4, v142
	v_add_u32_e32 v229, s74, v143
	s_and_b32 s74, s0, 1
	s_lshl_b32 s74, s74, 2
	v_add_u32_e32 v142, s74, v242
	v_and_b32_e32 v143, 7, v141
	v_xor_b32_e32 v142, v142, v143
	v_lshlrev_b32_e32 v142, 4, v142
	v_lshrrev_b32_e32 v143, 3, v141
	s_lshl_b32 s74, s0, 3
	v_add_u32_e32 v143, s74, v143
	v_lshl_add_u32 v232, v143, 7, v142
	v_add_u32_e32 v233, 0x2000, v232
	s_and_b32 s74, s0, 3
	s_lshl_b32 s74, s74, 2
	v_add_u32_e32 v142, s74, v242
	v_xor_b32_e32 v142, v142, v241
	v_lshlrev_b32_e32 v142, 4, v142
	s_lshl_b32 s74, s0, 2
	v_add_u32_e32 v143, s74, v242
	v_lshl_add_u32 v234, v143, 15, v142
	v_add_u32_e32 v235, 0x100000, v234
	s_lshl_b32 s74, s0, 4
	v_add_u32_e32 v142, s74, v241
	v_lshlrev_b32_e32 v142, 4, v142
	v_lshlrev_b32_e32 v238, 2, v142
	v_lshlrev_b32_e32 v142, 7, v142
	v_lshl_add_u32 v236, v242, 4, v142
	v_lshl_add_u32 v237, v242, 3, v142
	v_xor_b32_e32 v142, 16, v141
	v_lshlrev_b32_e32 v239, 2, v142
	v_xor_b32_e32 v142, 32, v141
	v_lshlrev_b32_e32 v240, 2, v142
	s_add_u32 s74, s2, 33
	v_cvt_f32_u32_e32 v142, s74
	v_mul_f32_e32 v142, 0xc1000000, v142
	v_mul_f32_e32 v142, 0x3caaaaab, v142
	v_exp_f32_e32 v142, v142
	v_lshlrev_b32_e32 v144, 2, v242
	v_sub_u32_e32 v145, v241, v144
	v_mul_f32_e32 v142, 0x41800000, v142
	v_add_u32_e32 v145, 0x80, v145
	v_mul_f32_e32 v142, 0x3fb8aa3b, v142
	v_cvt_f32_i32_e32 v145, v145
	s_nop 0
	v_mul_f32_e64 v143, -v142, v145
	v_fmamk_f32 v185, v142, 0x0, v143
	v_fmamk_f32 v186, v142, 0x3f800000, v143
	v_fmamk_f32 v187, v142, 0x40000000, v143
	v_fmamk_f32 v188, v142, 0x40400000, v143
	v_fmamk_f32 v189, v142, 0x41800000, v143
	v_fmamk_f32 v190, v142, 0x41880000, v143
	v_fmamk_f32 v191, v142, 0x41900000, v143
	v_fmamk_f32 v192, v142, 0x41980000, v143
	v_fmamk_f32 v193, v142, 0x42000000, v143
	v_fmamk_f32 v194, v142, 0x42040000, v143
	v_fmamk_f32 v195, v142, 0x42080000, v143
	v_fmamk_f32 v196, v142, 0x420c0000, v143
	v_fmamk_f32 v197, v142, 0x42400000, v143
	v_fmamk_f32 v198, v142, 0x42440000, v143
	v_fmamk_f32 v199, v142, 0x42480000, v143
	v_fmamk_f32 v200, v142, 0x424c0000, v143
	v_fmamk_f32 v201, v142, 0x42800000, v143
	v_fmamk_f32 v202, v142, 0x42820000, v143
	v_fmamk_f32 v203, v142, 0x42840000, v143
	v_fmamk_f32 v204, v142, 0x42860000, v143
	v_fmamk_f32 v205, v142, 0x42a00000, v143
	v_fmamk_f32 v206, v142, 0x42a20000, v143
	v_fmamk_f32 v207, v142, 0x42a40000, v143
	v_fmamk_f32 v208, v142, 0x42a60000, v143
	v_fmamk_f32 v209, v142, 0x42c00000, v143
	v_fmamk_f32 v210, v142, 0x42c20000, v143
	v_fmamk_f32 v211, v142, 0x42c40000, v143
	v_fmamk_f32 v212, v142, 0x42c60000, v143
	v_fmamk_f32 v213, v142, 0x42e00000, v143
	v_fmamk_f32 v214, v142, 0x42e20000, v143
	v_fmamk_f32 v215, v142, 0x42e40000, v143
	v_fmamk_f32 v216, v142, 0x42e60000, v143
	v_fmamk_f32 v217, v142, 0x43000000, v143
	v_fmamk_f32 v218, v142, 0x43010000, v143
	v_fmamk_f32 v219, v142, 0x43020000, v143
	v_fmamk_f32 v220, v142, 0x43030000, v143
	v_add_u32_e32 v145, 0, v144
	v_cmp_lt_u32_e32 vcc, v145, v241
	s_nop 1
	v_cndmask_b32_e32 v185, v185, v244, vcc
	v_cmp_gt_u32_e32 vcc, v145, v241
	s_nop 1
	v_cndmask_b32_e32 v217, v217, v244, vcc
	v_add_u32_e32 v145, 1, v144
	v_cmp_lt_u32_e32 vcc, v145, v241
	s_nop 1
	v_cndmask_b32_e32 v186, v186, v244, vcc
	v_cmp_gt_u32_e32 vcc, v145, v241
	s_nop 1
	v_cndmask_b32_e32 v218, v218, v244, vcc
	v_add_u32_e32 v145, 2, v144
	v_cmp_lt_u32_e32 vcc, v145, v241
	s_nop 1
	v_cndmask_b32_e32 v187, v187, v244, vcc
	v_cmp_gt_u32_e32 vcc, v145, v241
	s_nop 1
	v_cndmask_b32_e32 v219, v219, v244, vcc
	v_add_u32_e32 v145, 3, v144
	v_cmp_lt_u32_e32 vcc, v145, v241
	s_nop 1
	v_cndmask_b32_e32 v188, v188, v244, vcc
	v_cmp_gt_u32_e32 vcc, v145, v241
	s_nop 1
	v_cndmask_b32_e32 v220, v220, v244, vcc
	s_sub_u32 s76, s4, 1
	s_max_i32 s76, s76, 0
	s_mul_i32 s74, s5, 256
	s_lshl_b32 s75, s76, 7
	s_add_u32 s74, s74, s75
	s_lshl_b32 s75, s74, 7
	s_add_u32 s16, s60, s75
	s_addc_u32 s17, s61, 0
	s_lshl_b32 s75, s74, 1
	s_add_u32 s24, s64, s75
	s_addc_u32 s25, s65, 0
	s_add_u32 m0, s70, 0xc000
	s_nop 0
	global_load_lds_dwordx4 v232, s[16:17]
	s_add_u32 m0, s70, 0xe000
	s_nop 0
	global_load_lds_dwordx4 v233, s[16:17]
	s_add_u32 m0, s70, 0x1c000
	s_nop 0
	global_load_lds_dwordx4 v234, s[24:25]
	s_add_u32 m0, s70, 0x1e000
	s_nop 0
	global_load_lds_dwordx4 v235, s[24:25]
	s_mul_i32 s74, s5, 256
	s_lshl_b32 s75, s4, 7
	s_add_u32 s74, s74, s75
	s_lshl_b32 s75, s74, 7
	s_add_u32 s16, s60, s75
	s_addc_u32 s17, s61, 0
	s_lshl_b32 s75, s74, 1
	s_add_u32 s24, s64, s75
	s_addc_u32 s25, s65, 0
	s_add_u32 m0, s70, 0x0
	s_nop 0
	global_load_lds_dwordx4 v232, s[16:17]
	s_add_u32 m0, s70, 0x2000
	s_nop 0
	global_load_lds_dwordx4 v233, s[16:17]
	s_add_u32 m0, s70, 0x10000
	s_nop 0
	global_load_lds_dwordx4 v234, s[24:25]
	s_add_u32 m0, s70, 0x12000
	s_nop 0
	global_load_lds_dwordx4 v235, s[24:25]
	s_lshl_b32 s74, s4, 11
	s_add_u32 s74, s74, s5
	s_lshl_b32 s75, s74, 7
	s_add_u32 s10, s30, s75
	s_addc_u32 s11, s31, 0
	s_add_u32 s86, s34, s75
	s_addc_u32 s87, s35, 0
	s_lshl_b32 s75, s74, 2
	s_add_u32 s88, s58, s75
	s_addc_u32 s89, s59, 0
	global_load_dwordx4 v[96:99], v236, s[10:11]
	global_load_dwordx4 v[100:103], v236, s[10:11] offset:64
	global_load_dwordx2 v[112:113], v237, s[86:87]
	global_load_dwordx2 v[114:115], v237, s[86:87] offset:32
	global_load_dwordx2 v[116:117], v237, s[86:87] offset:64
	global_load_dwordx2 v[118:119], v237, s[86:87] offset:96
	global_load_dword v120, v238, s[88:89]
	s_mov_b32 s7, 0

.Lat991_i0_nopend:
	s_add_u32 s84, s5, s4
	s_xor_b32 s83, s4, 1
	s_mul_i32 s74, s84, 256
	s_lshl_b32 s75, s83, 7
	s_add_u32 s74, s74, s75
	s_lshl_b32 s75, s74, 7
	s_add_u32 s16, s60, s75
	s_addc_u32 s17, s61, 0
	s_lshl_b32 s75, s74, 1
	s_add_u32 s24, s64, s75
	s_addc_u32 s25, s65, 0
	s_add_u32 m0, s70, 0x4000
	s_nop 0
	global_load_lds_dwordx4 v232, s[16:17]
	s_add_u32 m0, s70, 0x6000
	s_nop 0
	global_load_lds_dwordx4 v233, s[16:17]
	s_add_u32 m0, s70, 0x14000
	s_nop 0
	global_load_lds_dwordx4 v234, s[24:25]
	s_add_u32 m0, s70, 0x16000
	s_nop 0
	global_load_lds_dwordx4 v235, s[24:25]
	s_lshl_b32 s74, s83, 11
	s_add_u32 s74, s74, s84
	s_lshl_b32 s75, s74, 7
	s_add_u32 s10, s30, s75
	s_addc_u32 s11, s31, 0
	s_add_u32 s12, s34, s75
	s_addc_u32 s13, s35, 0
	s_lshl_b32 s75, s74, 2
	s_add_u32 s14, s58, s75
	s_addc_u32 s15, s59, 0
	global_load_dwordx4 v[104:107], v236, s[10:11]
	global_load_dwordx4 v[108:111], v236, s[10:11] offset:64
	global_load_dwordx2 v[122:123], v237, s[12:13]
	global_load_dwordx2 v[124:125], v237, s[12:13] offset:32
	global_load_dwordx2 v[126:127], v237, s[12:13] offset:64
	global_load_dwordx2 v[128:129], v237, s[12:13] offset:96
	global_load_dword v121, v238, s[14:15]
	s_waitcnt lgkmcnt(0)
	v_mfma_f32_16x16x32_bf16 v[44:47], v[4:7], v[96:99], 0
	v_mfma_f32_16x16x32_bf16 v[48:51], v[12:15], v[96:99], 0
	v_mfma_f32_16x16x32_bf16 v[52:55], v[20:23], v[96:99], 0
	v_mfma_f32_16x16x32_bf16 v[56:59], v[28:31], v[96:99], 0
	v_mfma_f32_16x16x32_bf16 v[60:63], v[36:39], v[96:99], 0
	v_mfma_f32_16x16x32_bf16 v[44:47], v[8:11], v[100:103], v[44:47]
	v_mfma_f32_16x16x32_bf16 v[48:51], v[16:19], v[100:103], v[48:51]
	v_mfma_f32_16x16x32_bf16 v[52:55], v[24:27], v[100:103], v[52:55]
	v_mfma_f32_16x16x32_bf16 v[56:59], v[32:35], v[100:103], v[56:59]
	v_mfma_f32_16x16x32_bf16 v[60:63], v[40:43], v[100:103], v[60:63]
	s_cmp_gt_u32 s6, 5
	s_cselect_b32 s74, s77, s78
	v_add_u32_e32 v146, s74, v230
	v_xor_b32_e32 v147, 64, v146
	ds_read_b128 v[4:7], v146 offset:10240
	ds_read_b128 v[8:11], v147 offset:10240
	s_cmp_gt_u32 s6, 6
	s_cselect_b32 s74, s77, s78
	v_add_u32_e32 v146, s74, v230
	v_xor_b32_e32 v147, 64, v146
	ds_read_b128 v[12:15], v146 offset:12288
	ds_read_b128 v[16:19], v147 offset:12288
	s_cmp_gt_u32 s6, 7
	s_cselect_b32 s74, s77, s78
	v_add_u32_e32 v146, s74, v230
	v_xor_b32_e32 v147, 64, v146
	ds_read_b128 v[20:23], v146 offset:14336
	ds_read_b128 v[24:27], v147 offset:14336
	s_cmp_gt_u32 s6, 8
	s_cselect_b32 s74, s77, s78
	v_add_u32_e32 v146, s74, v230
	v_xor_b32_e32 v147, 64, v146
	ds_read_b128 v[28:31], v146 offset:16384
	ds_read_b128 v[32:35], v147 offset:16384
	s_nop 1
	v_fma_f32 v44, v44, s79, v185
	v_fma_f32 v45, v45, s79, v186
	v_fma_f32 v46, v46, s79, v187
	v_fma_f32 v47, v47, s79, v188
	v_fma_f32 v48, v48, s79, v189
	v_fma_f32 v49, v49, s79, v190
	v_fma_f32 v50, v50, s79, v191
	v_fma_f32 v51, v51, s79, v192
	v_fma_f32 v52, v52, s79, v193
	v_fma_f32 v53, v53, s79, v194
	v_fma_f32 v54, v54, s79, v195
	v_fma_f32 v55, v55, s79, v196
	v_fma_f32 v56, v56, s79, v197
	v_fma_f32 v57, v57, s79, v198
	v_fma_f32 v58, v58, s79, v199
	v_fma_f32 v59, v59, s79, v200
	v_fma_f32 v60, v60, s79, v201
	v_fma_f32 v61, v61, s79, v202
	v_fma_f32 v62, v62, s79, v203
	v_fma_f32 v63, v63, s79, v204
	s_waitcnt lgkmcnt(0)
	v_mfma_f32_16x16x32_bf16 v[64:67], v[4:7], v[96:99], 0
	v_mfma_f32_16x16x32_bf16 v[68:71], v[12:15], v[96:99], 0
	v_mfma_f32_16x16x32_bf16 v[72:75], v[20:23], v[96:99], 0
	v_mfma_f32_16x16x32_bf16 v[76:79], v[28:31], v[96:99], 0
	v_mfma_f32_16x16x32_bf16 v[64:67], v[8:11], v[100:103], v[64:67]
	v_mfma_f32_16x16x32_bf16 v[68:71], v[16:19], v[100:103], v[68:71]
	v_mfma_f32_16x16x32_bf16 v[72:75], v[24:27], v[100:103], v[72:75]
	v_mfma_f32_16x16x32_bf16 v[76:79], v[32:35], v[100:103], v[76:79]
	s_cmp_gt_u32 s6, 0
	s_cselect_b32 s74, 0, 0xffff0000
	v_add_u32_e32 v146, s74, v221
	ds_read_b64 v[4:5], v146 offset:49152
	ds_read_b64 v[8:9], v146 offset:53248
	ds_read_b64 v[12:13], v146 offset:57344
	ds_read_b64 v[16:17], v146 offset:61440
	s_cmp_gt_u32 s6, 1
	s_cselect_b32 s74, 0, 0xffff0000
	v_add_u32_e32 v146, s74, v222
	ds_read_b64 v[6:7], v146 offset:49152
	ds_read_b64 v[10:11], v146 offset:53248
	ds_read_b64 v[14:15], v146 offset:57344
	ds_read_b64 v[18:19], v146 offset:61440
	s_nop 1
	v_fma_f32 v64, v64, s79, v205
	v_fma_f32 v65, v65, s79, v206
	v_fma_f32 v66, v66, s79, v207
	v_fma_f32 v67, v67, s79, v208
	v_fma_f32 v68, v68, s79, v209
	v_fma_f32 v69, v69, s79, v210
	v_fma_f32 v70, v70, s79, v211
	v_fma_f32 v71, v71, s79, v212
	v_fma_f32 v72, v72, s79, v213
	v_fma_f32 v73, v73, s79, v214
	v_fma_f32 v74, v74, s79, v215
	v_fma_f32 v75, v75, s79, v216
	v_fma_f32 v76, v76, s79, v217
	v_fma_f32 v77, v77, s79, v218
	v_fma_f32 v78, v78, s79, v219
	v_fma_f32 v79, v79, s79, v220
	s_cmp_gt_u32 s6, 2
	s_cselect_b32 s74, 0, 0xffff0000
	v_add_u32_e32 v146, s74, v223
	ds_read_b64 v[20:21], v146 offset:49152
	ds_read_b64 v[24:25], v146 offset:53248
	ds_read_b64 v[28:29], v146 offset:57344
	ds_read_b64 v[32:33], v146 offset:61440
	s_cmp_gt_u32 s6, 3
	s_cselect_b32 s74, 0, 0xffff0000
	v_add_u32_e32 v146, s74, v224
	ds_read_b64 v[22:23], v146 offset:49152
	ds_read_b64 v[26:27], v146 offset:53248
	ds_read_b64 v[30:31], v146 offset:57344
	ds_read_b64 v[34:35], v146 offset:61440
	s_cmp_lg_u32 s4, 0
	s_cbranch_scc1 .Lat991_i0_nomask
	s_cmp_le_u32 s6, 0
	s_cbranch_scc1 .Lat991_i0_nomask
	v_mov_b32_e32 v44, v244
	v_mov_b32_e32 v45, v244
	v_mov_b32_e32 v46, v244
	v_mov_b32_e32 v47, v244
	s_cmp_le_u32 s6, 1
	s_cbranch_scc1 .Lat991_i0_nomask
	v_mov_b32_e32 v48, v244
	v_mov_b32_e32 v49, v244
	v_mov_b32_e32 v50, v244
	v_mov_b32_e32 v51, v244
	s_cmp_le_u32 s6, 2
	s_cbranch_scc1 .Lat991_i0_nomask
	v_mov_b32_e32 v52, v244
	v_mov_b32_e32 v53, v244
	v_mov_b32_e32 v54, v244
	v_mov_b32_e32 v55, v244
	s_cmp_le_u32 s6, 3
	s_cbranch_scc1 .Lat991_i0_nomask
	v_mov_b32_e32 v56, v244
	v_mov_b32_e32 v57, v244
	v_mov_b32_e32 v58, v244
	v_mov_b32_e32 v59, v244
	s_cmp_le_u32 s6, 4
	s_cbranch_scc1 .Lat991_i0_nomask
	v_mov_b32_e32 v60, v244
	v_mov_b32_e32 v61, v244
	v_mov_b32_e32 v62, v244
	v_mov_b32_e32 v63, v244
	s_cmp_le_u32 s6, 5
	s_cbranch_scc1 .Lat991_i0_nomask
	v_mov_b32_e32 v64, v244
	v_mov_b32_e32 v65, v244
	v_mov_b32_e32 v66, v244
	v_mov_b32_e32 v67, v244
	s_cmp_le_u32 s6, 6
	s_cbranch_scc1 .Lat991_i0_nomask
	v_mov_b32_e32 v68, v244
	v_mov_b32_e32 v69, v244
	v_mov_b32_e32 v70, v244
	v_mov_b32_e32 v71, v244
	s_cmp_le_u32 s6, 7
	s_cbranch_scc1 .Lat991_i0_nomask
	v_mov_b32_e32 v72, v244
	v_mov_b32_e32 v73, v244
	v_mov_b32_e32 v74, v244
	v_mov_b32_e32 v75, v244
.Lat991_i0_nomask:
	v_max3_f32 v245, v44, v45, v46
	v_max3_f32 v245, v245, v47, v48
	v_max3_f32 v245, v245, v49, v50
	v_max3_f32 v245, v245, v51, v52
	v_max3_f32 v245, v245, v53, v54
	v_max3_f32 v245, v245, v55, v56
	v_max3_f32 v245, v245, v57, v58
	v_max3_f32 v245, v245, v59, v60
	v_max3_f32 v245, v245, v61, v62
	v_max3_f32 v245, v245, v63, v64
	v_max3_f32 v245, v245, v65, v66
	v_max3_f32 v245, v245, v67, v68
	v_max3_f32 v245, v245, v69, v70
	v_max3_f32 v245, v245, v71, v72
	v_max3_f32 v245, v245, v73, v74
	v_max3_f32 v245, v245, v75, v76
	v_max3_f32 v245, v245, v77, v78
	v_max_f32_e32 v245, v245, v79
	ds_bpermute_b32 v148, v239, v245
	s_waitcnt lgkmcnt(0)
	v_max_f32_e32 v245, v245, v148
	ds_bpermute_b32 v148, v240, v245
	s_waitcnt lgkmcnt(0)
	v_max_f32_e32 v245, v245, v148
	v_sub_f32_e32 v44, v44, v245
	v_sub_f32_e32 v45, v45, v245
	v_sub_f32_e32 v46, v46, v245
	v_sub_f32_e32 v47, v47, v245
	v_exp_f32_e32 v44, v44
	v_exp_f32_e32 v45, v45
	v_exp_f32_e32 v46, v46
	v_exp_f32_e32 v47, v47
	v_sub_f32_e32 v48, v48, v245
	v_sub_f32_e32 v49, v49, v245
	v_sub_f32_e32 v50, v50, v245
	v_sub_f32_e32 v51, v51, v245
	v_exp_f32_e32 v48, v48
	v_exp_f32_e32 v49, v49
	v_exp_f32_e32 v50, v50
	v_exp_f32_e32 v51, v51
	v_mov_b32_e32 v149, v44
	v_mov_b32_e32 v150, v45
	v_mov_b32_e32 v151, v46
	v_mov_b32_e32 v152, v47
	v_cvt_pk_bf16_f32 v44, v44, v45
	v_cvt_pk_bf16_f32 v45, v46, v47
	v_sub_f32_e32 v52, v52, v245
	v_sub_f32_e32 v53, v53, v245
	v_sub_f32_e32 v54, v54, v245
	v_sub_f32_e32 v55, v55, v245
	v_exp_f32_e32 v52, v52
	v_exp_f32_e32 v53, v53
	v_exp_f32_e32 v54, v54
	v_exp_f32_e32 v55, v55
	v_add_f32_e32 v149, v149, v48
	v_add_f32_e32 v150, v150, v49
	v_add_f32_e32 v151, v151, v50
	v_add_f32_e32 v152, v152, v51
	v_cvt_pk_bf16_f32 v46, v48, v49
	v_cvt_pk_bf16_f32 v47, v50, v51
	v_sub_f32_e32 v56, v56, v245
	v_sub_f32_e32 v57, v57, v245
	v_sub_f32_e32 v58, v58, v245
	v_sub_f32_e32 v59, v59, v245
	v_exp_f32_e32 v56, v56
	v_exp_f32_e32 v57, v57
	v_exp_f32_e32 v58, v58
	v_exp_f32_e32 v59, v59
	v_add_f32_e32 v149, v149, v52
	v_add_f32_e32 v150, v150, v53
	v_add_f32_e32 v151, v151, v54
	v_add_f32_e32 v152, v152, v55
	v_cvt_pk_bf16_f32 v52, v52, v53
	v_cvt_pk_bf16_f32 v53, v54, v55
	v_sub_f32_e32 v60, v60, v245
	v_sub_f32_e32 v61, v61, v245
	v_sub_f32_e32 v62, v62, v245
	v_sub_f32_e32 v63, v63, v245
	v_exp_f32_e32 v60, v60
	v_exp_f32_e32 v61, v61
	v_exp_f32_e32 v62, v62
	v_exp_f32_e32 v63, v63
	v_add_f32_e32 v149, v149, v56
	v_add_f32_e32 v150, v150, v57
	v_add_f32_e32 v151, v151, v58
	v_add_f32_e32 v152, v152, v59
	v_cvt_pk_bf16_f32 v54, v56, v57
	v_cvt_pk_bf16_f32 v55, v58, v59
	v_sub_f32_e32 v64, v64, v245
	v_sub_f32_e32 v65, v65, v245
	v_sub_f32_e32 v66, v66, v245
	v_sub_f32_e32 v67, v67, v245
	v_exp_f32_e32 v64, v64
	v_exp_f32_e32 v65, v65
	v_exp_f32_e32 v66, v66
	v_exp_f32_e32 v67, v67
	v_add_f32_e32 v149, v149, v60
	v_add_f32_e32 v150, v150, v61
	v_add_f32_e32 v151, v151, v62
	v_add_f32_e32 v152, v152, v63
	v_cvt_pk_bf16_f32 v60, v60, v61
	v_cvt_pk_bf16_f32 v61, v62, v63
	v_sub_f32_e32 v68, v68, v245
	v_sub_f32_e32 v69, v69, v245
	v_sub_f32_e32 v70, v70, v245
	v_sub_f32_e32 v71, v71, v245
	v_exp_f32_e32 v68, v68
	v_exp_f32_e32 v69, v69
	v_exp_f32_e32 v70, v70
	v_exp_f32_e32 v71, v71
	v_add_f32_e32 v149, v149, v64
	v_add_f32_e32 v150, v150, v65
	v_add_f32_e32 v151, v151, v66
	v_add_f32_e32 v152, v152, v67
	v_cvt_pk_bf16_f32 v62, v64, v65
	v_cvt_pk_bf16_f32 v63, v66, v67
	v_sub_f32_e32 v72, v72, v245
	v_sub_f32_e32 v73, v73, v245
	v_sub_f32_e32 v74, v74, v245
	v_sub_f32_e32 v75, v75, v245
	v_exp_f32_e32 v72, v72
	v_exp_f32_e32 v73, v73
	v_exp_f32_e32 v74, v74
	v_exp_f32_e32 v75, v75
	v_add_f32_e32 v149, v149, v68
	v_add_f32_e32 v150, v150, v69
	v_add_f32_e32 v151, v151, v70
	v_add_f32_e32 v152, v152, v71
	v_cvt_pk_bf16_f32 v68, v68, v69
	v_cvt_pk_bf16_f32 v69, v70, v71
	v_sub_f32_e32 v76, v76, v245
	v_sub_f32_e32 v77, v77, v245
	v_sub_f32_e32 v78, v78, v245
	v_sub_f32_e32 v79, v79, v245
	v_exp_f32_e32 v76, v76
	v_exp_f32_e32 v77, v77
	v_exp_f32_e32 v78, v78
	v_exp_f32_e32 v79, v79
	v_add_f32_e32 v149, v149, v72
	v_add_f32_e32 v150, v150, v73
	v_add_f32_e32 v151, v151, v74
	v_add_f32_e32 v152, v152, v75
	v_cvt_pk_bf16_f32 v70, v72, v73
	v_cvt_pk_bf16_f32 v71, v74, v75
	s_nop 0
	v_add_f32_e32 v149, v149, v76
	v_add_f32_e32 v150, v150, v77
	v_add_f32_e32 v151, v151, v78
	v_add_f32_e32 v152, v152, v79
	v_cvt_pk_bf16_f32 v76, v76, v77
	v_cvt_pk_bf16_f32 v77, v78, v79
	v_mov_b32_e32 v78, 0
	v_mov_b32_e32 v79, 0
	v_add_f32_e32 v149, v149, v150
	v_add_f32_e32 v151, v151, v152
	v_add_f32_e32 v246, v149, v151
	s_waitcnt lgkmcnt(0)
	v_mfma_f32_16x16x32_bf16 v[80:83], v[4:7], v[44:47], 0
	v_mfma_f32_16x16x32_bf16 v[84:87], v[8:11], v[44:47], 0
	v_mfma_f32_16x16x32_bf16 v[88:91], v[12:15], v[44:47], 0
	v_mfma_f32_16x16x32_bf16 v[92:95], v[16:19], v[44:47], 0
	s_cmp_gt_u32 s6, 4
	s_cselect_b32 s74, 0, 0xffff0000
	v_add_u32_e32 v146, s74, v225
	ds_read_b64 v[4:5], v146 offset:49152
	ds_read_b64 v[8:9], v146 offset:53248
	ds_read_b64 v[12:13], v146 offset:57344
	ds_read_b64 v[16:17], v146 offset:61440
	s_cmp_gt_u32 s6, 5
	s_cselect_b32 s74, 0, 0xffff0000
	v_add_u32_e32 v146, s74, v226
	ds_read_b64 v[6:7], v146 offset:49152
	ds_read_b64 v[10:11], v146 offset:53248
	ds_read_b64 v[14:15], v146 offset:57344
	ds_read_b64 v[18:19], v146 offset:61440
	v_mfma_f32_16x16x32_bf16 v[80:83], v[20:23], v[52:55], v[80:83]
	v_mfma_f32_16x16x32_bf16 v[84:87], v[24:27], v[52:55], v[84:87]
	v_mfma_f32_16x16x32_bf16 v[88:91], v[28:31], v[52:55], v[88:91]
	v_mfma_f32_16x16x32_bf16 v[92:95], v[32:35], v[52:55], v[92:95]
	s_cmp_gt_u32 s6, 6
	s_cselect_b32 s74, 0, 0xffff0000
	v_add_u32_e32 v146, s74, v227
	ds_read_b64 v[20:21], v146 offset:49152
	ds_read_b64 v[24:25], v146 offset:53248
	ds_read_b64 v[28:29], v146 offset:57344
	ds_read_b64 v[32:33], v146 offset:61440
	s_cmp_gt_u32 s6, 7
	s_cselect_b32 s74, 0, 0xffff0000
	v_add_u32_e32 v146, s74, v228
	ds_read_b64 v[22:23], v146 offset:49152
	ds_read_b64 v[26:27], v146 offset:53248
	ds_read_b64 v[30:31], v146 offset:57344
	ds_read_b64 v[34:35], v146 offset:61440
	ds_bpermute_b32 v148, v239, v246
	s_waitcnt lgkmcnt(9)
	v_mfma_f32_16x16x32_bf16 v[80:83], v[4:7], v[60:63], v[80:83]
	v_mfma_f32_16x16x32_bf16 v[84:87], v[8:11], v[60:63], v[84:87]
	v_mfma_f32_16x16x32_bf16 v[88:91], v[12:15], v[60:63], v[88:91]
	v_mfma_f32_16x16x32_bf16 v[92:95], v[16:19], v[60:63], v[92:95]
	s_cmp_gt_u32 s6, 8
	s_cselect_b32 s74, 0, 0xffff0000
	v_add_u32_e32 v146, s74, v229
	ds_read_b64 v[4:5], v146 offset:49152
	ds_read_b64 v[8:9], v146 offset:53248
	ds_read_b64 v[12:13], v146 offset:57344
	ds_read_b64 v[16:17], v146 offset:61440
	v_mov_b32_e32 v6, 0
	v_mov_b32_e32 v7, 0
	v_mov_b32_e32 v10, 0
	v_mov_b32_e32 v11, 0
	v_mov_b32_e32 v14, 0
	v_mov_b32_e32 v15, 0
	v_mov_b32_e32 v18, 0
	v_mov_b32_e32 v19, 0
	s_waitcnt lgkmcnt(5)
	v_mfma_f32_16x16x32_bf16 v[80:83], v[20:23], v[68:71], v[80:83]
	v_mfma_f32_16x16x32_bf16 v[84:87], v[24:27], v[68:71], v[84:87]
	v_mfma_f32_16x16x32_bf16 v[88:91], v[28:31], v[68:71], v[88:91]
	v_mfma_f32_16x16x32_bf16 v[92:95], v[32:35], v[68:71], v[92:95]
	s_waitcnt lgkmcnt(0)
	v_add_f32_e32 v246, v246, v148
	s_nop 0
	v_mfma_f32_16x16x32_bf16 v[80:83], v[4:7], v[76:79], v[80:83]
	v_mfma_f32_16x16x32_bf16 v[84:87], v[8:11], v[76:79], v[84:87]
	v_mfma_f32_16x16x32_bf16 v[88:91], v[12:15], v[76:79], v[88:91]
	v_mfma_f32_16x16x32_bf16 v[92:95], v[16:19], v[76:79], v[92:95]
	ds_bpermute_b32 v148, v240, v246
	s_waitcnt lgkmcnt(0)
	v_add_f32_e32 v246, v246, v148
	v_rcp_f32_e32 v149, v246
	v_log_f32_e32 v150, v246
	s_nop 0
	v_add_f32_e32 v151, v245, v150
	v_mul_f32_e32 v151, 0x3f317218, v151
	v_max_f32_e32 v152, v120, v151
	v_sub_f32_e32 v153, v120, v152
	v_sub_f32_e32 v154, v151, v152
	v_mul_f32_e32 v153, 0x3fb8aa3b, v153
	v_mul_f32_e32 v154, 0x3fb8aa3b, v154
	v_exp_f32_e32 v153, v153
	v_exp_f32_e32 v154, v154
	s_nop 0
	v_add_f32_e32 v155, v153, v154
	v_rcp_f32_e32 v146, v155
	v_log_f32_e32 v150, v155
	s_nop 0
	v_mul_f32_e32 v154, v154, v146
	v_mul_f32_e32 v146, v153, v146
	v_mul_f32_e32 v147, v149, v154
	v_mul_f32_e32 v150, 0x3f317218, v150
	v_add_f32_e32 v140, v152, v150
	v_mul_f32_e32 v80, v80, v147
	v_mul_f32_e32 v81, v81, v147
	v_mul_f32_e32 v82, v82, v147
	v_mul_f32_e32 v83, v83, v147
	v_mul_f32_e32 v84, v84, v147
	v_mul_f32_e32 v85, v85, v147
	v_mul_f32_e32 v86, v86, v147
	v_mul_f32_e32 v87, v87, v147
	v_mul_f32_e32 v88, v88, v147
	v_mul_f32_e32 v89, v89, v147
	v_mul_f32_e32 v90, v90, v147
	v_mul_f32_e32 v91, v91, v147
	v_mul_f32_e32 v92, v92, v147
	v_mul_f32_e32 v93, v93, v147
	v_mul_f32_e32 v94, v94, v147
	v_mul_f32_e32 v95, v95, v147
	v_lshlrev_b32_e32 v141, 16, v112
	v_and_b32_e32 v142, 0xffff0000, v112
	v_lshlrev_b32_e32 v143, 16, v113
	v_and_b32_e32 v144, 0xffff0000, v113
	v_fmac_f32_e32 v80, v146, v141
	v_fmac_f32_e32 v81, v146, v142
	v_fmac_f32_e32 v82, v146, v143
	v_fmac_f32_e32 v83, v146, v144
	v_cvt_pk_bf16_f32 v132, v80, v81
	v_cvt_pk_bf16_f32 v133, v82, v83
	v_lshlrev_b32_e32 v141, 16, v114
	v_and_b32_e32 v142, 0xffff0000, v114
	v_lshlrev_b32_e32 v143, 16, v115
	v_and_b32_e32 v144, 0xffff0000, v115
	v_fmac_f32_e32 v84, v146, v141
	v_fmac_f32_e32 v85, v146, v142
	v_fmac_f32_e32 v86, v146, v143
	v_fmac_f32_e32 v87, v146, v144
	v_cvt_pk_bf16_f32 v134, v84, v85
	v_cvt_pk_bf16_f32 v135, v86, v87
	v_lshlrev_b32_e32 v141, 16, v116
	v_and_b32_e32 v142, 0xffff0000, v116
	v_lshlrev_b32_e32 v143, 16, v117
	v_and_b32_e32 v144, 0xffff0000, v117
	v_fmac_f32_e32 v88, v146, v141
	v_fmac_f32_e32 v89, v146, v142
	v_fmac_f32_e32 v90, v146, v143
	v_fmac_f32_e32 v91, v146, v144
	v_cvt_pk_bf16_f32 v136, v88, v89
	v_cvt_pk_bf16_f32 v137, v90, v91
	v_lshlrev_b32_e32 v141, 16, v118
	v_and_b32_e32 v142, 0xffff0000, v118
	v_lshlrev_b32_e32 v143, 16, v119
	v_and_b32_e32 v144, 0xffff0000, v119
	v_fmac_f32_e32 v92, v146, v141
	v_fmac_f32_e32 v93, v146, v142
	v_fmac_f32_e32 v94, v146, v143
	v_fmac_f32_e32 v95, v146, v144
	v_cvt_pk_bf16_f32 v138, v92, v93
	v_cvt_pk_bf16_f32 v139, v94, v95
	s_mov_b64 s[26:27], s[86:87]
	s_mov_b64 s[28:29], s[88:89]
	s_mov_b64 s[86:87], s[12:13]
	s_mov_b64 s[88:89], s[14:15]
	s_mov_b32 s4, s83
	s_mov_b32 s5, s84
	s_waitcnt vmcnt(0)
	s_barrier
	ds_read_b128 v[4:7], v230 offset:0
	ds_read_b128 v[8:11], v231 offset:0
	ds_read_b128 v[12:15], v230 offset:2048
	ds_read_b128 v[16:19], v231 offset:2048
	ds_read_b128 v[20:23], v230 offset:4096
	ds_read_b128 v[24:27], v231 offset:4096
	ds_read_b128 v[28:31], v230 offset:6144
	ds_read_b128 v[32:35], v231 offset:6144
	ds_read_b128 v[36:39], v230 offset:8192
	ds_read_b128 v[40:43], v231 offset:8192
	global_store_dwordx2 v237, v[132:133], s[26:27]
	global_store_dwordx2 v237, v[134:135], s[26:27] offset:32
	global_store_dwordx2 v237, v[136:137], s[26:27] offset:64
	global_store_dwordx2 v237, v[138:139], s[26:27] offset:96
	s_mov_b64 s[90:91], exec
	s_mov_b64 exec, 0xffff
	global_store_dword v238, v140, s[28:29]
	s_mov_b64 exec, s[90:91]
	s_add_u32 s84, s5, s4
	s_xor_b32 s83, s4, 1
	s_mul_i32 s74, s84, 256
	s_lshl_b32 s75, s83, 7
	s_add_u32 s74, s74, s75
	s_lshl_b32 s75, s74, 7
	s_add_u32 s16, s60, s75
	s_addc_u32 s17, s61, 0
	s_lshl_b32 s75, s74, 1
	s_add_u32 s24, s64, s75
	s_addc_u32 s25, s65, 0
	s_add_u32 m0, s70, 0x8000
	s_nop 0
	global_load_lds_dwordx4 v232, s[16:17]
	s_add_u32 m0, s70, 0xa000
	s_nop 0
	global_load_lds_dwordx4 v233, s[16:17]
	s_add_u32 m0, s70, 0x18000
	s_nop 0
	global_load_lds_dwordx4 v234, s[24:25]
	s_add_u32 m0, s70, 0x1a000
	s_nop 0
	global_load_lds_dwordx4 v235, s[24:25]
	s_lshl_b32 s74, s83, 11
	s_add_u32 s74, s74, s84
	s_lshl_b32 s75, s74, 7
	s_add_u32 s10, s30, s75
	s_addc_u32 s11, s31, 0
	s_add_u32 s12, s34, s75
	s_addc_u32 s13, s35, 0
	s_lshl_b32 s75, s74, 2
	s_add_u32 s14, s58, s75
	s_addc_u32 s15, s59, 0
	global_load_dwordx4 v[96:99], v236, s[10:11]
	global_load_dwordx4 v[100:103], v236, s[10:11] offset:64
	global_load_dwordx2 v[112:113], v237, s[12:13]
	global_load_dwordx2 v[114:115], v237, s[12:13] offset:32
	global_load_dwordx2 v[116:117], v237, s[12:13] offset:64
	global_load_dwordx2 v[118:119], v237, s[12:13] offset:96
	global_load_dword v120, v238, s[14:15]
	s_waitcnt lgkmcnt(0)
	v_mfma_f32_16x16x32_bf16 v[44:47], v[4:7], v[104:107], 0
	v_mfma_f32_16x16x32_bf16 v[48:51], v[12:15], v[104:107], 0
	v_mfma_f32_16x16x32_bf16 v[52:55], v[20:23], v[104:107], 0
	v_mfma_f32_16x16x32_bf16 v[56:59], v[28:31], v[104:107], 0
	v_mfma_f32_16x16x32_bf16 v[60:63], v[36:39], v[104:107], 0
	v_mfma_f32_16x16x32_bf16 v[44:47], v[8:11], v[108:111], v[44:47]
	v_mfma_f32_16x16x32_bf16 v[48:51], v[16:19], v[108:111], v[48:51]
	v_mfma_f32_16x16x32_bf16 v[52:55], v[24:27], v[108:111], v[52:55]
	v_mfma_f32_16x16x32_bf16 v[56:59], v[32:35], v[108:111], v[56:59]
	v_mfma_f32_16x16x32_bf16 v[60:63], v[40:43], v[108:111], v[60:63]
	ds_read_b128 v[4:7], v230 offset:10240
	ds_read_b128 v[8:11], v231 offset:10240
	ds_read_b128 v[12:15], v230 offset:12288
	ds_read_b128 v[16:19], v231 offset:12288
	ds_read_b128 v[20:23], v230 offset:14336
	ds_read_b128 v[24:27], v231 offset:14336
	ds_read_b128 v[28:31], v230 offset:16384
	ds_read_b128 v[32:35], v231 offset:16384
	s_nop 1
	v_fma_f32 v44, v44, s79, v185
	v_fma_f32 v45, v45, s79, v186
	v_fma_f32 v46, v46, s79, v187
	v_fma_f32 v47, v47, s79, v188
	v_fma_f32 v48, v48, s79, v189
	v_fma_f32 v49, v49, s79, v190
	v_fma_f32 v50, v50, s79, v191
	v_fma_f32 v51, v51, s79, v192
	v_fma_f32 v52, v52, s79, v193
	v_fma_f32 v53, v53, s79, v194
	v_fma_f32 v54, v54, s79, v195
	v_fma_f32 v55, v55, s79, v196
	v_fma_f32 v56, v56, s79, v197
	v_fma_f32 v57, v57, s79, v198
	v_fma_f32 v58, v58, s79, v199
	v_fma_f32 v59, v59, s79, v200
	v_fma_f32 v60, v60, s79, v201
	v_fma_f32 v61, v61, s79, v202
	v_fma_f32 v62, v62, s79, v203
	v_fma_f32 v63, v63, s79, v204
	s_waitcnt lgkmcnt(0)
	v_mfma_f32_16x16x32_bf16 v[64:67], v[4:7], v[104:107], 0
	v_mfma_f32_16x16x32_bf16 v[68:71], v[12:15], v[104:107], 0
	v_mfma_f32_16x16x32_bf16 v[72:75], v[20:23], v[104:107], 0
	v_mfma_f32_16x16x32_bf16 v[76:79], v[28:31], v[104:107], 0
	v_mfma_f32_16x16x32_bf16 v[64:67], v[8:11], v[108:111], v[64:67]
	v_mfma_f32_16x16x32_bf16 v[68:71], v[16:19], v[108:111], v[68:71]
	v_mfma_f32_16x16x32_bf16 v[72:75], v[24:27], v[108:111], v[72:75]
	v_mfma_f32_16x16x32_bf16 v[76:79], v[32:35], v[108:111], v[76:79]
	ds_read_b64 v[4:5], v221 offset:0
	ds_read_b64 v[8:9], v221 offset:4096
	ds_read_b64 v[12:13], v221 offset:8192
	ds_read_b64 v[16:17], v221 offset:12288
	ds_read_b64 v[6:7], v222 offset:0
	ds_read_b64 v[10:11], v222 offset:4096
	ds_read_b64 v[14:15], v222 offset:8192
	ds_read_b64 v[18:19], v222 offset:12288
	s_nop 1
	v_fma_f32 v64, v64, s79, v205
	v_fma_f32 v65, v65, s79, v206
	v_fma_f32 v66, v66, s79, v207
	v_fma_f32 v67, v67, s79, v208
	v_fma_f32 v68, v68, s79, v209
	v_fma_f32 v69, v69, s79, v210
	v_fma_f32 v70, v70, s79, v211
	v_fma_f32 v71, v71, s79, v212
	v_fma_f32 v72, v72, s79, v213
	v_fma_f32 v73, v73, s79, v214
	v_fma_f32 v74, v74, s79, v215
	v_fma_f32 v75, v75, s79, v216
	v_fma_f32 v76, v76, s79, v217
	v_fma_f32 v77, v77, s79, v218
	v_fma_f32 v78, v78, s79, v219
	v_fma_f32 v79, v79, s79, v220
	ds_read_b64 v[20:21], v223 offset:0
	ds_read_b64 v[24:25], v223 offset:4096
	ds_read_b64 v[28:29], v223 offset:8192
	ds_read_b64 v[32:33], v223 offset:12288
	ds_read_b64 v[22:23], v224 offset:0
	ds_read_b64 v[26:27], v224 offset:4096
	ds_read_b64 v[30:31], v224 offset:8192
	ds_read_b64 v[34:35], v224 offset:12288
	s_cmp_lg_u32 s4, 0
	s_cbranch_scc1 .Lat991_i1_nomask
	s_cmp_le_u32 s6, 0
	s_cbranch_scc1 .Lat991_i1_nomask
	v_mov_b32_e32 v44, v244
	v_mov_b32_e32 v45, v244
	v_mov_b32_e32 v46, v244
	v_mov_b32_e32 v47, v244
	s_cmp_le_u32 s6, 1
	s_cbranch_scc1 .Lat991_i1_nomask
	v_mov_b32_e32 v48, v244
	v_mov_b32_e32 v49, v244
	v_mov_b32_e32 v50, v244
	v_mov_b32_e32 v51, v244
	s_cmp_le_u32 s6, 2
	s_cbranch_scc1 .Lat991_i1_nomask
	v_mov_b32_e32 v52, v244
	v_mov_b32_e32 v53, v244
	v_mov_b32_e32 v54, v244
	v_mov_b32_e32 v55, v244
	s_cmp_le_u32 s6, 3
	s_cbranch_scc1 .Lat991_i1_nomask
	v_mov_b32_e32 v56, v244
	v_mov_b32_e32 v57, v244
	v_mov_b32_e32 v58, v244
	v_mov_b32_e32 v59, v244
	s_cmp_le_u32 s6, 4
	s_cbranch_scc1 .Lat991_i1_nomask
	v_mov_b32_e32 v60, v244
	v_mov_b32_e32 v61, v244
	v_mov_b32_e32 v62, v244
	v_mov_b32_e32 v63, v244
	s_cmp_le_u32 s6, 5
	s_cbranch_scc1 .Lat991_i1_nomask
	v_mov_b32_e32 v64, v244
	v_mov_b32_e32 v65, v244
	v_mov_b32_e32 v66, v244
	v_mov_b32_e32 v67, v244
	s_cmp_le_u32 s6, 6
	s_cbranch_scc1 .Lat991_i1_nomask
	v_mov_b32_e32 v68, v244
	v_mov_b32_e32 v69, v244
	v_mov_b32_e32 v70, v244
	v_mov_b32_e32 v71, v244
	s_cmp_le_u32 s6, 7
	s_cbranch_scc1 .Lat991_i1_nomask
	v_mov_b32_e32 v72, v244
	v_mov_b32_e32 v73, v244
	v_mov_b32_e32 v74, v244
	v_mov_b32_e32 v75, v244
.Lat991_i1_nomask:
	v_max3_f32 v245, v44, v45, v46
	v_max3_f32 v245, v245, v47, v48
	v_max3_f32 v245, v245, v49, v50
	v_max3_f32 v245, v245, v51, v52
	v_max3_f32 v245, v245, v53, v54
	v_max3_f32 v245, v245, v55, v56
	v_max3_f32 v245, v245, v57, v58
	v_max3_f32 v245, v245, v59, v60
	v_max3_f32 v245, v245, v61, v62
	v_max3_f32 v245, v245, v63, v64
	v_max3_f32 v245, v245, v65, v66
	v_max3_f32 v245, v245, v67, v68
	v_max3_f32 v245, v245, v69, v70
	v_max3_f32 v245, v245, v71, v72
	v_max3_f32 v245, v245, v73, v74
	v_max3_f32 v245, v245, v75, v76
	v_max3_f32 v245, v245, v77, v78
	v_max_f32_e32 v245, v245, v79
	ds_bpermute_b32 v148, v239, v245
	s_waitcnt lgkmcnt(0)
	v_max_f32_e32 v245, v245, v148
	ds_bpermute_b32 v148, v240, v245
	s_waitcnt lgkmcnt(0)
	v_max_f32_e32 v245, v245, v148
	v_sub_f32_e32 v44, v44, v245
	v_sub_f32_e32 v45, v45, v245
	v_sub_f32_e32 v46, v46, v245
	v_sub_f32_e32 v47, v47, v245
	v_exp_f32_e32 v44, v44
	v_exp_f32_e32 v45, v45
	v_exp_f32_e32 v46, v46
	v_exp_f32_e32 v47, v47
	v_sub_f32_e32 v48, v48, v245
	v_sub_f32_e32 v49, v49, v245
	v_sub_f32_e32 v50, v50, v245
	v_sub_f32_e32 v51, v51, v245
	v_exp_f32_e32 v48, v48
	v_exp_f32_e32 v49, v49
	v_exp_f32_e32 v50, v50
	v_exp_f32_e32 v51, v51
	v_mov_b32_e32 v149, v44
	v_mov_b32_e32 v150, v45
	v_mov_b32_e32 v151, v46
	v_mov_b32_e32 v152, v47
	v_cvt_pk_bf16_f32 v44, v44, v45
	v_cvt_pk_bf16_f32 v45, v46, v47
	v_sub_f32_e32 v52, v52, v245
	v_sub_f32_e32 v53, v53, v245
	v_sub_f32_e32 v54, v54, v245
	v_sub_f32_e32 v55, v55, v245
	v_exp_f32_e32 v52, v52
	v_exp_f32_e32 v53, v53
	v_exp_f32_e32 v54, v54
	v_exp_f32_e32 v55, v55
	v_add_f32_e32 v149, v149, v48
	v_add_f32_e32 v150, v150, v49
	v_add_f32_e32 v151, v151, v50
	v_add_f32_e32 v152, v152, v51
	v_cvt_pk_bf16_f32 v46, v48, v49
	v_cvt_pk_bf16_f32 v47, v50, v51
	v_sub_f32_e32 v56, v56, v245
	v_sub_f32_e32 v57, v57, v245
	v_sub_f32_e32 v58, v58, v245
	v_sub_f32_e32 v59, v59, v245
	v_exp_f32_e32 v56, v56
	v_exp_f32_e32 v57, v57
	v_exp_f32_e32 v58, v58
	v_exp_f32_e32 v59, v59
	v_add_f32_e32 v149, v149, v52
	v_add_f32_e32 v150, v150, v53
	v_add_f32_e32 v151, v151, v54
	v_add_f32_e32 v152, v152, v55
	v_cvt_pk_bf16_f32 v52, v52, v53
	v_cvt_pk_bf16_f32 v53, v54, v55
	v_sub_f32_e32 v60, v60, v245
	v_sub_f32_e32 v61, v61, v245
	v_sub_f32_e32 v62, v62, v245
	v_sub_f32_e32 v63, v63, v245
	v_exp_f32_e32 v60, v60
	v_exp_f32_e32 v61, v61
	v_exp_f32_e32 v62, v62
	v_exp_f32_e32 v63, v63
	v_add_f32_e32 v149, v149, v56
	v_add_f32_e32 v150, v150, v57
	v_add_f32_e32 v151, v151, v58
	v_add_f32_e32 v152, v152, v59
	v_cvt_pk_bf16_f32 v54, v56, v57
	v_cvt_pk_bf16_f32 v55, v58, v59
	v_sub_f32_e32 v64, v64, v245
	v_sub_f32_e32 v65, v65, v245
	v_sub_f32_e32 v66, v66, v245
	v_sub_f32_e32 v67, v67, v245
	v_exp_f32_e32 v64, v64
	v_exp_f32_e32 v65, v65
	v_exp_f32_e32 v66, v66
	v_exp_f32_e32 v67, v67
	v_add_f32_e32 v149, v149, v60
	v_add_f32_e32 v150, v150, v61
	v_add_f32_e32 v151, v151, v62
	v_add_f32_e32 v152, v152, v63
	v_cvt_pk_bf16_f32 v60, v60, v61
	v_cvt_pk_bf16_f32 v61, v62, v63
	v_sub_f32_e32 v68, v68, v245
	v_sub_f32_e32 v69, v69, v245
	v_sub_f32_e32 v70, v70, v245
	v_sub_f32_e32 v71, v71, v245
	v_exp_f32_e32 v68, v68
	v_exp_f32_e32 v69, v69
	v_exp_f32_e32 v70, v70
	v_exp_f32_e32 v71, v71
	v_add_f32_e32 v149, v149, v64
	v_add_f32_e32 v150, v150, v65
	v_add_f32_e32 v151, v151, v66
	v_add_f32_e32 v152, v152, v67
	v_cvt_pk_bf16_f32 v62, v64, v65
	v_cvt_pk_bf16_f32 v63, v66, v67
	v_sub_f32_e32 v72, v72, v245
	v_sub_f32_e32 v73, v73, v245
	v_sub_f32_e32 v74, v74, v245
	v_sub_f32_e32 v75, v75, v245
	v_exp_f32_e32 v72, v72
	v_exp_f32_e32 v73, v73
	v_exp_f32_e32 v74, v74
	v_exp_f32_e32 v75, v75
	v_add_f32_e32 v149, v149, v68
	v_add_f32_e32 v150, v150, v69
	v_add_f32_e32 v151, v151, v70
	v_add_f32_e32 v152, v152, v71
	v_cvt_pk_bf16_f32 v68, v68, v69
	v_cvt_pk_bf16_f32 v69, v70, v71
	v_sub_f32_e32 v76, v76, v245
	v_sub_f32_e32 v77, v77, v245
	v_sub_f32_e32 v78, v78, v245
	v_sub_f32_e32 v79, v79, v245
	v_exp_f32_e32 v76, v76
	v_exp_f32_e32 v77, v77
	v_exp_f32_e32 v78, v78
	v_exp_f32_e32 v79, v79
	v_add_f32_e32 v149, v149, v72
	v_add_f32_e32 v150, v150, v73
	v_add_f32_e32 v151, v151, v74
	v_add_f32_e32 v152, v152, v75
	v_cvt_pk_bf16_f32 v70, v72, v73
	v_cvt_pk_bf16_f32 v71, v74, v75
	s_nop 0
	v_add_f32_e32 v149, v149, v76
	v_add_f32_e32 v150, v150, v77
	v_add_f32_e32 v151, v151, v78
	v_add_f32_e32 v152, v152, v79
	v_cvt_pk_bf16_f32 v76, v76, v77
	v_cvt_pk_bf16_f32 v77, v78, v79
	v_mov_b32_e32 v78, 0
	v_mov_b32_e32 v79, 0
	v_add_f32_e32 v149, v149, v150
	v_add_f32_e32 v151, v151, v152
	v_add_f32_e32 v246, v149, v151
	s_waitcnt lgkmcnt(0)
	v_mfma_f32_16x16x32_bf16 v[80:83], v[4:7], v[44:47], 0
	v_mfma_f32_16x16x32_bf16 v[84:87], v[8:11], v[44:47], 0
	v_mfma_f32_16x16x32_bf16 v[88:91], v[12:15], v[44:47], 0
	v_mfma_f32_16x16x32_bf16 v[92:95], v[16:19], v[44:47], 0
	ds_read_b64 v[4:5], v225 offset:0
	ds_read_b64 v[8:9], v225 offset:4096
	ds_read_b64 v[12:13], v225 offset:8192
	ds_read_b64 v[16:17], v225 offset:12288
	ds_read_b64 v[6:7], v226 offset:0
	ds_read_b64 v[10:11], v226 offset:4096
	ds_read_b64 v[14:15], v226 offset:8192
	ds_read_b64 v[18:19], v226 offset:12288
	v_mfma_f32_16x16x32_bf16 v[80:83], v[20:23], v[52:55], v[80:83]
	v_mfma_f32_16x16x32_bf16 v[84:87], v[24:27], v[52:55], v[84:87]
	v_mfma_f32_16x16x32_bf16 v[88:91], v[28:31], v[52:55], v[88:91]
	v_mfma_f32_16x16x32_bf16 v[92:95], v[32:35], v[52:55], v[92:95]
	ds_read_b64 v[20:21], v227 offset:0
	ds_read_b64 v[24:25], v227 offset:4096
	ds_read_b64 v[28:29], v227 offset:8192
	ds_read_b64 v[32:33], v227 offset:12288
	ds_read_b64 v[22:23], v228 offset:0
	ds_read_b64 v[26:27], v228 offset:4096
	ds_read_b64 v[30:31], v228 offset:8192
	ds_read_b64 v[34:35], v228 offset:12288
	ds_bpermute_b32 v148, v239, v246
	s_waitcnt lgkmcnt(9)
	v_mfma_f32_16x16x32_bf16 v[80:83], v[4:7], v[60:63], v[80:83]
	v_mfma_f32_16x16x32_bf16 v[84:87], v[8:11], v[60:63], v[84:87]
	v_mfma_f32_16x16x32_bf16 v[88:91], v[12:15], v[60:63], v[88:91]
	v_mfma_f32_16x16x32_bf16 v[92:95], v[16:19], v[60:63], v[92:95]
	ds_read_b64 v[4:5], v229 offset:0
	ds_read_b64 v[8:9], v229 offset:4096
	ds_read_b64 v[12:13], v229 offset:8192
	ds_read_b64 v[16:17], v229 offset:12288
	v_mov_b32_e32 v6, 0
	v_mov_b32_e32 v7, 0
	v_mov_b32_e32 v10, 0
	v_mov_b32_e32 v11, 0
	v_mov_b32_e32 v14, 0
	v_mov_b32_e32 v15, 0
	v_mov_b32_e32 v18, 0
	v_mov_b32_e32 v19, 0
	s_waitcnt lgkmcnt(5)
	v_mfma_f32_16x16x32_bf16 v[80:83], v[20:23], v[68:71], v[80:83]
	v_mfma_f32_16x16x32_bf16 v[84:87], v[24:27], v[68:71], v[84:87]
	v_mfma_f32_16x16x32_bf16 v[88:91], v[28:31], v[68:71], v[88:91]
	v_mfma_f32_16x16x32_bf16 v[92:95], v[32:35], v[68:71], v[92:95]
	s_waitcnt lgkmcnt(0)
	v_add_f32_e32 v246, v246, v148
	s_nop 0
	v_mfma_f32_16x16x32_bf16 v[80:83], v[4:7], v[76:79], v[80:83]
	v_mfma_f32_16x16x32_bf16 v[84:87], v[8:11], v[76:79], v[84:87]
	v_mfma_f32_16x16x32_bf16 v[88:91], v[12:15], v[76:79], v[88:91]
	v_mfma_f32_16x16x32_bf16 v[92:95], v[16:19], v[76:79], v[92:95]
	ds_bpermute_b32 v148, v240, v246
	s_waitcnt lgkmcnt(0)
	v_add_f32_e32 v246, v246, v148
	v_rcp_f32_e32 v149, v246
	v_log_f32_e32 v150, v246
	s_nop 0
	v_add_f32_e32 v151, v245, v150
	v_mul_f32_e32 v151, 0x3f317218, v151
	v_max_f32_e32 v152, v121, v151
	v_sub_f32_e32 v153, v121, v152
	v_sub_f32_e32 v154, v151, v152
	v_mul_f32_e32 v153, 0x3fb8aa3b, v153
	v_mul_f32_e32 v154, 0x3fb8aa3b, v154
	v_exp_f32_e32 v153, v153
	v_exp_f32_e32 v154, v154
	s_nop 0
	v_add_f32_e32 v155, v153, v154
	v_rcp_f32_e32 v146, v155
	v_log_f32_e32 v150, v155
	s_nop 0
	v_mul_f32_e32 v154, v154, v146
	v_mul_f32_e32 v146, v153, v146
	v_mul_f32_e32 v147, v149, v154
	v_mul_f32_e32 v150, 0x3f317218, v150
	v_add_f32_e32 v140, v152, v150
	v_mul_f32_e32 v80, v80, v147
	v_mul_f32_e32 v81, v81, v147
	v_mul_f32_e32 v82, v82, v147
	v_mul_f32_e32 v83, v83, v147
	v_mul_f32_e32 v84, v84, v147
	v_mul_f32_e32 v85, v85, v147
	v_mul_f32_e32 v86, v86, v147
	v_mul_f32_e32 v87, v87, v147
	v_mul_f32_e32 v88, v88, v147
	v_mul_f32_e32 v89, v89, v147
	v_mul_f32_e32 v90, v90, v147
	v_mul_f32_e32 v91, v91, v147
	v_mul_f32_e32 v92, v92, v147
	v_mul_f32_e32 v93, v93, v147
	v_mul_f32_e32 v94, v94, v147
	v_mul_f32_e32 v95, v95, v147
	v_lshlrev_b32_e32 v141, 16, v122
	v_and_b32_e32 v142, 0xffff0000, v122
	v_lshlrev_b32_e32 v143, 16, v123
	v_and_b32_e32 v144, 0xffff0000, v123
	v_fmac_f32_e32 v80, v146, v141
	v_fmac_f32_e32 v81, v146, v142
	v_fmac_f32_e32 v82, v146, v143
	v_fmac_f32_e32 v83, v146, v144
	v_cvt_pk_bf16_f32 v132, v80, v81
	v_cvt_pk_bf16_f32 v133, v82, v83
	v_lshlrev_b32_e32 v141, 16, v124
	v_and_b32_e32 v142, 0xffff0000, v124
	v_lshlrev_b32_e32 v143, 16, v125
	v_and_b32_e32 v144, 0xffff0000, v125
	v_fmac_f32_e32 v84, v146, v141
	v_fmac_f32_e32 v85, v146, v142
	v_fmac_f32_e32 v86, v146, v143
	v_fmac_f32_e32 v87, v146, v144
	v_cvt_pk_bf16_f32 v134, v84, v85
	v_cvt_pk_bf16_f32 v135, v86, v87
	v_lshlrev_b32_e32 v141, 16, v126
	v_and_b32_e32 v142, 0xffff0000, v126
	v_lshlrev_b32_e32 v143, 16, v127
	v_and_b32_e32 v144, 0xffff0000, v127
	v_fmac_f32_e32 v88, v146, v141
	v_fmac_f32_e32 v89, v146, v142
	v_fmac_f32_e32 v90, v146, v143
	v_fmac_f32_e32 v91, v146, v144
	v_cvt_pk_bf16_f32 v136, v88, v89
	v_cvt_pk_bf16_f32 v137, v90, v91
	v_lshlrev_b32_e32 v141, 16, v128
	v_and_b32_e32 v142, 0xffff0000, v128
	v_lshlrev_b32_e32 v143, 16, v129
	v_and_b32_e32 v144, 0xffff0000, v129
	v_fmac_f32_e32 v92, v146, v141
	v_fmac_f32_e32 v93, v146, v142
	v_fmac_f32_e32 v94, v146, v143
	v_fmac_f32_e32 v95, v146, v144
	v_cvt_pk_bf16_f32 v138, v92, v93
	v_cvt_pk_bf16_f32 v139, v94, v95
	s_mov_b64 s[26:27], s[86:87]
	s_mov_b64 s[28:29], s[88:89]
	s_mov_b64 s[86:87], s[12:13]
	s_mov_b64 s[88:89], s[14:15]
	s_mov_b32 s4, s83
	s_mov_b32 s5, s84
	s_waitcnt vmcnt(0)
	s_barrier
	ds_read_b128 v[4:7], v230 offset:16384
	ds_read_b128 v[8:11], v231 offset:16384
	ds_read_b128 v[12:15], v230 offset:18432
	ds_read_b128 v[16:19], v231 offset:18432
	ds_read_b128 v[20:23], v230 offset:20480
	ds_read_b128 v[24:27], v231 offset:20480
	ds_read_b128 v[28:31], v230 offset:22528
	ds_read_b128 v[32:35], v231 offset:22528
	ds_read_b128 v[36:39], v230 offset:24576
	ds_read_b128 v[40:43], v231 offset:24576
	global_store_dwordx2 v237, v[132:133], s[26:27]
	global_store_dwordx2 v237, v[134:135], s[26:27] offset:32
	global_store_dwordx2 v237, v[136:137], s[26:27] offset:64
	global_store_dwordx2 v237, v[138:139], s[26:27] offset:96
	s_mov_b64 s[90:91], exec
	s_mov_b64 exec, 0xffff
	global_store_dword v238, v140, s[28:29]
	s_mov_b64 exec, s[90:91]
	s_add_u32 s84, s5, s4
	s_xor_b32 s83, s4, 1
	s_mul_i32 s74, s84, 256
	s_lshl_b32 s75, s83, 7
	s_add_u32 s74, s74, s75
	s_lshl_b32 s75, s74, 7
	s_add_u32 s16, s60, s75
	s_addc_u32 s17, s61, 0
	s_lshl_b32 s75, s74, 1
	s_add_u32 s24, s64, s75
	s_addc_u32 s25, s65, 0
	s_add_u32 m0, s70, 0xc000
	s_nop 0
	global_load_lds_dwordx4 v232, s[16:17]
	s_add_u32 m0, s70, 0xe000
	s_nop 0
	global_load_lds_dwordx4 v233, s[16:17]
	s_add_u32 m0, s70, 0x1c000
	s_nop 0
	global_load_lds_dwordx4 v234, s[24:25]
	s_add_u32 m0, s70, 0x1e000
	s_nop 0
	global_load_lds_dwordx4 v235, s[24:25]
	s_lshl_b32 s74, s83, 11
	s_add_u32 s74, s74, s84
	s_lshl_b32 s75, s74, 7
	s_add_u32 s10, s30, s75
	s_addc_u32 s11, s31, 0
	s_add_u32 s12, s34, s75
	s_addc_u32 s13, s35, 0
	s_lshl_b32 s75, s74, 2
	s_add_u32 s14, s58, s75
	s_addc_u32 s15, s59, 0
	global_load_dwordx4 v[104:107], v236, s[10:11]
	global_load_dwordx4 v[108:111], v236, s[10:11] offset:64
	global_load_dwordx2 v[122:123], v237, s[12:13]
	global_load_dwordx2 v[124:125], v237, s[12:13] offset:32
	global_load_dwordx2 v[126:127], v237, s[12:13] offset:64
	global_load_dwordx2 v[128:129], v237, s[12:13] offset:96
	global_load_dword v121, v238, s[14:15]
	s_waitcnt lgkmcnt(0)
	v_mfma_f32_16x16x32_bf16 v[44:47], v[4:7], v[96:99], 0
	v_mfma_f32_16x16x32_bf16 v[48:51], v[12:15], v[96:99], 0
	v_mfma_f32_16x16x32_bf16 v[52:55], v[20:23], v[96:99], 0
	v_mfma_f32_16x16x32_bf16 v[56:59], v[28:31], v[96:99], 0
	v_mfma_f32_16x16x32_bf16 v[60:63], v[36:39], v[96:99], 0
	v_mfma_f32_16x16x32_bf16 v[44:47], v[8:11], v[100:103], v[44:47]
	v_mfma_f32_16x16x32_bf16 v[48:51], v[16:19], v[100:103], v[48:51]
	v_mfma_f32_16x16x32_bf16 v[52:55], v[24:27], v[100:103], v[52:55]
	v_mfma_f32_16x16x32_bf16 v[56:59], v[32:35], v[100:103], v[56:59]
	v_mfma_f32_16x16x32_bf16 v[60:63], v[40:43], v[100:103], v[60:63]
	ds_read_b128 v[4:7], v230 offset:26624
	ds_read_b128 v[8:11], v231 offset:26624
	ds_read_b128 v[12:15], v230 offset:28672
	ds_read_b128 v[16:19], v231 offset:28672
	ds_read_b128 v[20:23], v230 offset:30720
	ds_read_b128 v[24:27], v231 offset:30720
	ds_read_b128 v[28:31], v230 offset:32768
	ds_read_b128 v[32:35], v231 offset:32768
	s_nop 1
	v_fma_f32 v44, v44, s79, v185
	v_fma_f32 v45, v45, s79, v186
	v_fma_f32 v46, v46, s79, v187
	v_fma_f32 v47, v47, s79, v188
	v_fma_f32 v48, v48, s79, v189
	v_fma_f32 v49, v49, s79, v190
	v_fma_f32 v50, v50, s79, v191
	v_fma_f32 v51, v51, s79, v192
	v_fma_f32 v52, v52, s79, v193
	v_fma_f32 v53, v53, s79, v194
	v_fma_f32 v54, v54, s79, v195
	v_fma_f32 v55, v55, s79, v196
	v_fma_f32 v56, v56, s79, v197
	v_fma_f32 v57, v57, s79, v198
	v_fma_f32 v58, v58, s79, v199
	v_fma_f32 v59, v59, s79, v200
	v_fma_f32 v60, v60, s79, v201
	v_fma_f32 v61, v61, s79, v202
	v_fma_f32 v62, v62, s79, v203
	v_fma_f32 v63, v63, s79, v204
	s_waitcnt lgkmcnt(0)
	v_mfma_f32_16x16x32_bf16 v[64:67], v[4:7], v[96:99], 0
	v_mfma_f32_16x16x32_bf16 v[68:71], v[12:15], v[96:99], 0
	v_mfma_f32_16x16x32_bf16 v[72:75], v[20:23], v[96:99], 0
	v_mfma_f32_16x16x32_bf16 v[76:79], v[28:31], v[96:99], 0
	v_mfma_f32_16x16x32_bf16 v[64:67], v[8:11], v[100:103], v[64:67]
	v_mfma_f32_16x16x32_bf16 v[68:71], v[16:19], v[100:103], v[68:71]
	v_mfma_f32_16x16x32_bf16 v[72:75], v[24:27], v[100:103], v[72:75]
	v_mfma_f32_16x16x32_bf16 v[76:79], v[32:35], v[100:103], v[76:79]
	ds_read_b64 v[4:5], v221 offset:16384
	ds_read_b64 v[8:9], v221 offset:20480
	ds_read_b64 v[12:13], v221 offset:24576
	ds_read_b64 v[16:17], v221 offset:28672
	ds_read_b64 v[6:7], v222 offset:16384
	ds_read_b64 v[10:11], v222 offset:20480
	ds_read_b64 v[14:15], v222 offset:24576
	ds_read_b64 v[18:19], v222 offset:28672
	s_nop 1
	v_fma_f32 v64, v64, s79, v205
	v_fma_f32 v65, v65, s79, v206
	v_fma_f32 v66, v66, s79, v207
	v_fma_f32 v67, v67, s79, v208
	v_fma_f32 v68, v68, s79, v209
	v_fma_f32 v69, v69, s79, v210
	v_fma_f32 v70, v70, s79, v211
	v_fma_f32 v71, v71, s79, v212
	v_fma_f32 v72, v72, s79, v213
	v_fma_f32 v73, v73, s79, v214
	v_fma_f32 v74, v74, s79, v215
	v_fma_f32 v75, v75, s79, v216
	v_fma_f32 v76, v76, s79, v217
	v_fma_f32 v77, v77, s79, v218
	v_fma_f32 v78, v78, s79, v219
	v_fma_f32 v79, v79, s79, v220
	ds_read_b64 v[20:21], v223 offset:16384
	ds_read_b64 v[24:25], v223 offset:20480
	ds_read_b64 v[28:29], v223 offset:24576
	ds_read_b64 v[32:33], v223 offset:28672
	ds_read_b64 v[22:23], v224 offset:16384
	ds_read_b64 v[26:27], v224 offset:20480
	ds_read_b64 v[30:31], v224 offset:24576
	ds_read_b64 v[34:35], v224 offset:28672
	s_cmp_lg_u32 s4, 0
	s_cbranch_scc1 .Lat991_i2_nomask
	s_cmp_le_u32 s6, 0
	s_cbranch_scc1 .Lat991_i2_nomask
	v_mov_b32_e32 v44, v244
	v_mov_b32_e32 v45, v244
	v_mov_b32_e32 v46, v244
	v_mov_b32_e32 v47, v244
	s_cmp_le_u32 s6, 1
	s_cbranch_scc1 .Lat991_i2_nomask
	v_mov_b32_e32 v48, v244
	v_mov_b32_e32 v49, v244
	v_mov_b32_e32 v50, v244
	v_mov_b32_e32 v51, v244
	s_cmp_le_u32 s6, 2
	s_cbranch_scc1 .Lat991_i2_nomask
	v_mov_b32_e32 v52, v244
	v_mov_b32_e32 v53, v244
	v_mov_b32_e32 v54, v244
	v_mov_b32_e32 v55, v244
	s_cmp_le_u32 s6, 3
	s_cbranch_scc1 .Lat991_i2_nomask
	v_mov_b32_e32 v56, v244
	v_mov_b32_e32 v57, v244
	v_mov_b32_e32 v58, v244
	v_mov_b32_e32 v59, v244
	s_cmp_le_u32 s6, 4
	s_cbranch_scc1 .Lat991_i2_nomask
	v_mov_b32_e32 v60, v244
	v_mov_b32_e32 v61, v244
	v_mov_b32_e32 v62, v244
	v_mov_b32_e32 v63, v244
	s_cmp_le_u32 s6, 5
	s_cbranch_scc1 .Lat991_i2_nomask
	v_mov_b32_e32 v64, v244
	v_mov_b32_e32 v65, v244
	v_mov_b32_e32 v66, v244
	v_mov_b32_e32 v67, v244
	s_cmp_le_u32 s6, 6
	s_cbranch_scc1 .Lat991_i2_nomask
	v_mov_b32_e32 v68, v244
	v_mov_b32_e32 v69, v244
	v_mov_b32_e32 v70, v244
	v_mov_b32_e32 v71, v244
	s_cmp_le_u32 s6, 7
	s_cbranch_scc1 .Lat991_i2_nomask
	v_mov_b32_e32 v72, v244
	v_mov_b32_e32 v73, v244
	v_mov_b32_e32 v74, v244
	v_mov_b32_e32 v75, v244
.Lat991_i2_nomask:
	v_max3_f32 v245, v44, v45, v46
	v_max3_f32 v245, v245, v47, v48
	v_max3_f32 v245, v245, v49, v50
	v_max3_f32 v245, v245, v51, v52
	v_max3_f32 v245, v245, v53, v54
	v_max3_f32 v245, v245, v55, v56
	v_max3_f32 v245, v245, v57, v58
	v_max3_f32 v245, v245, v59, v60
	v_max3_f32 v245, v245, v61, v62
	v_max3_f32 v245, v245, v63, v64
	v_max3_f32 v245, v245, v65, v66
	v_max3_f32 v245, v245, v67, v68
	v_max3_f32 v245, v245, v69, v70
	v_max3_f32 v245, v245, v71, v72
	v_max3_f32 v245, v245, v73, v74
	v_max3_f32 v245, v245, v75, v76
	v_max3_f32 v245, v245, v77, v78
	v_max_f32_e32 v245, v245, v79
	ds_bpermute_b32 v148, v239, v245
	s_waitcnt lgkmcnt(0)
	v_max_f32_e32 v245, v245, v148
	ds_bpermute_b32 v148, v240, v245
	s_waitcnt lgkmcnt(0)
	v_max_f32_e32 v245, v245, v148
	v_sub_f32_e32 v44, v44, v245
	v_sub_f32_e32 v45, v45, v245
	v_sub_f32_e32 v46, v46, v245
	v_sub_f32_e32 v47, v47, v245
	v_exp_f32_e32 v44, v44
	v_exp_f32_e32 v45, v45
	v_exp_f32_e32 v46, v46
	v_exp_f32_e32 v47, v47
	v_sub_f32_e32 v48, v48, v245
	v_sub_f32_e32 v49, v49, v245
	v_sub_f32_e32 v50, v50, v245
	v_sub_f32_e32 v51, v51, v245
	v_exp_f32_e32 v48, v48
	v_exp_f32_e32 v49, v49
	v_exp_f32_e32 v50, v50
	v_exp_f32_e32 v51, v51
	v_mov_b32_e32 v149, v44
	v_mov_b32_e32 v150, v45
	v_mov_b32_e32 v151, v46
	v_mov_b32_e32 v152, v47
	v_cvt_pk_bf16_f32 v44, v44, v45
	v_cvt_pk_bf16_f32 v45, v46, v47
	v_sub_f32_e32 v52, v52, v245
	v_sub_f32_e32 v53, v53, v245
	v_sub_f32_e32 v54, v54, v245
	v_sub_f32_e32 v55, v55, v245
	v_exp_f32_e32 v52, v52
	v_exp_f32_e32 v53, v53
	v_exp_f32_e32 v54, v54
	v_exp_f32_e32 v55, v55
	v_add_f32_e32 v149, v149, v48
	v_add_f32_e32 v150, v150, v49
	v_add_f32_e32 v151, v151, v50
	v_add_f32_e32 v152, v152, v51
	v_cvt_pk_bf16_f32 v46, v48, v49
	v_cvt_pk_bf16_f32 v47, v50, v51
	v_sub_f32_e32 v56, v56, v245
	v_sub_f32_e32 v57, v57, v245
	v_sub_f32_e32 v58, v58, v245
	v_sub_f32_e32 v59, v59, v245
	v_exp_f32_e32 v56, v56
	v_exp_f32_e32 v57, v57
	v_exp_f32_e32 v58, v58
	v_exp_f32_e32 v59, v59
	v_add_f32_e32 v149, v149, v52
	v_add_f32_e32 v150, v150, v53
	v_add_f32_e32 v151, v151, v54
	v_add_f32_e32 v152, v152, v55
	v_cvt_pk_bf16_f32 v52, v52, v53
	v_cvt_pk_bf16_f32 v53, v54, v55
	v_sub_f32_e32 v60, v60, v245
	v_sub_f32_e32 v61, v61, v245
	v_sub_f32_e32 v62, v62, v245
	v_sub_f32_e32 v63, v63, v245
	v_exp_f32_e32 v60, v60
	v_exp_f32_e32 v61, v61
	v_exp_f32_e32 v62, v62
	v_exp_f32_e32 v63, v63
	v_add_f32_e32 v149, v149, v56
	v_add_f32_e32 v150, v150, v57
	v_add_f32_e32 v151, v151, v58
	v_add_f32_e32 v152, v152, v59
	v_cvt_pk_bf16_f32 v54, v56, v57
	v_cvt_pk_bf16_f32 v55, v58, v59
	v_sub_f32_e32 v64, v64, v245
	v_sub_f32_e32 v65, v65, v245
	v_sub_f32_e32 v66, v66, v245
	v_sub_f32_e32 v67, v67, v245
	v_exp_f32_e32 v64, v64
	v_exp_f32_e32 v65, v65
	v_exp_f32_e32 v66, v66
	v_exp_f32_e32 v67, v67
	v_add_f32_e32 v149, v149, v60
	v_add_f32_e32 v150, v150, v61
	v_add_f32_e32 v151, v151, v62
	v_add_f32_e32 v152, v152, v63
	v_cvt_pk_bf16_f32 v60, v60, v61
	v_cvt_pk_bf16_f32 v61, v62, v63
	v_sub_f32_e32 v68, v68, v245
	v_sub_f32_e32 v69, v69, v245
	v_sub_f32_e32 v70, v70, v245
	v_sub_f32_e32 v71, v71, v245
	v_exp_f32_e32 v68, v68
	v_exp_f32_e32 v69, v69
	v_exp_f32_e32 v70, v70
	v_exp_f32_e32 v71, v71
	v_add_f32_e32 v149, v149, v64
	v_add_f32_e32 v150, v150, v65
	v_add_f32_e32 v151, v151, v66
	v_add_f32_e32 v152, v152, v67
	v_cvt_pk_bf16_f32 v62, v64, v65
	v_cvt_pk_bf16_f32 v63, v66, v67
	v_sub_f32_e32 v72, v72, v245
	v_sub_f32_e32 v73, v73, v245
	v_sub_f32_e32 v74, v74, v245
	v_sub_f32_e32 v75, v75, v245
	v_exp_f32_e32 v72, v72
	v_exp_f32_e32 v73, v73
	v_exp_f32_e32 v74, v74
	v_exp_f32_e32 v75, v75
	v_add_f32_e32 v149, v149, v68
	v_add_f32_e32 v150, v150, v69
	v_add_f32_e32 v151, v151, v70
	v_add_f32_e32 v152, v152, v71
	v_cvt_pk_bf16_f32 v68, v68, v69
	v_cvt_pk_bf16_f32 v69, v70, v71
	v_sub_f32_e32 v76, v76, v245
	v_sub_f32_e32 v77, v77, v245
	v_sub_f32_e32 v78, v78, v245
	v_sub_f32_e32 v79, v79, v245
	v_exp_f32_e32 v76, v76
	v_exp_f32_e32 v77, v77
	v_exp_f32_e32 v78, v78
	v_exp_f32_e32 v79, v79
	v_add_f32_e32 v149, v149, v72
	v_add_f32_e32 v150, v150, v73
	v_add_f32_e32 v151, v151, v74
	v_add_f32_e32 v152, v152, v75
	v_cvt_pk_bf16_f32 v70, v72, v73
	v_cvt_pk_bf16_f32 v71, v74, v75
	s_nop 0
	v_add_f32_e32 v149, v149, v76
	v_add_f32_e32 v150, v150, v77
	v_add_f32_e32 v151, v151, v78
	v_add_f32_e32 v152, v152, v79
	v_cvt_pk_bf16_f32 v76, v76, v77
	v_cvt_pk_bf16_f32 v77, v78, v79
	v_mov_b32_e32 v78, 0
	v_mov_b32_e32 v79, 0
	v_add_f32_e32 v149, v149, v150
	v_add_f32_e32 v151, v151, v152
	v_add_f32_e32 v246, v149, v151
	s_waitcnt lgkmcnt(0)
	v_mfma_f32_16x16x32_bf16 v[80:83], v[4:7], v[44:47], 0
	v_mfma_f32_16x16x32_bf16 v[84:87], v[8:11], v[44:47], 0
	v_mfma_f32_16x16x32_bf16 v[88:91], v[12:15], v[44:47], 0
	v_mfma_f32_16x16x32_bf16 v[92:95], v[16:19], v[44:47], 0
	ds_read_b64 v[4:5], v225 offset:16384
	ds_read_b64 v[8:9], v225 offset:20480
	ds_read_b64 v[12:13], v225 offset:24576
	ds_read_b64 v[16:17], v225 offset:28672
	ds_read_b64 v[6:7], v226 offset:16384
	ds_read_b64 v[10:11], v226 offset:20480
	ds_read_b64 v[14:15], v226 offset:24576
	ds_read_b64 v[18:19], v226 offset:28672
	v_mfma_f32_16x16x32_bf16 v[80:83], v[20:23], v[52:55], v[80:83]
	v_mfma_f32_16x16x32_bf16 v[84:87], v[24:27], v[52:55], v[84:87]
	v_mfma_f32_16x16x32_bf16 v[88:91], v[28:31], v[52:55], v[88:91]
	v_mfma_f32_16x16x32_bf16 v[92:95], v[32:35], v[52:55], v[92:95]
	ds_read_b64 v[20:21], v227 offset:16384
	ds_read_b64 v[24:25], v227 offset:20480
	ds_read_b64 v[28:29], v227 offset:24576
	ds_read_b64 v[32:33], v227 offset:28672
	ds_read_b64 v[22:23], v228 offset:16384
	ds_read_b64 v[26:27], v228 offset:20480
	ds_read_b64 v[30:31], v228 offset:24576
	ds_read_b64 v[34:35], v228 offset:28672
	ds_bpermute_b32 v148, v239, v246
	s_waitcnt lgkmcnt(9)
	v_mfma_f32_16x16x32_bf16 v[80:83], v[4:7], v[60:63], v[80:83]
	v_mfma_f32_16x16x32_bf16 v[84:87], v[8:11], v[60:63], v[84:87]
	v_mfma_f32_16x16x32_bf16 v[88:91], v[12:15], v[60:63], v[88:91]
	v_mfma_f32_16x16x32_bf16 v[92:95], v[16:19], v[60:63], v[92:95]
	ds_read_b64 v[4:5], v229 offset:16384
	ds_read_b64 v[8:9], v229 offset:20480
	ds_read_b64 v[12:13], v229 offset:24576
	ds_read_b64 v[16:17], v229 offset:28672
	v_mov_b32_e32 v6, 0
	v_mov_b32_e32 v7, 0
	v_mov_b32_e32 v10, 0
	v_mov_b32_e32 v11, 0
	v_mov_b32_e32 v14, 0
	v_mov_b32_e32 v15, 0
	v_mov_b32_e32 v18, 0
	v_mov_b32_e32 v19, 0
	s_waitcnt lgkmcnt(5)
	v_mfma_f32_16x16x32_bf16 v[80:83], v[20:23], v[68:71], v[80:83]
	v_mfma_f32_16x16x32_bf16 v[84:87], v[24:27], v[68:71], v[84:87]
	v_mfma_f32_16x16x32_bf16 v[88:91], v[28:31], v[68:71], v[88:91]
	v_mfma_f32_16x16x32_bf16 v[92:95], v[32:35], v[68:71], v[92:95]
	s_waitcnt lgkmcnt(0)
	v_add_f32_e32 v246, v246, v148
	s_nop 0
	v_mfma_f32_16x16x32_bf16 v[80:83], v[4:7], v[76:79], v[80:83]
	v_mfma_f32_16x16x32_bf16 v[84:87], v[8:11], v[76:79], v[84:87]
	v_mfma_f32_16x16x32_bf16 v[88:91], v[12:15], v[76:79], v[88:91]
	v_mfma_f32_16x16x32_bf16 v[92:95], v[16:19], v[76:79], v[92:95]
	ds_bpermute_b32 v148, v240, v246
	s_waitcnt lgkmcnt(0)
	v_add_f32_e32 v246, v246, v148
	v_rcp_f32_e32 v149, v246
	v_log_f32_e32 v150, v246
	s_nop 0
	v_add_f32_e32 v151, v245, v150
	v_mul_f32_e32 v151, 0x3f317218, v151
	v_max_f32_e32 v152, v120, v151
	v_sub_f32_e32 v153, v120, v152
	v_sub_f32_e32 v154, v151, v152
	v_mul_f32_e32 v153, 0x3fb8aa3b, v153
	v_mul_f32_e32 v154, 0x3fb8aa3b, v154
	v_exp_f32_e32 v153, v153
	v_exp_f32_e32 v154, v154
	s_nop 0
	v_add_f32_e32 v155, v153, v154
	v_rcp_f32_e32 v146, v155
	v_log_f32_e32 v150, v155
	s_nop 0
	v_mul_f32_e32 v154, v154, v146
	v_mul_f32_e32 v146, v153, v146
	v_mul_f32_e32 v147, v149, v154
	v_mul_f32_e32 v150, 0x3f317218, v150
	v_add_f32_e32 v140, v152, v150
	v_mul_f32_e32 v80, v80, v147
	v_mul_f32_e32 v81, v81, v147
	v_mul_f32_e32 v82, v82, v147
	v_mul_f32_e32 v83, v83, v147
	v_mul_f32_e32 v84, v84, v147
	v_mul_f32_e32 v85, v85, v147
	v_mul_f32_e32 v86, v86, v147
	v_mul_f32_e32 v87, v87, v147
	v_mul_f32_e32 v88, v88, v147
	v_mul_f32_e32 v89, v89, v147
	v_mul_f32_e32 v90, v90, v147
	v_mul_f32_e32 v91, v91, v147
	v_mul_f32_e32 v92, v92, v147
	v_mul_f32_e32 v93, v93, v147
	v_mul_f32_e32 v94, v94, v147
	v_mul_f32_e32 v95, v95, v147
	v_lshlrev_b32_e32 v141, 16, v112
	v_and_b32_e32 v142, 0xffff0000, v112
	v_lshlrev_b32_e32 v143, 16, v113
	v_and_b32_e32 v144, 0xffff0000, v113
	v_fmac_f32_e32 v80, v146, v141
	v_fmac_f32_e32 v81, v146, v142
	v_fmac_f32_e32 v82, v146, v143
	v_fmac_f32_e32 v83, v146, v144
	v_cvt_pk_bf16_f32 v132, v80, v81
	v_cvt_pk_bf16_f32 v133, v82, v83
	v_lshlrev_b32_e32 v141, 16, v114
	v_and_b32_e32 v142, 0xffff0000, v114
	v_lshlrev_b32_e32 v143, 16, v115
	v_and_b32_e32 v144, 0xffff0000, v115
	v_fmac_f32_e32 v84, v146, v141
	v_fmac_f32_e32 v85, v146, v142
	v_fmac_f32_e32 v86, v146, v143
	v_fmac_f32_e32 v87, v146, v144
	v_cvt_pk_bf16_f32 v134, v84, v85
	v_cvt_pk_bf16_f32 v135, v86, v87
	v_lshlrev_b32_e32 v141, 16, v116
	v_and_b32_e32 v142, 0xffff0000, v116
	v_lshlrev_b32_e32 v143, 16, v117
	v_and_b32_e32 v144, 0xffff0000, v117
	v_fmac_f32_e32 v88, v146, v141
	v_fmac_f32_e32 v89, v146, v142
	v_fmac_f32_e32 v90, v146, v143
	v_fmac_f32_e32 v91, v146, v144
	v_cvt_pk_bf16_f32 v136, v88, v89
	v_cvt_pk_bf16_f32 v137, v90, v91
	v_lshlrev_b32_e32 v141, 16, v118
	v_and_b32_e32 v142, 0xffff0000, v118
	v_lshlrev_b32_e32 v143, 16, v119
	v_and_b32_e32 v144, 0xffff0000, v119
	v_fmac_f32_e32 v92, v146, v141
	v_fmac_f32_e32 v93, v146, v142
	v_fmac_f32_e32 v94, v146, v143
	v_fmac_f32_e32 v95, v146, v144
	v_cvt_pk_bf16_f32 v138, v92, v93
	v_cvt_pk_bf16_f32 v139, v94, v95
	s_mov_b64 s[26:27], s[86:87]
	s_mov_b64 s[28:29], s[88:89]
	s_mov_b64 s[86:87], s[12:13]
	s_mov_b64 s[88:89], s[14:15]
	s_mov_b32 s4, s83
	s_mov_b32 s5, s84
	s_waitcnt vmcnt(0)
	s_barrier
	ds_read_b128 v[4:7], v230 offset:32768
	ds_read_b128 v[8:11], v231 offset:32768
	ds_read_b128 v[12:15], v230 offset:34816
	ds_read_b128 v[16:19], v231 offset:34816
	ds_read_b128 v[20:23], v230 offset:36864
	ds_read_b128 v[24:27], v231 offset:36864
	ds_read_b128 v[28:31], v230 offset:38912
	ds_read_b128 v[32:35], v231 offset:38912
	ds_read_b128 v[36:39], v230 offset:40960
	ds_read_b128 v[40:43], v231 offset:40960
	global_store_dwordx2 v237, v[132:133], s[26:27]
	global_store_dwordx2 v237, v[134:135], s[26:27] offset:32
	global_store_dwordx2 v237, v[136:137], s[26:27] offset:64
	global_store_dwordx2 v237, v[138:139], s[26:27] offset:96
	s_mov_b64 s[90:91], exec
	s_mov_b64 exec, 0xffff
	global_store_dword v238, v140, s[28:29]
	s_mov_b64 exec, s[90:91]
	s_cmp_eq_u32 s7, 1
	s_cbranch_scc1 .Lat991_i3_nonext
	s_add_u32 s84, s5, s4
	s_xor_b32 s83, s4, 1
	s_mul_i32 s74, s84, 256
	s_lshl_b32 s75, s83, 7
	s_add_u32 s74, s74, s75
	s_lshl_b32 s75, s74, 7
	s_add_u32 s16, s60, s75
	s_addc_u32 s17, s61, 0
	s_lshl_b32 s75, s74, 1
	s_add_u32 s24, s64, s75
	s_addc_u32 s25, s65, 0
	s_add_u32 m0, s70, 0x0
	s_nop 0
	global_load_lds_dwordx4 v232, s[16:17]
	s_add_u32 m0, s70, 0x2000
	s_nop 0
	global_load_lds_dwordx4 v233, s[16:17]
	s_add_u32 m0, s70, 0x10000
	s_nop 0
	global_load_lds_dwordx4 v234, s[24:25]
	s_add_u32 m0, s70, 0x12000
	s_nop 0
	global_load_lds_dwordx4 v235, s[24:25]
	s_lshl_b32 s74, s83, 11
	s_add_u32 s74, s74, s84
	s_lshl_b32 s75, s74, 7
	s_add_u32 s10, s30, s75
	s_addc_u32 s11, s31, 0
	s_add_u32 s12, s34, s75
	s_addc_u32 s13, s35, 0
	s_lshl_b32 s75, s74, 2
	s_add_u32 s14, s58, s75
	s_addc_u32 s15, s59, 0
	global_load_dwordx4 v[96:99], v236, s[10:11]
	global_load_dwordx4 v[100:103], v236, s[10:11] offset:64
	global_load_dwordx2 v[112:113], v237, s[12:13]
	global_load_dwordx2 v[114:115], v237, s[12:13] offset:32
	global_load_dwordx2 v[116:117], v237, s[12:13] offset:64
	global_load_dwordx2 v[118:119], v237, s[12:13] offset:96
	global_load_dword v120, v238, s[14:15]

.Lat991_i3_nomask:
	v_max3_f32 v245, v44, v45, v46
	v_max3_f32 v245, v245, v47, v48
	v_max3_f32 v245, v245, v49, v50
	v_max3_f32 v245, v245, v51, v52
	v_max3_f32 v245, v245, v53, v54
	v_max3_f32 v245, v245, v55, v56
	v_max3_f32 v245, v245, v57, v58
	v_max3_f32 v245, v245, v59, v60
	v_max3_f32 v245, v245, v61, v62
	v_max3_f32 v245, v245, v63, v64
	v_max3_f32 v245, v245, v65, v66
	v_max3_f32 v245, v245, v67, v68
	v_max3_f32 v245, v245, v69, v70
	v_max3_f32 v245, v245, v71, v72
	v_max3_f32 v245, v245, v73, v74
	v_max3_f32 v245, v245, v75, v76
	v_max3_f32 v245, v245, v77, v78
	v_max_f32_e32 v245, v245, v79
	ds_bpermute_b32 v148, v239, v245
	s_waitcnt lgkmcnt(0)
	v_max_f32_e32 v245, v245, v148
	ds_bpermute_b32 v148, v240, v245
	s_waitcnt lgkmcnt(0)
	v_max_f32_e32 v245, v245, v148
	v_sub_f32_e32 v44, v44, v245
	v_sub_f32_e32 v45, v45, v245
	v_sub_f32_e32 v46, v46, v245
	v_sub_f32_e32 v47, v47, v245
	v_exp_f32_e32 v44, v44
	v_exp_f32_e32 v45, v45
	v_exp_f32_e32 v46, v46
	v_exp_f32_e32 v47, v47
	v_sub_f32_e32 v48, v48, v245
	v_sub_f32_e32 v49, v49, v245
	v_sub_f32_e32 v50, v50, v245
	v_sub_f32_e32 v51, v51, v245
	v_exp_f32_e32 v48, v48
	v_exp_f32_e32 v49, v49
	v_exp_f32_e32 v50, v50
	v_exp_f32_e32 v51, v51
	v_mov_b32_e32 v149, v44
	v_mov_b32_e32 v150, v45
	v_mov_b32_e32 v151, v46
	v_mov_b32_e32 v152, v47
	v_cvt_pk_bf16_f32 v44, v44, v45
	v_cvt_pk_bf16_f32 v45, v46, v47
	v_sub_f32_e32 v52, v52, v245
	v_sub_f32_e32 v53, v53, v245
	v_sub_f32_e32 v54, v54, v245
	v_sub_f32_e32 v55, v55, v245
	v_exp_f32_e32 v52, v52
	v_exp_f32_e32 v53, v53
	v_exp_f32_e32 v54, v54
	v_exp_f32_e32 v55, v55
	v_add_f32_e32 v149, v149, v48
	v_add_f32_e32 v150, v150, v49
	v_add_f32_e32 v151, v151, v50
	v_add_f32_e32 v152, v152, v51
	v_cvt_pk_bf16_f32 v46, v48, v49
	v_cvt_pk_bf16_f32 v47, v50, v51
	v_sub_f32_e32 v56, v56, v245
	v_sub_f32_e32 v57, v57, v245
	v_sub_f32_e32 v58, v58, v245
	v_sub_f32_e32 v59, v59, v245
	v_exp_f32_e32 v56, v56
	v_exp_f32_e32 v57, v57
	v_exp_f32_e32 v58, v58
	v_exp_f32_e32 v59, v59
	v_add_f32_e32 v149, v149, v52
	v_add_f32_e32 v150, v150, v53
	v_add_f32_e32 v151, v151, v54
	v_add_f32_e32 v152, v152, v55
	v_cvt_pk_bf16_f32 v52, v52, v53
	v_cvt_pk_bf16_f32 v53, v54, v55
	v_sub_f32_e32 v60, v60, v245
	v_sub_f32_e32 v61, v61, v245
	v_sub_f32_e32 v62, v62, v245
	v_sub_f32_e32 v63, v63, v245
	v_exp_f32_e32 v60, v60
	v_exp_f32_e32 v61, v61
	v_exp_f32_e32 v62, v62
	v_exp_f32_e32 v63, v63
	v_add_f32_e32 v149, v149, v56
	v_add_f32_e32 v150, v150, v57
	v_add_f32_e32 v151, v151, v58
	v_add_f32_e32 v152, v152, v59
	v_cvt_pk_bf16_f32 v54, v56, v57
	v_cvt_pk_bf16_f32 v55, v58, v59
	v_sub_f32_e32 v64, v64, v245
	v_sub_f32_e32 v65, v65, v245
	v_sub_f32_e32 v66, v66, v245
	v_sub_f32_e32 v67, v67, v245
	v_exp_f32_e32 v64, v64
	v_exp_f32_e32 v65, v65
	v_exp_f32_e32 v66, v66
	v_exp_f32_e32 v67, v67
	v_add_f32_e32 v149, v149, v60
	v_add_f32_e32 v150, v150, v61
	v_add_f32_e32 v151, v151, v62
	v_add_f32_e32 v152, v152, v63
	v_cvt_pk_bf16_f32 v60, v60, v61
	v_cvt_pk_bf16_f32 v61, v62, v63
	v_sub_f32_e32 v68, v68, v245
	v_sub_f32_e32 v69, v69, v245
	v_sub_f32_e32 v70, v70, v245
	v_sub_f32_e32 v71, v71, v245
	v_exp_f32_e32 v68, v68
	v_exp_f32_e32 v69, v69
	v_exp_f32_e32 v70, v70
	v_exp_f32_e32 v71, v71
	v_add_f32_e32 v149, v149, v64
	v_add_f32_e32 v150, v150, v65
	v_add_f32_e32 v151, v151, v66
	v_add_f32_e32 v152, v152, v67
	v_cvt_pk_bf16_f32 v62, v64, v65
	v_cvt_pk_bf16_f32 v63, v66, v67
	v_sub_f32_e32 v72, v72, v245
	v_sub_f32_e32 v73, v73, v245
	v_sub_f32_e32 v74, v74, v245
	v_sub_f32_e32 v75, v75, v245
	v_exp_f32_e32 v72, v72
	v_exp_f32_e32 v73, v73
	v_exp_f32_e32 v74, v74
	v_exp_f32_e32 v75, v75
	v_add_f32_e32 v149, v149, v68
	v_add_f32_e32 v150, v150, v69
	v_add_f32_e32 v151, v151, v70
	v_add_f32_e32 v152, v152, v71
	v_cvt_pk_bf16_f32 v68, v68, v69
	v_cvt_pk_bf16_f32 v69, v70, v71
	v_sub_f32_e32 v76, v76, v245
	v_sub_f32_e32 v77, v77, v245
	v_sub_f32_e32 v78, v78, v245
	v_sub_f32_e32 v79, v79, v245
	v_exp_f32_e32 v76, v76
	v_exp_f32_e32 v77, v77
	v_exp_f32_e32 v78, v78
	v_exp_f32_e32 v79, v79
	v_add_f32_e32 v149, v149, v72
	v_add_f32_e32 v150, v150, v73
	v_add_f32_e32 v151, v151, v74
	v_add_f32_e32 v152, v152, v75
	v_cvt_pk_bf16_f32 v70, v72, v73
	v_cvt_pk_bf16_f32 v71, v74, v75
	s_nop 0
	v_add_f32_e32 v149, v149, v76
	v_add_f32_e32 v150, v150, v77
	v_add_f32_e32 v151, v151, v78
	v_add_f32_e32 v152, v152, v79
	v_cvt_pk_bf16_f32 v76, v76, v77
	v_cvt_pk_bf16_f32 v77, v78, v79
	v_mov_b32_e32 v78, 0
	v_mov_b32_e32 v79, 0
	v_add_f32_e32 v149, v149, v150
	v_add_f32_e32 v151, v151, v152
	v_add_f32_e32 v246, v149, v151
	s_waitcnt lgkmcnt(0)
	v_mfma_f32_16x16x32_bf16 v[80:83], v[4:7], v[44:47], 0
	v_mfma_f32_16x16x32_bf16 v[84:87], v[8:11], v[44:47], 0
	v_mfma_f32_16x16x32_bf16 v[88:91], v[12:15], v[44:47], 0
	v_mfma_f32_16x16x32_bf16 v[92:95], v[16:19], v[44:47], 0
	ds_read_b64 v[4:5], v225 offset:32768
	ds_read_b64 v[8:9], v225 offset:36864
	ds_read_b64 v[12:13], v225 offset:40960
	ds_read_b64 v[16:17], v225 offset:45056
	ds_read_b64 v[6:7], v226 offset:32768
	ds_read_b64 v[10:11], v226 offset:36864
	ds_read_b64 v[14:15], v226 offset:40960
	ds_read_b64 v[18:19], v226 offset:45056
	v_mfma_f32_16x16x32_bf16 v[80:83], v[20:23], v[52:55], v[80:83]
	v_mfma_f32_16x16x32_bf16 v[84:87], v[24:27], v[52:55], v[84:87]
	v_mfma_f32_16x16x32_bf16 v[88:91], v[28:31], v[52:55], v[88:91]
	v_mfma_f32_16x16x32_bf16 v[92:95], v[32:35], v[52:55], v[92:95]
	ds_read_b64 v[20:21], v227 offset:32768
	ds_read_b64 v[24:25], v227 offset:36864
	ds_read_b64 v[28:29], v227 offset:40960
	ds_read_b64 v[32:33], v227 offset:45056
	ds_read_b64 v[22:23], v228 offset:32768
	ds_read_b64 v[26:27], v228 offset:36864
	ds_read_b64 v[30:31], v228 offset:40960
	ds_read_b64 v[34:35], v228 offset:45056
	ds_bpermute_b32 v148, v239, v246
	s_waitcnt lgkmcnt(9)
	v_mfma_f32_16x16x32_bf16 v[80:83], v[4:7], v[60:63], v[80:83]
	v_mfma_f32_16x16x32_bf16 v[84:87], v[8:11], v[60:63], v[84:87]
	v_mfma_f32_16x16x32_bf16 v[88:91], v[12:15], v[60:63], v[88:91]
	v_mfma_f32_16x16x32_bf16 v[92:95], v[16:19], v[60:63], v[92:95]
	ds_read_b64 v[4:5], v229 offset:32768
	ds_read_b64 v[8:9], v229 offset:36864
	ds_read_b64 v[12:13], v229 offset:40960
	ds_read_b64 v[16:17], v229 offset:45056
	v_mov_b32_e32 v6, 0
	v_mov_b32_e32 v7, 0
	v_mov_b32_e32 v10, 0
	v_mov_b32_e32 v11, 0
	v_mov_b32_e32 v14, 0
	v_mov_b32_e32 v15, 0
	v_mov_b32_e32 v18, 0
	v_mov_b32_e32 v19, 0
	s_waitcnt lgkmcnt(5)
	v_mfma_f32_16x16x32_bf16 v[80:83], v[20:23], v[68:71], v[80:83]
	v_mfma_f32_16x16x32_bf16 v[84:87], v[24:27], v[68:71], v[84:87]
	v_mfma_f32_16x16x32_bf16 v[88:91], v[28:31], v[68:71], v[88:91]
	v_mfma_f32_16x16x32_bf16 v[92:95], v[32:35], v[68:71], v[92:95]
	s_waitcnt lgkmcnt(0)
	v_add_f32_e32 v246, v246, v148
	s_nop 0
	v_mfma_f32_16x16x32_bf16 v[80:83], v[4:7], v[76:79], v[80:83]
	v_mfma_f32_16x16x32_bf16 v[84:87], v[8:11], v[76:79], v[84:87]
	v_mfma_f32_16x16x32_bf16 v[88:91], v[12:15], v[76:79], v[88:91]
	v_mfma_f32_16x16x32_bf16 v[92:95], v[16:19], v[76:79], v[92:95]
	ds_bpermute_b32 v148, v240, v246
	s_waitcnt lgkmcnt(0)
	v_add_f32_e32 v246, v246, v148
	v_rcp_f32_e32 v149, v246
	v_log_f32_e32 v150, v246
	s_nop 0
	v_add_f32_e32 v151, v245, v150
	v_mul_f32_e32 v151, 0x3f317218, v151
	v_max_f32_e32 v152, v121, v151
	v_sub_f32_e32 v153, v121, v152
	v_sub_f32_e32 v154, v151, v152
	v_mul_f32_e32 v153, 0x3fb8aa3b, v153
	v_mul_f32_e32 v154, 0x3fb8aa3b, v154
	v_exp_f32_e32 v153, v153
	v_exp_f32_e32 v154, v154
	s_nop 0
	v_add_f32_e32 v155, v153, v154
	v_rcp_f32_e32 v146, v155
	v_log_f32_e32 v150, v155
	s_nop 0
	v_mul_f32_e32 v154, v154, v146
	v_mul_f32_e32 v146, v153, v146
	v_mul_f32_e32 v147, v149, v154
	v_mul_f32_e32 v150, 0x3f317218, v150
	v_add_f32_e32 v140, v152, v150
	v_mul_f32_e32 v80, v80, v147
	v_mul_f32_e32 v81, v81, v147
	v_mul_f32_e32 v82, v82, v147
	v_mul_f32_e32 v83, v83, v147
	v_mul_f32_e32 v84, v84, v147
	v_mul_f32_e32 v85, v85, v147
	v_mul_f32_e32 v86, v86, v147
	v_mul_f32_e32 v87, v87, v147
	v_mul_f32_e32 v88, v88, v147
	v_mul_f32_e32 v89, v89, v147
	v_mul_f32_e32 v90, v90, v147
	v_mul_f32_e32 v91, v91, v147
	v_mul_f32_e32 v92, v92, v147
	v_mul_f32_e32 v93, v93, v147
	v_mul_f32_e32 v94, v94, v147
	v_mul_f32_e32 v95, v95, v147
	v_lshlrev_b32_e32 v141, 16, v122
	v_and_b32_e32 v142, 0xffff0000, v122
	v_lshlrev_b32_e32 v143, 16, v123
	v_and_b32_e32 v144, 0xffff0000, v123
	v_fmac_f32_e32 v80, v146, v141
	v_fmac_f32_e32 v81, v146, v142
	v_fmac_f32_e32 v82, v146, v143
	v_fmac_f32_e32 v83, v146, v144
	v_cvt_pk_bf16_f32 v132, v80, v81
	v_cvt_pk_bf16_f32 v133, v82, v83
	v_lshlrev_b32_e32 v141, 16, v124
	v_and_b32_e32 v142, 0xffff0000, v124
	v_lshlrev_b32_e32 v143, 16, v125
	v_and_b32_e32 v144, 0xffff0000, v125
	v_fmac_f32_e32 v84, v146, v141
	v_fmac_f32_e32 v85, v146, v142
	v_fmac_f32_e32 v86, v146, v143
	v_fmac_f32_e32 v87, v146, v144
	v_cvt_pk_bf16_f32 v134, v84, v85
	v_cvt_pk_bf16_f32 v135, v86, v87
	v_lshlrev_b32_e32 v141, 16, v126
	v_and_b32_e32 v142, 0xffff0000, v126
	v_lshlrev_b32_e32 v143, 16, v127
	v_and_b32_e32 v144, 0xffff0000, v127
	v_fmac_f32_e32 v88, v146, v141
	v_fmac_f32_e32 v89, v146, v142
	v_fmac_f32_e32 v90, v146, v143
	v_fmac_f32_e32 v91, v146, v144
	v_cvt_pk_bf16_f32 v136, v88, v89
	v_cvt_pk_bf16_f32 v137, v90, v91
	v_lshlrev_b32_e32 v141, 16, v128
	v_and_b32_e32 v142, 0xffff0000, v128
	v_lshlrev_b32_e32 v143, 16, v129
	v_and_b32_e32 v144, 0xffff0000, v129
	v_fmac_f32_e32 v92, v146, v141
	v_fmac_f32_e32 v93, v146, v142
	v_fmac_f32_e32 v94, v146, v143
	v_fmac_f32_e32 v95, v146, v144
	v_cvt_pk_bf16_f32 v138, v92, v93
	v_cvt_pk_bf16_f32 v139, v94, v95
	s_mov_b64 s[26:27], s[86:87]
	s_mov_b64 s[28:29], s[88:89]
	s_mov_b64 s[86:87], s[12:13]
	s_mov_b64 s[88:89], s[14:15]
	s_mov_b32 s4, s83
	s_mov_b32 s5, s84
	s_add_u32 s7, s7, 1
	s_cmp_lt_u32 s7, 2
	s_cbranch_scc1 .Lat991_loop
	s_setprio 0
	global_store_dwordx2 v237, v[132:133], s[26:27]
	global_store_dwordx2 v237, v[134:135], s[26:27] offset:32
	global_store_dwordx2 v237, v[136:137], s[26:27] offset:64
	global_store_dwordx2 v237, v[138:139], s[26:27] offset:96
	s_mov_b64 s[90:91], exec
	s_mov_b64 exec, 0xffff
	global_store_dword v238, v140, s[28:29]
	s_mov_b64 exec, s[90:91]
	s_waitcnt vmcnt(0)
	s_barrier
	s_waitcnt vmcnt(0)
	s_barrier
	s_mov_b64 s[4:5], exec
	v_readlane_b32 s0, v252, 2
	v_readlane_b32 s1, v252, 3
	v_readlane_b32 s64, v253, 15
	v_readlane_b32 s34, v252, 27
	v_readlane_b32 s56, v253, 19
	v_readlane_b32 s16, v253, 21
	v_readlane_b32 s36, v252, 29
	v_readlane_b32 s70, v252, 31
	v_readlane_b32 s74, v252, 33
	v_readlane_b32 s76, v252, 35
	v_readlane_b32 s78, v252, 37
	s_and_b64 s[0:1], s[4:5], s[0:1]
	v_readlane_b32 s85, v253, 23
	v_readlane_b32 s92, v253, 24
	v_readlane_b32 s65, v253, 16
	v_readlane_b32 s63, v252, 26
	v_readlane_b32 s66, v253, 18
	v_readlane_b32 s35, v252, 28
	v_readlane_b32 s57, v253, 20
	v_readlane_b32 s17, v253, 22
	v_readlane_b32 s37, v252, 30
	v_readlane_b32 s71, v252, 32
	v_readlane_b32 s75, v252, 34
	v_readlane_b32 s77, v252, 36
	v_readlane_b32 s79, v252, 38
	v_readlane_b32 s93, v253, 25
	s_mov_b64 exec, s[0:1]
	s_cbranch_execz .LBB0_1061
	v_mov_b32_e32 v0, 0x20000
	ds_read_b64 v[0:1], v0
	s_getreg_b32 s44, hwreg(HW_REG_XCC_ID, 0, 4)
	s_lshl_b32 s44, s44, 7
	s_add_u32 s44, s44, 0xdc03600
	v_mov_b32_e32 v2, s44
	v_mov_b32_e32 v4, 1
	s_waitcnt vmcnt(0) lgkmcnt(0)
	global_atomic_add v5, v2, v4, s[42:43] sc0
	buffer_inv sc1
	s_add_u32 s100, s100, 1
	v_readfirstlane_b32 s46, v0
	v_readfirstlane_b32 s47, v1
	v_mov_b32_e32 v2, 0xdc03e00
	s_nop 3
	s_mul_i32 s48, s46, s100
	s_mul_i32 s49, s47, s100
	s_waitcnt vmcnt(1)
	v_readfirstlane_b32 s50, v5
	s_nop 3
	s_add_u32 s50, s50, 1
	s_cmp_lg_u32 s50, s48
	s_cbranch_scc1 .Lxb9_poll
	buffer_wbl2 sc1
	s_waitcnt vmcnt(0)
	global_atomic_add v2, v4, s[42:43]

.LBB0_1025:
	s_mov_b64 s[44:45], exec
	s_lshl_b32 s0, s0, 8
	v_readlane_b32 s2, v252, 0
	v_mbcnt_lo_u32_b32 v1, s44, 0
	v_readlane_b32 s3, v252, 1
	s_add_u32 s6, s2, s0
	v_mbcnt_hi_u32_b32 v1, s45, v1
	s_addc_u32 s7, s3, 0
	v_cmp_eq_u32_e32 vcc, 0, v1
	s_and_saveexec_b64 s[46:47], vcc
	s_cbranch_execz .LBB0_1027
	s_bcnt1_i32_b64 s0, s[44:45]
	v_mov_b32_e32 v4, s0
	v_mov_b32_e32 v5, 0x1000
	global_atomic_add v4, v5, v4, s[6:7] offset:1024 sc0
.LBB0_1027:
	s_or_b64 exec, exec, s[46:47]
	v_cvt_f32_u32_e32 v5, v2
	s_waitcnt vmcnt(0)
	v_readfirstlane_b32 s0, v4
	v_sub_u32_e32 v4, 0, v2
	v_rcp_iflag_f32_e32 v5, v5
	v_add_u32_e32 v6, s0, v1
	v_mul_f32_e32 v5, 0x4f7ffffe, v5
	v_cvt_u32_f32_e32 v5, v5
	v_mul_lo_u32 v1, v4, v5
	v_mul_hi_u32 v1, v5, v1
	v_add_u32_e32 v1, v5, v1
	v_mul_hi_u32 v1, v6, v1
	v_mul_lo_u32 v4, v1, v2
	v_sub_u32_e32 v4, v6, v4
	v_add_u32_e32 v5, 1, v1
	v_cmp_ge_u32_e32 vcc, v4, v2
	s_nop 1
	v_cndmask_b32_e32 v1, v1, v5, vcc
	v_sub_u32_e32 v5, v4, v2
	v_cndmask_b32_e32 v4, v4, v5, vcc
	v_add_u32_e32 v5, 1, v1
	v_cmp_ge_u32_e32 vcc, v4, v2
	v_add_u32_e32 v4, 1, v6
	s_nop 0
	v_cndmask_b32_e32 v1, v1, v5, vcc
	v_mul_lo_u32 v5, v2, v1
	v_add_u32_e32 v2, v5, v2
	v_cmp_ne_u32_e32 vcc, v4, v2
	s_and_saveexec_b64 s[0:1], vcc
	s_xor_b64 s[44:45], exec, s[0:1]
	s_cbranch_execz .LBB0_1041
	s_waitcnt lgkmcnt(0)
	global_load_dword v0, v182, s[6:7] offset:1024 sc1
	s_add_u32 s48, s6, 0x2400
	s_addc_u32 s49, s7, 0
	s_waitcnt vmcnt(0)
	v_cmp_eq_u32_e32 vcc, v0, v1
	s_and_saveexec_b64 s[46:47], vcc
	s_cbranch_execz .LBB0_1040
	s_mov_b32 s0, 1
	s_mov_b64 s[50:51], 0
	s_branch .LBB0_1031

.LBB0_1081:
	s_waitcnt vmcnt(0)
	s_barrier
	s_mov_b64 s[4:5], exec
	v_readlane_b32 s0, v252, 2
	v_readlane_b32 s1, v252, 3
	s_and_b64 s[0:1], s[4:5], s[0:1]
	s_mov_b64 exec, s[0:1]
	s_cbranch_execz .LBB0_1133
	v_mov_b32_e32 v0, 0x20000
	ds_read_b64 v[0:1], v0
	s_getreg_b32 s44, hwreg(HW_REG_XCC_ID, 0, 4)
	s_lshl_b32 s44, s44, 7
	s_add_u32 s44, s44, 0xdc03600
	v_mov_b32_e32 v2, s44
	v_mov_b32_e32 v4, 1
	s_waitcnt vmcnt(0) lgkmcnt(0)
	global_atomic_add v5, v2, v4, s[42:43] sc0
	buffer_inv sc1
	s_add_u32 s100, s100, 1
	v_readfirstlane_b32 s46, v0
	v_readfirstlane_b32 s47, v1
	v_mov_b32_e32 v2, 0xdc03e00
	s_nop 3
	s_mul_i32 s48, s46, s100
	s_mul_i32 s49, s47, s100
	s_waitcnt vmcnt(1)
	v_readfirstlane_b32 s50, v5
	s_nop 3
	s_add_u32 s50, s50, 1
	s_cmp_lg_u32 s50, s48
	s_cbranch_scc1 .Lxb10_poll
	buffer_wbl2 sc1
	s_waitcnt vmcnt(0)
	global_atomic_add v2, v4, s[42:43]

.LBB0_1097:
	s_mov_b64 s[44:45], exec
	s_lshl_b32 s0, s0, 8
	v_readlane_b32 s2, v252, 0
	v_mbcnt_lo_u32_b32 v1, s44, 0
	v_readlane_b32 s3, v252, 1
	s_add_u32 s6, s2, s0
	v_mbcnt_hi_u32_b32 v1, s45, v1
	s_addc_u32 s7, s3, 0
	v_cmp_eq_u32_e32 vcc, 0, v1
	s_and_saveexec_b64 s[46:47], vcc
	s_cbranch_execz .LBB0_1099
	s_bcnt1_i32_b64 s0, s[44:45]
	v_mov_b32_e32 v4, s0
	v_mov_b32_e32 v5, 0x1000
	global_atomic_add v4, v5, v4, s[6:7] offset:1024 sc0
.LBB0_1099:
	s_or_b64 exec, exec, s[46:47]
	v_cvt_f32_u32_e32 v5, v2
	s_waitcnt vmcnt(0)
	v_readfirstlane_b32 s0, v4
	v_sub_u32_e32 v4, 0, v2
	v_rcp_iflag_f32_e32 v5, v5
	v_add_u32_e32 v6, s0, v1
	v_mul_f32_e32 v5, 0x4f7ffffe, v5
	v_cvt_u32_f32_e32 v5, v5
	v_mul_lo_u32 v1, v4, v5
	v_mul_hi_u32 v1, v5, v1
	v_add_u32_e32 v1, v5, v1
	v_mul_hi_u32 v1, v6, v1
	v_mul_lo_u32 v4, v1, v2
	v_sub_u32_e32 v4, v6, v4
	v_add_u32_e32 v5, 1, v1
	v_cmp_ge_u32_e32 vcc, v4, v2
	s_nop 1
	v_cndmask_b32_e32 v1, v1, v5, vcc
	v_sub_u32_e32 v5, v4, v2
	v_cndmask_b32_e32 v4, v4, v5, vcc
	v_add_u32_e32 v5, 1, v1
	v_cmp_ge_u32_e32 vcc, v4, v2
	v_add_u32_e32 v4, 1, v6
	s_nop 0
	v_cndmask_b32_e32 v1, v1, v5, vcc
	v_mul_lo_u32 v5, v2, v1
	v_add_u32_e32 v2, v5, v2
	v_cmp_ne_u32_e32 vcc, v4, v2
	s_and_saveexec_b64 s[0:1], vcc
	s_xor_b64 s[44:45], exec, s[0:1]
	s_cbranch_execz .LBB0_1113
	s_waitcnt lgkmcnt(0)
	global_load_dword v0, v182, s[6:7] offset:1024 sc1
	s_add_u32 s48, s6, 0x2400
	s_addc_u32 s49, s7, 0
	s_waitcnt vmcnt(0)
	v_cmp_eq_u32_e32 vcc, v0, v1
	s_and_saveexec_b64 s[46:47], vcc
	s_cbranch_execz .LBB0_1112
	s_mov_b32 s0, 1
	s_mov_b64 s[50:51], 0
	s_branch .LBB0_1103

.Lxb11_far:
	s_getpc_b64 s[98:99]

.LBB0_1246:
	v_mov_b32_e32 v0, 0x20000
	ds_read_b64 v[0:1], v0
	s_getreg_b32 s44, hwreg(HW_REG_XCC_ID, 0, 4)
	s_lshl_b32 s44, s44, 7
	s_add_u32 s44, s44, 0xdc03600
	v_mov_b32_e32 v2, s44
	v_mov_b32_e32 v4, 1
	s_waitcnt vmcnt(0) lgkmcnt(0)
	global_atomic_add v5, v2, v4, s[42:43] sc0
	buffer_inv sc1
	s_add_u32 s100, s100, 1
	v_readfirstlane_b32 s46, v0
	v_readfirstlane_b32 s47, v1
	v_mov_b32_e32 v2, 0xdc03e00
	s_nop 3
	s_mul_i32 s48, s46, s100
	s_mul_i32 s49, s47, s100
	s_waitcnt vmcnt(1)
	v_readfirstlane_b32 s50, v5
	s_nop 3
	s_add_u32 s50, s50, 1
	s_cmp_lg_u32 s50, s48
	s_cbranch_scc1 .Lxb11_poll
	buffer_wbl2 sc1
	s_waitcnt vmcnt(0)
	global_atomic_add v2, v4, s[42:43]

.LBB0_1261:
	s_mov_b64 s[8:9], exec
	s_lshl_b32 s0, s0, 8
	v_readlane_b32 s2, v252, 0
	v_mbcnt_lo_u32_b32 v1, s8, 0
	v_readlane_b32 s3, v252, 1
	s_add_u32 s6, s2, s0
	v_mbcnt_hi_u32_b32 v1, s9, v1
	s_addc_u32 s7, s3, 0
	v_cmp_eq_u32_e32 vcc, 0, v1
	s_and_saveexec_b64 s[44:45], vcc
	s_cbranch_execz .LBB0_1263
	s_bcnt1_i32_b64 s0, s[8:9]
	v_mov_b32_e32 v4, s0
	v_mov_b32_e32 v5, 0x1000
	global_atomic_add v4, v5, v4, s[6:7] offset:1024 sc0
.LBB0_1263:
	s_or_b64 exec, exec, s[44:45]
	v_cvt_f32_u32_e32 v5, v2
	s_waitcnt vmcnt(0)
	v_readfirstlane_b32 s0, v4
	v_sub_u32_e32 v4, 0, v2
	v_rcp_iflag_f32_e32 v5, v5
	v_add_u32_e32 v6, s0, v1
	v_mul_f32_e32 v5, 0x4f7ffffe, v5
	v_cvt_u32_f32_e32 v5, v5
	v_mul_lo_u32 v1, v4, v5
	v_mul_hi_u32 v1, v5, v1
	v_add_u32_e32 v1, v5, v1
	v_mul_hi_u32 v1, v6, v1
	v_mul_lo_u32 v4, v1, v2
	v_sub_u32_e32 v4, v6, v4
	v_add_u32_e32 v5, 1, v1
	v_cmp_ge_u32_e32 vcc, v4, v2
	s_nop 1
	v_cndmask_b32_e32 v1, v1, v5, vcc
	v_sub_u32_e32 v5, v4, v2
	v_cndmask_b32_e32 v4, v4, v5, vcc
	v_add_u32_e32 v5, 1, v1
	v_cmp_ge_u32_e32 vcc, v4, v2
	v_add_u32_e32 v4, 1, v6
	s_nop 0
	v_cndmask_b32_e32 v1, v1, v5, vcc
	v_mul_lo_u32 v5, v2, v1
	v_add_u32_e32 v2, v5, v2
	v_cmp_ne_u32_e32 vcc, v4, v2
	s_and_saveexec_b64 s[0:1], vcc
	s_xor_b64 s[8:9], exec, s[0:1]
	s_cbranch_execz .LBB0_1277
	s_waitcnt lgkmcnt(0)
	global_load_dword v0, v182, s[6:7] offset:1024 sc1
	s_add_u32 s46, s6, 0x2400
	s_addc_u32 s47, s7, 0
	s_waitcnt vmcnt(0)
	v_cmp_eq_u32_e32 vcc, v0, v1
	s_and_saveexec_b64 s[44:45], vcc
	s_cbranch_execz .LBB0_1276
	s_mov_b32 s0, 1
	s_mov_b64 s[48:49], 0
	s_branch .LBB0_1267

.LBB0_1294:
	s_or_b64 exec, exec, s[8:9]
	s_mov_b64 s[8:9], exec
	v_mbcnt_lo_u32_b32 v0, s8, 0
	v_mbcnt_hi_u32_b32 v0, s9, v0
	v_cmp_eq_u32_e32 vcc, 0, v0
	s_waitcnt vmcnt(0)
	buffer_inv sc1
	s_and_saveexec_b64 s[44:45], vcc
	s_cbranch_execnz .LBB0_1295
	s_getpc_b64 s[98:99]

	.amdhsa_kernel _Z8yoco_fwd6Params
		.amdhsa_group_segment_fixed_size 0
		.amdhsa_private_segment_fixed_size 0
		.amdhsa_kernarg_size 352
		.amdhsa_user_sgpr_count 2
		.amdhsa_user_sgpr_dispatch_ptr 0
		.amdhsa_user_sgpr_queue_ptr 0
		.amdhsa_user_sgpr_kernarg_segment_ptr 1
		.amdhsa_user_sgpr_dispatch_id 0
		.amdhsa_user_sgpr_kernarg_preload_length 0
		.amdhsa_user_sgpr_kernarg_preload_offset 0
		.amdhsa_user_sgpr_private_segment_size 0
		.amdhsa_uses_dynamic_stack 0
		.amdhsa_enable_private_segment 0
		.amdhsa_system_sgpr_workgroup_id_x 1
		.amdhsa_system_sgpr_workgroup_id_y 0
		.amdhsa_system_sgpr_workgroup_id_z 0
		.amdhsa_system_sgpr_workgroup_info 0
		.amdhsa_system_vgpr_workitem_id 2
		.amdhsa_next_free_vgpr 256
		.amdhsa_next_free_sgpr 101
		.amdhsa_accum_offset 256
		.amdhsa_reserve_vcc 1
		.amdhsa_float_round_mode_32 0
		.amdhsa_float_round_mode_16_64 0
		.amdhsa_float_denorm_mode_32 3
		.amdhsa_float_denorm_mode_16_64 3
		.amdhsa_dx10_clamp 1
		.amdhsa_ieee_mode 1
		.amdhsa_fp16_overflow 0
		.amdhsa_tg_split 0
		.amdhsa_exception_fp_ieee_invalid_op 0
		.amdhsa_exception_fp_denorm_src 0
		.amdhsa_exception_fp_ieee_div_zero 0
		.amdhsa_exception_fp_ieee_overflow 0
		.amdhsa_exception_fp_ieee_underflow 0
		.amdhsa_exception_fp_ieee_inexact 0
		.amdhsa_exception_int_div_zero 0
	.end_amdhsa_kernel

amdhsa.kernels:
  - .agpr_count:     0
    .args:
      - .offset:         0
        .size:           96
        .value_kind:     by_value
      - .offset:         96
        .size:           4
        .value_kind:     hidden_block_count_x
      - .offset:         100
        .size:           4
        .value_kind:     hidden_block_count_y
      - .offset:         104
        .size:           4
        .value_kind:     hidden_block_count_z
      - .offset:         108
        .size:           2
        .value_kind:     hidden_group_size_x
      - .offset:         110
        .size:           2
        .value_kind:     hidden_group_size_y
      - .offset:         112
        .size:           2
        .value_kind:     hidden_group_size_z
      - .offset:         114
        .size:           2
        .value_kind:     hidden_remainder_x
      - .offset:         116
        .size:           2
        .value_kind:     hidden_remainder_y
      - .offset:         118
        .size:           2
        .value_kind:     hidden_remainder_z
      - .offset:         136
        .size:           8
        .value_kind:     hidden_global_offset_x
      - .offset:         144
        .size:           8
        .value_kind:     hidden_global_offset_y
      - .offset:         152
        .size:           8
        .value_kind:     hidden_global_offset_z
      - .offset:         160
        .size:           2
        .value_kind:     hidden_grid_dims
      - .offset:         184
        .size:           8
        .value_kind:     hidden_multigrid_sync_arg
      - .offset:         216
        .size:           4
        .value_kind:     hidden_dynamic_lds_size
    .group_segment_fixed_size: 0
    .kernarg_segment_align: 8
    .kernarg_segment_size: 352
    .language:       OpenCL C
    .language_version:
      - 2
      - 0
    .max_flat_workgroup_size: 512
    .name:           _Z8yoco_fwd6Params
    .private_segment_fixed_size: 0
    .sgpr_count:     107
    .sgpr_spill_count: 364
    .symbol:         _Z8yoco_fwd6Params.kd
    .uniform_work_group_size: 1
    .uses_dynamic_stack: false
    .vgpr_count:     256
    .vgpr_spill_count: 0
    .wavefront_size: 64
